# epilogue stores sc0 nt instead of nt
# speedup vs baseline: 1.0021x; 1.0021x over previous
.LBB0_99:
	s_lshr_b32 s8, s10, 1
	s_lshl_b32 s4, s4, 8
	s_and_b32 s9, s8, 64
	v_lshlrev_b32_e32 v140, 3, v140
	s_or_b32 s4, s9, s4
	v_and_or_b32 v140, s8, 32, v140
	s_lshl_b32 s8, s46, 6
	s_ashr_i32 s4, s4, 6
	s_waitcnt lgkmcnt(0)
	v_pk_mul_f32 v[122:123], v[122:123], v[164:165] op_sel_hi:[1,0]
	v_pk_mul_f32 v[120:121], v[120:121], v[164:165] op_sel_hi:[1,0]
	s_add_i32 s8, s4, s8
	v_pk_mul_f32 v[126:127], v[126:127], v[164:165] op_sel_hi:[1,0]
	v_pk_mul_f32 v[124:125], v[124:125], v[164:165] op_sel_hi:[1,0]
	v_max_f32_e32 v120, 0, v120
	v_max_f32_e32 v121, 0, v121
	v_max_f32_e32 v122, 0, v122
	s_ashr_i32 s9, s8, 31
	v_max_f32_e32 v124, 0, v124
	v_mul_f32_e32 v142, v120, v120
	v_max_f32_e32 v120, 0, v125
	v_mul_f32_e32 v125, v121, v121
	v_max_f32_e32 v121, 0, v126
	v_mul_f32_e32 v126, v122, v122
	v_max_f32_e32 v122, 0, v127
	s_lshl_b64 s[10:11], s[8:9], 15
	v_mul_f32_e32 v124, v124, v124
	v_mul_f32_e32 v120, v120, v120
	v_mul_f32_e32 v121, v121, v121
	v_max_f32_e32 v123, 0, v123
	v_mul_f32_e32 v122, v122, v122
	v_ashrrev_i32_e32 v159, 31, v158
	s_add_u32 s58, s86, s10
	v_mul_f32_e32 v123, v123, v123
	v_cvt_pk_bf16_f32 v120, v124, v120
	v_cvt_pk_bf16_f32 v121, v121, v122
	v_cvt_pk_bf16_f32 v122, v142, v125
	s_addc_u32 s59, s87, s11
	v_lshlrev_b64 v[124:125], 7, v[158:159]
	s_or_b32 s8, s8, 2
	v_cvt_pk_bf16_f32 v123, v126, v123
	v_lshl_add_u64 v[126:127], s[58:59], 0, v[124:125]
	v_lshlrev_b32_e32 v140, 1, v140
	v_pk_mul_f32 v[114:115], v[114:115], v[164:165] op_sel_hi:[1,0]
	v_pk_mul_f32 v[112:113], v[112:113], v[164:165] op_sel_hi:[1,0]
	s_ashr_i32 s9, s8, 31
	v_lshl_add_u64 v[126:127], v[126:127], 0, v[140:141]
	v_pk_mul_f32 v[118:119], v[118:119], v[164:165] op_sel_hi:[1,0]
	v_pk_mul_f32 v[116:117], v[116:117], v[164:165] op_sel_hi:[1,0]
	v_max_f32_e32 v112, 0, v112
	v_max_f32_e32 v113, 0, v113
	v_max_f32_e32 v114, 0, v114
	s_lshl_b64 s[8:9], s[8:9], 15
	ds_bpermute_b32 v172, v169, v120
	ds_bpermute_b32 v173, v169, v121
	ds_bpermute_b32 v174, v169, v122
	ds_bpermute_b32 v175, v169, v123
	v_lshl_add_u64 v[176:177], v[126:127], 0, v[170:171]
	v_max_f32_e32 v116, 0, v116
	s_add_u32 s74, s86, s8
	v_mul_f32_e32 v120, v112, v112
	v_max_f32_e32 v112, 0, v117
	v_mul_f32_e32 v117, v113, v113
	v_max_f32_e32 v113, 0, v118
	v_mul_f32_e32 v118, v114, v114
	v_max_f32_e32 v114, 0, v119
	v_mul_f32_e32 v116, v116, v116
	v_mul_f32_e32 v112, v112, v112
	v_mul_f32_e32 v113, v113, v113
	v_mul_f32_e32 v114, v114, v114
	s_addc_u32 s75, s87, s9
	v_max_f32_e32 v115, 0, v115
	v_cvt_pk_bf16_f32 v112, v116, v112
	v_cvt_pk_bf16_f32 v113, v113, v114
	v_cvt_pk_bf16_f32 v114, v120, v117
	v_lshl_add_u64 v[116:117], s[74:75], 0, v[124:125]
	v_mul_f32_e32 v115, v115, v115
	v_lshl_add_u64 v[116:117], v[116:117], 0, v[140:141]
	v_cvt_pk_bf16_f32 v115, v118, v115
	s_waitcnt lgkmcnt(0)
	global_store_dwordx4 v[176:177], v[172:175], off sc0 nt
	ds_bpermute_b32 v178, v169, v112
	ds_bpermute_b32 v179, v169, v113
	ds_bpermute_b32 v180, v169, v114
	ds_bpermute_b32 v181, v169, v115
	v_lshl_add_u64 v[182:183], v[116:117], 0, v[170:171]
	v_or_b32_e32 v116, 16, v162
	s_mov_b64 s[8:9], -1
	s_and_b64 vcc, exec, s[6:7]
	v_subrev_u32_e32 v113, s5, v116
	v_mov_b32_e32 v198, v220
	v_mov_b32_e32 v199, v221
	v_mov_b32_e32 v205, v223
	v_mov_b32_e32 v196, v224
	s_cbranch_vccz .LBB0_101
	v_ashrrev_i32_e32 v117, 31, v116
	v_lshlrev_b64 v[114:115], 6, v[116:117]
	v_lshl_add_u64 v[114:115], s[44:45], 0, v[114:115]
	v_mov_b32_e32 v161, v141
	v_lshl_add_u64 v[114:115], v[114:115], 0, v[160:161]
	flat_load_dwordx4 v[118:121], v[114:115]
	s_mov_b64 s[8:9], 0
	s_waitcnt vmcnt(0) lgkmcnt(0)
	v_mov_b32_e32 v114, v119
	v_mov_b32_e32 v115, v120
	v_mov_b32_e32 v119, v121
	v_pk_add_f32 v[114:115], v[114:115], v[118:119]
	s_nop 0
	v_add_f32_e32 v112, v114, v115
	ds_bpermute_b32 v114, v168, v112
	s_waitcnt lgkmcnt(0)
	v_add_f32_e32 v112, v112, v114
	ds_bpermute_b32 v114, v167, v112
	s_waitcnt lgkmcnt(0)
	v_add_f32_e32 v112, v112, v114
	v_fmamk_f32 v112, v112, 0x3a800000, v250
	v_rsq_f32_e32 v112, v112
	v_subrev_u32_e32 v114, s5, v116

.LBB0_103:
	s_waitcnt lgkmcnt(0)
	v_pk_mul_f32 v[106:107], v[106:107], v[112:113] op_sel_hi:[1,0]
	v_pk_mul_f32 v[104:105], v[104:105], v[112:113] op_sel_hi:[1,0]
	v_pk_mul_f32 v[110:111], v[110:111], v[112:113] op_sel_hi:[1,0]
	v_pk_mul_f32 v[108:109], v[108:109], v[112:113] op_sel_hi:[1,0]
	v_max_f32_e32 v104, 0, v104
	v_max_f32_e32 v105, 0, v105
	v_max_f32_e32 v106, 0, v106
	v_max_f32_e32 v108, 0, v108
	v_mul_f32_e32 v113, v104, v104
	v_max_f32_e32 v104, 0, v109
	v_mul_f32_e32 v109, v105, v105
	v_max_f32_e32 v105, 0, v110
	v_mul_f32_e32 v110, v106, v106
	v_max_f32_e32 v106, 0, v111
	v_mul_f32_e32 v108, v108, v108
	v_mul_f32_e32 v104, v104, v104
	v_mul_f32_e32 v105, v105, v105
	v_max_f32_e32 v107, 0, v107
	v_mul_f32_e32 v106, v106, v106
	v_ashrrev_i32_e32 v115, 31, v114
	v_mul_f32_e32 v107, v107, v107
	v_cvt_pk_bf16_f32 v104, v108, v104
	v_cvt_pk_bf16_f32 v105, v105, v106
	v_cvt_pk_bf16_f32 v106, v113, v109
	v_lshlrev_b64 v[108:109], 7, v[114:115]
	v_cvt_pk_bf16_f32 v107, v110, v107
	v_lshl_add_u64 v[110:111], s[58:59], 0, v[108:109]
	v_pk_mul_f32 v[98:99], v[98:99], v[112:113] op_sel_hi:[1,0]
	v_pk_mul_f32 v[96:97], v[96:97], v[112:113] op_sel_hi:[1,0]
	v_lshl_add_u64 v[110:111], v[110:111], 0, v[140:141]
	v_pk_mul_f32 v[102:103], v[102:103], v[112:113] op_sel_hi:[1,0]
	v_pk_mul_f32 v[100:101], v[100:101], v[112:113] op_sel_hi:[1,0]
	v_max_f32_e32 v96, 0, v96
	v_max_f32_e32 v97, 0, v97
	v_max_f32_e32 v98, 0, v98
	s_waitcnt lgkmcnt(0)
	global_store_dwordx4 v[182:183], v[178:181], off sc0 nt
	ds_bpermute_b32 v172, v169, v104
	ds_bpermute_b32 v173, v169, v105
	ds_bpermute_b32 v174, v169, v106
	ds_bpermute_b32 v175, v169, v107
	v_lshl_add_u64 v[176:177], v[110:111], 0, v[170:171]
	v_max_f32_e32 v100, 0, v100
	v_mul_f32_e32 v100, v100, v100
	v_mul_f32_e32 v104, v96, v96
	v_max_f32_e32 v96, 0, v101
	v_mul_f32_e32 v101, v97, v97
	v_max_f32_e32 v97, 0, v102
	v_mul_f32_e32 v102, v98, v98
	v_max_f32_e32 v98, 0, v103
	v_mul_f32_e32 v96, v96, v96
	v_mul_f32_e32 v97, v97, v97
	v_mul_f32_e32 v98, v98, v98
	v_max_f32_e32 v99, 0, v99
	v_cvt_pk_bf16_f32 v96, v100, v96
	v_cvt_pk_bf16_f32 v97, v97, v98
	v_cvt_pk_bf16_f32 v98, v104, v101
	v_lshl_add_u64 v[100:101], s[74:75], 0, v[108:109]
	v_mul_f32_e32 v99, v99, v99
	v_lshl_add_u64 v[100:101], v[100:101], 0, v[140:141]
	v_cvt_pk_bf16_f32 v99, v102, v99
	s_waitcnt lgkmcnt(0)
	global_store_dwordx4 v[176:177], v[172:175], off sc0 nt
	ds_bpermute_b32 v178, v169, v96
	ds_bpermute_b32 v179, v169, v97
	ds_bpermute_b32 v180, v169, v98
	ds_bpermute_b32 v181, v169, v99
	v_lshl_add_u64 v[182:183], v[100:101], 0, v[170:171]
	v_or_b32_e32 v100, 32, v162
	s_mov_b64 s[8:9], -1
	s_and_b64 vcc, exec, s[6:7]
	v_subrev_u32_e32 v97, s5, v100
	s_cbranch_vccz .LBB0_105
	v_ashrrev_i32_e32 v101, 31, v100
	v_lshlrev_b64 v[98:99], 6, v[100:101]
	v_lshl_add_u64 v[98:99], s[44:45], 0, v[98:99]
	v_mov_b32_e32 v161, v141
	v_lshl_add_u64 v[98:99], v[98:99], 0, v[160:161]
	flat_load_dwordx4 v[102:105], v[98:99]
	s_mov_b64 s[8:9], 0
	s_waitcnt vmcnt(0) lgkmcnt(0)
	v_mov_b32_e32 v98, v103
	v_mov_b32_e32 v99, v104
	v_mov_b32_e32 v103, v105
	v_pk_add_f32 v[98:99], v[98:99], v[102:103]
	s_nop 0
	v_add_f32_e32 v96, v98, v99
	ds_bpermute_b32 v98, v168, v96
	s_waitcnt lgkmcnt(0)
	v_add_f32_e32 v96, v96, v98
	ds_bpermute_b32 v98, v167, v96
	s_waitcnt lgkmcnt(0)
	v_add_f32_e32 v96, v96, v98
	v_fmamk_f32 v96, v96, 0x3a800000, v250
	v_rsq_f32_e32 v96, v96
	v_subrev_u32_e32 v98, s5, v100

.LBB0_107:
	s_waitcnt lgkmcnt(0)
	v_pk_mul_f32 v[90:91], v[90:91], v[96:97] op_sel_hi:[1,0]
	v_pk_mul_f32 v[88:89], v[88:89], v[96:97] op_sel_hi:[1,0]
	v_pk_mul_f32 v[94:95], v[94:95], v[96:97] op_sel_hi:[1,0]
	v_pk_mul_f32 v[92:93], v[92:93], v[96:97] op_sel_hi:[1,0]
	v_max_f32_e32 v88, 0, v88
	v_max_f32_e32 v89, 0, v89
	v_max_f32_e32 v90, 0, v90
	v_max_f32_e32 v92, 0, v92
	v_mul_f32_e32 v97, v88, v88
	v_max_f32_e32 v88, 0, v93
	v_mul_f32_e32 v93, v89, v89
	v_max_f32_e32 v89, 0, v94
	v_mul_f32_e32 v94, v90, v90
	v_max_f32_e32 v90, 0, v95
	v_mul_f32_e32 v92, v92, v92
	v_mul_f32_e32 v88, v88, v88
	v_mul_f32_e32 v89, v89, v89
	v_max_f32_e32 v91, 0, v91
	v_mul_f32_e32 v90, v90, v90
	v_ashrrev_i32_e32 v99, 31, v98
	v_mul_f32_e32 v91, v91, v91
	v_cvt_pk_bf16_f32 v88, v92, v88
	v_cvt_pk_bf16_f32 v89, v89, v90
	v_cvt_pk_bf16_f32 v90, v97, v93
	v_lshlrev_b64 v[92:93], 7, v[98:99]
	v_cvt_pk_bf16_f32 v91, v94, v91
	v_lshl_add_u64 v[94:95], s[58:59], 0, v[92:93]
	v_pk_mul_f32 v[82:83], v[82:83], v[96:97] op_sel_hi:[1,0]
	v_pk_mul_f32 v[80:81], v[80:81], v[96:97] op_sel_hi:[1,0]
	v_lshl_add_u64 v[94:95], v[94:95], 0, v[140:141]
	v_pk_mul_f32 v[86:87], v[86:87], v[96:97] op_sel_hi:[1,0]
	v_pk_mul_f32 v[84:85], v[84:85], v[96:97] op_sel_hi:[1,0]
	v_max_f32_e32 v80, 0, v80
	v_max_f32_e32 v81, 0, v81
	v_max_f32_e32 v82, 0, v82
	s_waitcnt lgkmcnt(0)
	global_store_dwordx4 v[182:183], v[178:181], off sc0 nt
	ds_bpermute_b32 v172, v169, v88
	ds_bpermute_b32 v173, v169, v89
	ds_bpermute_b32 v174, v169, v90
	ds_bpermute_b32 v175, v169, v91
	v_lshl_add_u64 v[176:177], v[94:95], 0, v[170:171]
	v_max_f32_e32 v84, 0, v84
	v_mul_f32_e32 v84, v84, v84
	v_mul_f32_e32 v88, v80, v80
	v_max_f32_e32 v80, 0, v85
	v_mul_f32_e32 v85, v81, v81
	v_max_f32_e32 v81, 0, v86
	v_mul_f32_e32 v86, v82, v82
	v_max_f32_e32 v82, 0, v87
	v_mul_f32_e32 v80, v80, v80
	v_mul_f32_e32 v81, v81, v81
	v_mul_f32_e32 v82, v82, v82
	v_max_f32_e32 v83, 0, v83
	v_cvt_pk_bf16_f32 v80, v84, v80
	v_cvt_pk_bf16_f32 v81, v81, v82
	v_cvt_pk_bf16_f32 v82, v88, v85
	v_lshl_add_u64 v[84:85], s[74:75], 0, v[92:93]
	v_mul_f32_e32 v83, v83, v83
	v_lshl_add_u64 v[84:85], v[84:85], 0, v[140:141]
	v_cvt_pk_bf16_f32 v83, v86, v83
	s_waitcnt lgkmcnt(0)
	global_store_dwordx4 v[176:177], v[172:175], off sc0 nt
	ds_bpermute_b32 v178, v169, v80
	ds_bpermute_b32 v179, v169, v81
	ds_bpermute_b32 v180, v169, v82
	ds_bpermute_b32 v181, v169, v83
	v_lshl_add_u64 v[182:183], v[84:85], 0, v[170:171]
	v_or_b32_e32 v84, 48, v162
	s_mov_b64 s[8:9], -1
	s_and_b64 vcc, exec, s[6:7]
	v_subrev_u32_e32 v81, s5, v84
	s_cbranch_vccz .LBB0_109
	v_ashrrev_i32_e32 v85, 31, v84
	v_lshlrev_b64 v[82:83], 6, v[84:85]
	v_lshl_add_u64 v[82:83], s[44:45], 0, v[82:83]
	v_mov_b32_e32 v161, v141
	v_lshl_add_u64 v[82:83], v[82:83], 0, v[160:161]
	flat_load_dwordx4 v[86:89], v[82:83]
	s_mov_b64 s[8:9], 0
	s_waitcnt vmcnt(0) lgkmcnt(0)
	v_mov_b32_e32 v82, v87
	v_mov_b32_e32 v83, v88
	v_mov_b32_e32 v87, v89
	v_pk_add_f32 v[82:83], v[82:83], v[86:87]
	s_nop 0
	v_add_f32_e32 v80, v82, v83
	ds_bpermute_b32 v82, v168, v80
	s_waitcnt lgkmcnt(0)
	v_add_f32_e32 v80, v80, v82
	ds_bpermute_b32 v82, v167, v80
	s_waitcnt lgkmcnt(0)
	v_add_f32_e32 v80, v80, v82
	v_fmamk_f32 v80, v80, 0x3a800000, v250
	v_rsq_f32_e32 v80, v80
	v_subrev_u32_e32 v82, s5, v84

.LBB0_111:
	s_waitcnt lgkmcnt(0)
	v_pk_mul_f32 v[74:75], v[74:75], v[80:81] op_sel_hi:[1,0]
	v_pk_mul_f32 v[72:73], v[72:73], v[80:81] op_sel_hi:[1,0]
	v_pk_mul_f32 v[78:79], v[78:79], v[80:81] op_sel_hi:[1,0]
	v_pk_mul_f32 v[76:77], v[76:77], v[80:81] op_sel_hi:[1,0]
	v_max_f32_e32 v72, 0, v72
	v_max_f32_e32 v73, 0, v73
	v_max_f32_e32 v74, 0, v74
	v_max_f32_e32 v76, 0, v76
	v_mul_f32_e32 v81, v72, v72
	v_max_f32_e32 v72, 0, v77
	v_mul_f32_e32 v77, v73, v73
	v_max_f32_e32 v73, 0, v78
	v_mul_f32_e32 v78, v74, v74
	v_max_f32_e32 v74, 0, v79
	v_mul_f32_e32 v76, v76, v76
	v_mul_f32_e32 v72, v72, v72
	v_mul_f32_e32 v73, v73, v73
	v_max_f32_e32 v75, 0, v75
	v_mul_f32_e32 v74, v74, v74
	v_ashrrev_i32_e32 v83, 31, v82
	v_mul_f32_e32 v75, v75, v75
	v_cvt_pk_bf16_f32 v72, v76, v72
	v_cvt_pk_bf16_f32 v73, v73, v74
	v_cvt_pk_bf16_f32 v74, v81, v77
	v_lshlrev_b64 v[76:77], 7, v[82:83]
	v_cvt_pk_bf16_f32 v75, v78, v75
	v_lshl_add_u64 v[78:79], s[58:59], 0, v[76:77]
	v_pk_mul_f32 v[66:67], v[66:67], v[80:81] op_sel_hi:[1,0]
	v_pk_mul_f32 v[64:65], v[64:65], v[80:81] op_sel_hi:[1,0]
	v_lshl_add_u64 v[78:79], v[78:79], 0, v[140:141]
	v_pk_mul_f32 v[70:71], v[70:71], v[80:81] op_sel_hi:[1,0]
	v_pk_mul_f32 v[68:69], v[68:69], v[80:81] op_sel_hi:[1,0]
	v_max_f32_e32 v64, 0, v64
	v_max_f32_e32 v65, 0, v65
	v_max_f32_e32 v66, 0, v66
	s_waitcnt lgkmcnt(0)
	global_store_dwordx4 v[182:183], v[178:181], off sc0 nt
	ds_bpermute_b32 v172, v169, v72
	ds_bpermute_b32 v173, v169, v73
	ds_bpermute_b32 v174, v169, v74
	ds_bpermute_b32 v175, v169, v75
	v_lshl_add_u64 v[176:177], v[78:79], 0, v[170:171]
	v_max_f32_e32 v68, 0, v68
	v_mul_f32_e32 v68, v68, v68
	v_mul_f32_e32 v72, v64, v64
	v_max_f32_e32 v64, 0, v69
	v_mul_f32_e32 v69, v65, v65
	v_max_f32_e32 v65, 0, v70
	v_mul_f32_e32 v70, v66, v66
	v_max_f32_e32 v66, 0, v71
	v_mul_f32_e32 v64, v64, v64
	v_mul_f32_e32 v65, v65, v65
	v_mul_f32_e32 v66, v66, v66
	v_max_f32_e32 v67, 0, v67
	v_cvt_pk_bf16_f32 v64, v68, v64
	v_cvt_pk_bf16_f32 v65, v65, v66
	v_cvt_pk_bf16_f32 v66, v72, v69
	v_lshl_add_u64 v[68:69], s[74:75], 0, v[76:77]
	v_mul_f32_e32 v67, v67, v67
	v_lshl_add_u64 v[68:69], v[68:69], 0, v[140:141]
	v_cvt_pk_bf16_f32 v67, v70, v67
	s_waitcnt lgkmcnt(0)
	global_store_dwordx4 v[176:177], v[172:175], off sc0 nt
	ds_bpermute_b32 v178, v169, v64
	ds_bpermute_b32 v179, v169, v65
	ds_bpermute_b32 v180, v169, v66
	ds_bpermute_b32 v181, v169, v67
	v_lshl_add_u64 v[182:183], v[68:69], 0, v[170:171]
	v_add_u32_e32 v68, 0x80, v162
	s_mov_b64 s[8:9], -1
	s_and_b64 vcc, exec, s[6:7]
	v_subrev_u32_e32 v65, s5, v68
	s_cbranch_vccz .LBB0_113
	v_ashrrev_i32_e32 v69, 31, v68
	v_lshlrev_b64 v[66:67], 6, v[68:69]
	v_lshl_add_u64 v[66:67], s[44:45], 0, v[66:67]
	v_mov_b32_e32 v161, v141
	v_lshl_add_u64 v[66:67], v[66:67], 0, v[160:161]
	flat_load_dwordx4 v[70:73], v[66:67]
	s_mov_b64 s[8:9], 0
	s_waitcnt vmcnt(0) lgkmcnt(0)
	v_mov_b32_e32 v66, v71
	v_mov_b32_e32 v67, v72
	v_mov_b32_e32 v71, v73
	v_pk_add_f32 v[66:67], v[66:67], v[70:71]
	s_nop 0
	v_add_f32_e32 v64, v66, v67
	ds_bpermute_b32 v66, v168, v64
	s_waitcnt lgkmcnt(0)
	v_add_f32_e32 v64, v64, v66
	ds_bpermute_b32 v66, v167, v64
	s_waitcnt lgkmcnt(0)
	v_add_f32_e32 v64, v64, v66
	v_fmamk_f32 v64, v64, 0x3a800000, v250
	v_rsq_f32_e32 v64, v64
	v_subrev_u32_e32 v66, s5, v68

.LBB0_115:
	s_waitcnt lgkmcnt(0)
	v_pk_mul_f32 v[58:59], v[58:59], v[64:65] op_sel_hi:[1,0]
	v_pk_mul_f32 v[56:57], v[56:57], v[64:65] op_sel_hi:[1,0]
	v_pk_mul_f32 v[62:63], v[62:63], v[64:65] op_sel_hi:[1,0]
	v_pk_mul_f32 v[60:61], v[60:61], v[64:65] op_sel_hi:[1,0]
	v_max_f32_e32 v56, 0, v56
	v_max_f32_e32 v57, 0, v57
	v_max_f32_e32 v58, 0, v58
	v_max_f32_e32 v60, 0, v60
	v_mul_f32_e32 v65, v56, v56
	v_max_f32_e32 v56, 0, v61
	v_mul_f32_e32 v61, v57, v57
	v_max_f32_e32 v57, 0, v62
	v_mul_f32_e32 v62, v58, v58
	v_max_f32_e32 v58, 0, v63
	v_mul_f32_e32 v60, v60, v60
	v_mul_f32_e32 v56, v56, v56
	v_mul_f32_e32 v57, v57, v57
	v_max_f32_e32 v59, 0, v59
	v_mul_f32_e32 v58, v58, v58
	v_ashrrev_i32_e32 v67, 31, v66
	v_mul_f32_e32 v59, v59, v59
	v_cvt_pk_bf16_f32 v56, v60, v56
	v_cvt_pk_bf16_f32 v57, v57, v58
	v_cvt_pk_bf16_f32 v58, v65, v61
	v_lshlrev_b64 v[60:61], 7, v[66:67]
	v_cvt_pk_bf16_f32 v59, v62, v59
	v_lshl_add_u64 v[62:63], s[58:59], 0, v[60:61]
	v_pk_mul_f32 v[50:51], v[50:51], v[64:65] op_sel_hi:[1,0]
	v_pk_mul_f32 v[48:49], v[48:49], v[64:65] op_sel_hi:[1,0]
	v_lshl_add_u64 v[62:63], v[62:63], 0, v[140:141]
	v_pk_mul_f32 v[54:55], v[54:55], v[64:65] op_sel_hi:[1,0]
	v_pk_mul_f32 v[52:53], v[52:53], v[64:65] op_sel_hi:[1,0]
	v_max_f32_e32 v48, 0, v48
	v_max_f32_e32 v49, 0, v49
	v_max_f32_e32 v50, 0, v50
	s_waitcnt lgkmcnt(0)
	global_store_dwordx4 v[182:183], v[178:181], off sc0 nt
	ds_bpermute_b32 v172, v169, v56
	ds_bpermute_b32 v173, v169, v57
	ds_bpermute_b32 v174, v169, v58
	ds_bpermute_b32 v175, v169, v59
	v_lshl_add_u64 v[176:177], v[62:63], 0, v[170:171]
	v_max_f32_e32 v52, 0, v52
	v_mul_f32_e32 v52, v52, v52
	v_mul_f32_e32 v56, v48, v48
	v_max_f32_e32 v48, 0, v53
	v_mul_f32_e32 v53, v49, v49
	v_max_f32_e32 v49, 0, v54
	v_mul_f32_e32 v54, v50, v50
	v_max_f32_e32 v50, 0, v55
	v_mul_f32_e32 v48, v48, v48
	v_mul_f32_e32 v49, v49, v49
	v_mul_f32_e32 v50, v50, v50
	v_max_f32_e32 v51, 0, v51
	v_cvt_pk_bf16_f32 v48, v52, v48
	v_cvt_pk_bf16_f32 v49, v49, v50
	v_cvt_pk_bf16_f32 v50, v56, v53
	v_lshl_add_u64 v[52:53], s[74:75], 0, v[60:61]
	v_mul_f32_e32 v51, v51, v51
	v_lshl_add_u64 v[52:53], v[52:53], 0, v[140:141]
	v_cvt_pk_bf16_f32 v51, v54, v51
	s_waitcnt lgkmcnt(0)
	global_store_dwordx4 v[176:177], v[172:175], off sc0 nt
	ds_bpermute_b32 v178, v169, v48
	ds_bpermute_b32 v179, v169, v49
	ds_bpermute_b32 v180, v169, v50
	ds_bpermute_b32 v181, v169, v51
	v_lshl_add_u64 v[182:183], v[52:53], 0, v[170:171]
	v_add_u32_e32 v52, 0x90, v162
	s_mov_b64 s[8:9], -1
	s_and_b64 vcc, exec, s[6:7]
	v_subrev_u32_e32 v49, s5, v52
	s_cbranch_vccz .LBB0_117
	v_ashrrev_i32_e32 v53, 31, v52
	v_lshlrev_b64 v[50:51], 6, v[52:53]
	v_lshl_add_u64 v[50:51], s[44:45], 0, v[50:51]
	v_mov_b32_e32 v161, v141
	v_lshl_add_u64 v[50:51], v[50:51], 0, v[160:161]
	flat_load_dwordx4 v[54:57], v[50:51]
	s_mov_b64 s[8:9], 0
	s_waitcnt vmcnt(0) lgkmcnt(0)
	v_mov_b32_e32 v50, v55
	v_mov_b32_e32 v51, v56
	v_mov_b32_e32 v55, v57
	v_pk_add_f32 v[50:51], v[50:51], v[54:55]
	s_nop 0
	v_add_f32_e32 v48, v50, v51
	ds_bpermute_b32 v50, v168, v48
	s_waitcnt lgkmcnt(0)
	v_add_f32_e32 v48, v48, v50
	ds_bpermute_b32 v50, v167, v48
	s_waitcnt lgkmcnt(0)
	v_add_f32_e32 v48, v48, v50
	v_fmamk_f32 v48, v48, 0x3a800000, v250
	v_rsq_f32_e32 v48, v48
	v_subrev_u32_e32 v50, s5, v52

.LBB0_119:
	s_waitcnt lgkmcnt(0)
	v_pk_mul_f32 v[42:43], v[42:43], v[48:49] op_sel_hi:[1,0]
	v_pk_mul_f32 v[40:41], v[40:41], v[48:49] op_sel_hi:[1,0]
	v_pk_mul_f32 v[46:47], v[46:47], v[48:49] op_sel_hi:[1,0]
	v_pk_mul_f32 v[44:45], v[44:45], v[48:49] op_sel_hi:[1,0]
	v_max_f32_e32 v40, 0, v40
	v_max_f32_e32 v41, 0, v41
	v_max_f32_e32 v42, 0, v42
	v_max_f32_e32 v44, 0, v44
	v_mul_f32_e32 v49, v40, v40
	v_max_f32_e32 v40, 0, v45
	v_mul_f32_e32 v45, v41, v41
	v_max_f32_e32 v41, 0, v46
	v_mul_f32_e32 v46, v42, v42
	v_max_f32_e32 v42, 0, v47
	v_mul_f32_e32 v44, v44, v44
	v_mul_f32_e32 v40, v40, v40
	v_mul_f32_e32 v41, v41, v41
	v_max_f32_e32 v43, 0, v43
	v_mul_f32_e32 v42, v42, v42
	v_ashrrev_i32_e32 v51, 31, v50
	v_mul_f32_e32 v43, v43, v43
	v_cvt_pk_bf16_f32 v40, v44, v40
	v_cvt_pk_bf16_f32 v41, v41, v42
	v_cvt_pk_bf16_f32 v42, v49, v45
	v_lshlrev_b64 v[44:45], 7, v[50:51]
	v_cvt_pk_bf16_f32 v43, v46, v43
	v_lshl_add_u64 v[46:47], s[58:59], 0, v[44:45]
	v_pk_mul_f32 v[34:35], v[34:35], v[48:49] op_sel_hi:[1,0]
	v_pk_mul_f32 v[32:33], v[32:33], v[48:49] op_sel_hi:[1,0]
	v_lshl_add_u64 v[46:47], v[46:47], 0, v[140:141]
	v_pk_mul_f32 v[38:39], v[38:39], v[48:49] op_sel_hi:[1,0]
	v_pk_mul_f32 v[36:37], v[36:37], v[48:49] op_sel_hi:[1,0]
	v_max_f32_e32 v32, 0, v32
	v_max_f32_e32 v33, 0, v33
	v_max_f32_e32 v34, 0, v34
	s_waitcnt lgkmcnt(0)
	global_store_dwordx4 v[182:183], v[178:181], off sc0 nt
	ds_bpermute_b32 v172, v169, v40
	ds_bpermute_b32 v173, v169, v41
	ds_bpermute_b32 v174, v169, v42
	ds_bpermute_b32 v175, v169, v43
	v_lshl_add_u64 v[176:177], v[46:47], 0, v[170:171]
	v_max_f32_e32 v36, 0, v36
	v_mul_f32_e32 v36, v36, v36
	v_mul_f32_e32 v40, v32, v32
	v_max_f32_e32 v32, 0, v37
	v_mul_f32_e32 v37, v33, v33
	v_max_f32_e32 v33, 0, v38
	v_mul_f32_e32 v38, v34, v34
	v_max_f32_e32 v34, 0, v39
	v_mul_f32_e32 v32, v32, v32
	v_mul_f32_e32 v33, v33, v33
	v_mul_f32_e32 v34, v34, v34
	v_max_f32_e32 v35, 0, v35
	v_cvt_pk_bf16_f32 v32, v36, v32
	v_cvt_pk_bf16_f32 v33, v33, v34
	v_cvt_pk_bf16_f32 v34, v40, v37
	v_lshl_add_u64 v[36:37], s[74:75], 0, v[44:45]
	v_mul_f32_e32 v35, v35, v35
	v_lshl_add_u64 v[36:37], v[36:37], 0, v[140:141]
	v_cvt_pk_bf16_f32 v35, v38, v35
	s_waitcnt lgkmcnt(0)
	global_store_dwordx4 v[176:177], v[172:175], off sc0 nt
	ds_bpermute_b32 v178, v169, v32
	ds_bpermute_b32 v179, v169, v33
	ds_bpermute_b32 v180, v169, v34
	ds_bpermute_b32 v181, v169, v35
	v_lshl_add_u64 v[182:183], v[36:37], 0, v[170:171]
	v_add_u32_e32 v36, 0xa0, v162
	s_mov_b64 s[8:9], -1
	s_and_b64 vcc, exec, s[6:7]
	v_subrev_u32_e32 v33, s5, v36
	s_cbranch_vccz .LBB0_121
	v_ashrrev_i32_e32 v37, 31, v36
	v_lshlrev_b64 v[34:35], 6, v[36:37]
	v_lshl_add_u64 v[34:35], s[44:45], 0, v[34:35]
	v_mov_b32_e32 v161, v141
	v_lshl_add_u64 v[34:35], v[34:35], 0, v[160:161]
	flat_load_dwordx4 v[38:41], v[34:35]
	s_mov_b64 s[8:9], 0
	s_waitcnt vmcnt(0) lgkmcnt(0)
	v_mov_b32_e32 v34, v39
	v_mov_b32_e32 v35, v40
	v_mov_b32_e32 v39, v41
	v_pk_add_f32 v[34:35], v[34:35], v[38:39]
	s_nop 0
	v_add_f32_e32 v32, v34, v35
	ds_bpermute_b32 v34, v168, v32
	s_waitcnt lgkmcnt(0)
	v_add_f32_e32 v32, v32, v34
	ds_bpermute_b32 v34, v167, v32
	s_waitcnt lgkmcnt(0)
	v_add_f32_e32 v32, v32, v34
	v_fmamk_f32 v32, v32, 0x3a800000, v250
	v_rsq_f32_e32 v32, v32
	v_subrev_u32_e32 v34, s5, v36

.LBB0_123:
	s_waitcnt lgkmcnt(0)
	v_pk_mul_f32 v[26:27], v[26:27], v[32:33] op_sel_hi:[1,0]
	v_pk_mul_f32 v[24:25], v[24:25], v[32:33] op_sel_hi:[1,0]
	v_pk_mul_f32 v[30:31], v[30:31], v[32:33] op_sel_hi:[1,0]
	v_pk_mul_f32 v[28:29], v[28:29], v[32:33] op_sel_hi:[1,0]
	v_max_f32_e32 v24, 0, v24
	v_max_f32_e32 v25, 0, v25
	v_max_f32_e32 v26, 0, v26
	v_max_f32_e32 v28, 0, v28
	v_mul_f32_e32 v33, v24, v24
	v_max_f32_e32 v24, 0, v29
	v_mul_f32_e32 v29, v25, v25
	v_max_f32_e32 v25, 0, v30
	v_mul_f32_e32 v30, v26, v26
	v_max_f32_e32 v26, 0, v31
	v_mul_f32_e32 v28, v28, v28
	v_mul_f32_e32 v24, v24, v24
	v_mul_f32_e32 v25, v25, v25
	v_max_f32_e32 v27, 0, v27
	v_mul_f32_e32 v26, v26, v26
	v_ashrrev_i32_e32 v35, 31, v34
	v_mul_f32_e32 v27, v27, v27
	v_cvt_pk_bf16_f32 v24, v28, v24
	v_cvt_pk_bf16_f32 v25, v25, v26
	v_cvt_pk_bf16_f32 v26, v33, v29
	v_lshlrev_b64 v[28:29], 7, v[34:35]
	v_cvt_pk_bf16_f32 v27, v30, v27
	v_lshl_add_u64 v[30:31], s[58:59], 0, v[28:29]
	v_pk_mul_f32 v[18:19], v[18:19], v[32:33] op_sel_hi:[1,0]
	v_pk_mul_f32 v[16:17], v[16:17], v[32:33] op_sel_hi:[1,0]
	v_lshl_add_u64 v[30:31], v[30:31], 0, v[140:141]
	v_pk_mul_f32 v[22:23], v[22:23], v[32:33] op_sel_hi:[1,0]
	v_pk_mul_f32 v[20:21], v[20:21], v[32:33] op_sel_hi:[1,0]
	v_max_f32_e32 v16, 0, v16
	v_max_f32_e32 v17, 0, v17
	v_max_f32_e32 v18, 0, v18
	s_waitcnt lgkmcnt(0)
	global_store_dwordx4 v[182:183], v[178:181], off sc0 nt
	ds_bpermute_b32 v172, v169, v24
	ds_bpermute_b32 v173, v169, v25
	ds_bpermute_b32 v174, v169, v26
	ds_bpermute_b32 v175, v169, v27
	v_lshl_add_u64 v[176:177], v[30:31], 0, v[170:171]
	v_max_f32_e32 v20, 0, v20
	v_mul_f32_e32 v20, v20, v20
	v_mul_f32_e32 v24, v16, v16
	v_max_f32_e32 v16, 0, v21
	v_mul_f32_e32 v21, v17, v17
	v_max_f32_e32 v17, 0, v22
	v_mul_f32_e32 v22, v18, v18
	v_max_f32_e32 v18, 0, v23
	v_mul_f32_e32 v16, v16, v16
	v_mul_f32_e32 v17, v17, v17
	v_mul_f32_e32 v18, v18, v18
	v_max_f32_e32 v19, 0, v19
	v_cvt_pk_bf16_f32 v16, v20, v16
	v_cvt_pk_bf16_f32 v17, v17, v18
	v_cvt_pk_bf16_f32 v18, v24, v21
	v_lshl_add_u64 v[20:21], s[74:75], 0, v[28:29]
	v_mul_f32_e32 v19, v19, v19
	v_lshl_add_u64 v[20:21], v[20:21], 0, v[140:141]
	v_cvt_pk_bf16_f32 v19, v22, v19
	s_waitcnt lgkmcnt(0)
	global_store_dwordx4 v[176:177], v[172:175], off sc0 nt
	ds_bpermute_b32 v178, v169, v16
	ds_bpermute_b32 v179, v169, v17
	ds_bpermute_b32 v180, v169, v18
	ds_bpermute_b32 v181, v169, v19
	v_lshl_add_u64 v[182:183], v[20:21], 0, v[170:171]
	v_add_u32_e32 v20, 0xb0, v162
	s_mov_b64 s[8:9], -1
	s_and_b64 vcc, exec, s[6:7]
	v_subrev_u32_e32 v17, s5, v20
	s_cbranch_vccz .LBB0_125
	v_ashrrev_i32_e32 v21, 31, v20
	v_lshlrev_b64 v[18:19], 6, v[20:21]
	v_lshl_add_u64 v[18:19], s[44:45], 0, v[18:19]
	v_mov_b32_e32 v161, v141
	v_lshl_add_u64 v[18:19], v[18:19], 0, v[160:161]
	flat_load_dwordx4 v[22:25], v[18:19]
	s_mov_b64 s[8:9], 0
	s_waitcnt vmcnt(0) lgkmcnt(0)
	v_mov_b32_e32 v18, v23
	v_mov_b32_e32 v19, v24
	v_mov_b32_e32 v23, v25
	v_pk_add_f32 v[18:19], v[18:19], v[22:23]
	s_nop 0
	v_add_f32_e32 v16, v18, v19
	ds_bpermute_b32 v18, v168, v16
	s_waitcnt lgkmcnt(0)
	v_add_f32_e32 v16, v16, v18
	ds_bpermute_b32 v18, v167, v16
	s_waitcnt lgkmcnt(0)
	v_add_f32_e32 v16, v16, v18
	v_fmamk_f32 v16, v16, 0x3a800000, v250
	v_rsq_f32_e32 v16, v16
	v_subrev_u32_e32 v18, s5, v20

.LBB0_127:
	s_waitcnt lgkmcnt(0)
	v_pk_mul_f32 v[10:11], v[10:11], v[16:17] op_sel_hi:[1,0]
	v_pk_mul_f32 v[8:9], v[8:9], v[16:17] op_sel_hi:[1,0]
	v_pk_mul_f32 v[14:15], v[14:15], v[16:17] op_sel_hi:[1,0]
	v_pk_mul_f32 v[12:13], v[12:13], v[16:17] op_sel_hi:[1,0]
	v_max_f32_e32 v8, 0, v8
	v_max_f32_e32 v9, 0, v9
	v_max_f32_e32 v10, 0, v10
	v_max_f32_e32 v12, 0, v12
	v_mul_f32_e32 v17, v8, v8
	v_max_f32_e32 v8, 0, v13
	v_mul_f32_e32 v13, v9, v9
	v_max_f32_e32 v9, 0, v14
	v_mul_f32_e32 v14, v10, v10
	v_max_f32_e32 v10, 0, v15
	v_mul_f32_e32 v12, v12, v12
	v_mul_f32_e32 v8, v8, v8
	v_mul_f32_e32 v9, v9, v9
	v_max_f32_e32 v11, 0, v11
	v_mul_f32_e32 v10, v10, v10
	v_ashrrev_i32_e32 v19, 31, v18
	v_mul_f32_e32 v11, v11, v11
	v_cvt_pk_bf16_f32 v8, v12, v8
	v_cvt_pk_bf16_f32 v9, v9, v10
	v_cvt_pk_bf16_f32 v10, v17, v13
	v_lshlrev_b64 v[12:13], 7, v[18:19]
	v_cvt_pk_bf16_f32 v11, v14, v11
	v_lshl_add_u64 v[14:15], s[58:59], 0, v[12:13]
	v_pk_mul_f32 v[2:3], v[2:3], v[16:17] op_sel_hi:[1,0]
	v_pk_mul_f32 v[0:1], v[0:1], v[16:17] op_sel_hi:[1,0]
	v_lshl_add_u64 v[14:15], v[14:15], 0, v[140:141]
	v_pk_mul_f32 v[6:7], v[6:7], v[16:17] op_sel_hi:[1,0]
	v_pk_mul_f32 v[4:5], v[4:5], v[16:17] op_sel_hi:[1,0]
	v_max_f32_e32 v0, 0, v0
	v_max_f32_e32 v1, 0, v1
	v_max_f32_e32 v2, 0, v2
	s_waitcnt lgkmcnt(0)
	global_store_dwordx4 v[182:183], v[178:181], off sc0 nt
	ds_bpermute_b32 v172, v169, v8
	ds_bpermute_b32 v173, v169, v9
	ds_bpermute_b32 v174, v169, v10
	ds_bpermute_b32 v175, v169, v11
	v_lshl_add_u64 v[176:177], v[14:15], 0, v[170:171]
	v_max_f32_e32 v4, 0, v4
	v_mul_f32_e32 v4, v4, v4
	v_mul_f32_e32 v8, v0, v0
	v_max_f32_e32 v0, 0, v5
	v_mul_f32_e32 v5, v1, v1
	v_max_f32_e32 v1, 0, v6
	v_mul_f32_e32 v6, v2, v2
	v_max_f32_e32 v2, 0, v7
	v_mul_f32_e32 v0, v0, v0
	v_mul_f32_e32 v1, v1, v1
	v_mul_f32_e32 v2, v2, v2
	v_max_f32_e32 v3, 0, v3
	v_cvt_pk_bf16_f32 v0, v4, v0
	v_cvt_pk_bf16_f32 v1, v1, v2
	v_cvt_pk_bf16_f32 v2, v8, v5
	v_lshl_add_u64 v[4:5], s[74:75], 0, v[12:13]
	v_mul_f32_e32 v3, v3, v3
	v_lshl_add_u64 v[4:5], v[4:5], 0, v[140:141]
	s_andn2_b64 vcc, exec, s[40:41]
	s_mov_b64 s[6:7], -1
	v_cvt_pk_bf16_f32 v3, v6, v3
	s_waitcnt lgkmcnt(0)
	global_store_dwordx4 v[176:177], v[172:175], off sc0 nt
	ds_bpermute_b32 v178, v169, v0
	ds_bpermute_b32 v179, v169, v1
	ds_bpermute_b32 v180, v169, v2
	ds_bpermute_b32 v181, v169, v3
	v_lshl_add_u64 v[182:183], v[4:5], 0, v[170:171]
	s_waitcnt lgkmcnt(0)
	global_store_dwordx4 v[182:183], v[178:181], off sc0 nt
	s_cbranch_vccnz .LBB0_84
	s_cmp_lg_u32 s52, s46
	s_cselect_b64 s[4:5], -1, 0
	s_and_b64 s[4:5], s[40:41], s[4:5]
	v_cndmask_b32_e64 v0, 0, 1, s[4:5]
	s_andn2_b64 vcc, exec, s[2:3]
	v_readfirstlane_b32 s4, v0
	s_cbranch_vccnz .LBB0_83
	s_barrier
	s_branch .LBB0_83

.LBB0_150:
	s_mov_b32 s6, -1
	s_lshl_b32 s5, s5, 8
	v_mbcnt_lo_u32_b32 v128, s6, 0
	v_mbcnt_hi_u32_b32 v128, s6, v128
	s_getreg_b32 s6, hwreg(HW_REG_HW_ID, 0, 6)
	s_and_b32 s6, s6, 63
	s_lshl_b32 s6, s6, 2
	s_add_i32 s6, s6, 0
	s_add_i32 s6, s6, 0x20200
	v_mov_b32_e32 v129, s6
	ds_read_b32 v129, v129
	v_bfrev_b32_e32 v130, 0.5
	s_movk_i32 s84, 0x80
	s_lshl_b32 s74, s4, 2
	s_ashr_i32 s75, s74, 31
	s_waitcnt lgkmcnt(0)
	v_readfirstlane_b32 s6, v129
	s_nop 1
	v_lshl_add_u32 v128, s6, 6, v128
	s_nop 0
	v_readfirstlane_b32 s6, v128
	s_bfe_u32 s8, s6, 0x20006
	s_ashr_i32 s6, s6, 2
	s_andn2_b32 s6, s6, 63
	s_add_i32 s6, s6, s5
	v_and_or_b32 v170, v128, 15, s6
	s_lshl_b32 s5, s4, 8
	s_lshl_b32 s6, s8, 5
	v_bfe_u32 v129, v128, 4, 2
	s_or_b32 s5, s6, s5
	v_lshl_or_b32 v168, v129, 3, s5
	v_ashrrev_i32_e32 v169, 31, v168
	v_lshlrev_b64 v[146:147], 1, v[168:169]
	v_ashrrev_i32_e32 v171, 31, v170
	v_lshlrev_b32_e32 v128, 2, v128
	v_lshl_add_u64 v[172:173], s[68:69], 0, v[146:147]
	v_lshlrev_b64 v[148:149], 11, v[170:171]
	v_bitop3_b32 v180, v128, 64, v130 bitop3:0x6c
	v_bitop3_b32 v181, v128, s84, v130 bitop3:0x6c
	v_cmp_eq_u32_e32 vcc, 0, v129
	v_lshl_add_u64 v[128:129], v[172:173], 0, v[148:149]
	global_load_dwordx4 v[142:145], v[128:129], off
	global_load_dwordx4 v[136:139], v[128:129], off offset:256
	v_or_b32_e32 v174, 16, v170
	v_ashrrev_i32_e32 v175, 31, v174
	v_lshlrev_b64 v[176:177], 11, v[174:175]
	v_lshl_add_u64 v[128:129], v[172:173], 0, v[176:177]
	global_load_dwordx4 v[132:135], v[128:129], off
	s_nop 0
	global_load_dwordx4 v[128:131], v[128:129], off offset:256
	s_waitcnt vmcnt(0)
	v_lshlrev_b32_e32 v150, 16, v142
	v_and_b32_e32 v151, 0xffff0000, v142
	v_lshlrev_b32_e32 v142, 16, v143
	v_and_b32_e32 v143, 0xffff0000, v143
	v_lshlrev_b32_e32 v152, 16, v144
	v_and_b32_e32 v153, 0xffff0000, v144
	v_lshlrev_b32_e32 v144, 16, v145
	v_and_b32_e32 v145, 0xffff0000, v145
	v_pk_add_f32 v[124:125], v[124:125], v[150:151]
	v_pk_add_f32 v[126:127], v[126:127], v[142:143]
	v_pk_add_f32 v[142:143], v[122:123], v[144:145]
	v_pk_add_f32 v[122:123], v[120:121], v[152:153]
	v_cvt_pk_bf16_f32 v120, v124, v125
	v_lshl_add_u64 v[124:125], s[68:69], 0, v[148:149]
	v_lshl_add_u64 v[124:125], v[124:125], 0, v[146:147]
	v_cvt_pk_bf16_f32 v121, v126, v127
	v_cvt_pk_bf16_f32 v122, v122, v123
	v_cvt_pk_bf16_f32 v123, v142, v143
	global_store_dwordx4 v[124:125], v[120:123], off sc0 nt
	v_lshlrev_b32_e32 v126, 16, v120
	v_and_b32_e32 v127, 0xffff0000, v138
	v_and_b32_e32 v120, 0xffff0000, v120
	v_mul_f32_e32 v120, v120, v120
	v_fmac_f32_e32 v120, v126, v126
	v_lshlrev_b32_e32 v126, 16, v121
	v_and_b32_e32 v121, 0xffff0000, v121
	v_mul_f32_e32 v121, v121, v121
	v_fmac_f32_e32 v121, v126, v126
	v_add_f32_e32 v120, v120, v121
	v_lshlrev_b32_e32 v121, 16, v122
	v_and_b32_e32 v122, 0xffff0000, v122
	v_mul_f32_e32 v122, v122, v122
	v_fmac_f32_e32 v122, v121, v121
	v_add_f32_e32 v120, v120, v122
	v_and_b32_e32 v122, 0xffff0000, v123
	v_lshlrev_b32_e32 v121, 16, v123
	v_mul_f32_e32 v122, v122, v122
	v_fmac_f32_e32 v122, v121, v121
	v_add_f32_e32 v142, v120, v122
	v_lshlrev_b32_e32 v120, 16, v136
	v_and_b32_e32 v121, 0xffff0000, v136
	v_lshlrev_b32_e32 v122, 16, v137
	v_and_b32_e32 v123, 0xffff0000, v137
	v_lshlrev_b32_e32 v126, 16, v138
	v_lshlrev_b32_e32 v136, 16, v139
	v_and_b32_e32 v137, 0xffff0000, v139
	v_pk_add_f32 v[116:117], v[116:117], v[120:121]
	v_pk_add_f32 v[120:121], v[114:115], v[136:137]
	v_pk_add_f32 v[114:115], v[112:113], v[126:127]
	v_cvt_pk_bf16_f32 v112, v116, v117
	v_pk_add_f32 v[118:119], v[118:119], v[122:123]
	v_lshlrev_b32_e32 v116, 16, v112
	v_cvt_pk_bf16_f32 v113, v118, v119
	v_cvt_pk_bf16_f32 v114, v114, v115
	v_cvt_pk_bf16_f32 v115, v120, v121
	global_store_dwordx4 v[124:125], v[112:115], off offset:256 sc0 nt
	s_nop 1
	v_and_b32_e32 v112, 0xffff0000, v112
	v_mul_f32_e32 v112, v112, v112
	v_fmac_f32_e32 v112, v116, v116
	v_lshlrev_b32_e32 v116, 16, v113
	v_and_b32_e32 v113, 0xffff0000, v113
	v_mul_f32_e32 v113, v113, v113
	v_add_f32_e32 v112, v142, v112
	v_fmac_f32_e32 v113, v116, v116
	v_add_f32_e32 v112, v112, v113
	v_lshlrev_b32_e32 v113, 16, v114
	v_and_b32_e32 v114, 0xffff0000, v114
	v_mul_f32_e32 v114, v114, v114
	v_fmac_f32_e32 v114, v113, v113
	v_add_f32_e32 v112, v112, v114
	v_and_b32_e32 v114, 0xffff0000, v115
	v_lshlrev_b32_e32 v113, 16, v115
	v_mul_f32_e32 v114, v114, v114
	v_fmac_f32_e32 v114, v113, v113
	v_add_f32_e32 v112, v112, v114
	ds_bpermute_b32 v113, v180, v112
	s_waitcnt lgkmcnt(0)
	v_add_f32_e32 v112, v112, v113
	ds_bpermute_b32 v113, v181, v112
	s_and_saveexec_b64 s[6:7], vcc
	s_cbranch_execz .LBB0_152
	s_waitcnt lgkmcnt(0)
	v_add_f32_e32 v114, v112, v113
	v_lshlrev_b64 v[112:113], 6, v[170:171]
	v_lshl_add_u64 v[112:113], s[48:49], 0, v[112:113]
	v_lshl_add_u64 v[112:113], s[74:75], 2, v[112:113]
	s_lshl_b32 s38, s8, 2
	v_lshl_add_u64 v[112:113], v[112:113], 0, s[38:39]
	flat_store_dword v[112:113], v114
.LBB0_152:
	s_or_b64 exec, exec, s[6:7]
	v_lshlrev_b32_e32 v112, 16, v132
	s_waitcnt lgkmcnt(0)
	v_and_b32_e32 v113, 0xffff0000, v132
	v_lshlrev_b32_e32 v116, 16, v134
	v_and_b32_e32 v117, 0xffff0000, v134
	v_lshlrev_b32_e32 v118, 16, v135
	v_and_b32_e32 v119, 0xffff0000, v135
	v_pk_add_f32 v[108:109], v[108:109], v[112:113]
	v_lshlrev_b32_e32 v114, 16, v133
	v_and_b32_e32 v115, 0xffff0000, v133
	v_pk_add_f32 v[112:113], v[106:107], v[118:119]
	v_pk_add_f32 v[106:107], v[104:105], v[116:117]
	v_cvt_pk_bf16_f32 v104, v108, v109
	v_lshl_add_u64 v[108:109], s[68:69], 0, v[176:177]
	v_pk_add_f32 v[110:111], v[110:111], v[114:115]
	v_lshl_add_u64 v[108:109], v[168:169], 1, v[108:109]
	v_cvt_pk_bf16_f32 v105, v110, v111
	v_cvt_pk_bf16_f32 v106, v106, v107
	v_cvt_pk_bf16_f32 v107, v112, v113
	global_store_dwordx4 v[108:109], v[104:107], off sc0 nt
	v_lshlrev_b32_e32 v110, 16, v104
	v_and_b32_e32 v111, 0xffff0000, v130
	v_and_b32_e32 v104, 0xffff0000, v104
	v_mul_f32_e32 v104, v104, v104
	v_fmac_f32_e32 v104, v110, v110
	v_lshlrev_b32_e32 v110, 16, v105
	v_and_b32_e32 v105, 0xffff0000, v105
	v_mul_f32_e32 v105, v105, v105
	v_fmac_f32_e32 v105, v110, v110
	v_add_f32_e32 v104, v104, v105
	v_lshlrev_b32_e32 v105, 16, v106
	v_and_b32_e32 v106, 0xffff0000, v106
	v_mul_f32_e32 v106, v106, v106
	v_fmac_f32_e32 v106, v105, v105
	v_add_f32_e32 v104, v104, v106
	v_and_b32_e32 v106, 0xffff0000, v107
	v_lshlrev_b32_e32 v105, 16, v107
	v_mul_f32_e32 v106, v106, v106
	v_fmac_f32_e32 v106, v105, v105
	v_add_f32_e32 v114, v104, v106
	v_lshlrev_b32_e32 v104, 16, v128
	v_and_b32_e32 v105, 0xffff0000, v128
	v_lshlrev_b32_e32 v110, 16, v130
	v_lshlrev_b32_e32 v106, 16, v129
	v_and_b32_e32 v107, 0xffff0000, v129
	v_lshlrev_b32_e32 v112, 16, v131
	v_and_b32_e32 v113, 0xffff0000, v131
	v_pk_add_f32 v[100:101], v[100:101], v[104:105]
	v_pk_add_f32 v[96:97], v[96:97], v[110:111]
	v_pk_add_f32 v[102:103], v[102:103], v[106:107]
	v_pk_add_f32 v[104:105], v[98:99], v[112:113]
	v_cvt_pk_bf16_f32 v98, v100, v101
	v_cvt_pk_bf16_f32 v99, v102, v103
	v_cvt_pk_bf16_f32 v100, v96, v97
	s_nop 0
	v_and_b32_e32 v97, 0xffff0000, v98
	v_lshlrev_b32_e32 v96, 16, v98
	v_mul_f32_e32 v97, v97, v97
	v_fmac_f32_e32 v97, v96, v96
	v_and_b32_e32 v102, 0xffff0000, v99
	v_add_f32_e32 v96, v114, v97
	v_lshlrev_b32_e32 v97, 16, v99
	v_mul_f32_e32 v102, v102, v102
	v_fmac_f32_e32 v102, v97, v97
	v_add_f32_e32 v96, v96, v102
	v_and_b32_e32 v102, 0xffff0000, v100
	v_lshlrev_b32_e32 v97, 16, v100
	v_mul_f32_e32 v102, v102, v102
	v_fmac_f32_e32 v102, v97, v97
	v_cvt_pk_bf16_f32 v101, v104, v105
	v_add_f32_e32 v96, v96, v102
	v_and_b32_e32 v102, 0xffff0000, v101
	v_lshlrev_b32_e32 v97, 16, v101
	v_mul_f32_e32 v102, v102, v102
	v_fmac_f32_e32 v102, v97, v97
	v_add_f32_e32 v96, v96, v102
	ds_bpermute_b32 v97, v180, v96
	global_store_dwordx4 v[108:109], v[98:101], off offset:256 sc0 nt
	s_waitcnt lgkmcnt(0)
	v_add_f32_e32 v96, v96, v97
	ds_bpermute_b32 v97, v181, v96
	s_and_saveexec_b64 s[6:7], vcc
	s_cbranch_execz .LBB0_154
	s_waitcnt lgkmcnt(0)
	v_add_f32_e32 v98, v96, v97
	v_lshlrev_b64 v[96:97], 6, v[174:175]
	v_lshl_add_u64 v[96:97], s[48:49], 0, v[96:97]
	v_lshl_add_u64 v[96:97], s[74:75], 2, v[96:97]
	s_lshl_b32 s38, s8, 2
	v_lshl_add_u64 v[96:97], v[96:97], 0, s[38:39]
	flat_store_dword v[96:97], v98
.LBB0_154:
	s_or_b64 exec, exec, s[6:7]
	v_or_b32_e32 v112, 32, v170
	v_ashrrev_i32_e32 v113, 31, v112
	v_lshlrev_b64 v[118:119], 11, v[112:113]
	s_waitcnt lgkmcnt(0)
	v_lshl_add_u64 v[96:97], v[172:173], 0, v[118:119]
	global_load_dwordx4 v[114:117], v[96:97], off
	global_load_dwordx4 v[104:107], v[96:97], off offset:256
	v_or_b32_e32 v108, 48, v170
	v_ashrrev_i32_e32 v109, 31, v108
	v_lshlrev_b64 v[110:111], 11, v[108:109]
	v_lshl_add_u64 v[96:97], v[172:173], 0, v[110:111]
	global_load_dwordx4 v[100:103], v[96:97], off
	s_nop 0
	global_load_dwordx4 v[96:99], v[96:97], off offset:256
	s_waitcnt vmcnt(0)
	v_lshlrev_b32_e32 v120, 16, v114
	v_and_b32_e32 v121, 0xffff0000, v114
	v_lshlrev_b32_e32 v114, 16, v115
	v_and_b32_e32 v115, 0xffff0000, v115
	v_lshlrev_b32_e32 v122, 16, v116
	v_and_b32_e32 v123, 0xffff0000, v116
	v_lshlrev_b32_e32 v116, 16, v117
	v_and_b32_e32 v117, 0xffff0000, v117
	v_pk_add_f32 v[92:93], v[92:93], v[120:121]
	v_pk_add_f32 v[94:95], v[94:95], v[114:115]
	v_pk_add_f32 v[114:115], v[90:91], v[116:117]
	v_pk_add_f32 v[90:91], v[88:89], v[122:123]
	v_cvt_pk_bf16_f32 v88, v92, v93
	v_lshl_add_u64 v[92:93], s[68:69], 0, v[118:119]
	v_lshl_add_u64 v[92:93], v[168:169], 1, v[92:93]
	v_cvt_pk_bf16_f32 v89, v94, v95
	v_cvt_pk_bf16_f32 v90, v90, v91
	v_cvt_pk_bf16_f32 v91, v114, v115
	global_store_dwordx4 v[92:93], v[88:91], off sc0 nt
	v_lshlrev_b32_e32 v94, 16, v88
	v_and_b32_e32 v95, 0xffff0000, v106
	v_and_b32_e32 v88, 0xffff0000, v88
	v_mul_f32_e32 v88, v88, v88
	v_fmac_f32_e32 v88, v94, v94
	v_lshlrev_b32_e32 v94, 16, v89
	v_and_b32_e32 v89, 0xffff0000, v89
	v_mul_f32_e32 v89, v89, v89
	v_fmac_f32_e32 v89, v94, v94
	v_add_f32_e32 v88, v88, v89
	v_lshlrev_b32_e32 v89, 16, v90
	v_and_b32_e32 v90, 0xffff0000, v90
	v_mul_f32_e32 v90, v90, v90
	v_fmac_f32_e32 v90, v89, v89
	v_add_f32_e32 v88, v88, v90
	v_and_b32_e32 v90, 0xffff0000, v91
	v_lshlrev_b32_e32 v89, 16, v91
	v_mul_f32_e32 v90, v90, v90
	v_fmac_f32_e32 v90, v89, v89
	v_add_f32_e32 v114, v88, v90
	v_lshlrev_b32_e32 v88, 16, v104
	v_and_b32_e32 v89, 0xffff0000, v104
	v_lshlrev_b32_e32 v90, 16, v105
	v_and_b32_e32 v91, 0xffff0000, v105
	v_lshlrev_b32_e32 v94, 16, v106
	v_lshlrev_b32_e32 v104, 16, v107
	v_and_b32_e32 v105, 0xffff0000, v107
	v_pk_add_f32 v[84:85], v[84:85], v[88:89]
	v_pk_add_f32 v[88:89], v[82:83], v[104:105]
	v_pk_add_f32 v[82:83], v[80:81], v[94:95]
	v_cvt_pk_bf16_f32 v80, v84, v85
	v_pk_add_f32 v[86:87], v[86:87], v[90:91]
	v_lshlrev_b32_e32 v84, 16, v80
	v_cvt_pk_bf16_f32 v81, v86, v87
	v_cvt_pk_bf16_f32 v82, v82, v83
	v_cvt_pk_bf16_f32 v83, v88, v89
	global_store_dwordx4 v[92:93], v[80:83], off offset:256 sc0 nt
	s_nop 1
	v_and_b32_e32 v80, 0xffff0000, v80
	v_mul_f32_e32 v80, v80, v80
	v_fmac_f32_e32 v80, v84, v84
	v_lshlrev_b32_e32 v84, 16, v81
	v_and_b32_e32 v81, 0xffff0000, v81
	v_mul_f32_e32 v81, v81, v81
	v_add_f32_e32 v80, v114, v80
	v_fmac_f32_e32 v81, v84, v84
	v_add_f32_e32 v80, v80, v81
	v_lshlrev_b32_e32 v81, 16, v82
	v_and_b32_e32 v82, 0xffff0000, v82
	v_mul_f32_e32 v82, v82, v82
	v_fmac_f32_e32 v82, v81, v81
	v_add_f32_e32 v80, v80, v82
	v_and_b32_e32 v82, 0xffff0000, v83
	v_lshlrev_b32_e32 v81, 16, v83
	v_mul_f32_e32 v82, v82, v82
	v_fmac_f32_e32 v82, v81, v81
	v_add_f32_e32 v80, v80, v82
	ds_bpermute_b32 v81, v180, v80
	s_waitcnt lgkmcnt(0)
	v_add_f32_e32 v80, v80, v81
	ds_bpermute_b32 v81, v181, v80
	s_mov_b64 s[6:7], exec
	s_and_b64 s[4:5], s[6:7], vcc
	v_mov_b32_e32 v198, v216
	v_mov_b32_e32 v199, v217
	v_mov_b32_e32 v248, v218
	v_mov_b32_e32 v205, v219
	v_mov_b32_e32 v196, v220
	s_mov_b64 exec, s[4:5]
	s_cbranch_execz .LBB0_156
	s_waitcnt lgkmcnt(0)
	v_add_f32_e32 v82, v80, v81
	v_lshlrev_b64 v[80:81], 6, v[112:113]
	v_lshl_add_u64 v[80:81], s[48:49], 0, v[80:81]
	v_lshl_add_u64 v[80:81], s[74:75], 2, v[80:81]
	s_lshl_b32 s38, s8, 2
	v_lshl_add_u64 v[80:81], v[80:81], 0, s[38:39]
	flat_store_dword v[80:81], v82
.LBB0_156:
	s_or_b64 exec, exec, s[6:7]
	v_lshlrev_b32_e32 v80, 16, v100
	s_waitcnt lgkmcnt(0)
	v_and_b32_e32 v81, 0xffff0000, v100
	v_lshlrev_b32_e32 v84, 16, v102
	v_and_b32_e32 v85, 0xffff0000, v102
	v_lshlrev_b32_e32 v86, 16, v103
	v_and_b32_e32 v87, 0xffff0000, v103
	v_pk_add_f32 v[76:77], v[76:77], v[80:81]
	v_lshlrev_b32_e32 v82, 16, v101
	v_and_b32_e32 v83, 0xffff0000, v101
	v_pk_add_f32 v[80:81], v[74:75], v[86:87]
	v_pk_add_f32 v[74:75], v[72:73], v[84:85]
	v_cvt_pk_bf16_f32 v72, v76, v77
	v_lshl_add_u64 v[76:77], s[68:69], 0, v[110:111]
	v_pk_add_f32 v[78:79], v[78:79], v[82:83]
	v_lshl_add_u64 v[76:77], v[168:169], 1, v[76:77]
	v_cvt_pk_bf16_f32 v73, v78, v79
	v_cvt_pk_bf16_f32 v74, v74, v75
	v_cvt_pk_bf16_f32 v75, v80, v81
	global_store_dwordx4 v[76:77], v[72:75], off sc0 nt
	v_lshlrev_b32_e32 v78, 16, v72
	v_and_b32_e32 v79, 0xffff0000, v98
	v_and_b32_e32 v72, 0xffff0000, v72
	v_mul_f32_e32 v72, v72, v72
	v_fmac_f32_e32 v72, v78, v78
	v_lshlrev_b32_e32 v78, 16, v73
	v_and_b32_e32 v73, 0xffff0000, v73
	v_mul_f32_e32 v73, v73, v73
	v_fmac_f32_e32 v73, v78, v78
	v_add_f32_e32 v72, v72, v73
	v_lshlrev_b32_e32 v73, 16, v74
	v_and_b32_e32 v74, 0xffff0000, v74
	v_mul_f32_e32 v74, v74, v74
	v_fmac_f32_e32 v74, v73, v73
	v_add_f32_e32 v72, v72, v74
	v_and_b32_e32 v74, 0xffff0000, v75
	v_lshlrev_b32_e32 v73, 16, v75
	v_mul_f32_e32 v74, v74, v74
	v_fmac_f32_e32 v74, v73, v73
	v_add_f32_e32 v82, v72, v74
	v_lshlrev_b32_e32 v72, 16, v96
	v_and_b32_e32 v73, 0xffff0000, v96
	v_lshlrev_b32_e32 v78, 16, v98
	v_lshlrev_b32_e32 v74, 16, v97
	v_and_b32_e32 v75, 0xffff0000, v97
	v_lshlrev_b32_e32 v80, 16, v99
	v_and_b32_e32 v81, 0xffff0000, v99
	v_pk_add_f32 v[68:69], v[68:69], v[72:73]
	v_pk_add_f32 v[64:65], v[64:65], v[78:79]
	v_pk_add_f32 v[70:71], v[70:71], v[74:75]
	v_pk_add_f32 v[72:73], v[66:67], v[80:81]
	v_cvt_pk_bf16_f32 v66, v68, v69
	v_cvt_pk_bf16_f32 v67, v70, v71
	v_cvt_pk_bf16_f32 v68, v64, v65
	s_nop 0
	v_and_b32_e32 v65, 0xffff0000, v66
	v_lshlrev_b32_e32 v64, 16, v66
	v_mul_f32_e32 v65, v65, v65
	v_fmac_f32_e32 v65, v64, v64
	v_and_b32_e32 v70, 0xffff0000, v67
	v_add_f32_e32 v64, v82, v65
	v_lshlrev_b32_e32 v65, 16, v67
	v_mul_f32_e32 v70, v70, v70
	v_fmac_f32_e32 v70, v65, v65
	v_add_f32_e32 v64, v64, v70
	v_and_b32_e32 v70, 0xffff0000, v68
	v_lshlrev_b32_e32 v65, 16, v68
	v_mul_f32_e32 v70, v70, v70
	v_fmac_f32_e32 v70, v65, v65
	v_cvt_pk_bf16_f32 v69, v72, v73
	v_add_f32_e32 v64, v64, v70
	v_and_b32_e32 v70, 0xffff0000, v69
	v_lshlrev_b32_e32 v65, 16, v69
	v_mul_f32_e32 v70, v70, v70
	v_fmac_f32_e32 v70, v65, v65
	v_add_f32_e32 v64, v64, v70
	ds_bpermute_b32 v65, v180, v64
	global_store_dwordx4 v[76:77], v[66:69], off offset:256 sc0 nt
	s_waitcnt lgkmcnt(0)
	v_add_f32_e32 v64, v64, v65
	ds_bpermute_b32 v65, v181, v64
	s_and_saveexec_b64 s[6:7], vcc
	s_cbranch_execz .LBB0_158
	s_waitcnt lgkmcnt(0)
	v_add_f32_e32 v66, v64, v65
	v_lshlrev_b64 v[64:65], 6, v[108:109]
	v_lshl_add_u64 v[64:65], s[48:49], 0, v[64:65]
	v_lshl_add_u64 v[64:65], s[74:75], 2, v[64:65]
	s_lshl_b32 s38, s8, 2
	v_lshl_add_u64 v[64:65], v[64:65], 0, s[38:39]
	flat_store_dword v[64:65], v66
.LBB0_158:
	s_or_b64 exec, exec, s[6:7]
	v_add_u32_e32 v80, 0x80, v170
	v_ashrrev_i32_e32 v81, 31, v80
	v_lshlrev_b64 v[86:87], 11, v[80:81]
	s_waitcnt lgkmcnt(0)
	v_lshl_add_u64 v[64:65], v[172:173], 0, v[86:87]
	global_load_dwordx4 v[82:85], v[64:65], off
	global_load_dwordx4 v[72:75], v[64:65], off offset:256
	v_add_u32_e32 v76, 0x90, v170
	v_ashrrev_i32_e32 v77, 31, v76
	v_lshlrev_b64 v[78:79], 11, v[76:77]
	v_lshl_add_u64 v[64:65], v[172:173], 0, v[78:79]
	global_load_dwordx4 v[68:71], v[64:65], off
	s_nop 0
	global_load_dwordx4 v[64:67], v[64:65], off offset:256
	s_waitcnt vmcnt(0)
	v_lshlrev_b32_e32 v88, 16, v82
	v_and_b32_e32 v89, 0xffff0000, v82
	v_lshlrev_b32_e32 v82, 16, v83
	v_and_b32_e32 v83, 0xffff0000, v83
	v_lshlrev_b32_e32 v90, 16, v84
	v_and_b32_e32 v91, 0xffff0000, v84
	v_lshlrev_b32_e32 v84, 16, v85
	v_and_b32_e32 v85, 0xffff0000, v85
	v_pk_add_f32 v[60:61], v[60:61], v[88:89]
	v_pk_add_f32 v[62:63], v[62:63], v[82:83]
	v_pk_add_f32 v[82:83], v[58:59], v[84:85]
	v_pk_add_f32 v[58:59], v[56:57], v[90:91]
	v_cvt_pk_bf16_f32 v56, v60, v61
	v_lshl_add_u64 v[60:61], s[68:69], 0, v[86:87]
	v_lshl_add_u64 v[60:61], v[168:169], 1, v[60:61]
	v_cvt_pk_bf16_f32 v57, v62, v63
	v_cvt_pk_bf16_f32 v58, v58, v59
	v_cvt_pk_bf16_f32 v59, v82, v83
	global_store_dwordx4 v[60:61], v[56:59], off sc0 nt
	v_lshlrev_b32_e32 v62, 16, v56
	v_and_b32_e32 v63, 0xffff0000, v74
	v_and_b32_e32 v56, 0xffff0000, v56
	v_mul_f32_e32 v56, v56, v56
	v_fmac_f32_e32 v56, v62, v62
	v_lshlrev_b32_e32 v62, 16, v57
	v_and_b32_e32 v57, 0xffff0000, v57
	v_mul_f32_e32 v57, v57, v57
	v_fmac_f32_e32 v57, v62, v62
	v_add_f32_e32 v56, v56, v57
	v_lshlrev_b32_e32 v57, 16, v58
	v_and_b32_e32 v58, 0xffff0000, v58
	v_mul_f32_e32 v58, v58, v58
	v_fmac_f32_e32 v58, v57, v57
	v_add_f32_e32 v56, v56, v58
	v_and_b32_e32 v58, 0xffff0000, v59
	v_lshlrev_b32_e32 v57, 16, v59
	v_mul_f32_e32 v58, v58, v58
	v_fmac_f32_e32 v58, v57, v57
	v_add_f32_e32 v82, v56, v58
	v_lshlrev_b32_e32 v56, 16, v72
	v_and_b32_e32 v57, 0xffff0000, v72
	v_lshlrev_b32_e32 v58, 16, v73
	v_and_b32_e32 v59, 0xffff0000, v73
	v_lshlrev_b32_e32 v62, 16, v74
	v_lshlrev_b32_e32 v72, 16, v75
	v_and_b32_e32 v73, 0xffff0000, v75
	v_pk_add_f32 v[52:53], v[52:53], v[56:57]
	v_pk_add_f32 v[56:57], v[50:51], v[72:73]
	v_pk_add_f32 v[50:51], v[48:49], v[62:63]
	v_cvt_pk_bf16_f32 v48, v52, v53
	v_pk_add_f32 v[54:55], v[54:55], v[58:59]
	v_lshlrev_b32_e32 v52, 16, v48
	v_cvt_pk_bf16_f32 v49, v54, v55
	v_cvt_pk_bf16_f32 v50, v50, v51
	v_cvt_pk_bf16_f32 v51, v56, v57
	global_store_dwordx4 v[60:61], v[48:51], off offset:256 sc0 nt
	s_nop 1
	v_and_b32_e32 v48, 0xffff0000, v48
	v_mul_f32_e32 v48, v48, v48
	v_fmac_f32_e32 v48, v52, v52
	v_lshlrev_b32_e32 v52, 16, v49
	v_and_b32_e32 v49, 0xffff0000, v49
	v_mul_f32_e32 v49, v49, v49
	v_add_f32_e32 v48, v82, v48
	v_fmac_f32_e32 v49, v52, v52
	v_add_f32_e32 v48, v48, v49
	v_lshlrev_b32_e32 v49, 16, v50
	v_and_b32_e32 v50, 0xffff0000, v50
	v_mul_f32_e32 v50, v50, v50
	v_fmac_f32_e32 v50, v49, v49
	v_add_f32_e32 v48, v48, v50
	v_and_b32_e32 v50, 0xffff0000, v51
	v_lshlrev_b32_e32 v49, 16, v51
	v_mul_f32_e32 v50, v50, v50
	v_fmac_f32_e32 v50, v49, v49
	v_add_f32_e32 v48, v48, v50
	ds_bpermute_b32 v49, v180, v48
	s_waitcnt lgkmcnt(0)
	v_add_f32_e32 v48, v48, v49
	ds_bpermute_b32 v49, v181, v48
	s_and_saveexec_b64 s[6:7], vcc
	s_cbranch_execz .LBB0_160
	s_waitcnt lgkmcnt(0)
	v_add_f32_e32 v50, v48, v49
	v_lshlrev_b64 v[48:49], 6, v[80:81]
	v_lshl_add_u64 v[48:49], s[48:49], 0, v[48:49]
	v_lshl_add_u64 v[48:49], s[74:75], 2, v[48:49]
	s_lshl_b32 s38, s8, 2
	v_lshl_add_u64 v[48:49], v[48:49], 0, s[38:39]
	flat_store_dword v[48:49], v50
.LBB0_160:
	s_or_b64 exec, exec, s[6:7]
	v_lshlrev_b32_e32 v48, 16, v68
	s_waitcnt lgkmcnt(0)
	v_and_b32_e32 v49, 0xffff0000, v68
	v_lshlrev_b32_e32 v52, 16, v70
	v_and_b32_e32 v53, 0xffff0000, v70
	v_lshlrev_b32_e32 v54, 16, v71
	v_and_b32_e32 v55, 0xffff0000, v71
	v_pk_add_f32 v[44:45], v[44:45], v[48:49]
	v_lshlrev_b32_e32 v50, 16, v69
	v_and_b32_e32 v51, 0xffff0000, v69
	v_pk_add_f32 v[48:49], v[42:43], v[54:55]
	v_pk_add_f32 v[42:43], v[40:41], v[52:53]
	v_cvt_pk_bf16_f32 v40, v44, v45
	v_lshl_add_u64 v[44:45], s[68:69], 0, v[78:79]
	v_pk_add_f32 v[46:47], v[46:47], v[50:51]
	v_lshl_add_u64 v[44:45], v[168:169], 1, v[44:45]
	v_cvt_pk_bf16_f32 v41, v46, v47
	v_cvt_pk_bf16_f32 v42, v42, v43
	v_cvt_pk_bf16_f32 v43, v48, v49
	global_store_dwordx4 v[44:45], v[40:43], off sc0 nt
	v_lshlrev_b32_e32 v46, 16, v40
	v_and_b32_e32 v47, 0xffff0000, v66
	v_and_b32_e32 v40, 0xffff0000, v40
	v_mul_f32_e32 v40, v40, v40
	v_fmac_f32_e32 v40, v46, v46
	v_lshlrev_b32_e32 v46, 16, v41
	v_and_b32_e32 v41, 0xffff0000, v41
	v_mul_f32_e32 v41, v41, v41
	v_fmac_f32_e32 v41, v46, v46
	v_add_f32_e32 v40, v40, v41
	v_lshlrev_b32_e32 v41, 16, v42
	v_and_b32_e32 v42, 0xffff0000, v42
	v_mul_f32_e32 v42, v42, v42
	v_fmac_f32_e32 v42, v41, v41
	v_add_f32_e32 v40, v40, v42
	v_and_b32_e32 v42, 0xffff0000, v43
	v_lshlrev_b32_e32 v41, 16, v43
	v_mul_f32_e32 v42, v42, v42
	v_fmac_f32_e32 v42, v41, v41
	v_add_f32_e32 v50, v40, v42
	v_lshlrev_b32_e32 v40, 16, v64
	v_and_b32_e32 v41, 0xffff0000, v64
	v_lshlrev_b32_e32 v46, 16, v66
	v_lshlrev_b32_e32 v42, 16, v65
	v_and_b32_e32 v43, 0xffff0000, v65
	v_lshlrev_b32_e32 v48, 16, v67
	v_and_b32_e32 v49, 0xffff0000, v67
	v_pk_add_f32 v[36:37], v[36:37], v[40:41]
	v_pk_add_f32 v[32:33], v[32:33], v[46:47]
	v_pk_add_f32 v[38:39], v[38:39], v[42:43]
	v_pk_add_f32 v[40:41], v[34:35], v[48:49]
	v_cvt_pk_bf16_f32 v34, v36, v37
	v_cvt_pk_bf16_f32 v35, v38, v39
	v_cvt_pk_bf16_f32 v36, v32, v33
	s_nop 0
	v_and_b32_e32 v33, 0xffff0000, v34
	v_lshlrev_b32_e32 v32, 16, v34
	v_mul_f32_e32 v33, v33, v33
	v_fmac_f32_e32 v33, v32, v32
	v_and_b32_e32 v38, 0xffff0000, v35
	v_add_f32_e32 v32, v50, v33
	v_lshlrev_b32_e32 v33, 16, v35
	v_mul_f32_e32 v38, v38, v38
	v_fmac_f32_e32 v38, v33, v33
	v_add_f32_e32 v32, v32, v38
	v_and_b32_e32 v38, 0xffff0000, v36
	v_lshlrev_b32_e32 v33, 16, v36
	v_mul_f32_e32 v38, v38, v38
	v_fmac_f32_e32 v38, v33, v33
	v_cvt_pk_bf16_f32 v37, v40, v41
	v_add_f32_e32 v32, v32, v38
	v_and_b32_e32 v38, 0xffff0000, v37
	v_lshlrev_b32_e32 v33, 16, v37
	v_mul_f32_e32 v38, v38, v38
	v_fmac_f32_e32 v38, v33, v33
	v_add_f32_e32 v32, v32, v38
	ds_bpermute_b32 v33, v180, v32
	global_store_dwordx4 v[44:45], v[34:37], off offset:256 sc0 nt
	s_waitcnt lgkmcnt(0)
	v_add_f32_e32 v32, v32, v33
	ds_bpermute_b32 v33, v181, v32
	s_and_saveexec_b64 s[6:7], vcc
	s_cbranch_execz .LBB0_162
	s_waitcnt lgkmcnt(0)
	v_add_f32_e32 v34, v32, v33
	v_lshlrev_b64 v[32:33], 6, v[76:77]
	v_lshl_add_u64 v[32:33], s[48:49], 0, v[32:33]
	v_lshl_add_u64 v[32:33], s[74:75], 2, v[32:33]
	s_lshl_b32 s38, s8, 2
	v_lshl_add_u64 v[32:33], v[32:33], 0, s[38:39]
	flat_store_dword v[32:33], v34
.LBB0_162:
	s_or_b64 exec, exec, s[6:7]
	v_add_u32_e32 v48, 0xa0, v170
	v_ashrrev_i32_e32 v49, 31, v48
	v_lshlrev_b64 v[54:55], 11, v[48:49]
	s_waitcnt lgkmcnt(0)
	v_lshl_add_u64 v[32:33], v[172:173], 0, v[54:55]
	global_load_dwordx4 v[50:53], v[32:33], off
	global_load_dwordx4 v[40:43], v[32:33], off offset:256
	v_add_u32_e32 v44, 0xb0, v170
	v_ashrrev_i32_e32 v45, 31, v44
	v_lshlrev_b64 v[46:47], 11, v[44:45]
	v_lshl_add_u64 v[32:33], v[172:173], 0, v[46:47]
	global_load_dwordx4 v[36:39], v[32:33], off
	s_nop 0
	global_load_dwordx4 v[32:35], v[32:33], off offset:256
	s_waitcnt vmcnt(0)
	v_lshlrev_b32_e32 v56, 16, v50
	v_and_b32_e32 v57, 0xffff0000, v50
	v_lshlrev_b32_e32 v50, 16, v51
	v_and_b32_e32 v51, 0xffff0000, v51
	v_lshlrev_b32_e32 v58, 16, v52
	v_and_b32_e32 v59, 0xffff0000, v52
	v_lshlrev_b32_e32 v52, 16, v53
	v_and_b32_e32 v53, 0xffff0000, v53
	v_pk_add_f32 v[28:29], v[28:29], v[56:57]
	v_pk_add_f32 v[30:31], v[30:31], v[50:51]
	v_pk_add_f32 v[50:51], v[26:27], v[52:53]
	v_pk_add_f32 v[26:27], v[24:25], v[58:59]
	v_cvt_pk_bf16_f32 v24, v28, v29
	v_lshl_add_u64 v[28:29], s[68:69], 0, v[54:55]
	v_lshl_add_u64 v[28:29], v[168:169], 1, v[28:29]
	v_cvt_pk_bf16_f32 v25, v30, v31
	v_cvt_pk_bf16_f32 v26, v26, v27
	v_cvt_pk_bf16_f32 v27, v50, v51
	global_store_dwordx4 v[28:29], v[24:27], off sc0 nt
	v_lshlrev_b32_e32 v30, 16, v24
	v_and_b32_e32 v31, 0xffff0000, v42
	v_and_b32_e32 v24, 0xffff0000, v24
	v_mul_f32_e32 v24, v24, v24
	v_fmac_f32_e32 v24, v30, v30
	v_lshlrev_b32_e32 v30, 16, v25
	v_and_b32_e32 v25, 0xffff0000, v25
	v_mul_f32_e32 v25, v25, v25
	v_fmac_f32_e32 v25, v30, v30
	v_add_f32_e32 v24, v24, v25
	v_lshlrev_b32_e32 v25, 16, v26
	v_and_b32_e32 v26, 0xffff0000, v26
	v_mul_f32_e32 v26, v26, v26
	v_fmac_f32_e32 v26, v25, v25
	v_add_f32_e32 v24, v24, v26
	v_and_b32_e32 v26, 0xffff0000, v27
	v_lshlrev_b32_e32 v25, 16, v27
	v_mul_f32_e32 v26, v26, v26
	v_fmac_f32_e32 v26, v25, v25
	v_add_f32_e32 v50, v24, v26
	v_lshlrev_b32_e32 v24, 16, v40
	v_and_b32_e32 v25, 0xffff0000, v40
	v_lshlrev_b32_e32 v26, 16, v41
	v_and_b32_e32 v27, 0xffff0000, v41
	v_lshlrev_b32_e32 v30, 16, v42
	v_lshlrev_b32_e32 v40, 16, v43
	v_and_b32_e32 v41, 0xffff0000, v43
	v_pk_add_f32 v[20:21], v[20:21], v[24:25]
	v_pk_add_f32 v[24:25], v[18:19], v[40:41]
	v_pk_add_f32 v[18:19], v[16:17], v[30:31]
	v_cvt_pk_bf16_f32 v16, v20, v21
	v_pk_add_f32 v[22:23], v[22:23], v[26:27]
	v_lshlrev_b32_e32 v20, 16, v16
	v_cvt_pk_bf16_f32 v17, v22, v23
	v_cvt_pk_bf16_f32 v18, v18, v19
	v_cvt_pk_bf16_f32 v19, v24, v25
	global_store_dwordx4 v[28:29], v[16:19], off offset:256 sc0 nt
	s_nop 1
	v_and_b32_e32 v16, 0xffff0000, v16
	v_mul_f32_e32 v16, v16, v16
	v_fmac_f32_e32 v16, v20, v20
	v_lshlrev_b32_e32 v20, 16, v17
	v_and_b32_e32 v17, 0xffff0000, v17
	v_mul_f32_e32 v17, v17, v17
	v_add_f32_e32 v16, v50, v16
	v_fmac_f32_e32 v17, v20, v20
	v_add_f32_e32 v16, v16, v17
	v_lshlrev_b32_e32 v17, 16, v18
	v_and_b32_e32 v18, 0xffff0000, v18
	v_mul_f32_e32 v18, v18, v18
	v_fmac_f32_e32 v18, v17, v17
	v_add_f32_e32 v16, v16, v18
	v_and_b32_e32 v18, 0xffff0000, v19
	v_lshlrev_b32_e32 v17, 16, v19
	v_mul_f32_e32 v18, v18, v18
	v_fmac_f32_e32 v18, v17, v17
	v_add_f32_e32 v16, v16, v18
	ds_bpermute_b32 v17, v180, v16
	s_waitcnt lgkmcnt(0)
	v_add_f32_e32 v16, v16, v17
	ds_bpermute_b32 v17, v181, v16
	s_and_saveexec_b64 s[6:7], vcc
	s_cbranch_execz .LBB0_164
	s_waitcnt lgkmcnt(0)
	v_add_f32_e32 v18, v16, v17
	v_lshlrev_b64 v[16:17], 6, v[48:49]
	v_lshl_add_u64 v[16:17], s[48:49], 0, v[16:17]
	v_lshl_add_u64 v[16:17], s[74:75], 2, v[16:17]
	s_lshl_b32 s38, s8, 2
	v_lshl_add_u64 v[16:17], v[16:17], 0, s[38:39]
	flat_store_dword v[16:17], v18
.LBB0_164:
	s_or_b64 exec, exec, s[6:7]
	v_lshlrev_b32_e32 v16, 16, v36
	s_waitcnt lgkmcnt(0)
	v_and_b32_e32 v17, 0xffff0000, v36
	v_lshlrev_b32_e32 v20, 16, v38
	v_and_b32_e32 v21, 0xffff0000, v38
	v_lshlrev_b32_e32 v22, 16, v39
	v_and_b32_e32 v23, 0xffff0000, v39
	v_pk_add_f32 v[12:13], v[12:13], v[16:17]
	v_lshlrev_b32_e32 v18, 16, v37
	v_and_b32_e32 v19, 0xffff0000, v37
	v_pk_add_f32 v[16:17], v[10:11], v[22:23]
	v_pk_add_f32 v[10:11], v[8:9], v[20:21]
	v_cvt_pk_bf16_f32 v8, v12, v13
	v_lshl_add_u64 v[12:13], s[68:69], 0, v[46:47]
	v_pk_add_f32 v[14:15], v[14:15], v[18:19]
	v_lshl_add_u64 v[12:13], v[168:169], 1, v[12:13]
	v_cvt_pk_bf16_f32 v9, v14, v15
	v_cvt_pk_bf16_f32 v10, v10, v11
	v_cvt_pk_bf16_f32 v11, v16, v17
	global_store_dwordx4 v[12:13], v[8:11], off sc0 nt
	v_lshlrev_b32_e32 v14, 16, v8
	v_and_b32_e32 v15, 0xffff0000, v34
	v_and_b32_e32 v8, 0xffff0000, v8
	v_mul_f32_e32 v8, v8, v8
	v_fmac_f32_e32 v8, v14, v14
	v_lshlrev_b32_e32 v14, 16, v9
	v_and_b32_e32 v9, 0xffff0000, v9
	v_mul_f32_e32 v9, v9, v9
	v_fmac_f32_e32 v9, v14, v14
	v_add_f32_e32 v8, v8, v9
	v_lshlrev_b32_e32 v9, 16, v10
	v_and_b32_e32 v10, 0xffff0000, v10
	v_mul_f32_e32 v10, v10, v10
	v_fmac_f32_e32 v10, v9, v9
	v_add_f32_e32 v8, v8, v10
	v_and_b32_e32 v10, 0xffff0000, v11
	v_lshlrev_b32_e32 v9, 16, v11
	v_mul_f32_e32 v10, v10, v10
	v_fmac_f32_e32 v10, v9, v9
	v_add_f32_e32 v18, v8, v10
	v_lshlrev_b32_e32 v8, 16, v32
	v_and_b32_e32 v9, 0xffff0000, v32
	v_lshlrev_b32_e32 v14, 16, v34
	v_lshlrev_b32_e32 v10, 16, v33
	v_and_b32_e32 v11, 0xffff0000, v33
	v_lshlrev_b32_e32 v16, 16, v35
	v_and_b32_e32 v17, 0xffff0000, v35
	v_pk_add_f32 v[4:5], v[4:5], v[8:9]
	v_pk_add_f32 v[0:1], v[0:1], v[14:15]
	v_pk_add_f32 v[6:7], v[6:7], v[10:11]
	v_pk_add_f32 v[8:9], v[2:3], v[16:17]
	v_cvt_pk_bf16_f32 v2, v4, v5
	v_cvt_pk_bf16_f32 v3, v6, v7
	v_cvt_pk_bf16_f32 v4, v0, v1
	s_nop 0
	v_and_b32_e32 v1, 0xffff0000, v2
	v_lshlrev_b32_e32 v0, 16, v2
	v_mul_f32_e32 v1, v1, v1
	v_fmac_f32_e32 v1, v0, v0
	v_and_b32_e32 v6, 0xffff0000, v3
	v_add_f32_e32 v0, v18, v1
	v_lshlrev_b32_e32 v1, 16, v3
	v_mul_f32_e32 v6, v6, v6
	v_fmac_f32_e32 v6, v1, v1
	v_add_f32_e32 v0, v0, v6
	v_and_b32_e32 v6, 0xffff0000, v4
	v_lshlrev_b32_e32 v1, 16, v4
	v_mul_f32_e32 v6, v6, v6
	v_fmac_f32_e32 v6, v1, v1
	v_cvt_pk_bf16_f32 v5, v8, v9
	v_add_f32_e32 v0, v0, v6
	v_and_b32_e32 v6, 0xffff0000, v5
	v_lshlrev_b32_e32 v1, 16, v5
	v_mul_f32_e32 v6, v6, v6
	v_fmac_f32_e32 v6, v1, v1
	v_add_f32_e32 v0, v0, v6
	ds_bpermute_b32 v1, v180, v0
	global_store_dwordx4 v[12:13], v[2:5], off offset:256 sc0 nt
	s_waitcnt lgkmcnt(0)
	v_add_f32_e32 v0, v0, v1
	ds_bpermute_b32 v1, v181, v0
	s_and_saveexec_b64 s[6:7], vcc
	s_cbranch_execz .LBB0_166
	s_waitcnt lgkmcnt(0)
	v_add_f32_e32 v2, v0, v1
	v_lshlrev_b64 v[0:1], 6, v[44:45]
	v_lshl_add_u64 v[0:1], s[48:49], 0, v[0:1]
	v_lshl_add_u64 v[0:1], s[74:75], 2, v[0:1]
	s_lshl_b32 s38, s8, 2
	v_lshl_add_u64 v[0:1], v[0:1], 0, s[38:39]
	flat_store_dword v[0:1], v2

.LBB0_301:
	s_or_b64 exec, exec, s[6:7]
	v_readlane_b32 s2, v255, 14
	s_waitcnt lgkmcnt(0)
	s_barrier
	s_lshl_b32 s7, s4, 5
	v_add_u32_e32 v76, s2, v140
	ds_read_b128 v[142:145], v76
	s_lshl_b32 s6, s75, 8
	v_ashrrev_i32_e32 v159, 31, v158
	s_mov_b32 s3, 0x40000
	s_waitcnt lgkmcnt(0)
	v_mov_b32_e32 v76, v143
	v_mov_b32_e32 v77, v144
	v_mov_b32_e32 v143, v145
	v_pk_add_f32 v[76:77], v[76:77], v[142:143]
	s_nop 0
	v_add_f32_e32 v140, v76, v77
	v_div_scale_f32 v142, s[4:5], v140, v140, 1.0
	v_rcp_f32_e32 v143, v142
	s_or_b32 s4, s7, s6
	v_lshl_or_b32 v76, v208, 3, s4
	v_ashrrev_i32_e32 v77, 31, v76
	v_fma_f32 v144, -v142, v143, 1.0
	v_fmac_f32_e32 v143, v144, v143
	v_div_scale_f32 v144, vcc, 1.0, v140, 1.0
	v_mul_f32_e32 v145, v144, v143
	v_fma_f32 v146, -v142, v145, v144
	v_fmac_f32_e32 v145, v146, v143
	v_fma_f32 v142, -v142, v145, v144
	v_div_fmas_f32 v142, v142, v143, v145
	v_div_fixup_f32 v140, v142, v140, 1.0
	v_lshlrev_b64 v[142:143], 11, v[158:159]
	v_lshl_add_u64 v[142:143], s[86:87], 0, v[142:143]
	v_lshlrev_b64 v[160:161], 1, v[76:77]
	v_lshl_add_u64 v[76:77], v[142:143], 0, v[160:161]
	v_pk_mul_f32 v[126:127], v[126:127], v[140:141] op_sel_hi:[1,0]
	v_pk_mul_f32 v[124:125], v[124:125], v[140:141] op_sel_hi:[1,0]
	v_pk_mul_f32 v[120:121], v[120:121], v[140:141] op_sel_hi:[1,0]
	v_pk_mul_f32 v[116:117], v[116:117], v[140:141] op_sel_hi:[1,0]
	v_pk_mul_f32 v[118:119], v[118:119], v[140:141] op_sel_hi:[1,0]
	v_pk_mul_f32 v[142:143], v[172:173], v[140:141] op_sel_hi:[1,0]
	v_cvt_pk_bf16_f32 v124, v124, v125
	v_cvt_pk_bf16_f32 v125, v126, v127
	v_cvt_pk_bf16_f32 v126, v120, v121
	v_pk_mul_f32 v[120:121], v[122:123], v[140:141] op_sel_hi:[1,0]
	v_cvt_pk_bf16_f32 v127, v142, v143
	global_store_dwordx4 v[76:77], v[124:127], off sc0 nt
	v_pk_mul_f32 v[122:123], v[114:115], v[140:141] op_sel_hi:[1,0]
	v_cvt_pk_bf16_f32 v114, v116, v117
	v_cvt_pk_bf16_f32 v115, v120, v121
	v_cvt_pk_bf16_f32 v116, v118, v119
	v_lshl_add_u32 v118, v209, 4, s2
	v_cvt_pk_bf16_f32 v117, v122, v123
	ds_read_b128 v[118:121], v118
	global_store_dwordx4 v[76:77], v[114:117], off offset:256 sc0 nt
	s_mov_b64 s[6:7], -1
	s_waitcnt lgkmcnt(0)
	v_mov_b32_e32 v122, v119
	v_mov_b32_e32 v123, v120
	v_mov_b32_e32 v119, v121
	v_pk_add_f32 v[118:119], v[122:123], v[118:119]
	s_nop 0
	v_add_f32_e32 v118, v118, v119
	v_div_scale_f32 v119, s[4:5], v118, v118, 1.0
	v_rcp_f32_e32 v120, v119
	s_nop 0
	v_fma_f32 v114, -v119, v120, 1.0
	v_fmac_f32_e32 v120, v114, v120
	v_div_scale_f32 v114, vcc, 1.0, v118, 1.0
	v_mul_f32_e32 v115, v114, v120
	v_fma_f32 v116, -v119, v115, v114
	v_fmac_f32_e32 v115, v116, v120
	v_or_b32_e32 v116, 16, v158
	v_fma_f32 v114, -v119, v115, v114
	v_ashrrev_i32_e32 v117, 31, v116
	v_div_fmas_f32 v114, v114, v120, v115
	v_lshlrev_b64 v[116:117], 11, v[116:117]
	v_div_fixup_f32 v114, v114, v118, 1.0
	v_lshl_add_u64 v[116:117], s[86:87], 0, v[116:117]
	v_lshl_add_u64 v[116:117], v[116:117], 0, v[160:161]
	v_pk_mul_f32 v[110:111], v[110:111], v[114:115] op_sel_hi:[1,0]
	v_pk_mul_f32 v[108:109], v[108:109], v[114:115] op_sel_hi:[1,0]
	v_pk_mul_f32 v[104:105], v[104:105], v[114:115] op_sel_hi:[1,0]
	v_pk_mul_f32 v[100:101], v[100:101], v[114:115] op_sel_hi:[1,0]
	v_pk_mul_f32 v[102:103], v[102:103], v[114:115] op_sel_hi:[1,0]
	v_pk_mul_f32 v[112:113], v[112:113], v[114:115] op_sel_hi:[1,0]
	v_cvt_pk_bf16_f32 v108, v108, v109
	v_cvt_pk_bf16_f32 v109, v110, v111
	v_cvt_pk_bf16_f32 v110, v104, v105
	v_pk_mul_f32 v[104:105], v[106:107], v[114:115] op_sel_hi:[1,0]
	v_cvt_pk_bf16_f32 v111, v112, v113
	global_store_dwordx4 v[116:117], v[108:111], off sc0 nt
	v_pk_mul_f32 v[106:107], v[98:99], v[114:115] op_sel_hi:[1,0]
	v_cvt_pk_bf16_f32 v98, v100, v101
	v_cvt_pk_bf16_f32 v99, v104, v105
	v_cvt_pk_bf16_f32 v100, v102, v103
	v_lshl_add_u32 v102, v212, 4, s2
	v_cvt_pk_bf16_f32 v101, v106, v107
	ds_read_b128 v[102:105], v102
	global_store_dwordx4 v[116:117], v[98:101], off offset:256 sc0 nt
	s_waitcnt lgkmcnt(0)
	v_mov_b32_e32 v106, v103
	v_mov_b32_e32 v107, v104
	v_mov_b32_e32 v103, v105
	v_pk_add_f32 v[102:103], v[106:107], v[102:103]
	s_nop 0
	v_add_f32_e32 v102, v102, v103
	v_div_scale_f32 v103, s[4:5], v102, v102, 1.0
	v_rcp_f32_e32 v104, v103
	s_nop 0
	v_fma_f32 v98, -v103, v104, 1.0
	v_fmac_f32_e32 v104, v98, v104
	v_div_scale_f32 v98, vcc, 1.0, v102, 1.0
	v_mul_f32_e32 v99, v98, v104
	v_fma_f32 v100, -v103, v99, v98
	v_fmac_f32_e32 v99, v100, v104
	v_or_b32_e32 v100, 32, v158
	v_fma_f32 v98, -v103, v99, v98
	v_ashrrev_i32_e32 v101, 31, v100
	v_div_fmas_f32 v98, v98, v104, v99
	v_lshlrev_b64 v[100:101], 11, v[100:101]
	v_div_fixup_f32 v98, v98, v102, 1.0
	v_lshl_add_u64 v[100:101], s[86:87], 0, v[100:101]
	v_lshl_add_u64 v[100:101], v[100:101], 0, v[160:161]
	v_pk_mul_f32 v[94:95], v[94:95], v[98:99] op_sel_hi:[1,0]
	v_pk_mul_f32 v[92:93], v[92:93], v[98:99] op_sel_hi:[1,0]
	v_pk_mul_f32 v[88:89], v[88:89], v[98:99] op_sel_hi:[1,0]
	v_pk_mul_f32 v[84:85], v[84:85], v[98:99] op_sel_hi:[1,0]
	v_pk_mul_f32 v[86:87], v[86:87], v[98:99] op_sel_hi:[1,0]
	v_pk_mul_f32 v[96:97], v[96:97], v[98:99] op_sel_hi:[1,0]
	v_cvt_pk_bf16_f32 v92, v92, v93
	v_cvt_pk_bf16_f32 v93, v94, v95
	v_cvt_pk_bf16_f32 v94, v88, v89
	v_pk_mul_f32 v[88:89], v[90:91], v[98:99] op_sel_hi:[1,0]
	v_cvt_pk_bf16_f32 v95, v96, v97
	global_store_dwordx4 v[100:101], v[92:95], off sc0 nt
	v_pk_mul_f32 v[90:91], v[82:83], v[98:99] op_sel_hi:[1,0]
	v_cvt_pk_bf16_f32 v82, v84, v85
	v_cvt_pk_bf16_f32 v83, v88, v89
	v_cvt_pk_bf16_f32 v84, v86, v87
	v_lshl_add_u32 v86, v213, 4, s2
	v_cvt_pk_bf16_f32 v85, v90, v91
	ds_read_b128 v[86:89], v86
	global_store_dwordx4 v[100:101], v[82:85], off offset:256 sc0 nt
	s_waitcnt lgkmcnt(0)
	v_mov_b32_e32 v90, v87
	v_mov_b32_e32 v91, v88
	v_mov_b32_e32 v87, v89
	v_pk_add_f32 v[86:87], v[90:91], v[86:87]
	s_nop 0
	v_add_f32_e32 v86, v86, v87
	v_div_scale_f32 v87, s[4:5], v86, v86, 1.0
	v_rcp_f32_e32 v88, v87
	s_nop 0
	v_fma_f32 v82, -v87, v88, 1.0
	v_fmac_f32_e32 v88, v82, v88
	v_div_scale_f32 v82, vcc, 1.0, v86, 1.0
	v_mul_f32_e32 v83, v82, v88
	v_fma_f32 v84, -v87, v83, v82
	v_fmac_f32_e32 v83, v84, v88
	v_or_b32_e32 v84, 48, v158
	v_fma_f32 v82, -v87, v83, v82
	v_ashrrev_i32_e32 v85, 31, v84
	v_div_fmas_f32 v82, v82, v88, v83
	v_lshlrev_b64 v[84:85], 11, v[84:85]
	v_div_fixup_f32 v82, v82, v86, 1.0
	v_lshl_add_u64 v[84:85], s[86:87], 0, v[84:85]
	v_lshl_add_u64 v[84:85], v[84:85], 0, v[160:161]
	v_pk_mul_f32 v[78:79], v[78:79], v[82:83] op_sel_hi:[1,0]
	v_pk_mul_f32 v[60:61], v[60:61], v[82:83] op_sel_hi:[1,0]
	v_pk_mul_f32 v[86:87], v[74:75], v[82:83] op_sel_hi:[1,0]
	v_pk_mul_f32 v[74:75], v[72:73], v[82:83] op_sel_hi:[1,0]
	v_cvt_pk_bf16_f32 v72, v60, v61
	v_cvt_pk_bf16_f32 v73, v78, v79
	v_pk_mul_f32 v[52:53], v[52:53], v[82:83] op_sel_hi:[1,0]
	v_cvt_pk_bf16_f32 v74, v74, v75
	v_cvt_pk_bf16_f32 v75, v86, v87
	global_store_dwordx4 v[84:85], v[72:75], off sc0 nt
	v_pk_mul_f32 v[60:61], v[70:71], v[82:83] op_sel_hi:[1,0]
	v_pk_mul_f32 v[70:71], v[68:69], v[82:83] op_sel_hi:[1,0]
	v_pk_mul_f32 v[72:73], v[80:81], v[82:83] op_sel_hi:[1,0]
	v_cvt_pk_bf16_f32 v68, v52, v53
	v_lshl_add_u32 v52, v214, 4, s2
	v_cvt_pk_bf16_f32 v69, v60, v61
	v_cvt_pk_bf16_f32 v70, v70, v71
	v_cvt_pk_bf16_f32 v71, v72, v73
	ds_read_b128 v[72:75], v52
	global_store_dwordx4 v[84:85], v[68:71], off offset:256 sc0 nt
	s_waitcnt lgkmcnt(0)
	v_mov_b32_e32 v52, v73
	v_mov_b32_e32 v53, v74
	v_mov_b32_e32 v73, v75
	v_pk_add_f32 v[52:53], v[52:53], v[72:73]
	s_nop 0
	v_add_f32_e32 v52, v52, v53
	v_div_scale_f32 v53, s[4:5], v52, v52, 1.0
	v_rcp_f32_e32 v60, v53
	s_nop 0
	v_fma_f32 v61, -v53, v60, 1.0
	v_fmac_f32_e32 v60, v61, v60
	v_div_scale_f32 v61, vcc, 1.0, v52, 1.0
	v_mul_f32_e32 v68, v61, v60
	v_fma_f32 v69, -v53, v68, v61
	v_fmac_f32_e32 v68, v69, v60
	v_fma_f32 v53, -v53, v68, v61
	v_div_fmas_f32 v53, v53, v60, v68
	v_div_fixup_f32 v52, v53, v52, 1.0
	v_pk_mul_f32 v[60:61], v[62:63], v[52:53] op_sel_hi:[1,0]
	v_pk_mul_f32 v[56:57], v[56:57], v[52:53] op_sel_hi:[1,0]
	v_pk_mul_f32 v[58:59], v[58:59], v[52:53] op_sel_hi:[1,0]
	v_cvt_pk_bf16_f32 v56, v56, v57
	v_cvt_pk_bf16_f32 v57, v60, v61
	v_add_co_u32_e32 v60, vcc, s3, v76
	v_pk_mul_f32 v[40:41], v[40:41], v[52:53] op_sel_hi:[1,0]
	s_nop 0
	v_addc_co_u32_e32 v61, vcc, 0, v77, vcc
	v_pk_mul_f32 v[62:63], v[66:67], v[52:53] op_sel_hi:[1,0]
	v_cvt_pk_bf16_f32 v58, v58, v59
	v_pk_mul_f32 v[50:51], v[50:51], v[52:53] op_sel_hi:[1,0]
	v_cvt_pk_bf16_f32 v59, v62, v63
	global_store_dwordx4 v[60:61], v[56:59], off sc0 nt
	s_mov_b32 s3, 0x48000
	s_nop 0
	v_pk_mul_f32 v[56:57], v[64:65], v[52:53] op_sel_hi:[1,0]
	v_pk_mul_f32 v[52:53], v[48:49], v[52:53] op_sel_hi:[1,0]
	v_cvt_pk_bf16_f32 v48, v40, v41
	v_lshl_add_u32 v40, v215, 4, s2
	v_cvt_pk_bf16_f32 v49, v50, v51
	v_cvt_pk_bf16_f32 v50, v52, v53
	v_cvt_pk_bf16_f32 v51, v56, v57
	ds_read_b128 v[56:59], v40
	s_waitcnt lgkmcnt(0)
	v_mov_b32_e32 v40, v57
	v_mov_b32_e32 v41, v58
	v_mov_b32_e32 v57, v59
	v_pk_add_f32 v[40:41], v[40:41], v[56:57]
	s_nop 0
	v_add_f32_e32 v52, v40, v41
	v_div_scale_f32 v53, s[4:5], v52, v52, 1.0
	v_rcp_f32_e32 v56, v53
	s_mov_b64 s[4:5], 0x40000
	v_lshl_add_u64 v[40:41], v[76:77], 0, s[4:5]
	global_store_dwordx4 v[40:41], v[48:51], off offset:256 sc0 nt
	v_fma_f32 v40, -v53, v56, 1.0
	v_fmac_f32_e32 v56, v40, v56
	v_div_scale_f32 v40, vcc, 1.0, v52, 1.0
	v_mul_f32_e32 v41, v40, v56
	v_fma_f32 v48, -v53, v41, v40
	v_fmac_f32_e32 v41, v48, v56
	v_fma_f32 v40, -v53, v41, v40
	v_div_fmas_f32 v40, v40, v56, v41
	v_div_fixup_f32 v48, v40, v52, 1.0
	v_pk_mul_f32 v[36:37], v[36:37], v[48:49] op_sel_hi:[1,0]
	v_pk_mul_f32 v[44:45], v[44:45], v[48:49] op_sel_hi:[1,0]
	v_cvt_pk_bf16_f32 v40, v36, v37
	v_add_co_u32_e32 v36, vcc, s3, v76
	v_pk_mul_f32 v[42:43], v[42:43], v[48:49] op_sel_hi:[1,0]
	v_cvt_pk_bf16_f32 v41, v44, v45
	s_nop 0
	v_addc_co_u32_e32 v37, vcc, 0, v77, vcc
	v_pk_mul_f32 v[24:25], v[24:25], v[48:49] op_sel_hi:[1,0]
	v_pk_mul_f32 v[50:51], v[54:55], v[48:49] op_sel_hi:[1,0]
	v_cvt_pk_bf16_f32 v42, v42, v43
	v_pk_mul_f32 v[34:35], v[34:35], v[48:49] op_sel_hi:[1,0]
	v_cvt_pk_bf16_f32 v43, v50, v51
	global_store_dwordx4 v[36:37], v[40:43], off sc0 nt
	v_pk_mul_f32 v[36:37], v[46:47], v[48:49] op_sel_hi:[1,0]
	s_mov_b32 s3, 0x50000
	v_pk_mul_f32 v[40:41], v[32:33], v[48:49] op_sel_hi:[1,0]
	v_cvt_pk_bf16_f32 v32, v24, v25
	v_lshl_add_u32 v24, v216, 4, s2
	v_cvt_pk_bf16_f32 v33, v34, v35
	v_cvt_pk_bf16_f32 v34, v40, v41
	v_cvt_pk_bf16_f32 v35, v36, v37
	ds_read_b128 v[40:43], v24
	s_waitcnt lgkmcnt(0)
	v_mov_b32_e32 v24, v41
	v_mov_b32_e32 v25, v42
	v_mov_b32_e32 v41, v43
	v_pk_add_f32 v[24:25], v[24:25], v[40:41]
	s_nop 0
	v_add_f32_e32 v36, v24, v25
	v_div_scale_f32 v37, s[4:5], v36, v36, 1.0
	v_rcp_f32_e32 v40, v37
	s_mov_b64 s[4:5], 0x48000
	v_lshl_add_u64 v[24:25], v[76:77], 0, s[4:5]
	global_store_dwordx4 v[24:25], v[32:35], off offset:256 sc0 nt
	v_fma_f32 v24, -v37, v40, 1.0
	v_fmac_f32_e32 v40, v24, v40
	v_div_scale_f32 v24, vcc, 1.0, v36, 1.0
	v_mul_f32_e32 v25, v24, v40
	v_fma_f32 v32, -v37, v25, v24
	v_fmac_f32_e32 v25, v32, v40
	v_fma_f32 v24, -v37, v25, v24
	v_div_fmas_f32 v24, v24, v40, v25
	v_div_fixup_f32 v32, v24, v36, 1.0
	v_pk_mul_f32 v[24:25], v[28:29], v[32:33] op_sel_hi:[1,0]
	v_pk_mul_f32 v[22:23], v[22:23], v[32:33] op_sel_hi:[1,0]
	v_pk_mul_f32 v[26:27], v[26:27], v[32:33] op_sel_hi:[1,0]
	v_cvt_pk_bf16_f32 v22, v22, v23
	v_cvt_pk_bf16_f32 v23, v24, v25
	v_pk_mul_f32 v[28:29], v[38:39], v[32:33] op_sel_hi:[1,0]
	v_cvt_pk_bf16_f32 v24, v26, v27
	v_add_co_u32_e32 v26, vcc, s3, v76
	v_cvt_pk_bf16_f32 v25, v28, v29
	v_pk_mul_f32 v[10:11], v[10:11], v[32:33] op_sel_hi:[1,0]
	s_nop 0
	v_addc_co_u32_e32 v27, vcc, 0, v77, vcc
	global_store_dwordx4 v[26:27], v[22:25], off sc0 nt
	v_pk_mul_f32 v[20:21], v[20:21], v[32:33] op_sel_hi:[1,0]
	s_nop 0
	v_pk_mul_f32 v[22:23], v[30:31], v[32:33] op_sel_hi:[1,0]
	v_pk_mul_f32 v[24:25], v[18:19], v[32:33] op_sel_hi:[1,0]
	v_cvt_pk_bf16_f32 v18, v10, v11
	v_lshl_add_u32 v10, v217, 4, s2
	v_cvt_pk_bf16_f32 v19, v20, v21
	v_cvt_pk_bf16_f32 v20, v24, v25
	v_cvt_pk_bf16_f32 v21, v22, v23
	ds_read_b128 v[22:25], v10
	s_mov_b64 s[2:3], 0x50000
	s_waitcnt lgkmcnt(0)
	v_mov_b32_e32 v10, v23
	v_mov_b32_e32 v11, v24
	v_mov_b32_e32 v23, v25
	v_pk_add_f32 v[10:11], v[10:11], v[22:23]
	s_nop 0
	v_add_f32_e32 v22, v10, v11
	v_div_scale_f32 v23, s[4:5], v22, v22, 1.0
	v_rcp_f32_e32 v24, v23
	v_lshl_add_u64 v[10:11], v[76:77], 0, s[2:3]
	global_store_dwordx4 v[10:11], v[18:21], off offset:256 sc0 nt
	s_mov_b64 s[2:3], 0x58000
	v_fma_f32 v10, -v23, v24, 1.0
	v_fmac_f32_e32 v24, v10, v24
	v_div_scale_f32 v10, vcc, 1.0, v22, 1.0
	v_mul_f32_e32 v11, v10, v24
	v_fma_f32 v18, -v23, v11, v10
	v_fmac_f32_e32 v11, v18, v24
	v_fma_f32 v10, -v23, v11, v10
	v_div_fmas_f32 v10, v10, v24, v11
	v_div_fixup_f32 v10, v10, v22, 1.0
	v_lshl_add_u64 v[18:19], v[76:77], 0, s[2:3]
	v_pk_mul_f32 v[12:13], v[12:13], v[10:11] op_sel_hi:[1,0]
	v_pk_mul_f32 v[6:7], v[6:7], v[10:11] op_sel_hi:[1,0]
	s_mov_b32 s2, 0x58000
	v_cvt_pk_bf16_f32 v6, v6, v7
	v_cvt_pk_bf16_f32 v7, v12, v13
	v_add_co_u32_e32 v12, vcc, s2, v76
	v_pk_mul_f32 v[8:9], v[8:9], v[10:11] op_sel_hi:[1,0]
	s_nop 0
	v_addc_co_u32_e32 v13, vcc, 0, v77, vcc
	v_pk_mul_f32 v[0:1], v[0:1], v[10:11] op_sel_hi:[1,0]
	v_pk_mul_f32 v[2:3], v[2:3], v[10:11] op_sel_hi:[1,0]
	s_andn2_b64 vcc, exec, s[40:41]
	v_pk_mul_f32 v[16:17], v[16:17], v[10:11] op_sel_hi:[1,0]
	v_cvt_pk_bf16_f32 v8, v8, v9
	v_pk_mul_f32 v[4:5], v[4:5], v[10:11] op_sel_hi:[1,0]
	v_cvt_pk_bf16_f32 v9, v16, v17
	global_store_dwordx4 v[12:13], v[6:9], off sc0 nt
	v_cvt_pk_bf16_f32 v0, v0, v1
	v_cvt_pk_bf16_f32 v1, v4, v5
	v_cvt_pk_bf16_f32 v2, v2, v3
	s_nop 1
	v_pk_mul_f32 v[6:7], v[14:15], v[10:11] op_sel_hi:[1,0]
	s_nop 0
	v_cvt_pk_bf16_f32 v3, v6, v7
	global_store_dwordx4 v[18:19], v[0:3], off offset:256 sc0 nt
	s_cbranch_vccnz .LBB0_226
	s_cmp_lg_u32 s52, s74
	s_cselect_b64 s[4:5], -1, 0
	s_and_b64 s[4:5], s[40:41], s[4:5]
	v_cndmask_b32_e64 v0, 0, 1, s[4:5]
	s_andn2_b64 vcc, exec, s[46:47]
	v_readfirstlane_b32 s4, v0
	s_cbranch_vccnz .LBB0_225
	s_barrier
	s_branch .LBB0_225

.LBB0_336:
	s_mov_b32 s6, -1
	s_lshl_b32 s5, s5, 8
	v_mbcnt_lo_u32_b32 v128, s6, 0
	v_mbcnt_hi_u32_b32 v128, s6, v128
	s_getreg_b32 s6, hwreg(HW_REG_HW_ID, 0, 6)
	s_and_b32 s6, s6, 63
	s_lshl_b32 s6, s6, 2
	s_add_i32 s6, s6, 0
	s_add_i32 s6, s6, 0x20200
	v_mov_b32_e32 v129, s6
	ds_read_b32 v129, v129
	v_bfrev_b32_e32 v130, 0.5
	s_lshl_b32 s56, s4, 2
	s_ashr_i32 s57, s56, 31
	s_waitcnt lgkmcnt(0)
	v_readfirstlane_b32 s6, v129
	s_nop 1
	v_lshl_add_u32 v128, s6, 6, v128
	s_nop 0
	v_readfirstlane_b32 s6, v128
	s_bfe_u32 s8, s6, 0x20006
	s_ashr_i32 s6, s6, 2
	s_andn2_b32 s6, s6, 63
	s_add_i32 s6, s6, s5
	v_and_or_b32 v170, v128, 15, s6
	s_lshl_b32 s5, s4, 8
	s_lshl_b32 s6, s8, 5
	v_bfe_u32 v129, v128, 4, 2
	s_or_b32 s5, s6, s5
	v_lshl_or_b32 v168, v129, 3, s5
	v_ashrrev_i32_e32 v169, 31, v168
	v_lshlrev_b64 v[146:147], 1, v[168:169]
	v_ashrrev_i32_e32 v171, 31, v170
	v_lshlrev_b32_e32 v128, 2, v128
	v_lshl_add_u64 v[172:173], s[68:69], 0, v[146:147]
	v_lshlrev_b64 v[148:149], 11, v[170:171]
	v_bitop3_b32 v181, v128, 64, v130 bitop3:0x6c
	v_bitop3_b32 v180, v128, s84, v130 bitop3:0x6c
	v_cmp_eq_u32_e32 vcc, 0, v129
	v_lshl_add_u64 v[128:129], v[172:173], 0, v[148:149]
	global_load_dwordx4 v[142:145], v[128:129], off
	global_load_dwordx4 v[136:139], v[128:129], off offset:256
	v_or_b32_e32 v174, 16, v170
	v_ashrrev_i32_e32 v175, 31, v174
	v_lshlrev_b64 v[176:177], 11, v[174:175]
	v_lshl_add_u64 v[128:129], v[172:173], 0, v[176:177]
	global_load_dwordx4 v[132:135], v[128:129], off
	s_nop 0
	global_load_dwordx4 v[128:131], v[128:129], off offset:256
	s_waitcnt vmcnt(0)
	v_lshlrev_b32_e32 v150, 16, v142
	v_and_b32_e32 v151, 0xffff0000, v142
	v_lshlrev_b32_e32 v142, 16, v143
	v_and_b32_e32 v143, 0xffff0000, v143
	v_lshlrev_b32_e32 v152, 16, v144
	v_and_b32_e32 v153, 0xffff0000, v144
	v_lshlrev_b32_e32 v144, 16, v145
	v_and_b32_e32 v145, 0xffff0000, v145
	v_pk_add_f32 v[124:125], v[124:125], v[150:151]
	v_pk_add_f32 v[126:127], v[126:127], v[142:143]
	v_pk_add_f32 v[142:143], v[122:123], v[144:145]
	v_pk_add_f32 v[122:123], v[120:121], v[152:153]
	v_cvt_pk_bf16_f32 v120, v124, v125
	v_lshl_add_u64 v[124:125], s[68:69], 0, v[148:149]
	v_lshl_add_u64 v[124:125], v[124:125], 0, v[146:147]
	v_cvt_pk_bf16_f32 v121, v126, v127
	v_cvt_pk_bf16_f32 v122, v122, v123
	v_cvt_pk_bf16_f32 v123, v142, v143
	global_store_dwordx4 v[124:125], v[120:123], off sc0 nt
	v_lshlrev_b32_e32 v126, 16, v120
	v_and_b32_e32 v127, 0xffff0000, v138
	v_and_b32_e32 v120, 0xffff0000, v120
	v_mul_f32_e32 v120, v120, v120
	v_fmac_f32_e32 v120, v126, v126
	v_lshlrev_b32_e32 v126, 16, v121
	v_and_b32_e32 v121, 0xffff0000, v121
	v_mul_f32_e32 v121, v121, v121
	v_fmac_f32_e32 v121, v126, v126
	v_add_f32_e32 v120, v120, v121
	v_lshlrev_b32_e32 v121, 16, v122
	v_and_b32_e32 v122, 0xffff0000, v122
	v_mul_f32_e32 v122, v122, v122
	v_fmac_f32_e32 v122, v121, v121
	v_add_f32_e32 v120, v120, v122
	v_and_b32_e32 v122, 0xffff0000, v123
	v_lshlrev_b32_e32 v121, 16, v123
	v_mul_f32_e32 v122, v122, v122
	v_fmac_f32_e32 v122, v121, v121
	v_add_f32_e32 v142, v120, v122
	v_lshlrev_b32_e32 v120, 16, v136
	v_and_b32_e32 v121, 0xffff0000, v136
	v_lshlrev_b32_e32 v122, 16, v137
	v_and_b32_e32 v123, 0xffff0000, v137
	v_lshlrev_b32_e32 v126, 16, v138
	v_lshlrev_b32_e32 v136, 16, v139
	v_and_b32_e32 v137, 0xffff0000, v139
	v_pk_add_f32 v[116:117], v[116:117], v[120:121]
	v_pk_add_f32 v[120:121], v[114:115], v[136:137]
	v_pk_add_f32 v[114:115], v[112:113], v[126:127]
	v_cvt_pk_bf16_f32 v112, v116, v117
	v_pk_add_f32 v[118:119], v[118:119], v[122:123]
	v_lshlrev_b32_e32 v116, 16, v112
	v_cvt_pk_bf16_f32 v113, v118, v119
	v_cvt_pk_bf16_f32 v114, v114, v115
	v_cvt_pk_bf16_f32 v115, v120, v121
	global_store_dwordx4 v[124:125], v[112:115], off offset:256 sc0 nt
	s_nop 1
	v_and_b32_e32 v112, 0xffff0000, v112
	v_mul_f32_e32 v112, v112, v112
	v_fmac_f32_e32 v112, v116, v116
	v_lshlrev_b32_e32 v116, 16, v113
	v_and_b32_e32 v113, 0xffff0000, v113
	v_mul_f32_e32 v113, v113, v113
	v_add_f32_e32 v112, v142, v112
	v_fmac_f32_e32 v113, v116, v116
	v_add_f32_e32 v112, v112, v113
	v_lshlrev_b32_e32 v113, 16, v114
	v_and_b32_e32 v114, 0xffff0000, v114
	v_mul_f32_e32 v114, v114, v114
	v_fmac_f32_e32 v114, v113, v113
	v_add_f32_e32 v112, v112, v114
	v_and_b32_e32 v114, 0xffff0000, v115
	v_lshlrev_b32_e32 v113, 16, v115
	v_mul_f32_e32 v114, v114, v114
	v_fmac_f32_e32 v114, v113, v113
	v_add_f32_e32 v112, v112, v114
	ds_bpermute_b32 v113, v181, v112
	s_waitcnt lgkmcnt(0)
	v_add_f32_e32 v112, v112, v113
	ds_bpermute_b32 v113, v180, v112
	s_and_saveexec_b64 s[6:7], vcc
	s_cbranch_execz .LBB0_338
	s_waitcnt lgkmcnt(0)
	v_add_f32_e32 v114, v112, v113
	v_lshlrev_b64 v[112:113], 6, v[170:171]
	v_lshl_add_u64 v[112:113], s[46:47], 0, v[112:113]
	v_lshl_add_u64 v[112:113], s[56:57], 2, v[112:113]
	s_lshl_b32 s38, s8, 2
	v_lshl_add_u64 v[112:113], v[112:113], 0, s[38:39]
	flat_store_dword v[112:113], v114
.LBB0_338:
	s_or_b64 exec, exec, s[6:7]
	v_lshlrev_b32_e32 v112, 16, v132
	s_waitcnt lgkmcnt(0)
	v_and_b32_e32 v113, 0xffff0000, v132
	v_lshlrev_b32_e32 v116, 16, v134
	v_and_b32_e32 v117, 0xffff0000, v134
	v_lshlrev_b32_e32 v118, 16, v135
	v_and_b32_e32 v119, 0xffff0000, v135
	v_pk_add_f32 v[108:109], v[108:109], v[112:113]
	v_lshlrev_b32_e32 v114, 16, v133
	v_and_b32_e32 v115, 0xffff0000, v133
	v_pk_add_f32 v[112:113], v[106:107], v[118:119]
	v_pk_add_f32 v[106:107], v[104:105], v[116:117]
	v_cvt_pk_bf16_f32 v104, v108, v109
	v_lshl_add_u64 v[108:109], s[68:69], 0, v[176:177]
	v_pk_add_f32 v[110:111], v[110:111], v[114:115]
	v_lshl_add_u64 v[108:109], v[168:169], 1, v[108:109]
	v_cvt_pk_bf16_f32 v105, v110, v111
	v_cvt_pk_bf16_f32 v106, v106, v107
	v_cvt_pk_bf16_f32 v107, v112, v113
	global_store_dwordx4 v[108:109], v[104:107], off sc0 nt
	v_lshlrev_b32_e32 v110, 16, v104
	v_and_b32_e32 v111, 0xffff0000, v130
	v_and_b32_e32 v104, 0xffff0000, v104
	v_mul_f32_e32 v104, v104, v104
	v_fmac_f32_e32 v104, v110, v110
	v_lshlrev_b32_e32 v110, 16, v105
	v_and_b32_e32 v105, 0xffff0000, v105
	v_mul_f32_e32 v105, v105, v105
	v_fmac_f32_e32 v105, v110, v110
	v_add_f32_e32 v104, v104, v105
	v_lshlrev_b32_e32 v105, 16, v106
	v_and_b32_e32 v106, 0xffff0000, v106
	v_mul_f32_e32 v106, v106, v106
	v_fmac_f32_e32 v106, v105, v105
	v_add_f32_e32 v104, v104, v106
	v_and_b32_e32 v106, 0xffff0000, v107
	v_lshlrev_b32_e32 v105, 16, v107
	v_mul_f32_e32 v106, v106, v106
	v_fmac_f32_e32 v106, v105, v105
	v_add_f32_e32 v114, v104, v106
	v_lshlrev_b32_e32 v104, 16, v128
	v_and_b32_e32 v105, 0xffff0000, v128
	v_lshlrev_b32_e32 v110, 16, v130
	v_lshlrev_b32_e32 v106, 16, v129
	v_and_b32_e32 v107, 0xffff0000, v129
	v_lshlrev_b32_e32 v112, 16, v131
	v_and_b32_e32 v113, 0xffff0000, v131
	v_pk_add_f32 v[100:101], v[100:101], v[104:105]
	v_pk_add_f32 v[96:97], v[96:97], v[110:111]
	v_pk_add_f32 v[102:103], v[102:103], v[106:107]
	v_pk_add_f32 v[104:105], v[98:99], v[112:113]
	v_cvt_pk_bf16_f32 v98, v100, v101
	v_cvt_pk_bf16_f32 v99, v102, v103
	v_cvt_pk_bf16_f32 v100, v96, v97
	s_nop 0
	v_and_b32_e32 v97, 0xffff0000, v98
	v_lshlrev_b32_e32 v96, 16, v98
	v_mul_f32_e32 v97, v97, v97
	v_fmac_f32_e32 v97, v96, v96
	v_and_b32_e32 v102, 0xffff0000, v99
	v_add_f32_e32 v96, v114, v97
	v_lshlrev_b32_e32 v97, 16, v99
	v_mul_f32_e32 v102, v102, v102
	v_fmac_f32_e32 v102, v97, v97
	v_add_f32_e32 v96, v96, v102
	v_and_b32_e32 v102, 0xffff0000, v100
	v_lshlrev_b32_e32 v97, 16, v100
	v_mul_f32_e32 v102, v102, v102
	v_fmac_f32_e32 v102, v97, v97
	v_cvt_pk_bf16_f32 v101, v104, v105
	v_add_f32_e32 v96, v96, v102
	v_and_b32_e32 v102, 0xffff0000, v101
	v_lshlrev_b32_e32 v97, 16, v101
	v_mul_f32_e32 v102, v102, v102
	v_fmac_f32_e32 v102, v97, v97
	v_add_f32_e32 v96, v96, v102
	ds_bpermute_b32 v97, v181, v96
	global_store_dwordx4 v[108:109], v[98:101], off offset:256 sc0 nt
	s_waitcnt lgkmcnt(0)
	v_add_f32_e32 v96, v96, v97
	ds_bpermute_b32 v97, v180, v96
	s_and_saveexec_b64 s[6:7], vcc
	s_cbranch_execz .LBB0_340
	s_waitcnt lgkmcnt(0)
	v_add_f32_e32 v98, v96, v97
	v_lshlrev_b64 v[96:97], 6, v[174:175]
	v_lshl_add_u64 v[96:97], s[46:47], 0, v[96:97]
	v_lshl_add_u64 v[96:97], s[56:57], 2, v[96:97]
	s_lshl_b32 s38, s8, 2
	v_lshl_add_u64 v[96:97], v[96:97], 0, s[38:39]
	flat_store_dword v[96:97], v98
.LBB0_340:
	s_or_b64 exec, exec, s[6:7]
	v_or_b32_e32 v112, 32, v170
	v_ashrrev_i32_e32 v113, 31, v112
	v_lshlrev_b64 v[118:119], 11, v[112:113]
	s_waitcnt lgkmcnt(0)
	v_lshl_add_u64 v[96:97], v[172:173], 0, v[118:119]
	global_load_dwordx4 v[114:117], v[96:97], off
	global_load_dwordx4 v[104:107], v[96:97], off offset:256
	v_or_b32_e32 v108, 48, v170
	v_ashrrev_i32_e32 v109, 31, v108
	v_lshlrev_b64 v[110:111], 11, v[108:109]
	v_lshl_add_u64 v[96:97], v[172:173], 0, v[110:111]
	global_load_dwordx4 v[100:103], v[96:97], off
	s_nop 0
	global_load_dwordx4 v[96:99], v[96:97], off offset:256
	s_waitcnt vmcnt(0)
	v_lshlrev_b32_e32 v120, 16, v114
	v_and_b32_e32 v121, 0xffff0000, v114
	v_lshlrev_b32_e32 v114, 16, v115
	v_and_b32_e32 v115, 0xffff0000, v115
	v_lshlrev_b32_e32 v122, 16, v116
	v_and_b32_e32 v123, 0xffff0000, v116
	v_lshlrev_b32_e32 v116, 16, v117
	v_and_b32_e32 v117, 0xffff0000, v117
	v_pk_add_f32 v[92:93], v[92:93], v[120:121]
	v_pk_add_f32 v[94:95], v[94:95], v[114:115]
	v_pk_add_f32 v[114:115], v[90:91], v[116:117]
	v_pk_add_f32 v[90:91], v[88:89], v[122:123]
	v_cvt_pk_bf16_f32 v88, v92, v93
	v_lshl_add_u64 v[92:93], s[68:69], 0, v[118:119]
	v_lshl_add_u64 v[92:93], v[168:169], 1, v[92:93]
	v_cvt_pk_bf16_f32 v89, v94, v95
	v_cvt_pk_bf16_f32 v90, v90, v91
	v_cvt_pk_bf16_f32 v91, v114, v115
	global_store_dwordx4 v[92:93], v[88:91], off sc0 nt
	v_lshlrev_b32_e32 v94, 16, v88
	v_and_b32_e32 v95, 0xffff0000, v106
	v_and_b32_e32 v88, 0xffff0000, v88
	v_mul_f32_e32 v88, v88, v88
	v_fmac_f32_e32 v88, v94, v94
	v_lshlrev_b32_e32 v94, 16, v89
	v_and_b32_e32 v89, 0xffff0000, v89
	v_mul_f32_e32 v89, v89, v89
	v_fmac_f32_e32 v89, v94, v94
	v_add_f32_e32 v88, v88, v89
	v_lshlrev_b32_e32 v89, 16, v90
	v_and_b32_e32 v90, 0xffff0000, v90
	v_mul_f32_e32 v90, v90, v90
	v_fmac_f32_e32 v90, v89, v89
	v_add_f32_e32 v88, v88, v90
	v_and_b32_e32 v90, 0xffff0000, v91
	v_lshlrev_b32_e32 v89, 16, v91
	v_mul_f32_e32 v90, v90, v90
	v_fmac_f32_e32 v90, v89, v89
	v_add_f32_e32 v114, v88, v90
	v_lshlrev_b32_e32 v88, 16, v104
	v_and_b32_e32 v89, 0xffff0000, v104
	v_lshlrev_b32_e32 v90, 16, v105
	v_and_b32_e32 v91, 0xffff0000, v105
	v_lshlrev_b32_e32 v94, 16, v106
	v_lshlrev_b32_e32 v104, 16, v107
	v_and_b32_e32 v105, 0xffff0000, v107
	v_pk_add_f32 v[84:85], v[84:85], v[88:89]
	v_pk_add_f32 v[88:89], v[82:83], v[104:105]
	v_pk_add_f32 v[82:83], v[80:81], v[94:95]
	v_cvt_pk_bf16_f32 v80, v84, v85
	v_pk_add_f32 v[86:87], v[86:87], v[90:91]
	v_lshlrev_b32_e32 v84, 16, v80
	v_cvt_pk_bf16_f32 v81, v86, v87
	v_cvt_pk_bf16_f32 v82, v82, v83
	v_cvt_pk_bf16_f32 v83, v88, v89
	global_store_dwordx4 v[92:93], v[80:83], off offset:256 sc0 nt
	s_nop 1
	v_and_b32_e32 v80, 0xffff0000, v80
	v_mul_f32_e32 v80, v80, v80
	v_fmac_f32_e32 v80, v84, v84
	v_lshlrev_b32_e32 v84, 16, v81
	v_and_b32_e32 v81, 0xffff0000, v81
	v_mul_f32_e32 v81, v81, v81
	v_add_f32_e32 v80, v114, v80
	v_fmac_f32_e32 v81, v84, v84
	v_add_f32_e32 v80, v80, v81
	v_lshlrev_b32_e32 v81, 16, v82
	v_and_b32_e32 v82, 0xffff0000, v82
	v_mul_f32_e32 v82, v82, v82
	v_fmac_f32_e32 v82, v81, v81
	v_add_f32_e32 v80, v80, v82
	v_and_b32_e32 v82, 0xffff0000, v83
	v_lshlrev_b32_e32 v81, 16, v83
	v_mul_f32_e32 v82, v82, v82
	v_fmac_f32_e32 v82, v81, v81
	v_add_f32_e32 v80, v80, v82
	ds_bpermute_b32 v81, v181, v80
	s_waitcnt lgkmcnt(0)
	v_add_f32_e32 v80, v80, v81
	ds_bpermute_b32 v81, v180, v80
	s_mov_b64 s[6:7], exec
	s_and_b64 s[4:5], s[6:7], vcc
	v_mov_b32_e32 v198, v216
	v_mov_b32_e32 v199, v217
	v_mov_b32_e32 v248, v218
	v_mov_b32_e32 v205, v219
	v_mov_b32_e32 v196, v220
	s_mov_b64 exec, s[4:5]
	s_cbranch_execz .LBB0_342
	s_waitcnt lgkmcnt(0)
	v_add_f32_e32 v82, v80, v81
	v_lshlrev_b64 v[80:81], 6, v[112:113]
	v_lshl_add_u64 v[80:81], s[46:47], 0, v[80:81]
	v_lshl_add_u64 v[80:81], s[56:57], 2, v[80:81]
	s_lshl_b32 s38, s8, 2
	v_lshl_add_u64 v[80:81], v[80:81], 0, s[38:39]
	flat_store_dword v[80:81], v82
.LBB0_342:
	s_or_b64 exec, exec, s[6:7]
	v_lshlrev_b32_e32 v80, 16, v100
	s_waitcnt lgkmcnt(0)
	v_and_b32_e32 v81, 0xffff0000, v100
	v_lshlrev_b32_e32 v84, 16, v102
	v_and_b32_e32 v85, 0xffff0000, v102
	v_lshlrev_b32_e32 v86, 16, v103
	v_and_b32_e32 v87, 0xffff0000, v103
	v_pk_add_f32 v[76:77], v[76:77], v[80:81]
	v_lshlrev_b32_e32 v82, 16, v101
	v_and_b32_e32 v83, 0xffff0000, v101
	v_pk_add_f32 v[80:81], v[74:75], v[86:87]
	v_pk_add_f32 v[74:75], v[72:73], v[84:85]
	v_cvt_pk_bf16_f32 v72, v76, v77
	v_lshl_add_u64 v[76:77], s[68:69], 0, v[110:111]
	v_pk_add_f32 v[78:79], v[78:79], v[82:83]
	v_lshl_add_u64 v[76:77], v[168:169], 1, v[76:77]
	v_cvt_pk_bf16_f32 v73, v78, v79
	v_cvt_pk_bf16_f32 v74, v74, v75
	v_cvt_pk_bf16_f32 v75, v80, v81
	global_store_dwordx4 v[76:77], v[72:75], off sc0 nt
	v_lshlrev_b32_e32 v78, 16, v72
	v_and_b32_e32 v79, 0xffff0000, v98
	v_and_b32_e32 v72, 0xffff0000, v72
	v_mul_f32_e32 v72, v72, v72
	v_fmac_f32_e32 v72, v78, v78
	v_lshlrev_b32_e32 v78, 16, v73
	v_and_b32_e32 v73, 0xffff0000, v73
	v_mul_f32_e32 v73, v73, v73
	v_fmac_f32_e32 v73, v78, v78
	v_add_f32_e32 v72, v72, v73
	v_lshlrev_b32_e32 v73, 16, v74
	v_and_b32_e32 v74, 0xffff0000, v74
	v_mul_f32_e32 v74, v74, v74
	v_fmac_f32_e32 v74, v73, v73
	v_add_f32_e32 v72, v72, v74
	v_and_b32_e32 v74, 0xffff0000, v75
	v_lshlrev_b32_e32 v73, 16, v75
	v_mul_f32_e32 v74, v74, v74
	v_fmac_f32_e32 v74, v73, v73
	v_add_f32_e32 v82, v72, v74
	v_lshlrev_b32_e32 v72, 16, v96
	v_and_b32_e32 v73, 0xffff0000, v96
	v_lshlrev_b32_e32 v78, 16, v98
	v_lshlrev_b32_e32 v74, 16, v97
	v_and_b32_e32 v75, 0xffff0000, v97
	v_lshlrev_b32_e32 v80, 16, v99
	v_and_b32_e32 v81, 0xffff0000, v99
	v_pk_add_f32 v[68:69], v[68:69], v[72:73]
	v_pk_add_f32 v[64:65], v[64:65], v[78:79]
	v_pk_add_f32 v[70:71], v[70:71], v[74:75]
	v_pk_add_f32 v[72:73], v[66:67], v[80:81]
	v_cvt_pk_bf16_f32 v66, v68, v69
	v_cvt_pk_bf16_f32 v67, v70, v71
	v_cvt_pk_bf16_f32 v68, v64, v65
	s_nop 0
	v_and_b32_e32 v65, 0xffff0000, v66
	v_lshlrev_b32_e32 v64, 16, v66
	v_mul_f32_e32 v65, v65, v65
	v_fmac_f32_e32 v65, v64, v64
	v_and_b32_e32 v70, 0xffff0000, v67
	v_add_f32_e32 v64, v82, v65
	v_lshlrev_b32_e32 v65, 16, v67
	v_mul_f32_e32 v70, v70, v70
	v_fmac_f32_e32 v70, v65, v65
	v_add_f32_e32 v64, v64, v70
	v_and_b32_e32 v70, 0xffff0000, v68
	v_lshlrev_b32_e32 v65, 16, v68
	v_mul_f32_e32 v70, v70, v70
	v_fmac_f32_e32 v70, v65, v65
	v_cvt_pk_bf16_f32 v69, v72, v73
	v_add_f32_e32 v64, v64, v70
	v_and_b32_e32 v70, 0xffff0000, v69
	v_lshlrev_b32_e32 v65, 16, v69
	v_mul_f32_e32 v70, v70, v70
	v_fmac_f32_e32 v70, v65, v65
	v_add_f32_e32 v64, v64, v70
	ds_bpermute_b32 v65, v181, v64
	global_store_dwordx4 v[76:77], v[66:69], off offset:256 sc0 nt
	s_waitcnt lgkmcnt(0)
	v_add_f32_e32 v64, v64, v65
	ds_bpermute_b32 v65, v180, v64
	s_and_saveexec_b64 s[6:7], vcc
	s_cbranch_execz .LBB0_344
	s_waitcnt lgkmcnt(0)
	v_add_f32_e32 v66, v64, v65
	v_lshlrev_b64 v[64:65], 6, v[108:109]
	v_lshl_add_u64 v[64:65], s[46:47], 0, v[64:65]
	v_lshl_add_u64 v[64:65], s[56:57], 2, v[64:65]
	s_lshl_b32 s38, s8, 2
	v_lshl_add_u64 v[64:65], v[64:65], 0, s[38:39]
	flat_store_dword v[64:65], v66
.LBB0_344:
	s_or_b64 exec, exec, s[6:7]
	v_add_u32_e32 v80, 0x80, v170
	v_ashrrev_i32_e32 v81, 31, v80
	v_lshlrev_b64 v[86:87], 11, v[80:81]
	s_waitcnt lgkmcnt(0)
	v_lshl_add_u64 v[64:65], v[172:173], 0, v[86:87]
	global_load_dwordx4 v[82:85], v[64:65], off
	global_load_dwordx4 v[72:75], v[64:65], off offset:256
	v_add_u32_e32 v76, 0x90, v170
	v_ashrrev_i32_e32 v77, 31, v76
	v_lshlrev_b64 v[78:79], 11, v[76:77]
	v_lshl_add_u64 v[64:65], v[172:173], 0, v[78:79]
	global_load_dwordx4 v[68:71], v[64:65], off
	s_nop 0
	global_load_dwordx4 v[64:67], v[64:65], off offset:256
	s_waitcnt vmcnt(0)
	v_lshlrev_b32_e32 v88, 16, v82
	v_and_b32_e32 v89, 0xffff0000, v82
	v_lshlrev_b32_e32 v82, 16, v83
	v_and_b32_e32 v83, 0xffff0000, v83
	v_lshlrev_b32_e32 v90, 16, v84
	v_and_b32_e32 v91, 0xffff0000, v84
	v_lshlrev_b32_e32 v84, 16, v85
	v_and_b32_e32 v85, 0xffff0000, v85
	v_pk_add_f32 v[60:61], v[60:61], v[88:89]
	v_pk_add_f32 v[62:63], v[62:63], v[82:83]
	v_pk_add_f32 v[82:83], v[58:59], v[84:85]
	v_pk_add_f32 v[58:59], v[56:57], v[90:91]
	v_cvt_pk_bf16_f32 v56, v60, v61
	v_lshl_add_u64 v[60:61], s[68:69], 0, v[86:87]
	v_lshl_add_u64 v[60:61], v[168:169], 1, v[60:61]
	v_cvt_pk_bf16_f32 v57, v62, v63
	v_cvt_pk_bf16_f32 v58, v58, v59
	v_cvt_pk_bf16_f32 v59, v82, v83
	global_store_dwordx4 v[60:61], v[56:59], off sc0 nt
	v_lshlrev_b32_e32 v62, 16, v56
	v_and_b32_e32 v63, 0xffff0000, v74
	v_and_b32_e32 v56, 0xffff0000, v56
	v_mul_f32_e32 v56, v56, v56
	v_fmac_f32_e32 v56, v62, v62
	v_lshlrev_b32_e32 v62, 16, v57
	v_and_b32_e32 v57, 0xffff0000, v57
	v_mul_f32_e32 v57, v57, v57
	v_fmac_f32_e32 v57, v62, v62
	v_add_f32_e32 v56, v56, v57
	v_lshlrev_b32_e32 v57, 16, v58
	v_and_b32_e32 v58, 0xffff0000, v58
	v_mul_f32_e32 v58, v58, v58
	v_fmac_f32_e32 v58, v57, v57
	v_add_f32_e32 v56, v56, v58
	v_and_b32_e32 v58, 0xffff0000, v59
	v_lshlrev_b32_e32 v57, 16, v59
	v_mul_f32_e32 v58, v58, v58
	v_fmac_f32_e32 v58, v57, v57
	v_add_f32_e32 v82, v56, v58
	v_lshlrev_b32_e32 v56, 16, v72
	v_and_b32_e32 v57, 0xffff0000, v72
	v_lshlrev_b32_e32 v58, 16, v73
	v_and_b32_e32 v59, 0xffff0000, v73
	v_lshlrev_b32_e32 v62, 16, v74
	v_lshlrev_b32_e32 v72, 16, v75
	v_and_b32_e32 v73, 0xffff0000, v75
	v_pk_add_f32 v[52:53], v[52:53], v[56:57]
	v_pk_add_f32 v[56:57], v[50:51], v[72:73]
	v_pk_add_f32 v[50:51], v[48:49], v[62:63]
	v_cvt_pk_bf16_f32 v48, v52, v53
	v_pk_add_f32 v[54:55], v[54:55], v[58:59]
	v_lshlrev_b32_e32 v52, 16, v48
	v_cvt_pk_bf16_f32 v49, v54, v55
	v_cvt_pk_bf16_f32 v50, v50, v51
	v_cvt_pk_bf16_f32 v51, v56, v57
	global_store_dwordx4 v[60:61], v[48:51], off offset:256 sc0 nt
	s_nop 1
	v_and_b32_e32 v48, 0xffff0000, v48
	v_mul_f32_e32 v48, v48, v48
	v_fmac_f32_e32 v48, v52, v52
	v_lshlrev_b32_e32 v52, 16, v49
	v_and_b32_e32 v49, 0xffff0000, v49
	v_mul_f32_e32 v49, v49, v49
	v_add_f32_e32 v48, v82, v48
	v_fmac_f32_e32 v49, v52, v52
	v_add_f32_e32 v48, v48, v49
	v_lshlrev_b32_e32 v49, 16, v50
	v_and_b32_e32 v50, 0xffff0000, v50
	v_mul_f32_e32 v50, v50, v50
	v_fmac_f32_e32 v50, v49, v49
	v_add_f32_e32 v48, v48, v50
	v_and_b32_e32 v50, 0xffff0000, v51
	v_lshlrev_b32_e32 v49, 16, v51
	v_mul_f32_e32 v50, v50, v50
	v_fmac_f32_e32 v50, v49, v49
	v_add_f32_e32 v48, v48, v50
	ds_bpermute_b32 v49, v181, v48
	s_waitcnt lgkmcnt(0)
	v_add_f32_e32 v48, v48, v49
	ds_bpermute_b32 v49, v180, v48
	s_and_saveexec_b64 s[6:7], vcc
	s_cbranch_execz .LBB0_346
	s_waitcnt lgkmcnt(0)
	v_add_f32_e32 v50, v48, v49
	v_lshlrev_b64 v[48:49], 6, v[80:81]
	v_lshl_add_u64 v[48:49], s[46:47], 0, v[48:49]
	v_lshl_add_u64 v[48:49], s[56:57], 2, v[48:49]
	s_lshl_b32 s38, s8, 2
	v_lshl_add_u64 v[48:49], v[48:49], 0, s[38:39]
	flat_store_dword v[48:49], v50
.LBB0_346:
	s_or_b64 exec, exec, s[6:7]
	v_lshlrev_b32_e32 v48, 16, v68
	s_waitcnt lgkmcnt(0)
	v_and_b32_e32 v49, 0xffff0000, v68
	v_lshlrev_b32_e32 v52, 16, v70
	v_and_b32_e32 v53, 0xffff0000, v70
	v_lshlrev_b32_e32 v54, 16, v71
	v_and_b32_e32 v55, 0xffff0000, v71
	v_pk_add_f32 v[44:45], v[44:45], v[48:49]
	v_lshlrev_b32_e32 v50, 16, v69
	v_and_b32_e32 v51, 0xffff0000, v69
	v_pk_add_f32 v[48:49], v[42:43], v[54:55]
	v_pk_add_f32 v[42:43], v[40:41], v[52:53]
	v_cvt_pk_bf16_f32 v40, v44, v45
	v_lshl_add_u64 v[44:45], s[68:69], 0, v[78:79]
	v_pk_add_f32 v[46:47], v[46:47], v[50:51]
	v_lshl_add_u64 v[44:45], v[168:169], 1, v[44:45]
	v_cvt_pk_bf16_f32 v41, v46, v47
	v_cvt_pk_bf16_f32 v42, v42, v43
	v_cvt_pk_bf16_f32 v43, v48, v49
	global_store_dwordx4 v[44:45], v[40:43], off sc0 nt
	v_lshlrev_b32_e32 v46, 16, v40
	v_and_b32_e32 v47, 0xffff0000, v66
	v_and_b32_e32 v40, 0xffff0000, v40
	v_mul_f32_e32 v40, v40, v40
	v_fmac_f32_e32 v40, v46, v46
	v_lshlrev_b32_e32 v46, 16, v41
	v_and_b32_e32 v41, 0xffff0000, v41
	v_mul_f32_e32 v41, v41, v41
	v_fmac_f32_e32 v41, v46, v46
	v_add_f32_e32 v40, v40, v41
	v_lshlrev_b32_e32 v41, 16, v42
	v_and_b32_e32 v42, 0xffff0000, v42
	v_mul_f32_e32 v42, v42, v42
	v_fmac_f32_e32 v42, v41, v41
	v_add_f32_e32 v40, v40, v42
	v_and_b32_e32 v42, 0xffff0000, v43
	v_lshlrev_b32_e32 v41, 16, v43
	v_mul_f32_e32 v42, v42, v42
	v_fmac_f32_e32 v42, v41, v41
	v_add_f32_e32 v50, v40, v42
	v_lshlrev_b32_e32 v40, 16, v64
	v_and_b32_e32 v41, 0xffff0000, v64
	v_lshlrev_b32_e32 v46, 16, v66
	v_lshlrev_b32_e32 v42, 16, v65
	v_and_b32_e32 v43, 0xffff0000, v65
	v_lshlrev_b32_e32 v48, 16, v67
	v_and_b32_e32 v49, 0xffff0000, v67
	v_pk_add_f32 v[36:37], v[36:37], v[40:41]
	v_pk_add_f32 v[32:33], v[32:33], v[46:47]
	v_pk_add_f32 v[38:39], v[38:39], v[42:43]
	v_pk_add_f32 v[40:41], v[34:35], v[48:49]
	v_cvt_pk_bf16_f32 v34, v36, v37
	v_cvt_pk_bf16_f32 v35, v38, v39
	v_cvt_pk_bf16_f32 v36, v32, v33
	s_nop 0
	v_and_b32_e32 v33, 0xffff0000, v34
	v_lshlrev_b32_e32 v32, 16, v34
	v_mul_f32_e32 v33, v33, v33
	v_fmac_f32_e32 v33, v32, v32
	v_and_b32_e32 v38, 0xffff0000, v35
	v_add_f32_e32 v32, v50, v33
	v_lshlrev_b32_e32 v33, 16, v35
	v_mul_f32_e32 v38, v38, v38
	v_fmac_f32_e32 v38, v33, v33
	v_add_f32_e32 v32, v32, v38
	v_and_b32_e32 v38, 0xffff0000, v36
	v_lshlrev_b32_e32 v33, 16, v36
	v_mul_f32_e32 v38, v38, v38
	v_fmac_f32_e32 v38, v33, v33
	v_cvt_pk_bf16_f32 v37, v40, v41
	v_add_f32_e32 v32, v32, v38
	v_and_b32_e32 v38, 0xffff0000, v37
	v_lshlrev_b32_e32 v33, 16, v37
	v_mul_f32_e32 v38, v38, v38
	v_fmac_f32_e32 v38, v33, v33
	v_add_f32_e32 v32, v32, v38
	ds_bpermute_b32 v33, v181, v32
	global_store_dwordx4 v[44:45], v[34:37], off offset:256 sc0 nt
	s_waitcnt lgkmcnt(0)
	v_add_f32_e32 v32, v32, v33
	ds_bpermute_b32 v33, v180, v32
	s_and_saveexec_b64 s[6:7], vcc
	s_cbranch_execz .LBB0_348
	s_waitcnt lgkmcnt(0)
	v_add_f32_e32 v34, v32, v33
	v_lshlrev_b64 v[32:33], 6, v[76:77]
	v_lshl_add_u64 v[32:33], s[46:47], 0, v[32:33]
	v_lshl_add_u64 v[32:33], s[56:57], 2, v[32:33]
	s_lshl_b32 s38, s8, 2
	v_lshl_add_u64 v[32:33], v[32:33], 0, s[38:39]
	flat_store_dword v[32:33], v34
.LBB0_348:
	s_or_b64 exec, exec, s[6:7]
	v_add_u32_e32 v48, 0xa0, v170
	v_ashrrev_i32_e32 v49, 31, v48
	v_lshlrev_b64 v[54:55], 11, v[48:49]
	s_waitcnt lgkmcnt(0)
	v_lshl_add_u64 v[32:33], v[172:173], 0, v[54:55]
	global_load_dwordx4 v[50:53], v[32:33], off
	global_load_dwordx4 v[40:43], v[32:33], off offset:256
	v_add_u32_e32 v44, 0xb0, v170
	v_ashrrev_i32_e32 v45, 31, v44
	v_lshlrev_b64 v[46:47], 11, v[44:45]
	v_lshl_add_u64 v[32:33], v[172:173], 0, v[46:47]
	global_load_dwordx4 v[36:39], v[32:33], off
	s_nop 0
	global_load_dwordx4 v[32:35], v[32:33], off offset:256
	s_waitcnt vmcnt(0)
	v_lshlrev_b32_e32 v56, 16, v50
	v_and_b32_e32 v57, 0xffff0000, v50
	v_lshlrev_b32_e32 v50, 16, v51
	v_and_b32_e32 v51, 0xffff0000, v51
	v_lshlrev_b32_e32 v58, 16, v52
	v_and_b32_e32 v59, 0xffff0000, v52
	v_lshlrev_b32_e32 v52, 16, v53
	v_and_b32_e32 v53, 0xffff0000, v53
	v_pk_add_f32 v[28:29], v[28:29], v[56:57]
	v_pk_add_f32 v[30:31], v[30:31], v[50:51]
	v_pk_add_f32 v[50:51], v[26:27], v[52:53]
	v_pk_add_f32 v[26:27], v[24:25], v[58:59]
	v_cvt_pk_bf16_f32 v24, v28, v29
	v_lshl_add_u64 v[28:29], s[68:69], 0, v[54:55]
	v_lshl_add_u64 v[28:29], v[168:169], 1, v[28:29]
	v_cvt_pk_bf16_f32 v25, v30, v31
	v_cvt_pk_bf16_f32 v26, v26, v27
	v_cvt_pk_bf16_f32 v27, v50, v51
	global_store_dwordx4 v[28:29], v[24:27], off sc0 nt
	v_lshlrev_b32_e32 v30, 16, v24
	v_and_b32_e32 v31, 0xffff0000, v42
	v_and_b32_e32 v24, 0xffff0000, v24
	v_mul_f32_e32 v24, v24, v24
	v_fmac_f32_e32 v24, v30, v30
	v_lshlrev_b32_e32 v30, 16, v25
	v_and_b32_e32 v25, 0xffff0000, v25
	v_mul_f32_e32 v25, v25, v25
	v_fmac_f32_e32 v25, v30, v30
	v_add_f32_e32 v24, v24, v25
	v_lshlrev_b32_e32 v25, 16, v26
	v_and_b32_e32 v26, 0xffff0000, v26
	v_mul_f32_e32 v26, v26, v26
	v_fmac_f32_e32 v26, v25, v25
	v_add_f32_e32 v24, v24, v26
	v_and_b32_e32 v26, 0xffff0000, v27
	v_lshlrev_b32_e32 v25, 16, v27
	v_mul_f32_e32 v26, v26, v26
	v_fmac_f32_e32 v26, v25, v25
	v_add_f32_e32 v50, v24, v26
	v_lshlrev_b32_e32 v24, 16, v40
	v_and_b32_e32 v25, 0xffff0000, v40
	v_lshlrev_b32_e32 v26, 16, v41
	v_and_b32_e32 v27, 0xffff0000, v41
	v_lshlrev_b32_e32 v30, 16, v42
	v_lshlrev_b32_e32 v40, 16, v43
	v_and_b32_e32 v41, 0xffff0000, v43
	v_pk_add_f32 v[20:21], v[20:21], v[24:25]
	v_pk_add_f32 v[24:25], v[18:19], v[40:41]
	v_pk_add_f32 v[18:19], v[16:17], v[30:31]
	v_cvt_pk_bf16_f32 v16, v20, v21
	v_pk_add_f32 v[22:23], v[22:23], v[26:27]
	v_lshlrev_b32_e32 v20, 16, v16
	v_cvt_pk_bf16_f32 v17, v22, v23
	v_cvt_pk_bf16_f32 v18, v18, v19
	v_cvt_pk_bf16_f32 v19, v24, v25
	global_store_dwordx4 v[28:29], v[16:19], off offset:256 sc0 nt
	s_nop 1
	v_and_b32_e32 v16, 0xffff0000, v16
	v_mul_f32_e32 v16, v16, v16
	v_fmac_f32_e32 v16, v20, v20
	v_lshlrev_b32_e32 v20, 16, v17
	v_and_b32_e32 v17, 0xffff0000, v17
	v_mul_f32_e32 v17, v17, v17
	v_add_f32_e32 v16, v50, v16
	v_fmac_f32_e32 v17, v20, v20
	v_add_f32_e32 v16, v16, v17
	v_lshlrev_b32_e32 v17, 16, v18
	v_and_b32_e32 v18, 0xffff0000, v18
	v_mul_f32_e32 v18, v18, v18
	v_fmac_f32_e32 v18, v17, v17
	v_add_f32_e32 v16, v16, v18
	v_and_b32_e32 v18, 0xffff0000, v19
	v_lshlrev_b32_e32 v17, 16, v19
	v_mul_f32_e32 v18, v18, v18
	v_fmac_f32_e32 v18, v17, v17
	v_add_f32_e32 v16, v16, v18
	ds_bpermute_b32 v17, v181, v16
	s_waitcnt lgkmcnt(0)
	v_add_f32_e32 v16, v16, v17
	ds_bpermute_b32 v17, v180, v16
	s_and_saveexec_b64 s[6:7], vcc
	s_cbranch_execz .LBB0_350
	s_waitcnt lgkmcnt(0)
	v_add_f32_e32 v18, v16, v17
	v_lshlrev_b64 v[16:17], 6, v[48:49]
	v_lshl_add_u64 v[16:17], s[46:47], 0, v[16:17]
	v_lshl_add_u64 v[16:17], s[56:57], 2, v[16:17]
	s_lshl_b32 s38, s8, 2
	v_lshl_add_u64 v[16:17], v[16:17], 0, s[38:39]
	flat_store_dword v[16:17], v18
.LBB0_350:
	s_or_b64 exec, exec, s[6:7]
	v_lshlrev_b32_e32 v16, 16, v36
	s_waitcnt lgkmcnt(0)
	v_and_b32_e32 v17, 0xffff0000, v36
	v_lshlrev_b32_e32 v20, 16, v38
	v_and_b32_e32 v21, 0xffff0000, v38
	v_lshlrev_b32_e32 v22, 16, v39
	v_and_b32_e32 v23, 0xffff0000, v39
	v_pk_add_f32 v[12:13], v[12:13], v[16:17]
	v_lshlrev_b32_e32 v18, 16, v37
	v_and_b32_e32 v19, 0xffff0000, v37
	v_pk_add_f32 v[16:17], v[10:11], v[22:23]
	v_pk_add_f32 v[10:11], v[8:9], v[20:21]
	v_cvt_pk_bf16_f32 v8, v12, v13
	v_lshl_add_u64 v[12:13], s[68:69], 0, v[46:47]
	v_pk_add_f32 v[14:15], v[14:15], v[18:19]
	v_lshl_add_u64 v[12:13], v[168:169], 1, v[12:13]
	v_cvt_pk_bf16_f32 v9, v14, v15
	v_cvt_pk_bf16_f32 v10, v10, v11
	v_cvt_pk_bf16_f32 v11, v16, v17
	global_store_dwordx4 v[12:13], v[8:11], off sc0 nt
	v_lshlrev_b32_e32 v14, 16, v8
	v_and_b32_e32 v15, 0xffff0000, v34
	v_and_b32_e32 v8, 0xffff0000, v8
	v_mul_f32_e32 v8, v8, v8
	v_fmac_f32_e32 v8, v14, v14
	v_lshlrev_b32_e32 v14, 16, v9
	v_and_b32_e32 v9, 0xffff0000, v9
	v_mul_f32_e32 v9, v9, v9
	v_fmac_f32_e32 v9, v14, v14
	v_add_f32_e32 v8, v8, v9
	v_lshlrev_b32_e32 v9, 16, v10
	v_and_b32_e32 v10, 0xffff0000, v10
	v_mul_f32_e32 v10, v10, v10
	v_fmac_f32_e32 v10, v9, v9
	v_add_f32_e32 v8, v8, v10
	v_and_b32_e32 v10, 0xffff0000, v11
	v_lshlrev_b32_e32 v9, 16, v11
	v_mul_f32_e32 v10, v10, v10
	v_fmac_f32_e32 v10, v9, v9
	v_add_f32_e32 v18, v8, v10
	v_lshlrev_b32_e32 v8, 16, v32
	v_and_b32_e32 v9, 0xffff0000, v32
	v_lshlrev_b32_e32 v14, 16, v34
	v_lshlrev_b32_e32 v10, 16, v33
	v_and_b32_e32 v11, 0xffff0000, v33
	v_lshlrev_b32_e32 v16, 16, v35
	v_and_b32_e32 v17, 0xffff0000, v35
	v_pk_add_f32 v[4:5], v[4:5], v[8:9]
	v_pk_add_f32 v[0:1], v[0:1], v[14:15]
	v_pk_add_f32 v[6:7], v[6:7], v[10:11]
	v_pk_add_f32 v[8:9], v[2:3], v[16:17]
	v_cvt_pk_bf16_f32 v2, v4, v5
	v_cvt_pk_bf16_f32 v3, v6, v7
	v_cvt_pk_bf16_f32 v4, v0, v1
	s_nop 0
	v_and_b32_e32 v1, 0xffff0000, v2
	v_lshlrev_b32_e32 v0, 16, v2
	v_mul_f32_e32 v1, v1, v1
	v_fmac_f32_e32 v1, v0, v0
	v_and_b32_e32 v6, 0xffff0000, v3
	v_add_f32_e32 v0, v18, v1
	v_lshlrev_b32_e32 v1, 16, v3
	v_mul_f32_e32 v6, v6, v6
	v_fmac_f32_e32 v6, v1, v1
	v_add_f32_e32 v0, v0, v6
	v_and_b32_e32 v6, 0xffff0000, v4
	v_lshlrev_b32_e32 v1, 16, v4
	v_mul_f32_e32 v6, v6, v6
	v_fmac_f32_e32 v6, v1, v1
	v_cvt_pk_bf16_f32 v5, v8, v9
	v_add_f32_e32 v0, v0, v6
	v_and_b32_e32 v6, 0xffff0000, v5
	v_lshlrev_b32_e32 v1, 16, v5
	v_mul_f32_e32 v6, v6, v6
	v_fmac_f32_e32 v6, v1, v1
	v_add_f32_e32 v0, v0, v6
	ds_bpermute_b32 v1, v181, v0
	global_store_dwordx4 v[12:13], v[2:5], off offset:256 sc0 nt
	s_waitcnt lgkmcnt(0)
	v_add_f32_e32 v0, v0, v1
	ds_bpermute_b32 v1, v180, v0
	s_and_saveexec_b64 s[6:7], vcc
	s_cbranch_execz .LBB0_352
	s_waitcnt lgkmcnt(0)
	v_add_f32_e32 v2, v0, v1
	v_lshlrev_b64 v[0:1], 6, v[44:45]
	v_lshl_add_u64 v[0:1], s[46:47], 0, v[0:1]
	v_lshl_add_u64 v[0:1], s[56:57], 2, v[0:1]
	s_lshl_b32 s38, s8, 2
	v_lshl_add_u64 v[0:1], v[0:1], 0, s[38:39]
	flat_store_dword v[0:1], v2

.LBB0_378:
	s_mov_b32 s6, -1
	s_lshl_b32 s5, s5, 8
	v_mbcnt_lo_u32_b32 v128, s6, 0
	v_mbcnt_hi_u32_b32 v128, s6, v128
	s_getreg_b32 s6, hwreg(HW_REG_HW_ID, 0, 6)
	s_and_b32 s6, s6, 63
	s_lshl_b32 s6, s6, 2
	s_add_i32 s6, s6, 0
	s_add_i32 s6, s6, 0x20200
	v_mov_b32_e32 v129, s6
	ds_read_b32 v129, v129
	v_bfrev_b32_e32 v130, 0.5
	s_lshl_b32 s56, s4, 2
	s_ashr_i32 s57, s56, 31
	s_waitcnt lgkmcnt(0)
	v_readfirstlane_b32 s6, v129
	s_nop 1
	v_lshl_add_u32 v128, s6, 6, v128
	s_nop 0
	v_readfirstlane_b32 s6, v128
	s_bfe_u32 s8, s6, 0x20006
	s_ashr_i32 s6, s6, 2
	s_andn2_b32 s6, s6, 63
	s_add_i32 s6, s6, s5
	v_and_or_b32 v170, v128, 15, s6
	s_lshl_b32 s5, s4, 8
	s_lshl_b32 s6, s8, 5
	v_bfe_u32 v129, v128, 4, 2
	s_or_b32 s5, s6, s5
	v_lshl_or_b32 v168, v129, 3, s5
	v_ashrrev_i32_e32 v169, 31, v168
	v_lshlrev_b64 v[146:147], 1, v[168:169]
	v_ashrrev_i32_e32 v171, 31, v170
	v_lshlrev_b32_e32 v128, 2, v128
	v_lshl_add_u64 v[172:173], s[68:69], 0, v[146:147]
	v_lshlrev_b64 v[148:149], 11, v[170:171]
	v_bitop3_b32 v181, v128, 64, v130 bitop3:0x6c
	v_bitop3_b32 v180, v128, s84, v130 bitop3:0x6c
	v_cmp_eq_u32_e32 vcc, 0, v129
	v_lshl_add_u64 v[128:129], v[172:173], 0, v[148:149]
	global_load_dwordx4 v[142:145], v[128:129], off
	global_load_dwordx4 v[136:139], v[128:129], off offset:256
	v_or_b32_e32 v174, 16, v170
	v_ashrrev_i32_e32 v175, 31, v174
	v_lshlrev_b64 v[176:177], 11, v[174:175]
	v_lshl_add_u64 v[128:129], v[172:173], 0, v[176:177]
	global_load_dwordx4 v[132:135], v[128:129], off
	s_nop 0
	global_load_dwordx4 v[128:131], v[128:129], off offset:256
	s_waitcnt vmcnt(0)
	v_lshlrev_b32_e32 v150, 16, v142
	v_and_b32_e32 v151, 0xffff0000, v142
	v_lshlrev_b32_e32 v142, 16, v143
	v_and_b32_e32 v143, 0xffff0000, v143
	v_lshlrev_b32_e32 v152, 16, v144
	v_and_b32_e32 v153, 0xffff0000, v144
	v_lshlrev_b32_e32 v144, 16, v145
	v_and_b32_e32 v145, 0xffff0000, v145
	v_pk_add_f32 v[124:125], v[124:125], v[150:151]
	v_pk_add_f32 v[126:127], v[126:127], v[142:143]
	v_pk_add_f32 v[142:143], v[122:123], v[144:145]
	v_pk_add_f32 v[122:123], v[120:121], v[152:153]
	v_cvt_pk_bf16_f32 v120, v124, v125
	v_lshl_add_u64 v[124:125], s[68:69], 0, v[148:149]
	v_lshl_add_u64 v[124:125], v[124:125], 0, v[146:147]
	v_cvt_pk_bf16_f32 v121, v126, v127
	v_cvt_pk_bf16_f32 v122, v122, v123
	v_cvt_pk_bf16_f32 v123, v142, v143
	global_store_dwordx4 v[124:125], v[120:123], off sc0 nt
	v_lshlrev_b32_e32 v126, 16, v120
	v_and_b32_e32 v127, 0xffff0000, v138
	v_and_b32_e32 v120, 0xffff0000, v120
	v_mul_f32_e32 v120, v120, v120
	v_fmac_f32_e32 v120, v126, v126
	v_lshlrev_b32_e32 v126, 16, v121
	v_and_b32_e32 v121, 0xffff0000, v121
	v_mul_f32_e32 v121, v121, v121
	v_fmac_f32_e32 v121, v126, v126
	v_add_f32_e32 v120, v120, v121
	v_lshlrev_b32_e32 v121, 16, v122
	v_and_b32_e32 v122, 0xffff0000, v122
	v_mul_f32_e32 v122, v122, v122
	v_fmac_f32_e32 v122, v121, v121
	v_add_f32_e32 v120, v120, v122
	v_and_b32_e32 v122, 0xffff0000, v123
	v_lshlrev_b32_e32 v121, 16, v123
	v_mul_f32_e32 v122, v122, v122
	v_fmac_f32_e32 v122, v121, v121
	v_add_f32_e32 v142, v120, v122
	v_lshlrev_b32_e32 v120, 16, v136
	v_and_b32_e32 v121, 0xffff0000, v136
	v_lshlrev_b32_e32 v122, 16, v137
	v_and_b32_e32 v123, 0xffff0000, v137
	v_lshlrev_b32_e32 v126, 16, v138
	v_lshlrev_b32_e32 v136, 16, v139
	v_and_b32_e32 v137, 0xffff0000, v139
	v_pk_add_f32 v[116:117], v[116:117], v[120:121]
	v_pk_add_f32 v[120:121], v[114:115], v[136:137]
	v_pk_add_f32 v[114:115], v[112:113], v[126:127]
	v_cvt_pk_bf16_f32 v112, v116, v117
	v_pk_add_f32 v[118:119], v[118:119], v[122:123]
	v_lshlrev_b32_e32 v116, 16, v112
	v_cvt_pk_bf16_f32 v113, v118, v119
	v_cvt_pk_bf16_f32 v114, v114, v115
	v_cvt_pk_bf16_f32 v115, v120, v121
	global_store_dwordx4 v[124:125], v[112:115], off offset:256 sc0 nt
	s_nop 1
	v_and_b32_e32 v112, 0xffff0000, v112
	v_mul_f32_e32 v112, v112, v112
	v_fmac_f32_e32 v112, v116, v116
	v_lshlrev_b32_e32 v116, 16, v113
	v_and_b32_e32 v113, 0xffff0000, v113
	v_mul_f32_e32 v113, v113, v113
	v_add_f32_e32 v112, v142, v112
	v_fmac_f32_e32 v113, v116, v116
	v_add_f32_e32 v112, v112, v113
	v_lshlrev_b32_e32 v113, 16, v114
	v_and_b32_e32 v114, 0xffff0000, v114
	v_mul_f32_e32 v114, v114, v114
	v_fmac_f32_e32 v114, v113, v113
	v_add_f32_e32 v112, v112, v114
	v_and_b32_e32 v114, 0xffff0000, v115
	v_lshlrev_b32_e32 v113, 16, v115
	v_mul_f32_e32 v114, v114, v114
	v_fmac_f32_e32 v114, v113, v113
	v_add_f32_e32 v112, v112, v114
	ds_bpermute_b32 v113, v181, v112
	s_waitcnt lgkmcnt(0)
	v_add_f32_e32 v112, v112, v113
	ds_bpermute_b32 v113, v180, v112
	s_and_saveexec_b64 s[6:7], vcc
	s_cbranch_execz .LBB0_380
	v_lshlrev_b64 v[114:115], 6, v[170:171]
	v_lshl_add_u64 v[114:115], s[46:47], 0, v[114:115]
	v_lshl_add_u64 v[114:115], s[56:57], 2, v[114:115]
	s_lshl_b32 s38, s8, 2
	v_lshl_add_u64 v[114:115], v[114:115], 0, s[38:39]
	s_waitcnt lgkmcnt(0)
	v_add_f32_e32 v112, v112, v113
	flat_store_dword v[114:115], v112
.LBB0_380:
	s_or_b64 exec, exec, s[6:7]
	v_lshlrev_b32_e32 v112, 16, v132
	s_waitcnt lgkmcnt(0)
	v_and_b32_e32 v113, 0xffff0000, v132
	v_lshlrev_b32_e32 v116, 16, v134
	v_and_b32_e32 v117, 0xffff0000, v134
	v_lshlrev_b32_e32 v118, 16, v135
	v_and_b32_e32 v119, 0xffff0000, v135
	v_pk_add_f32 v[108:109], v[108:109], v[112:113]
	v_lshlrev_b32_e32 v114, 16, v133
	v_and_b32_e32 v115, 0xffff0000, v133
	v_pk_add_f32 v[112:113], v[106:107], v[118:119]
	v_pk_add_f32 v[106:107], v[104:105], v[116:117]
	v_cvt_pk_bf16_f32 v104, v108, v109
	v_lshl_add_u64 v[108:109], s[68:69], 0, v[176:177]
	v_pk_add_f32 v[110:111], v[110:111], v[114:115]
	v_lshl_add_u64 v[108:109], v[168:169], 1, v[108:109]
	v_cvt_pk_bf16_f32 v105, v110, v111
	v_cvt_pk_bf16_f32 v106, v106, v107
	v_cvt_pk_bf16_f32 v107, v112, v113
	global_store_dwordx4 v[108:109], v[104:107], off sc0 nt
	v_lshlrev_b32_e32 v110, 16, v104
	v_and_b32_e32 v111, 0xffff0000, v130
	v_and_b32_e32 v104, 0xffff0000, v104
	v_mul_f32_e32 v104, v104, v104
	v_fmac_f32_e32 v104, v110, v110
	v_lshlrev_b32_e32 v110, 16, v105
	v_and_b32_e32 v105, 0xffff0000, v105
	v_mul_f32_e32 v105, v105, v105
	v_fmac_f32_e32 v105, v110, v110
	v_add_f32_e32 v104, v104, v105
	v_lshlrev_b32_e32 v105, 16, v106
	v_and_b32_e32 v106, 0xffff0000, v106
	v_mul_f32_e32 v106, v106, v106
	v_fmac_f32_e32 v106, v105, v105
	v_add_f32_e32 v104, v104, v106
	v_and_b32_e32 v106, 0xffff0000, v107
	v_lshlrev_b32_e32 v105, 16, v107
	v_mul_f32_e32 v106, v106, v106
	v_fmac_f32_e32 v106, v105, v105
	v_add_f32_e32 v114, v104, v106
	v_lshlrev_b32_e32 v104, 16, v128
	v_and_b32_e32 v105, 0xffff0000, v128
	v_lshlrev_b32_e32 v110, 16, v130
	v_lshlrev_b32_e32 v106, 16, v129
	v_and_b32_e32 v107, 0xffff0000, v129
	v_lshlrev_b32_e32 v112, 16, v131
	v_and_b32_e32 v113, 0xffff0000, v131
	v_pk_add_f32 v[100:101], v[100:101], v[104:105]
	v_pk_add_f32 v[96:97], v[96:97], v[110:111]
	v_pk_add_f32 v[102:103], v[102:103], v[106:107]
	v_pk_add_f32 v[104:105], v[98:99], v[112:113]
	v_cvt_pk_bf16_f32 v98, v100, v101
	v_cvt_pk_bf16_f32 v99, v102, v103
	v_cvt_pk_bf16_f32 v100, v96, v97
	s_nop 0
	v_and_b32_e32 v97, 0xffff0000, v98
	v_lshlrev_b32_e32 v96, 16, v98
	v_mul_f32_e32 v97, v97, v97
	v_fmac_f32_e32 v97, v96, v96
	v_and_b32_e32 v102, 0xffff0000, v99
	v_add_f32_e32 v96, v114, v97
	v_lshlrev_b32_e32 v97, 16, v99
	v_mul_f32_e32 v102, v102, v102
	v_fmac_f32_e32 v102, v97, v97
	v_add_f32_e32 v96, v96, v102
	v_and_b32_e32 v102, 0xffff0000, v100
	v_lshlrev_b32_e32 v97, 16, v100
	v_mul_f32_e32 v102, v102, v102
	v_fmac_f32_e32 v102, v97, v97
	v_cvt_pk_bf16_f32 v101, v104, v105
	v_add_f32_e32 v96, v96, v102
	v_and_b32_e32 v102, 0xffff0000, v101
	v_lshlrev_b32_e32 v97, 16, v101
	v_mul_f32_e32 v102, v102, v102
	v_fmac_f32_e32 v102, v97, v97
	v_add_f32_e32 v96, v96, v102
	ds_bpermute_b32 v97, v181, v96
	global_store_dwordx4 v[108:109], v[98:101], off offset:256 sc0 nt
	s_waitcnt lgkmcnt(0)
	v_add_f32_e32 v96, v96, v97
	ds_bpermute_b32 v97, v180, v96
	s_and_saveexec_b64 s[6:7], vcc
	s_cbranch_execz .LBB0_382
	v_lshlrev_b64 v[98:99], 6, v[174:175]
	v_lshl_add_u64 v[98:99], s[46:47], 0, v[98:99]
	v_lshl_add_u64 v[98:99], s[56:57], 2, v[98:99]
	s_lshl_b32 s38, s8, 2
	v_lshl_add_u64 v[98:99], v[98:99], 0, s[38:39]
	s_waitcnt lgkmcnt(0)
	v_add_f32_e32 v96, v96, v97
	flat_store_dword v[98:99], v96
.LBB0_382:
	s_or_b64 exec, exec, s[6:7]
	v_or_b32_e32 v112, 32, v170
	v_ashrrev_i32_e32 v113, 31, v112
	v_lshlrev_b64 v[118:119], 11, v[112:113]
	s_waitcnt lgkmcnt(0)
	v_lshl_add_u64 v[96:97], v[172:173], 0, v[118:119]
	global_load_dwordx4 v[114:117], v[96:97], off
	global_load_dwordx4 v[104:107], v[96:97], off offset:256
	v_or_b32_e32 v108, 48, v170
	v_ashrrev_i32_e32 v109, 31, v108
	v_lshlrev_b64 v[110:111], 11, v[108:109]
	v_lshl_add_u64 v[96:97], v[172:173], 0, v[110:111]
	global_load_dwordx4 v[100:103], v[96:97], off
	s_nop 0
	global_load_dwordx4 v[96:99], v[96:97], off offset:256
	s_waitcnt vmcnt(0)
	v_lshlrev_b32_e32 v120, 16, v114
	v_and_b32_e32 v121, 0xffff0000, v114
	v_lshlrev_b32_e32 v114, 16, v115
	v_and_b32_e32 v115, 0xffff0000, v115
	v_lshlrev_b32_e32 v122, 16, v116
	v_and_b32_e32 v123, 0xffff0000, v116
	v_lshlrev_b32_e32 v116, 16, v117
	v_and_b32_e32 v117, 0xffff0000, v117
	v_pk_add_f32 v[92:93], v[92:93], v[120:121]
	v_pk_add_f32 v[94:95], v[94:95], v[114:115]
	v_pk_add_f32 v[114:115], v[90:91], v[116:117]
	v_pk_add_f32 v[90:91], v[88:89], v[122:123]
	v_cvt_pk_bf16_f32 v88, v92, v93
	v_lshl_add_u64 v[92:93], s[68:69], 0, v[118:119]
	v_lshl_add_u64 v[92:93], v[168:169], 1, v[92:93]
	v_cvt_pk_bf16_f32 v89, v94, v95
	v_cvt_pk_bf16_f32 v90, v90, v91
	v_cvt_pk_bf16_f32 v91, v114, v115
	global_store_dwordx4 v[92:93], v[88:91], off sc0 nt
	v_lshlrev_b32_e32 v94, 16, v88
	v_and_b32_e32 v95, 0xffff0000, v106
	v_and_b32_e32 v88, 0xffff0000, v88
	v_mul_f32_e32 v88, v88, v88
	v_fmac_f32_e32 v88, v94, v94
	v_lshlrev_b32_e32 v94, 16, v89
	v_and_b32_e32 v89, 0xffff0000, v89
	v_mul_f32_e32 v89, v89, v89
	v_fmac_f32_e32 v89, v94, v94
	v_add_f32_e32 v88, v88, v89
	v_lshlrev_b32_e32 v89, 16, v90
	v_and_b32_e32 v90, 0xffff0000, v90
	v_mul_f32_e32 v90, v90, v90
	v_fmac_f32_e32 v90, v89, v89
	v_add_f32_e32 v88, v88, v90
	v_and_b32_e32 v90, 0xffff0000, v91
	v_lshlrev_b32_e32 v89, 16, v91
	v_mul_f32_e32 v90, v90, v90
	v_fmac_f32_e32 v90, v89, v89
	v_add_f32_e32 v114, v88, v90
	v_lshlrev_b32_e32 v88, 16, v104
	v_and_b32_e32 v89, 0xffff0000, v104
	v_lshlrev_b32_e32 v90, 16, v105
	v_and_b32_e32 v91, 0xffff0000, v105
	v_lshlrev_b32_e32 v94, 16, v106
	v_lshlrev_b32_e32 v104, 16, v107
	v_and_b32_e32 v105, 0xffff0000, v107
	v_pk_add_f32 v[84:85], v[84:85], v[88:89]
	v_pk_add_f32 v[88:89], v[82:83], v[104:105]
	v_pk_add_f32 v[82:83], v[80:81], v[94:95]
	v_cvt_pk_bf16_f32 v80, v84, v85
	v_pk_add_f32 v[86:87], v[86:87], v[90:91]
	v_lshlrev_b32_e32 v84, 16, v80
	v_cvt_pk_bf16_f32 v81, v86, v87
	v_cvt_pk_bf16_f32 v82, v82, v83
	v_cvt_pk_bf16_f32 v83, v88, v89
	global_store_dwordx4 v[92:93], v[80:83], off offset:256 sc0 nt
	s_nop 1
	v_and_b32_e32 v80, 0xffff0000, v80
	v_mul_f32_e32 v80, v80, v80
	v_fmac_f32_e32 v80, v84, v84
	v_lshlrev_b32_e32 v84, 16, v81
	v_and_b32_e32 v81, 0xffff0000, v81
	v_mul_f32_e32 v81, v81, v81
	v_add_f32_e32 v80, v114, v80
	v_fmac_f32_e32 v81, v84, v84
	v_add_f32_e32 v80, v80, v81
	v_lshlrev_b32_e32 v81, 16, v82
	v_and_b32_e32 v82, 0xffff0000, v82
	v_mul_f32_e32 v82, v82, v82
	v_fmac_f32_e32 v82, v81, v81
	v_add_f32_e32 v80, v80, v82
	v_and_b32_e32 v82, 0xffff0000, v83
	v_lshlrev_b32_e32 v81, 16, v83
	v_mul_f32_e32 v82, v82, v82
	v_fmac_f32_e32 v82, v81, v81
	v_add_f32_e32 v80, v80, v82
	ds_bpermute_b32 v81, v181, v80
	s_waitcnt lgkmcnt(0)
	v_add_f32_e32 v80, v80, v81
	ds_bpermute_b32 v81, v180, v80
	s_mov_b64 s[6:7], exec
	s_and_b64 s[4:5], s[6:7], vcc
	v_mov_b32_e32 v198, v220
	v_mov_b32_e32 v199, v221
	v_mov_b32_e32 v248, v222
	v_mov_b32_e32 v205, v223
	v_mov_b32_e32 v196, v224
	s_mov_b64 exec, s[4:5]
	s_cbranch_execz .LBB0_384
	v_lshlrev_b64 v[82:83], 6, v[112:113]
	v_lshl_add_u64 v[82:83], s[46:47], 0, v[82:83]
	v_lshl_add_u64 v[82:83], s[56:57], 2, v[82:83]
	s_lshl_b32 s38, s8, 2
	v_lshl_add_u64 v[82:83], v[82:83], 0, s[38:39]
	s_waitcnt lgkmcnt(0)
	v_add_f32_e32 v80, v80, v81
	flat_store_dword v[82:83], v80
.LBB0_384:
	s_or_b64 exec, exec, s[6:7]
	v_lshlrev_b32_e32 v80, 16, v100
	s_waitcnt lgkmcnt(0)
	v_and_b32_e32 v81, 0xffff0000, v100
	v_lshlrev_b32_e32 v84, 16, v102
	v_and_b32_e32 v85, 0xffff0000, v102
	v_lshlrev_b32_e32 v86, 16, v103
	v_and_b32_e32 v87, 0xffff0000, v103
	v_pk_add_f32 v[76:77], v[76:77], v[80:81]
	v_lshlrev_b32_e32 v82, 16, v101
	v_and_b32_e32 v83, 0xffff0000, v101
	v_pk_add_f32 v[80:81], v[74:75], v[86:87]
	v_pk_add_f32 v[74:75], v[72:73], v[84:85]
	v_cvt_pk_bf16_f32 v72, v76, v77
	v_lshl_add_u64 v[76:77], s[68:69], 0, v[110:111]
	v_pk_add_f32 v[78:79], v[78:79], v[82:83]
	v_lshl_add_u64 v[76:77], v[168:169], 1, v[76:77]
	v_cvt_pk_bf16_f32 v73, v78, v79
	v_cvt_pk_bf16_f32 v74, v74, v75
	v_cvt_pk_bf16_f32 v75, v80, v81
	global_store_dwordx4 v[76:77], v[72:75], off sc0 nt
	v_lshlrev_b32_e32 v78, 16, v72
	v_and_b32_e32 v79, 0xffff0000, v98
	v_and_b32_e32 v72, 0xffff0000, v72
	v_mul_f32_e32 v72, v72, v72
	v_fmac_f32_e32 v72, v78, v78
	v_lshlrev_b32_e32 v78, 16, v73
	v_and_b32_e32 v73, 0xffff0000, v73
	v_mul_f32_e32 v73, v73, v73
	v_fmac_f32_e32 v73, v78, v78
	v_add_f32_e32 v72, v72, v73
	v_lshlrev_b32_e32 v73, 16, v74
	v_and_b32_e32 v74, 0xffff0000, v74
	v_mul_f32_e32 v74, v74, v74
	v_fmac_f32_e32 v74, v73, v73
	v_add_f32_e32 v72, v72, v74
	v_and_b32_e32 v74, 0xffff0000, v75
	v_lshlrev_b32_e32 v73, 16, v75
	v_mul_f32_e32 v74, v74, v74
	v_fmac_f32_e32 v74, v73, v73
	v_add_f32_e32 v82, v72, v74
	v_lshlrev_b32_e32 v72, 16, v96
	v_and_b32_e32 v73, 0xffff0000, v96
	v_lshlrev_b32_e32 v78, 16, v98
	v_lshlrev_b32_e32 v74, 16, v97
	v_and_b32_e32 v75, 0xffff0000, v97
	v_lshlrev_b32_e32 v80, 16, v99
	v_and_b32_e32 v81, 0xffff0000, v99
	v_pk_add_f32 v[68:69], v[68:69], v[72:73]
	v_pk_add_f32 v[64:65], v[64:65], v[78:79]
	v_pk_add_f32 v[70:71], v[70:71], v[74:75]
	v_pk_add_f32 v[72:73], v[66:67], v[80:81]
	v_cvt_pk_bf16_f32 v66, v68, v69
	v_cvt_pk_bf16_f32 v67, v70, v71
	v_cvt_pk_bf16_f32 v68, v64, v65
	s_nop 0
	v_and_b32_e32 v65, 0xffff0000, v66
	v_lshlrev_b32_e32 v64, 16, v66
	v_mul_f32_e32 v65, v65, v65
	v_fmac_f32_e32 v65, v64, v64
	v_and_b32_e32 v70, 0xffff0000, v67
	v_add_f32_e32 v64, v82, v65
	v_lshlrev_b32_e32 v65, 16, v67
	v_mul_f32_e32 v70, v70, v70
	v_fmac_f32_e32 v70, v65, v65
	v_add_f32_e32 v64, v64, v70
	v_and_b32_e32 v70, 0xffff0000, v68
	v_lshlrev_b32_e32 v65, 16, v68
	v_mul_f32_e32 v70, v70, v70
	v_fmac_f32_e32 v70, v65, v65
	v_cvt_pk_bf16_f32 v69, v72, v73
	v_add_f32_e32 v64, v64, v70
	v_and_b32_e32 v70, 0xffff0000, v69
	v_lshlrev_b32_e32 v65, 16, v69
	v_mul_f32_e32 v70, v70, v70
	v_fmac_f32_e32 v70, v65, v65
	v_add_f32_e32 v64, v64, v70
	ds_bpermute_b32 v65, v181, v64
	global_store_dwordx4 v[76:77], v[66:69], off offset:256 sc0 nt
	s_waitcnt lgkmcnt(0)
	v_add_f32_e32 v64, v64, v65
	ds_bpermute_b32 v65, v180, v64
	s_and_saveexec_b64 s[6:7], vcc
	s_cbranch_execz .LBB0_386
	v_lshlrev_b64 v[66:67], 6, v[108:109]
	v_lshl_add_u64 v[66:67], s[46:47], 0, v[66:67]
	v_lshl_add_u64 v[66:67], s[56:57], 2, v[66:67]
	s_lshl_b32 s38, s8, 2
	v_lshl_add_u64 v[66:67], v[66:67], 0, s[38:39]
	s_waitcnt lgkmcnt(0)
	v_add_f32_e32 v64, v64, v65
	flat_store_dword v[66:67], v64
.LBB0_386:
	s_or_b64 exec, exec, s[6:7]
	v_add_u32_e32 v80, 0x80, v170
	v_ashrrev_i32_e32 v81, 31, v80
	v_lshlrev_b64 v[86:87], 11, v[80:81]
	s_waitcnt lgkmcnt(0)
	v_lshl_add_u64 v[64:65], v[172:173], 0, v[86:87]
	global_load_dwordx4 v[82:85], v[64:65], off
	global_load_dwordx4 v[72:75], v[64:65], off offset:256
	v_add_u32_e32 v76, 0x90, v170
	v_ashrrev_i32_e32 v77, 31, v76
	v_lshlrev_b64 v[78:79], 11, v[76:77]
	v_lshl_add_u64 v[64:65], v[172:173], 0, v[78:79]
	global_load_dwordx4 v[68:71], v[64:65], off
	s_nop 0
	global_load_dwordx4 v[64:67], v[64:65], off offset:256
	s_waitcnt vmcnt(0)
	v_lshlrev_b32_e32 v88, 16, v82
	v_and_b32_e32 v89, 0xffff0000, v82
	v_lshlrev_b32_e32 v82, 16, v83
	v_and_b32_e32 v83, 0xffff0000, v83
	v_lshlrev_b32_e32 v90, 16, v84
	v_and_b32_e32 v91, 0xffff0000, v84
	v_lshlrev_b32_e32 v84, 16, v85
	v_and_b32_e32 v85, 0xffff0000, v85
	v_pk_add_f32 v[60:61], v[60:61], v[88:89]
	v_pk_add_f32 v[62:63], v[62:63], v[82:83]
	v_pk_add_f32 v[82:83], v[58:59], v[84:85]
	v_pk_add_f32 v[58:59], v[56:57], v[90:91]
	v_cvt_pk_bf16_f32 v56, v60, v61
	v_lshl_add_u64 v[60:61], s[68:69], 0, v[86:87]
	v_lshl_add_u64 v[60:61], v[168:169], 1, v[60:61]
	v_cvt_pk_bf16_f32 v57, v62, v63
	v_cvt_pk_bf16_f32 v58, v58, v59
	v_cvt_pk_bf16_f32 v59, v82, v83
	global_store_dwordx4 v[60:61], v[56:59], off sc0 nt
	v_lshlrev_b32_e32 v62, 16, v56
	v_and_b32_e32 v63, 0xffff0000, v74
	v_and_b32_e32 v56, 0xffff0000, v56
	v_mul_f32_e32 v56, v56, v56
	v_fmac_f32_e32 v56, v62, v62
	v_lshlrev_b32_e32 v62, 16, v57
	v_and_b32_e32 v57, 0xffff0000, v57
	v_mul_f32_e32 v57, v57, v57
	v_fmac_f32_e32 v57, v62, v62
	v_add_f32_e32 v56, v56, v57
	v_lshlrev_b32_e32 v57, 16, v58
	v_and_b32_e32 v58, 0xffff0000, v58
	v_mul_f32_e32 v58, v58, v58
	v_fmac_f32_e32 v58, v57, v57
	v_add_f32_e32 v56, v56, v58
	v_and_b32_e32 v58, 0xffff0000, v59
	v_lshlrev_b32_e32 v57, 16, v59
	v_mul_f32_e32 v58, v58, v58
	v_fmac_f32_e32 v58, v57, v57
	v_add_f32_e32 v82, v56, v58
	v_lshlrev_b32_e32 v56, 16, v72
	v_and_b32_e32 v57, 0xffff0000, v72
	v_lshlrev_b32_e32 v58, 16, v73
	v_and_b32_e32 v59, 0xffff0000, v73
	v_lshlrev_b32_e32 v62, 16, v74
	v_lshlrev_b32_e32 v72, 16, v75
	v_and_b32_e32 v73, 0xffff0000, v75
	v_pk_add_f32 v[52:53], v[52:53], v[56:57]
	v_pk_add_f32 v[56:57], v[50:51], v[72:73]
	v_pk_add_f32 v[50:51], v[48:49], v[62:63]
	v_cvt_pk_bf16_f32 v48, v52, v53
	v_pk_add_f32 v[54:55], v[54:55], v[58:59]
	v_lshlrev_b32_e32 v52, 16, v48
	v_cvt_pk_bf16_f32 v49, v54, v55
	v_cvt_pk_bf16_f32 v50, v50, v51
	v_cvt_pk_bf16_f32 v51, v56, v57
	global_store_dwordx4 v[60:61], v[48:51], off offset:256 sc0 nt
	s_nop 1
	v_and_b32_e32 v48, 0xffff0000, v48
	v_mul_f32_e32 v48, v48, v48
	v_fmac_f32_e32 v48, v52, v52
	v_lshlrev_b32_e32 v52, 16, v49
	v_and_b32_e32 v49, 0xffff0000, v49
	v_mul_f32_e32 v49, v49, v49
	v_add_f32_e32 v48, v82, v48
	v_fmac_f32_e32 v49, v52, v52
	v_add_f32_e32 v48, v48, v49
	v_lshlrev_b32_e32 v49, 16, v50
	v_and_b32_e32 v50, 0xffff0000, v50
	v_mul_f32_e32 v50, v50, v50
	v_fmac_f32_e32 v50, v49, v49
	v_add_f32_e32 v48, v48, v50
	v_and_b32_e32 v50, 0xffff0000, v51
	v_lshlrev_b32_e32 v49, 16, v51
	v_mul_f32_e32 v50, v50, v50
	v_fmac_f32_e32 v50, v49, v49
	v_add_f32_e32 v48, v48, v50
	ds_bpermute_b32 v49, v181, v48
	s_waitcnt lgkmcnt(0)
	v_add_f32_e32 v48, v48, v49
	ds_bpermute_b32 v49, v180, v48
	s_and_saveexec_b64 s[6:7], vcc
	s_cbranch_execz .LBB0_388
	v_lshlrev_b64 v[50:51], 6, v[80:81]
	v_lshl_add_u64 v[50:51], s[46:47], 0, v[50:51]
	v_lshl_add_u64 v[50:51], s[56:57], 2, v[50:51]
	s_lshl_b32 s38, s8, 2
	v_lshl_add_u64 v[50:51], v[50:51], 0, s[38:39]
	s_waitcnt lgkmcnt(0)
	v_add_f32_e32 v48, v48, v49
	flat_store_dword v[50:51], v48
.LBB0_388:
	s_or_b64 exec, exec, s[6:7]
	v_lshlrev_b32_e32 v48, 16, v68
	s_waitcnt lgkmcnt(0)
	v_and_b32_e32 v49, 0xffff0000, v68
	v_lshlrev_b32_e32 v52, 16, v70
	v_and_b32_e32 v53, 0xffff0000, v70
	v_lshlrev_b32_e32 v54, 16, v71
	v_and_b32_e32 v55, 0xffff0000, v71
	v_pk_add_f32 v[44:45], v[44:45], v[48:49]
	v_lshlrev_b32_e32 v50, 16, v69
	v_and_b32_e32 v51, 0xffff0000, v69
	v_pk_add_f32 v[48:49], v[42:43], v[54:55]
	v_pk_add_f32 v[42:43], v[40:41], v[52:53]
	v_cvt_pk_bf16_f32 v40, v44, v45
	v_lshl_add_u64 v[44:45], s[68:69], 0, v[78:79]
	v_pk_add_f32 v[46:47], v[46:47], v[50:51]
	v_lshl_add_u64 v[44:45], v[168:169], 1, v[44:45]
	v_cvt_pk_bf16_f32 v41, v46, v47
	v_cvt_pk_bf16_f32 v42, v42, v43
	v_cvt_pk_bf16_f32 v43, v48, v49
	global_store_dwordx4 v[44:45], v[40:43], off sc0 nt
	v_lshlrev_b32_e32 v46, 16, v40
	v_and_b32_e32 v47, 0xffff0000, v66
	v_and_b32_e32 v40, 0xffff0000, v40
	v_mul_f32_e32 v40, v40, v40
	v_fmac_f32_e32 v40, v46, v46
	v_lshlrev_b32_e32 v46, 16, v41
	v_and_b32_e32 v41, 0xffff0000, v41
	v_mul_f32_e32 v41, v41, v41
	v_fmac_f32_e32 v41, v46, v46
	v_add_f32_e32 v40, v40, v41
	v_lshlrev_b32_e32 v41, 16, v42
	v_and_b32_e32 v42, 0xffff0000, v42
	v_mul_f32_e32 v42, v42, v42
	v_fmac_f32_e32 v42, v41, v41
	v_add_f32_e32 v40, v40, v42
	v_and_b32_e32 v42, 0xffff0000, v43
	v_lshlrev_b32_e32 v41, 16, v43
	v_mul_f32_e32 v42, v42, v42
	v_fmac_f32_e32 v42, v41, v41
	v_add_f32_e32 v50, v40, v42
	v_lshlrev_b32_e32 v40, 16, v64
	v_and_b32_e32 v41, 0xffff0000, v64
	v_lshlrev_b32_e32 v46, 16, v66
	v_lshlrev_b32_e32 v42, 16, v65
	v_and_b32_e32 v43, 0xffff0000, v65
	v_lshlrev_b32_e32 v48, 16, v67
	v_and_b32_e32 v49, 0xffff0000, v67
	v_pk_add_f32 v[36:37], v[36:37], v[40:41]
	v_pk_add_f32 v[32:33], v[32:33], v[46:47]
	v_pk_add_f32 v[38:39], v[38:39], v[42:43]
	v_pk_add_f32 v[40:41], v[34:35], v[48:49]
	v_cvt_pk_bf16_f32 v34, v36, v37
	v_cvt_pk_bf16_f32 v35, v38, v39
	v_cvt_pk_bf16_f32 v36, v32, v33
	s_nop 0
	v_and_b32_e32 v33, 0xffff0000, v34
	v_lshlrev_b32_e32 v32, 16, v34
	v_mul_f32_e32 v33, v33, v33
	v_fmac_f32_e32 v33, v32, v32
	v_and_b32_e32 v38, 0xffff0000, v35
	v_add_f32_e32 v32, v50, v33
	v_lshlrev_b32_e32 v33, 16, v35
	v_mul_f32_e32 v38, v38, v38
	v_fmac_f32_e32 v38, v33, v33
	v_add_f32_e32 v32, v32, v38
	v_and_b32_e32 v38, 0xffff0000, v36
	v_lshlrev_b32_e32 v33, 16, v36
	v_mul_f32_e32 v38, v38, v38
	v_fmac_f32_e32 v38, v33, v33
	v_cvt_pk_bf16_f32 v37, v40, v41
	v_add_f32_e32 v32, v32, v38
	v_and_b32_e32 v38, 0xffff0000, v37
	v_lshlrev_b32_e32 v33, 16, v37
	v_mul_f32_e32 v38, v38, v38
	v_fmac_f32_e32 v38, v33, v33
	v_add_f32_e32 v32, v32, v38
	ds_bpermute_b32 v33, v181, v32
	global_store_dwordx4 v[44:45], v[34:37], off offset:256 sc0 nt
	s_waitcnt lgkmcnt(0)
	v_add_f32_e32 v32, v32, v33
	ds_bpermute_b32 v33, v180, v32
	s_and_saveexec_b64 s[6:7], vcc
	s_cbranch_execz .LBB0_390
	v_lshlrev_b64 v[34:35], 6, v[76:77]
	v_lshl_add_u64 v[34:35], s[46:47], 0, v[34:35]
	v_lshl_add_u64 v[34:35], s[56:57], 2, v[34:35]
	s_lshl_b32 s38, s8, 2
	v_lshl_add_u64 v[34:35], v[34:35], 0, s[38:39]
	s_waitcnt lgkmcnt(0)
	v_add_f32_e32 v32, v32, v33
	flat_store_dword v[34:35], v32
.LBB0_390:
	s_or_b64 exec, exec, s[6:7]
	v_add_u32_e32 v48, 0xa0, v170
	v_ashrrev_i32_e32 v49, 31, v48
	v_lshlrev_b64 v[54:55], 11, v[48:49]
	s_waitcnt lgkmcnt(0)
	v_lshl_add_u64 v[32:33], v[172:173], 0, v[54:55]
	global_load_dwordx4 v[50:53], v[32:33], off
	global_load_dwordx4 v[40:43], v[32:33], off offset:256
	v_add_u32_e32 v44, 0xb0, v170
	v_ashrrev_i32_e32 v45, 31, v44
	v_lshlrev_b64 v[46:47], 11, v[44:45]
	v_lshl_add_u64 v[32:33], v[172:173], 0, v[46:47]
	global_load_dwordx4 v[36:39], v[32:33], off
	s_nop 0
	global_load_dwordx4 v[32:35], v[32:33], off offset:256
	s_waitcnt vmcnt(0)
	v_lshlrev_b32_e32 v56, 16, v50
	v_and_b32_e32 v57, 0xffff0000, v50
	v_lshlrev_b32_e32 v50, 16, v51
	v_and_b32_e32 v51, 0xffff0000, v51
	v_lshlrev_b32_e32 v58, 16, v52
	v_and_b32_e32 v59, 0xffff0000, v52
	v_lshlrev_b32_e32 v52, 16, v53
	v_and_b32_e32 v53, 0xffff0000, v53
	v_pk_add_f32 v[28:29], v[28:29], v[56:57]
	v_pk_add_f32 v[30:31], v[30:31], v[50:51]
	v_pk_add_f32 v[50:51], v[26:27], v[52:53]
	v_pk_add_f32 v[26:27], v[24:25], v[58:59]
	v_cvt_pk_bf16_f32 v24, v28, v29
	v_lshl_add_u64 v[28:29], s[68:69], 0, v[54:55]
	v_lshl_add_u64 v[28:29], v[168:169], 1, v[28:29]
	v_cvt_pk_bf16_f32 v25, v30, v31
	v_cvt_pk_bf16_f32 v26, v26, v27
	v_cvt_pk_bf16_f32 v27, v50, v51
	global_store_dwordx4 v[28:29], v[24:27], off sc0 nt
	v_lshlrev_b32_e32 v30, 16, v24
	v_and_b32_e32 v31, 0xffff0000, v42
	v_and_b32_e32 v24, 0xffff0000, v24
	v_mul_f32_e32 v24, v24, v24
	v_fmac_f32_e32 v24, v30, v30
	v_lshlrev_b32_e32 v30, 16, v25
	v_and_b32_e32 v25, 0xffff0000, v25
	v_mul_f32_e32 v25, v25, v25
	v_fmac_f32_e32 v25, v30, v30
	v_add_f32_e32 v24, v24, v25
	v_lshlrev_b32_e32 v25, 16, v26
	v_and_b32_e32 v26, 0xffff0000, v26
	v_mul_f32_e32 v26, v26, v26
	v_fmac_f32_e32 v26, v25, v25
	v_add_f32_e32 v24, v24, v26
	v_and_b32_e32 v26, 0xffff0000, v27
	v_lshlrev_b32_e32 v25, 16, v27
	v_mul_f32_e32 v26, v26, v26
	v_fmac_f32_e32 v26, v25, v25
	v_add_f32_e32 v50, v24, v26
	v_lshlrev_b32_e32 v24, 16, v40
	v_and_b32_e32 v25, 0xffff0000, v40
	v_lshlrev_b32_e32 v26, 16, v41
	v_and_b32_e32 v27, 0xffff0000, v41
	v_lshlrev_b32_e32 v30, 16, v42
	v_lshlrev_b32_e32 v40, 16, v43
	v_and_b32_e32 v41, 0xffff0000, v43
	v_pk_add_f32 v[20:21], v[20:21], v[24:25]
	v_pk_add_f32 v[24:25], v[18:19], v[40:41]
	v_pk_add_f32 v[18:19], v[16:17], v[30:31]
	v_cvt_pk_bf16_f32 v16, v20, v21
	v_pk_add_f32 v[22:23], v[22:23], v[26:27]
	v_lshlrev_b32_e32 v20, 16, v16
	v_cvt_pk_bf16_f32 v17, v22, v23
	v_cvt_pk_bf16_f32 v18, v18, v19
	v_cvt_pk_bf16_f32 v19, v24, v25
	global_store_dwordx4 v[28:29], v[16:19], off offset:256 sc0 nt
	s_nop 1
	v_and_b32_e32 v16, 0xffff0000, v16
	v_mul_f32_e32 v16, v16, v16
	v_fmac_f32_e32 v16, v20, v20
	v_lshlrev_b32_e32 v20, 16, v17
	v_and_b32_e32 v17, 0xffff0000, v17
	v_mul_f32_e32 v17, v17, v17
	v_add_f32_e32 v16, v50, v16
	v_fmac_f32_e32 v17, v20, v20
	v_add_f32_e32 v16, v16, v17
	v_lshlrev_b32_e32 v17, 16, v18
	v_and_b32_e32 v18, 0xffff0000, v18
	v_mul_f32_e32 v18, v18, v18
	v_fmac_f32_e32 v18, v17, v17
	v_add_f32_e32 v16, v16, v18
	v_and_b32_e32 v18, 0xffff0000, v19
	v_lshlrev_b32_e32 v17, 16, v19
	v_mul_f32_e32 v18, v18, v18
	v_fmac_f32_e32 v18, v17, v17
	v_add_f32_e32 v16, v16, v18
	ds_bpermute_b32 v17, v181, v16
	s_waitcnt lgkmcnt(0)
	v_add_f32_e32 v16, v16, v17
	ds_bpermute_b32 v17, v180, v16
	s_and_saveexec_b64 s[6:7], vcc
	s_cbranch_execz .LBB0_392
	v_lshlrev_b64 v[18:19], 6, v[48:49]
	v_lshl_add_u64 v[18:19], s[46:47], 0, v[18:19]
	v_lshl_add_u64 v[18:19], s[56:57], 2, v[18:19]
	s_lshl_b32 s38, s8, 2
	v_lshl_add_u64 v[18:19], v[18:19], 0, s[38:39]
	s_waitcnt lgkmcnt(0)
	v_add_f32_e32 v16, v16, v17
	flat_store_dword v[18:19], v16
.LBB0_392:
	s_or_b64 exec, exec, s[6:7]
	v_lshlrev_b32_e32 v16, 16, v36
	s_waitcnt lgkmcnt(0)
	v_and_b32_e32 v17, 0xffff0000, v36
	v_lshlrev_b32_e32 v20, 16, v38
	v_and_b32_e32 v21, 0xffff0000, v38
	v_lshlrev_b32_e32 v22, 16, v39
	v_and_b32_e32 v23, 0xffff0000, v39
	v_pk_add_f32 v[12:13], v[12:13], v[16:17]
	v_lshlrev_b32_e32 v18, 16, v37
	v_and_b32_e32 v19, 0xffff0000, v37
	v_pk_add_f32 v[16:17], v[10:11], v[22:23]
	v_pk_add_f32 v[10:11], v[8:9], v[20:21]
	v_cvt_pk_bf16_f32 v8, v12, v13
	v_lshl_add_u64 v[12:13], s[68:69], 0, v[46:47]
	v_pk_add_f32 v[14:15], v[14:15], v[18:19]
	v_lshl_add_u64 v[12:13], v[168:169], 1, v[12:13]
	v_cvt_pk_bf16_f32 v9, v14, v15
	v_cvt_pk_bf16_f32 v10, v10, v11
	v_cvt_pk_bf16_f32 v11, v16, v17
	global_store_dwordx4 v[12:13], v[8:11], off sc0 nt
	v_lshlrev_b32_e32 v14, 16, v8
	v_and_b32_e32 v15, 0xffff0000, v34
	v_and_b32_e32 v8, 0xffff0000, v8
	v_mul_f32_e32 v8, v8, v8
	v_fmac_f32_e32 v8, v14, v14
	v_lshlrev_b32_e32 v14, 16, v9
	v_and_b32_e32 v9, 0xffff0000, v9
	v_mul_f32_e32 v9, v9, v9
	v_fmac_f32_e32 v9, v14, v14
	v_add_f32_e32 v8, v8, v9
	v_lshlrev_b32_e32 v9, 16, v10
	v_and_b32_e32 v10, 0xffff0000, v10
	v_mul_f32_e32 v10, v10, v10
	v_fmac_f32_e32 v10, v9, v9
	v_add_f32_e32 v8, v8, v10
	v_and_b32_e32 v10, 0xffff0000, v11
	v_lshlrev_b32_e32 v9, 16, v11
	v_mul_f32_e32 v10, v10, v10
	v_fmac_f32_e32 v10, v9, v9
	v_add_f32_e32 v18, v8, v10
	v_lshlrev_b32_e32 v8, 16, v32
	v_and_b32_e32 v9, 0xffff0000, v32
	v_lshlrev_b32_e32 v14, 16, v34
	v_lshlrev_b32_e32 v10, 16, v33
	v_and_b32_e32 v11, 0xffff0000, v33
	v_lshlrev_b32_e32 v16, 16, v35
	v_and_b32_e32 v17, 0xffff0000, v35
	v_pk_add_f32 v[4:5], v[4:5], v[8:9]
	v_pk_add_f32 v[0:1], v[0:1], v[14:15]
	v_pk_add_f32 v[6:7], v[6:7], v[10:11]
	v_pk_add_f32 v[8:9], v[2:3], v[16:17]
	v_cvt_pk_bf16_f32 v2, v4, v5
	v_cvt_pk_bf16_f32 v3, v6, v7
	v_cvt_pk_bf16_f32 v4, v0, v1
	s_nop 0
	v_and_b32_e32 v1, 0xffff0000, v2
	v_lshlrev_b32_e32 v0, 16, v2
	v_mul_f32_e32 v1, v1, v1
	v_fmac_f32_e32 v1, v0, v0
	v_and_b32_e32 v6, 0xffff0000, v3
	v_add_f32_e32 v0, v18, v1
	v_lshlrev_b32_e32 v1, 16, v3
	v_mul_f32_e32 v6, v6, v6
	v_fmac_f32_e32 v6, v1, v1
	v_add_f32_e32 v0, v0, v6
	v_and_b32_e32 v6, 0xffff0000, v4
	v_lshlrev_b32_e32 v1, 16, v4
	v_mul_f32_e32 v6, v6, v6
	v_fmac_f32_e32 v6, v1, v1
	v_cvt_pk_bf16_f32 v5, v8, v9
	v_add_f32_e32 v0, v0, v6
	v_and_b32_e32 v6, 0xffff0000, v5
	v_lshlrev_b32_e32 v1, 16, v5
	v_mul_f32_e32 v6, v6, v6
	v_fmac_f32_e32 v6, v1, v1
	v_add_f32_e32 v0, v0, v6
	ds_bpermute_b32 v1, v181, v0
	global_store_dwordx4 v[12:13], v[2:5], off offset:256 sc0 nt
	s_waitcnt lgkmcnt(0)
	v_add_f32_e32 v0, v0, v1
	ds_bpermute_b32 v1, v180, v0
	s_and_saveexec_b64 s[6:7], vcc
	s_cbranch_execz .LBB0_394
	v_lshlrev_b64 v[2:3], 6, v[44:45]
	v_lshl_add_u64 v[2:3], s[46:47], 0, v[2:3]
	v_lshl_add_u64 v[2:3], s[56:57], 2, v[2:3]
	s_lshl_b32 s38, s8, 2
	v_lshl_add_u64 v[2:3], v[2:3], 0, s[38:39]
	s_waitcnt lgkmcnt(0)
	v_add_f32_e32 v0, v0, v1
	flat_store_dword v[2:3], v0

.LBB0_419:
	s_mov_b32 s6, -1
	s_lshl_b32 s5, s5, 8
	v_mbcnt_lo_u32_b32 v112, s6, 0
	v_mbcnt_hi_u32_b32 v112, s6, v112
	s_getreg_b32 s6, hwreg(HW_REG_HW_ID, 0, 6)
	s_and_b32 s6, s6, 63
	s_lshl_b32 s6, s6, 2
	s_add_i32 s6, s6, 0
	s_add_i32 s6, s6, 0x20200
	v_mov_b32_e32 v113, s6
	ds_read_b32 v113, v113
	v_bfrev_b32_e32 v114, 0.5
	s_movk_i32 s84, 0x80
	s_lshl_b32 s58, s4, 2
	s_ashr_i32 s59, s58, 31
	s_waitcnt lgkmcnt(0)
	v_readfirstlane_b32 s6, v113
	s_nop 1
	v_lshl_add_u32 v112, s6, 6, v112
	s_nop 0
	v_readfirstlane_b32 s6, v112
	s_bfe_u32 s8, s6, 0x20006
	s_ashr_i32 s6, s6, 2
	s_andn2_b32 s6, s6, 63
	s_add_i32 s6, s6, s5
	v_and_or_b32 v166, v112, 15, s6
	s_lshl_b32 s5, s4, 8
	s_lshl_b32 s6, s8, 5
	v_bfe_u32 v113, v112, 4, 2
	s_or_b32 s5, s6, s5
	v_lshl_or_b32 v164, v113, 3, s5
	v_ashrrev_i32_e32 v165, 31, v164
	v_lshlrev_b64 v[146:147], 1, v[164:165]
	v_ashrrev_i32_e32 v167, 31, v166
	v_lshlrev_b32_e32 v112, 2, v112
	v_lshl_add_u64 v[168:169], s[68:69], 0, v[146:147]
	v_lshlrev_b64 v[148:149], 11, v[166:167]
	v_bitop3_b32 v176, v112, 64, v114 bitop3:0x6c
	v_bitop3_b32 v177, v112, s84, v114 bitop3:0x6c
	v_cmp_eq_u32_e32 vcc, 0, v113
	v_lshl_add_u64 v[112:113], v[168:169], 0, v[148:149]
	global_load_dwordx4 v[142:145], v[112:113], off
	global_load_dwordx4 v[128:131], v[112:113], off offset:256
	v_or_b32_e32 v170, 16, v166
	v_ashrrev_i32_e32 v171, 31, v170
	v_lshlrev_b64 v[172:173], 11, v[170:171]
	v_lshl_add_u64 v[112:113], v[168:169], 0, v[172:173]
	global_load_dwordx4 v[116:119], v[112:113], off
	s_nop 0
	global_load_dwordx4 v[112:115], v[112:113], off offset:256
	s_waitcnt vmcnt(0)
	v_lshlrev_b32_e32 v150, 16, v142
	v_and_b32_e32 v151, 0xffff0000, v142
	v_lshlrev_b32_e32 v142, 16, v143
	v_and_b32_e32 v143, 0xffff0000, v143
	v_lshlrev_b32_e32 v152, 16, v144
	v_and_b32_e32 v153, 0xffff0000, v144
	v_pk_add_f32 v[134:135], v[134:135], v[142:143]
	v_pk_add_f32 v[132:133], v[132:133], v[150:151]
	v_pk_add_f32 v[136:137], v[136:137], v[152:153]
	v_lshlrev_b32_e32 v144, 16, v145
	v_and_b32_e32 v145, 0xffff0000, v145
	v_cvt_pk_bf16_f32 v132, v132, v133
	v_cvt_pk_bf16_f32 v133, v134, v135
	v_cvt_pk_bf16_f32 v134, v136, v137
	v_lshl_add_u64 v[136:137], s[68:69], 0, v[148:149]
	v_pk_add_f32 v[138:139], v[138:139], v[144:145]
	v_lshl_add_u64 v[136:137], v[136:137], 0, v[146:147]
	v_cvt_pk_bf16_f32 v135, v138, v139
	global_store_dwordx4 v[136:137], v[132:135], off sc0 nt
	v_lshlrev_b32_e32 v138, 16, v132
	s_nop 0
	v_and_b32_e32 v132, 0xffff0000, v132
	v_mul_f32_e32 v132, v132, v132
	v_fmac_f32_e32 v132, v138, v138
	v_lshlrev_b32_e32 v138, 16, v133
	v_and_b32_e32 v133, 0xffff0000, v133
	v_mul_f32_e32 v133, v133, v133
	v_fmac_f32_e32 v133, v138, v138
	v_add_f32_e32 v132, v132, v133
	v_lshlrev_b32_e32 v133, 16, v134
	v_and_b32_e32 v134, 0xffff0000, v134
	v_mul_f32_e32 v134, v134, v134
	v_fmac_f32_e32 v134, v133, v133
	v_add_f32_e32 v132, v132, v134
	v_and_b32_e32 v134, 0xffff0000, v135
	v_lshlrev_b32_e32 v133, 16, v135
	v_mul_f32_e32 v134, v134, v134
	v_fmac_f32_e32 v134, v133, v133
	v_add_f32_e32 v138, v132, v134
	v_lshlrev_b32_e32 v132, 16, v128
	v_and_b32_e32 v133, 0xffff0000, v128
	v_lshlrev_b32_e32 v128, 16, v129
	v_and_b32_e32 v129, 0xffff0000, v129
	v_lshlrev_b32_e32 v134, 16, v130
	v_and_b32_e32 v135, 0xffff0000, v130
	v_lshlrev_b32_e32 v130, 16, v131
	v_and_b32_e32 v131, 0xffff0000, v131
	v_pk_add_f32 v[126:127], v[126:127], v[128:129]
	v_pk_add_f32 v[124:125], v[124:125], v[132:133]
	v_pk_add_f32 v[128:129], v[122:123], v[130:131]
	v_pk_add_f32 v[122:123], v[120:121], v[134:135]
	v_cvt_pk_bf16_f32 v120, v124, v125
	v_cvt_pk_bf16_f32 v121, v126, v127
	s_nop 0
	v_cvt_pk_bf16_f32 v122, v122, v123
	v_cvt_pk_bf16_f32 v123, v128, v129
	global_store_dwordx4 v[136:137], v[120:123], off offset:256 sc0 nt
	v_lshlrev_b32_e32 v124, 16, v120
	s_nop 0
	v_and_b32_e32 v120, 0xffff0000, v120
	v_mul_f32_e32 v120, v120, v120
	v_fmac_f32_e32 v120, v124, v124
	v_lshlrev_b32_e32 v124, 16, v121
	v_and_b32_e32 v121, 0xffff0000, v121
	v_mul_f32_e32 v121, v121, v121
	v_add_f32_e32 v120, v138, v120
	v_fmac_f32_e32 v121, v124, v124
	v_add_f32_e32 v120, v120, v121
	v_lshlrev_b32_e32 v121, 16, v122
	v_and_b32_e32 v122, 0xffff0000, v122
	v_mul_f32_e32 v122, v122, v122
	v_fmac_f32_e32 v122, v121, v121
	v_add_f32_e32 v120, v120, v122
	v_and_b32_e32 v122, 0xffff0000, v123
	v_lshlrev_b32_e32 v121, 16, v123
	v_mul_f32_e32 v122, v122, v122
	v_fmac_f32_e32 v122, v121, v121
	v_add_f32_e32 v120, v120, v122
	ds_bpermute_b32 v121, v176, v120
	s_waitcnt lgkmcnt(0)
	v_add_f32_e32 v120, v120, v121
	ds_bpermute_b32 v121, v177, v120
	s_and_saveexec_b64 s[6:7], vcc
	s_cbranch_execz .LBB0_421
	s_waitcnt lgkmcnt(0)
	v_add_f32_e32 v122, v120, v121
	v_lshlrev_b64 v[120:121], 6, v[166:167]
	v_lshl_add_u64 v[120:121], s[46:47], 0, v[120:121]
	v_lshl_add_u64 v[120:121], s[58:59], 2, v[120:121]
	s_lshl_b32 s38, s8, 2
	v_lshl_add_u64 v[120:121], v[120:121], 0, s[38:39]
	flat_store_dword v[120:121], v122
.LBB0_421:
	s_or_b64 exec, exec, s[6:7]
	v_lshlrev_b32_e32 v120, 16, v116
	s_waitcnt lgkmcnt(0)
	v_and_b32_e32 v121, 0xffff0000, v116
	v_lshlrev_b32_e32 v116, 16, v117
	v_and_b32_e32 v117, 0xffff0000, v117
	v_lshlrev_b32_e32 v122, 16, v118
	v_and_b32_e32 v123, 0xffff0000, v118
	v_lshlrev_b32_e32 v118, 16, v119
	v_and_b32_e32 v119, 0xffff0000, v119
	v_pk_add_f32 v[108:109], v[108:109], v[120:121]
	v_pk_add_f32 v[110:111], v[110:111], v[116:117]
	v_pk_add_f32 v[116:117], v[106:107], v[118:119]
	v_pk_add_f32 v[106:107], v[104:105], v[122:123]
	v_cvt_pk_bf16_f32 v104, v108, v109
	v_lshl_add_u64 v[108:109], s[68:69], 0, v[172:173]
	v_lshl_add_u64 v[108:109], v[164:165], 1, v[108:109]
	v_cvt_pk_bf16_f32 v105, v110, v111
	v_cvt_pk_bf16_f32 v106, v106, v107
	v_cvt_pk_bf16_f32 v107, v116, v117
	global_store_dwordx4 v[108:109], v[104:107], off sc0 nt
	v_lshlrev_b32_e32 v110, 16, v104
	v_and_b32_e32 v111, 0xffff0000, v114
	v_and_b32_e32 v104, 0xffff0000, v104
	v_mul_f32_e32 v104, v104, v104
	v_fmac_f32_e32 v104, v110, v110
	v_lshlrev_b32_e32 v110, 16, v105
	v_and_b32_e32 v105, 0xffff0000, v105
	v_mul_f32_e32 v105, v105, v105
	v_fmac_f32_e32 v105, v110, v110
	v_add_f32_e32 v104, v104, v105
	v_lshlrev_b32_e32 v105, 16, v106
	v_and_b32_e32 v106, 0xffff0000, v106
	v_mul_f32_e32 v106, v106, v106
	v_fmac_f32_e32 v106, v105, v105
	v_add_f32_e32 v104, v104, v106
	v_and_b32_e32 v106, 0xffff0000, v107
	v_lshlrev_b32_e32 v105, 16, v107
	v_mul_f32_e32 v106, v106, v106
	v_fmac_f32_e32 v106, v105, v105
	v_add_f32_e32 v116, v104, v106
	v_lshlrev_b32_e32 v104, 16, v112
	v_and_b32_e32 v105, 0xffff0000, v112
	v_lshlrev_b32_e32 v110, 16, v114
	v_lshlrev_b32_e32 v106, 16, v113
	v_and_b32_e32 v107, 0xffff0000, v113
	v_lshlrev_b32_e32 v112, 16, v115
	v_and_b32_e32 v113, 0xffff0000, v115
	v_pk_add_f32 v[100:101], v[100:101], v[104:105]
	v_pk_add_f32 v[96:97], v[96:97], v[110:111]
	v_pk_add_f32 v[102:103], v[102:103], v[106:107]
	v_pk_add_f32 v[104:105], v[98:99], v[112:113]
	v_cvt_pk_bf16_f32 v98, v100, v101
	v_cvt_pk_bf16_f32 v99, v102, v103
	v_cvt_pk_bf16_f32 v100, v96, v97
	s_nop 0
	v_and_b32_e32 v97, 0xffff0000, v98
	v_lshlrev_b32_e32 v96, 16, v98
	v_mul_f32_e32 v97, v97, v97
	v_fmac_f32_e32 v97, v96, v96
	v_and_b32_e32 v102, 0xffff0000, v99
	v_add_f32_e32 v96, v116, v97
	v_lshlrev_b32_e32 v97, 16, v99
	v_mul_f32_e32 v102, v102, v102
	v_fmac_f32_e32 v102, v97, v97
	v_add_f32_e32 v96, v96, v102
	v_and_b32_e32 v102, 0xffff0000, v100
	v_lshlrev_b32_e32 v97, 16, v100
	v_mul_f32_e32 v102, v102, v102
	v_fmac_f32_e32 v102, v97, v97
	v_cvt_pk_bf16_f32 v101, v104, v105
	v_add_f32_e32 v96, v96, v102
	v_and_b32_e32 v102, 0xffff0000, v101
	v_lshlrev_b32_e32 v97, 16, v101
	v_mul_f32_e32 v102, v102, v102
	v_fmac_f32_e32 v102, v97, v97
	v_add_f32_e32 v96, v96, v102
	ds_bpermute_b32 v97, v176, v96
	global_store_dwordx4 v[108:109], v[98:101], off offset:256 sc0 nt
	s_waitcnt lgkmcnt(0)
	v_add_f32_e32 v96, v96, v97
	ds_bpermute_b32 v97, v177, v96
	s_mov_b64 s[6:7], exec
	s_and_b64 s[4:5], s[6:7], vcc
	v_mov_b32_e32 v198, v246
	v_mov_b32_e32 v199, v247
	v_mov_b32_e32 v205, v249
	v_mov_b32_e32 v196, v251
	v_mov_b32_e32 v251, 0x260
	s_mov_b64 exec, s[4:5]
	s_cbranch_execz .LBB0_423
	s_waitcnt lgkmcnt(0)
	v_add_f32_e32 v98, v96, v97
	v_lshlrev_b64 v[96:97], 6, v[170:171]
	v_lshl_add_u64 v[96:97], s[46:47], 0, v[96:97]
	v_lshl_add_u64 v[96:97], s[58:59], 2, v[96:97]
	s_lshl_b32 s38, s8, 2
	v_lshl_add_u64 v[96:97], v[96:97], 0, s[38:39]
	flat_store_dword v[96:97], v98
.LBB0_423:
	s_or_b64 exec, exec, s[6:7]
	v_or_b32_e32 v112, 32, v166
	v_ashrrev_i32_e32 v113, 31, v112
	v_lshlrev_b64 v[118:119], 11, v[112:113]
	s_waitcnt lgkmcnt(0)
	v_lshl_add_u64 v[96:97], v[168:169], 0, v[118:119]
	global_load_dwordx4 v[114:117], v[96:97], off
	global_load_dwordx4 v[104:107], v[96:97], off offset:256
	v_or_b32_e32 v108, 48, v166
	v_ashrrev_i32_e32 v109, 31, v108
	v_lshlrev_b64 v[110:111], 11, v[108:109]
	v_lshl_add_u64 v[96:97], v[168:169], 0, v[110:111]
	global_load_dwordx4 v[100:103], v[96:97], off
	s_nop 0
	global_load_dwordx4 v[96:99], v[96:97], off offset:256
	s_waitcnt vmcnt(0)
	v_lshlrev_b32_e32 v120, 16, v114
	v_and_b32_e32 v121, 0xffff0000, v114
	v_lshlrev_b32_e32 v114, 16, v115
	v_and_b32_e32 v115, 0xffff0000, v115
	v_lshlrev_b32_e32 v122, 16, v116
	v_and_b32_e32 v123, 0xffff0000, v116
	v_pk_add_f32 v[90:91], v[90:91], v[114:115]
	v_pk_add_f32 v[88:89], v[88:89], v[120:121]
	v_pk_add_f32 v[92:93], v[92:93], v[122:123]
	v_lshlrev_b32_e32 v116, 16, v117
	v_and_b32_e32 v117, 0xffff0000, v117
	v_cvt_pk_bf16_f32 v88, v88, v89
	v_cvt_pk_bf16_f32 v89, v90, v91
	v_cvt_pk_bf16_f32 v90, v92, v93
	v_lshl_add_u64 v[92:93], s[68:69], 0, v[118:119]
	v_pk_add_f32 v[94:95], v[94:95], v[116:117]
	v_lshl_add_u64 v[92:93], v[164:165], 1, v[92:93]
	v_cvt_pk_bf16_f32 v91, v94, v95
	global_store_dwordx4 v[92:93], v[88:91], off sc0 nt
	v_lshlrev_b32_e32 v94, 16, v88
	v_and_b32_e32 v95, 0xffff0000, v106
	v_and_b32_e32 v88, 0xffff0000, v88
	v_mul_f32_e32 v88, v88, v88
	v_fmac_f32_e32 v88, v94, v94
	v_lshlrev_b32_e32 v94, 16, v89
	v_and_b32_e32 v89, 0xffff0000, v89
	v_mul_f32_e32 v89, v89, v89
	v_fmac_f32_e32 v89, v94, v94
	v_add_f32_e32 v88, v88, v89
	v_lshlrev_b32_e32 v89, 16, v90
	v_and_b32_e32 v90, 0xffff0000, v90
	v_mul_f32_e32 v90, v90, v90
	v_fmac_f32_e32 v90, v89, v89
	v_add_f32_e32 v88, v88, v90
	v_and_b32_e32 v90, 0xffff0000, v91
	v_lshlrev_b32_e32 v89, 16, v91
	v_mul_f32_e32 v90, v90, v90
	v_fmac_f32_e32 v90, v89, v89
	v_add_f32_e32 v114, v88, v90
	v_lshlrev_b32_e32 v88, 16, v104
	v_and_b32_e32 v89, 0xffff0000, v104
	v_lshlrev_b32_e32 v90, 16, v105
	v_and_b32_e32 v91, 0xffff0000, v105
	v_lshlrev_b32_e32 v94, 16, v106
	v_lshlrev_b32_e32 v104, 16, v107
	v_and_b32_e32 v105, 0xffff0000, v107
	v_pk_add_f32 v[84:85], v[84:85], v[88:89]
	v_pk_add_f32 v[88:89], v[82:83], v[104:105]
	v_pk_add_f32 v[82:83], v[80:81], v[94:95]
	v_cvt_pk_bf16_f32 v80, v84, v85
	v_pk_add_f32 v[86:87], v[86:87], v[90:91]
	v_lshlrev_b32_e32 v84, 16, v80
	v_cvt_pk_bf16_f32 v81, v86, v87
	v_cvt_pk_bf16_f32 v82, v82, v83
	v_cvt_pk_bf16_f32 v83, v88, v89
	global_store_dwordx4 v[92:93], v[80:83], off offset:256 sc0 nt
	s_nop 1
	v_and_b32_e32 v80, 0xffff0000, v80
	v_mul_f32_e32 v80, v80, v80
	v_fmac_f32_e32 v80, v84, v84
	v_lshlrev_b32_e32 v84, 16, v81
	v_and_b32_e32 v81, 0xffff0000, v81
	v_mul_f32_e32 v81, v81, v81
	v_add_f32_e32 v80, v114, v80
	v_fmac_f32_e32 v81, v84, v84
	v_add_f32_e32 v80, v80, v81
	v_lshlrev_b32_e32 v81, 16, v82
	v_and_b32_e32 v82, 0xffff0000, v82
	v_mul_f32_e32 v82, v82, v82
	v_fmac_f32_e32 v82, v81, v81
	v_add_f32_e32 v80, v80, v82
	v_and_b32_e32 v82, 0xffff0000, v83
	v_lshlrev_b32_e32 v81, 16, v83
	v_mul_f32_e32 v82, v82, v82
	v_fmac_f32_e32 v82, v81, v81
	v_add_f32_e32 v80, v80, v82
	ds_bpermute_b32 v81, v176, v80
	s_waitcnt lgkmcnt(0)
	v_add_f32_e32 v80, v80, v81
	ds_bpermute_b32 v81, v177, v80
	s_and_saveexec_b64 s[6:7], vcc
	s_cbranch_execz .LBB0_425
	s_waitcnt lgkmcnt(0)
	v_add_f32_e32 v82, v80, v81
	v_lshlrev_b64 v[80:81], 6, v[112:113]
	v_lshl_add_u64 v[80:81], s[46:47], 0, v[80:81]
	v_lshl_add_u64 v[80:81], s[58:59], 2, v[80:81]
	s_lshl_b32 s38, s8, 2
	v_lshl_add_u64 v[80:81], v[80:81], 0, s[38:39]
	flat_store_dword v[80:81], v82
.LBB0_425:
	s_or_b64 exec, exec, s[6:7]
	v_lshlrev_b32_e32 v80, 16, v100
	s_waitcnt lgkmcnt(0)
	v_and_b32_e32 v81, 0xffff0000, v100
	v_lshlrev_b32_e32 v84, 16, v102
	v_and_b32_e32 v85, 0xffff0000, v102
	v_lshlrev_b32_e32 v86, 16, v103
	v_and_b32_e32 v87, 0xffff0000, v103
	v_pk_add_f32 v[76:77], v[76:77], v[80:81]
	v_lshlrev_b32_e32 v82, 16, v101
	v_and_b32_e32 v83, 0xffff0000, v101
	v_pk_add_f32 v[80:81], v[74:75], v[86:87]
	v_pk_add_f32 v[74:75], v[72:73], v[84:85]
	v_cvt_pk_bf16_f32 v72, v76, v77
	v_lshl_add_u64 v[76:77], s[68:69], 0, v[110:111]
	v_pk_add_f32 v[78:79], v[78:79], v[82:83]
	v_lshl_add_u64 v[76:77], v[164:165], 1, v[76:77]
	v_cvt_pk_bf16_f32 v73, v78, v79
	v_cvt_pk_bf16_f32 v74, v74, v75
	v_cvt_pk_bf16_f32 v75, v80, v81
	global_store_dwordx4 v[76:77], v[72:75], off sc0 nt
	v_lshlrev_b32_e32 v78, 16, v72
	v_and_b32_e32 v79, 0xffff0000, v98
	v_and_b32_e32 v72, 0xffff0000, v72
	v_mul_f32_e32 v72, v72, v72
	v_fmac_f32_e32 v72, v78, v78
	v_lshlrev_b32_e32 v78, 16, v73
	v_and_b32_e32 v73, 0xffff0000, v73
	v_mul_f32_e32 v73, v73, v73
	v_fmac_f32_e32 v73, v78, v78
	v_add_f32_e32 v72, v72, v73
	v_lshlrev_b32_e32 v73, 16, v74
	v_and_b32_e32 v74, 0xffff0000, v74
	v_mul_f32_e32 v74, v74, v74
	v_fmac_f32_e32 v74, v73, v73
	v_add_f32_e32 v72, v72, v74
	v_and_b32_e32 v74, 0xffff0000, v75
	v_lshlrev_b32_e32 v73, 16, v75
	v_mul_f32_e32 v74, v74, v74
	v_fmac_f32_e32 v74, v73, v73
	v_add_f32_e32 v82, v72, v74
	v_lshlrev_b32_e32 v72, 16, v96
	v_and_b32_e32 v73, 0xffff0000, v96
	v_lshlrev_b32_e32 v78, 16, v98
	v_lshlrev_b32_e32 v74, 16, v97
	v_and_b32_e32 v75, 0xffff0000, v97
	v_lshlrev_b32_e32 v80, 16, v99
	v_and_b32_e32 v81, 0xffff0000, v99
	v_pk_add_f32 v[68:69], v[68:69], v[72:73]
	v_pk_add_f32 v[64:65], v[64:65], v[78:79]
	v_pk_add_f32 v[70:71], v[70:71], v[74:75]
	v_pk_add_f32 v[72:73], v[66:67], v[80:81]
	v_cvt_pk_bf16_f32 v66, v68, v69
	v_cvt_pk_bf16_f32 v67, v70, v71
	v_cvt_pk_bf16_f32 v68, v64, v65
	s_nop 0
	v_and_b32_e32 v65, 0xffff0000, v66
	v_lshlrev_b32_e32 v64, 16, v66
	v_mul_f32_e32 v65, v65, v65
	v_fmac_f32_e32 v65, v64, v64
	v_and_b32_e32 v70, 0xffff0000, v67
	v_add_f32_e32 v64, v82, v65
	v_lshlrev_b32_e32 v65, 16, v67
	v_mul_f32_e32 v70, v70, v70
	v_fmac_f32_e32 v70, v65, v65
	v_add_f32_e32 v64, v64, v70
	v_and_b32_e32 v70, 0xffff0000, v68
	v_lshlrev_b32_e32 v65, 16, v68
	v_mul_f32_e32 v70, v70, v70
	v_fmac_f32_e32 v70, v65, v65
	v_cvt_pk_bf16_f32 v69, v72, v73
	v_add_f32_e32 v64, v64, v70
	v_and_b32_e32 v70, 0xffff0000, v69
	v_lshlrev_b32_e32 v65, 16, v69
	v_mul_f32_e32 v70, v70, v70
	v_fmac_f32_e32 v70, v65, v65
	v_add_f32_e32 v64, v64, v70
	ds_bpermute_b32 v65, v176, v64
	global_store_dwordx4 v[76:77], v[66:69], off offset:256 sc0 nt
	s_waitcnt lgkmcnt(0)
	v_add_f32_e32 v64, v64, v65
	ds_bpermute_b32 v65, v177, v64
	s_and_saveexec_b64 s[6:7], vcc
	s_cbranch_execz .LBB0_427
	s_waitcnt lgkmcnt(0)
	v_add_f32_e32 v66, v64, v65
	v_lshlrev_b64 v[64:65], 6, v[108:109]
	v_lshl_add_u64 v[64:65], s[46:47], 0, v[64:65]
	v_lshl_add_u64 v[64:65], s[58:59], 2, v[64:65]
	s_lshl_b32 s38, s8, 2
	v_lshl_add_u64 v[64:65], v[64:65], 0, s[38:39]
	flat_store_dword v[64:65], v66
.LBB0_427:
	s_or_b64 exec, exec, s[6:7]
	v_add_u32_e32 v80, 0x80, v166
	v_ashrrev_i32_e32 v81, 31, v80
	v_lshlrev_b64 v[86:87], 11, v[80:81]
	s_waitcnt lgkmcnt(0)
	v_lshl_add_u64 v[64:65], v[168:169], 0, v[86:87]
	global_load_dwordx4 v[82:85], v[64:65], off
	global_load_dwordx4 v[72:75], v[64:65], off offset:256
	v_add_u32_e32 v76, 0x90, v166
	v_ashrrev_i32_e32 v77, 31, v76
	v_lshlrev_b64 v[78:79], 11, v[76:77]
	v_lshl_add_u64 v[64:65], v[168:169], 0, v[78:79]
	global_load_dwordx4 v[68:71], v[64:65], off
	s_nop 0
	global_load_dwordx4 v[64:67], v[64:65], off offset:256
	s_waitcnt vmcnt(0)
	v_lshlrev_b32_e32 v88, 16, v82
	v_and_b32_e32 v89, 0xffff0000, v82
	v_lshlrev_b32_e32 v82, 16, v83
	v_and_b32_e32 v83, 0xffff0000, v83
	v_lshlrev_b32_e32 v90, 16, v84
	v_and_b32_e32 v91, 0xffff0000, v84
	v_pk_add_f32 v[58:59], v[58:59], v[82:83]
	v_pk_add_f32 v[56:57], v[56:57], v[88:89]
	v_pk_add_f32 v[60:61], v[60:61], v[90:91]
	v_lshlrev_b32_e32 v84, 16, v85
	v_and_b32_e32 v85, 0xffff0000, v85
	v_cvt_pk_bf16_f32 v56, v56, v57
	v_cvt_pk_bf16_f32 v57, v58, v59
	v_cvt_pk_bf16_f32 v58, v60, v61
	v_lshl_add_u64 v[60:61], s[68:69], 0, v[86:87]
	v_pk_add_f32 v[62:63], v[62:63], v[84:85]
	v_lshl_add_u64 v[60:61], v[164:165], 1, v[60:61]
	v_cvt_pk_bf16_f32 v59, v62, v63
	global_store_dwordx4 v[60:61], v[56:59], off sc0 nt
	v_lshlrev_b32_e32 v62, 16, v56
	v_and_b32_e32 v63, 0xffff0000, v74
	v_and_b32_e32 v56, 0xffff0000, v56
	v_mul_f32_e32 v56, v56, v56
	v_fmac_f32_e32 v56, v62, v62
	v_lshlrev_b32_e32 v62, 16, v57
	v_and_b32_e32 v57, 0xffff0000, v57
	v_mul_f32_e32 v57, v57, v57
	v_fmac_f32_e32 v57, v62, v62
	v_add_f32_e32 v56, v56, v57
	v_lshlrev_b32_e32 v57, 16, v58
	v_and_b32_e32 v58, 0xffff0000, v58
	v_mul_f32_e32 v58, v58, v58
	v_fmac_f32_e32 v58, v57, v57
	v_add_f32_e32 v56, v56, v58
	v_and_b32_e32 v58, 0xffff0000, v59
	v_lshlrev_b32_e32 v57, 16, v59
	v_mul_f32_e32 v58, v58, v58
	v_fmac_f32_e32 v58, v57, v57
	v_add_f32_e32 v82, v56, v58
	v_lshlrev_b32_e32 v56, 16, v72
	v_and_b32_e32 v57, 0xffff0000, v72
	v_lshlrev_b32_e32 v58, 16, v73
	v_and_b32_e32 v59, 0xffff0000, v73
	v_lshlrev_b32_e32 v62, 16, v74
	v_lshlrev_b32_e32 v72, 16, v75
	v_and_b32_e32 v73, 0xffff0000, v75
	v_pk_add_f32 v[52:53], v[52:53], v[56:57]
	v_pk_add_f32 v[56:57], v[50:51], v[72:73]
	v_pk_add_f32 v[50:51], v[48:49], v[62:63]
	v_cvt_pk_bf16_f32 v48, v52, v53
	v_pk_add_f32 v[54:55], v[54:55], v[58:59]
	v_lshlrev_b32_e32 v52, 16, v48
	v_cvt_pk_bf16_f32 v49, v54, v55
	v_cvt_pk_bf16_f32 v50, v50, v51
	v_cvt_pk_bf16_f32 v51, v56, v57
	global_store_dwordx4 v[60:61], v[48:51], off offset:256 sc0 nt
	s_nop 1
	v_and_b32_e32 v48, 0xffff0000, v48
	v_mul_f32_e32 v48, v48, v48
	v_fmac_f32_e32 v48, v52, v52
	v_lshlrev_b32_e32 v52, 16, v49
	v_and_b32_e32 v49, 0xffff0000, v49
	v_mul_f32_e32 v49, v49, v49
	v_add_f32_e32 v48, v82, v48
	v_fmac_f32_e32 v49, v52, v52
	v_add_f32_e32 v48, v48, v49
	v_lshlrev_b32_e32 v49, 16, v50
	v_and_b32_e32 v50, 0xffff0000, v50
	v_mul_f32_e32 v50, v50, v50
	v_fmac_f32_e32 v50, v49, v49
	v_add_f32_e32 v48, v48, v50
	v_and_b32_e32 v50, 0xffff0000, v51
	v_lshlrev_b32_e32 v49, 16, v51
	v_mul_f32_e32 v50, v50, v50
	v_fmac_f32_e32 v50, v49, v49
	v_add_f32_e32 v48, v48, v50
	ds_bpermute_b32 v49, v176, v48
	s_waitcnt lgkmcnt(0)
	v_add_f32_e32 v48, v48, v49
	ds_bpermute_b32 v49, v177, v48
	s_and_saveexec_b64 s[6:7], vcc
	s_cbranch_execz .LBB0_429
	s_waitcnt lgkmcnt(0)
	v_add_f32_e32 v50, v48, v49
	v_lshlrev_b64 v[48:49], 6, v[80:81]
	v_lshl_add_u64 v[48:49], s[46:47], 0, v[48:49]
	v_lshl_add_u64 v[48:49], s[58:59], 2, v[48:49]
	s_lshl_b32 s38, s8, 2
	v_lshl_add_u64 v[48:49], v[48:49], 0, s[38:39]
	flat_store_dword v[48:49], v50
.LBB0_429:
	s_or_b64 exec, exec, s[6:7]
	v_lshlrev_b32_e32 v48, 16, v68
	s_waitcnt lgkmcnt(0)
	v_and_b32_e32 v49, 0xffff0000, v68
	v_lshlrev_b32_e32 v52, 16, v70
	v_and_b32_e32 v53, 0xffff0000, v70
	v_lshlrev_b32_e32 v54, 16, v71
	v_and_b32_e32 v55, 0xffff0000, v71
	v_pk_add_f32 v[44:45], v[44:45], v[48:49]
	v_lshlrev_b32_e32 v50, 16, v69
	v_and_b32_e32 v51, 0xffff0000, v69
	v_pk_add_f32 v[48:49], v[42:43], v[54:55]
	v_pk_add_f32 v[42:43], v[40:41], v[52:53]
	v_cvt_pk_bf16_f32 v40, v44, v45
	v_lshl_add_u64 v[44:45], s[68:69], 0, v[78:79]
	v_pk_add_f32 v[46:47], v[46:47], v[50:51]
	v_lshl_add_u64 v[44:45], v[164:165], 1, v[44:45]
	v_cvt_pk_bf16_f32 v41, v46, v47
	v_cvt_pk_bf16_f32 v42, v42, v43
	v_cvt_pk_bf16_f32 v43, v48, v49
	global_store_dwordx4 v[44:45], v[40:43], off sc0 nt
	v_lshlrev_b32_e32 v46, 16, v40
	v_and_b32_e32 v47, 0xffff0000, v66
	v_and_b32_e32 v40, 0xffff0000, v40
	v_mul_f32_e32 v40, v40, v40
	v_fmac_f32_e32 v40, v46, v46
	v_lshlrev_b32_e32 v46, 16, v41
	v_and_b32_e32 v41, 0xffff0000, v41
	v_mul_f32_e32 v41, v41, v41
	v_fmac_f32_e32 v41, v46, v46
	v_add_f32_e32 v40, v40, v41
	v_lshlrev_b32_e32 v41, 16, v42
	v_and_b32_e32 v42, 0xffff0000, v42
	v_mul_f32_e32 v42, v42, v42
	v_fmac_f32_e32 v42, v41, v41
	v_add_f32_e32 v40, v40, v42
	v_and_b32_e32 v42, 0xffff0000, v43
	v_lshlrev_b32_e32 v41, 16, v43
	v_mul_f32_e32 v42, v42, v42
	v_fmac_f32_e32 v42, v41, v41
	v_add_f32_e32 v50, v40, v42
	v_lshlrev_b32_e32 v40, 16, v64
	v_and_b32_e32 v41, 0xffff0000, v64
	v_lshlrev_b32_e32 v46, 16, v66
	v_lshlrev_b32_e32 v42, 16, v65
	v_and_b32_e32 v43, 0xffff0000, v65
	v_lshlrev_b32_e32 v48, 16, v67
	v_and_b32_e32 v49, 0xffff0000, v67
	v_pk_add_f32 v[36:37], v[36:37], v[40:41]
	v_pk_add_f32 v[32:33], v[32:33], v[46:47]
	v_pk_add_f32 v[38:39], v[38:39], v[42:43]
	v_pk_add_f32 v[40:41], v[34:35], v[48:49]
	v_cvt_pk_bf16_f32 v34, v36, v37
	v_cvt_pk_bf16_f32 v35, v38, v39
	v_cvt_pk_bf16_f32 v36, v32, v33
	s_nop 0
	v_and_b32_e32 v33, 0xffff0000, v34
	v_lshlrev_b32_e32 v32, 16, v34
	v_mul_f32_e32 v33, v33, v33
	v_fmac_f32_e32 v33, v32, v32
	v_and_b32_e32 v38, 0xffff0000, v35
	v_add_f32_e32 v32, v50, v33
	v_lshlrev_b32_e32 v33, 16, v35
	v_mul_f32_e32 v38, v38, v38
	v_fmac_f32_e32 v38, v33, v33
	v_add_f32_e32 v32, v32, v38
	v_and_b32_e32 v38, 0xffff0000, v36
	v_lshlrev_b32_e32 v33, 16, v36
	v_mul_f32_e32 v38, v38, v38
	v_fmac_f32_e32 v38, v33, v33
	v_cvt_pk_bf16_f32 v37, v40, v41
	v_add_f32_e32 v32, v32, v38
	v_and_b32_e32 v38, 0xffff0000, v37
	v_lshlrev_b32_e32 v33, 16, v37
	v_mul_f32_e32 v38, v38, v38
	v_fmac_f32_e32 v38, v33, v33
	v_add_f32_e32 v32, v32, v38
	ds_bpermute_b32 v33, v176, v32
	global_store_dwordx4 v[44:45], v[34:37], off offset:256 sc0 nt
	s_waitcnt lgkmcnt(0)
	v_add_f32_e32 v32, v32, v33
	ds_bpermute_b32 v33, v177, v32
	s_and_saveexec_b64 s[6:7], vcc
	s_cbranch_execz .LBB0_431
	s_waitcnt lgkmcnt(0)
	v_add_f32_e32 v34, v32, v33
	v_lshlrev_b64 v[32:33], 6, v[76:77]
	v_lshl_add_u64 v[32:33], s[46:47], 0, v[32:33]
	v_lshl_add_u64 v[32:33], s[58:59], 2, v[32:33]
	s_lshl_b32 s38, s8, 2
	v_lshl_add_u64 v[32:33], v[32:33], 0, s[38:39]
	flat_store_dword v[32:33], v34
.LBB0_431:
	s_or_b64 exec, exec, s[6:7]
	v_add_u32_e32 v48, 0xa0, v166
	v_ashrrev_i32_e32 v49, 31, v48
	v_lshlrev_b64 v[54:55], 11, v[48:49]
	s_waitcnt lgkmcnt(0)
	v_lshl_add_u64 v[32:33], v[168:169], 0, v[54:55]
	global_load_dwordx4 v[50:53], v[32:33], off
	global_load_dwordx4 v[40:43], v[32:33], off offset:256
	v_add_u32_e32 v44, 0xb0, v166
	v_ashrrev_i32_e32 v45, 31, v44
	v_lshlrev_b64 v[46:47], 11, v[44:45]
	v_lshl_add_u64 v[32:33], v[168:169], 0, v[46:47]
	global_load_dwordx4 v[36:39], v[32:33], off
	s_nop 0
	global_load_dwordx4 v[32:35], v[32:33], off offset:256
	s_waitcnt vmcnt(0)
	v_lshlrev_b32_e32 v56, 16, v50
	v_and_b32_e32 v57, 0xffff0000, v50
	v_lshlrev_b32_e32 v50, 16, v51
	v_and_b32_e32 v51, 0xffff0000, v51
	v_lshlrev_b32_e32 v58, 16, v52
	v_and_b32_e32 v59, 0xffff0000, v52
	v_pk_add_f32 v[26:27], v[26:27], v[50:51]
	v_pk_add_f32 v[24:25], v[24:25], v[56:57]
	v_pk_add_f32 v[28:29], v[28:29], v[58:59]
	v_lshlrev_b32_e32 v52, 16, v53
	v_and_b32_e32 v53, 0xffff0000, v53
	v_cvt_pk_bf16_f32 v24, v24, v25
	v_cvt_pk_bf16_f32 v25, v26, v27
	v_cvt_pk_bf16_f32 v26, v28, v29
	v_lshl_add_u64 v[28:29], s[68:69], 0, v[54:55]
	v_pk_add_f32 v[30:31], v[30:31], v[52:53]
	v_lshl_add_u64 v[28:29], v[164:165], 1, v[28:29]
	v_cvt_pk_bf16_f32 v27, v30, v31
	global_store_dwordx4 v[28:29], v[24:27], off sc0 nt
	v_lshlrev_b32_e32 v30, 16, v24
	v_and_b32_e32 v31, 0xffff0000, v42
	v_and_b32_e32 v24, 0xffff0000, v24
	v_mul_f32_e32 v24, v24, v24
	v_fmac_f32_e32 v24, v30, v30
	v_lshlrev_b32_e32 v30, 16, v25
	v_and_b32_e32 v25, 0xffff0000, v25
	v_mul_f32_e32 v25, v25, v25
	v_fmac_f32_e32 v25, v30, v30
	v_add_f32_e32 v24, v24, v25
	v_lshlrev_b32_e32 v25, 16, v26
	v_and_b32_e32 v26, 0xffff0000, v26
	v_mul_f32_e32 v26, v26, v26
	v_fmac_f32_e32 v26, v25, v25
	v_add_f32_e32 v24, v24, v26
	v_and_b32_e32 v26, 0xffff0000, v27
	v_lshlrev_b32_e32 v25, 16, v27
	v_mul_f32_e32 v26, v26, v26
	v_fmac_f32_e32 v26, v25, v25
	v_add_f32_e32 v50, v24, v26
	v_lshlrev_b32_e32 v24, 16, v40
	v_and_b32_e32 v25, 0xffff0000, v40
	v_lshlrev_b32_e32 v26, 16, v41
	v_and_b32_e32 v27, 0xffff0000, v41
	v_lshlrev_b32_e32 v30, 16, v42
	v_lshlrev_b32_e32 v40, 16, v43
	v_and_b32_e32 v41, 0xffff0000, v43
	v_pk_add_f32 v[20:21], v[20:21], v[24:25]
	v_pk_add_f32 v[24:25], v[18:19], v[40:41]
	v_pk_add_f32 v[18:19], v[16:17], v[30:31]
	v_cvt_pk_bf16_f32 v16, v20, v21
	v_pk_add_f32 v[22:23], v[22:23], v[26:27]
	v_lshlrev_b32_e32 v20, 16, v16
	v_cvt_pk_bf16_f32 v17, v22, v23
	v_cvt_pk_bf16_f32 v18, v18, v19
	v_cvt_pk_bf16_f32 v19, v24, v25
	global_store_dwordx4 v[28:29], v[16:19], off offset:256 sc0 nt
	s_nop 1
	v_and_b32_e32 v16, 0xffff0000, v16
	v_mul_f32_e32 v16, v16, v16
	v_fmac_f32_e32 v16, v20, v20
	v_lshlrev_b32_e32 v20, 16, v17
	v_and_b32_e32 v17, 0xffff0000, v17
	v_mul_f32_e32 v17, v17, v17
	v_add_f32_e32 v16, v50, v16
	v_fmac_f32_e32 v17, v20, v20
	v_add_f32_e32 v16, v16, v17
	v_lshlrev_b32_e32 v17, 16, v18
	v_and_b32_e32 v18, 0xffff0000, v18
	v_mul_f32_e32 v18, v18, v18
	v_fmac_f32_e32 v18, v17, v17
	v_add_f32_e32 v16, v16, v18
	v_and_b32_e32 v18, 0xffff0000, v19
	v_lshlrev_b32_e32 v17, 16, v19
	v_mul_f32_e32 v18, v18, v18
	v_fmac_f32_e32 v18, v17, v17
	v_add_f32_e32 v16, v16, v18
	ds_bpermute_b32 v17, v176, v16
	s_waitcnt lgkmcnt(0)
	v_add_f32_e32 v16, v16, v17
	ds_bpermute_b32 v17, v177, v16
	s_and_saveexec_b64 s[6:7], vcc
	s_cbranch_execz .LBB0_433
	s_waitcnt lgkmcnt(0)
	v_add_f32_e32 v18, v16, v17
	v_lshlrev_b64 v[16:17], 6, v[48:49]
	v_lshl_add_u64 v[16:17], s[46:47], 0, v[16:17]
	v_lshl_add_u64 v[16:17], s[58:59], 2, v[16:17]
	s_lshl_b32 s38, s8, 2
	v_lshl_add_u64 v[16:17], v[16:17], 0, s[38:39]
	flat_store_dword v[16:17], v18
.LBB0_433:
	s_or_b64 exec, exec, s[6:7]
	v_lshlrev_b32_e32 v16, 16, v36
	s_waitcnt lgkmcnt(0)
	v_and_b32_e32 v17, 0xffff0000, v36
	v_lshlrev_b32_e32 v20, 16, v38
	v_and_b32_e32 v21, 0xffff0000, v38
	v_lshlrev_b32_e32 v22, 16, v39
	v_and_b32_e32 v23, 0xffff0000, v39
	v_pk_add_f32 v[12:13], v[12:13], v[16:17]
	v_lshlrev_b32_e32 v18, 16, v37
	v_and_b32_e32 v19, 0xffff0000, v37
	v_pk_add_f32 v[16:17], v[10:11], v[22:23]
	v_pk_add_f32 v[10:11], v[8:9], v[20:21]
	v_cvt_pk_bf16_f32 v8, v12, v13
	v_lshl_add_u64 v[12:13], s[68:69], 0, v[46:47]
	v_pk_add_f32 v[14:15], v[14:15], v[18:19]
	v_lshl_add_u64 v[12:13], v[164:165], 1, v[12:13]
	v_cvt_pk_bf16_f32 v9, v14, v15
	v_cvt_pk_bf16_f32 v10, v10, v11
	v_cvt_pk_bf16_f32 v11, v16, v17
	global_store_dwordx4 v[12:13], v[8:11], off sc0 nt
	v_lshlrev_b32_e32 v14, 16, v8
	v_and_b32_e32 v15, 0xffff0000, v34
	v_and_b32_e32 v8, 0xffff0000, v8
	v_mul_f32_e32 v8, v8, v8
	v_fmac_f32_e32 v8, v14, v14
	v_lshlrev_b32_e32 v14, 16, v9
	v_and_b32_e32 v9, 0xffff0000, v9
	v_mul_f32_e32 v9, v9, v9
	v_fmac_f32_e32 v9, v14, v14
	v_add_f32_e32 v8, v8, v9
	v_lshlrev_b32_e32 v9, 16, v10
	v_and_b32_e32 v10, 0xffff0000, v10
	v_mul_f32_e32 v10, v10, v10
	v_fmac_f32_e32 v10, v9, v9
	v_add_f32_e32 v8, v8, v10
	v_and_b32_e32 v10, 0xffff0000, v11
	v_lshlrev_b32_e32 v9, 16, v11
	v_mul_f32_e32 v10, v10, v10
	v_fmac_f32_e32 v10, v9, v9
	v_add_f32_e32 v18, v8, v10
	v_lshlrev_b32_e32 v8, 16, v32
	v_and_b32_e32 v9, 0xffff0000, v32
	v_lshlrev_b32_e32 v14, 16, v34
	v_lshlrev_b32_e32 v10, 16, v33
	v_and_b32_e32 v11, 0xffff0000, v33
	v_lshlrev_b32_e32 v16, 16, v35
	v_and_b32_e32 v17, 0xffff0000, v35
	v_pk_add_f32 v[4:5], v[4:5], v[8:9]
	v_pk_add_f32 v[0:1], v[0:1], v[14:15]
	v_pk_add_f32 v[6:7], v[6:7], v[10:11]
	v_pk_add_f32 v[8:9], v[2:3], v[16:17]
	v_cvt_pk_bf16_f32 v2, v4, v5
	v_cvt_pk_bf16_f32 v3, v6, v7
	v_cvt_pk_bf16_f32 v4, v0, v1
	s_nop 0
	v_and_b32_e32 v1, 0xffff0000, v2
	v_lshlrev_b32_e32 v0, 16, v2
	v_mul_f32_e32 v1, v1, v1
	v_fmac_f32_e32 v1, v0, v0
	v_and_b32_e32 v6, 0xffff0000, v3
	v_add_f32_e32 v0, v18, v1
	v_lshlrev_b32_e32 v1, 16, v3
	v_mul_f32_e32 v6, v6, v6
	v_fmac_f32_e32 v6, v1, v1
	v_add_f32_e32 v0, v0, v6
	v_and_b32_e32 v6, 0xffff0000, v4
	v_lshlrev_b32_e32 v1, 16, v4
	v_mul_f32_e32 v6, v6, v6
	v_fmac_f32_e32 v6, v1, v1
	v_cvt_pk_bf16_f32 v5, v8, v9
	v_add_f32_e32 v0, v0, v6
	v_and_b32_e32 v6, 0xffff0000, v5
	v_lshlrev_b32_e32 v1, 16, v5
	v_mul_f32_e32 v6, v6, v6
	v_fmac_f32_e32 v6, v1, v1
	v_add_f32_e32 v0, v0, v6
	ds_bpermute_b32 v1, v176, v0
	global_store_dwordx4 v[12:13], v[2:5], off offset:256 sc0 nt
	s_waitcnt lgkmcnt(0)
	v_add_f32_e32 v0, v0, v1
	ds_bpermute_b32 v1, v177, v0
	s_and_saveexec_b64 s[6:7], vcc
	s_cbranch_execz .LBB0_435
	s_waitcnt lgkmcnt(0)
	v_add_f32_e32 v2, v0, v1
	v_lshlrev_b64 v[0:1], 6, v[44:45]
	v_lshl_add_u64 v[0:1], s[46:47], 0, v[0:1]
	v_lshl_add_u64 v[0:1], s[58:59], 2, v[0:1]
	s_lshl_b32 s38, s8, 2
	v_lshl_add_u64 v[0:1], v[0:1], 0, s[38:39]
	flat_store_dword v[0:1], v2

.LBB0_459:
	s_mov_b32 s6, -1
	s_lshl_b32 s5, s5, 8
	v_mbcnt_lo_u32_b32 v134, s6, 0
	v_mbcnt_hi_u32_b32 v134, s6, v134
	s_getreg_b32 s6, hwreg(HW_REG_HW_ID, 0, 6)
	s_and_b32 s6, s6, 63
	s_lshl_b32 s6, s6, 2
	s_add_i32 s6, s6, 0
	s_add_i32 s6, s6, 0x20200
	v_mov_b32_e32 v135, s6
	ds_read_b32 v135, v135
	v_bfrev_b32_e32 v143, 0.5
	s_movk_i32 s84, 0x80
	s_waitcnt lgkmcnt(0)
	v_readfirstlane_b32 s6, v135
	s_nop 1
	v_lshl_add_u32 v137, s6, 6, v134
	s_nop 0
	v_readfirstlane_b32 s6, v137
	s_bfe_u32 s10, s6, 0x20006
	s_ashr_i32 s6, s6, 2
	s_andn2_b32 s6, s6, 63
	s_add_i32 s6, s6, s5
	v_bfe_u32 v142, v137, 4, 2
	v_and_or_b32 v136, v137, 15, s6
	s_lshl_b32 s5, s4, 8
	s_lshl_b32 s6, s10, 5
	v_lshlrev_b32_e32 v137, 2, v137
	s_or_b32 s5, s6, s5
	v_bitop3_b32 v158, v137, 64, v143 bitop3:0x6c
	v_bitop3_b32 v159, v137, s84, v143 bitop3:0x6c
	v_ashrrev_i32_e32 v137, 31, v136
	v_lshl_or_b32 v134, v142, 3, s5
	v_cmp_eq_u32_e32 vcc, 0, v142
	v_lshlrev_b64 v[142:143], 12, v[136:137]
	v_ashrrev_i32_e32 v135, 31, v134
	v_lshl_add_u64 v[142:143], s[44:45], 0, v[142:143]
	v_lshl_add_u64 v[154:155], v[134:135], 2, v[142:143]
	v_mov_b32_e32 v162, v154
	v_mov_b32_e32 v163, v155
	global_load_dwordx4 v[142:145], v[154:155], off offset:16
	global_load_dwordx4 v[146:149], v[154:155], off
	global_load_dwordx4 v[150:153], v[154:155], off offset:528
	s_nop 0
	global_load_dwordx4 v[154:157], v[154:155], off offset:512
	s_mov_b64 s[100:101], 0x10000
	v_lshl_add_u64 v[164:165], v[162:163], 0, s[100:101]
	global_load_dwordx4 v[168:171], v[164:165], off
	global_load_dwordx4 v[172:175], v[164:165], off offset:16
	global_load_dwordx4 v[176:179], v[164:165], off offset:512
	global_load_dwordx4 v[180:183], v[164:165], off offset:528
	s_mov_b64 s[100:101], 0x20000
	v_lshl_add_u64 v[164:165], v[162:163], 0, s[100:101]
	global_load_dwordx4 v[184:187], v[164:165], off
	global_load_dwordx4 v[188:191], v[164:165], off offset:16
	global_load_dwordx4 v[192:195], v[164:165], off offset:512
	global_load_dwordx4 v[208:211], v[164:165], off offset:528
	s_mov_b64 s[100:101], 0x30000
	v_lshl_add_u64 v[164:165], v[162:163], 0, s[100:101]
	global_load_dwordx4 v[212:215], v[164:165], off
	global_load_dwordx4 v[216:219], v[164:165], off offset:16
	global_load_dwordx4 v[220:223], v[164:165], off offset:512
	global_load_dwordx4 v[224:227], v[164:165], off offset:528
	s_mov_b64 s[100:101], 0x80000
	v_lshl_add_u64 v[164:165], v[162:163], 0, s[100:101]
	global_load_dwordx4 v[228:231], v[164:165], off
	global_load_dwordx4 v[232:235], v[164:165], off offset:16
	global_load_dwordx4 v[236:239], v[164:165], off offset:512
	global_load_dwordx4 v[240:243], v[164:165], off offset:528
	v_lshlrev_b64 v[160:161], 11, v[136:137]
	s_lshl_b32 s6, s4, 2
	s_ashr_i32 s7, s6, 31
	s_waitcnt vmcnt(16)
	v_pk_add_f32 v[124:125], v[124:125], v[142:143]
	v_pk_add_f32 v[122:123], v[122:123], v[148:149]
	v_pk_add_f32 v[120:121], v[120:121], v[146:147]
	v_pk_add_f32 v[126:127], v[126:127], v[144:145]
	v_cvt_pk_bf16_f32 v120, v120, v121
	v_cvt_pk_bf16_f32 v121, v122, v123
	v_cvt_pk_bf16_f32 v122, v124, v125
	v_lshl_add_u64 v[124:125], s[68:69], 0, v[160:161]
	v_lshl_add_u64 v[124:125], v[134:135], 1, v[124:125]
	v_cvt_pk_bf16_f32 v123, v126, v127
	global_store_dwordx4 v[124:125], v[120:123], off sc0 nt
	v_lshlrev_b32_e32 v126, 16, v120
	v_pk_add_f32 v[116:117], v[116:117], v[154:155]
	v_and_b32_e32 v120, 0xffff0000, v120
	v_mul_f32_e32 v120, v120, v120
	v_fmac_f32_e32 v120, v126, v126
	v_lshlrev_b32_e32 v126, 16, v121
	v_and_b32_e32 v121, 0xffff0000, v121
	v_mul_f32_e32 v121, v121, v121
	v_fmac_f32_e32 v121, v126, v126
	v_add_f32_e32 v120, v120, v121
	v_lshlrev_b32_e32 v121, 16, v122
	v_and_b32_e32 v122, 0xffff0000, v122
	v_mul_f32_e32 v122, v122, v122
	v_fmac_f32_e32 v122, v121, v121
	v_add_f32_e32 v120, v120, v122
	v_and_b32_e32 v122, 0xffff0000, v123
	v_lshlrev_b32_e32 v121, 16, v123
	v_mul_f32_e32 v122, v122, v122
	v_fmac_f32_e32 v122, v121, v121
	v_add_f32_e32 v122, v120, v122
	v_pk_add_f32 v[120:121], v[114:115], v[152:153]
	v_pk_add_f32 v[114:115], v[112:113], v[150:151]
	v_cvt_pk_bf16_f32 v112, v116, v117
	v_pk_add_f32 v[118:119], v[118:119], v[156:157]
	v_lshlrev_b32_e32 v116, 16, v112
	v_cvt_pk_bf16_f32 v113, v118, v119
	v_cvt_pk_bf16_f32 v114, v114, v115
	v_cvt_pk_bf16_f32 v115, v120, v121
	global_store_dwordx4 v[124:125], v[112:115], off offset:256 sc0 nt
	s_nop 1
	v_and_b32_e32 v112, 0xffff0000, v112
	v_mul_f32_e32 v112, v112, v112
	v_fmac_f32_e32 v112, v116, v116
	v_lshlrev_b32_e32 v116, 16, v113
	v_and_b32_e32 v113, 0xffff0000, v113
	v_mul_f32_e32 v113, v113, v113
	v_add_f32_e32 v112, v122, v112
	v_fmac_f32_e32 v113, v116, v116
	v_add_f32_e32 v112, v112, v113
	v_lshlrev_b32_e32 v113, 16, v114
	v_and_b32_e32 v114, 0xffff0000, v114
	v_mul_f32_e32 v114, v114, v114
	v_fmac_f32_e32 v114, v113, v113
	v_add_f32_e32 v112, v112, v114
	v_and_b32_e32 v114, 0xffff0000, v115
	v_lshlrev_b32_e32 v113, 16, v115
	v_mul_f32_e32 v114, v114, v114
	v_fmac_f32_e32 v114, v113, v113
	v_add_f32_e32 v112, v112, v114
	ds_bpermute_b32 v113, v158, v112
	s_waitcnt lgkmcnt(0)
	v_add_f32_e32 v112, v112, v113
	ds_bpermute_b32 v113, v159, v112
	s_and_saveexec_b64 s[8:9], vcc
	s_cbranch_execz .LBB0_461
	v_lshlrev_b64 v[114:115], 6, v[136:137]
	v_lshl_add_u64 v[114:115], s[66:67], 0, v[114:115]
	v_lshl_add_u64 v[114:115], s[6:7], 2, v[114:115]
	s_lshl_b32 s38, s10, 2
	v_lshl_add_u64 v[114:115], v[114:115], 0, s[38:39]
	s_waitcnt lgkmcnt(0)
	v_add_f32_e32 v112, v112, v113
	global_store_dword v[114:115], v112, off
.LBB0_461:
	s_or_b64 exec, exec, s[8:9]
	v_or_b32_e32 v112, 16, v136
	s_waitcnt lgkmcnt(0)
	v_ashrrev_i32_e32 v113, 31, v112
	v_lshlrev_b64 v[114:115], 12, v[112:113]
	v_lshl_add_u64 v[114:115], s[44:45], 0, v[114:115]
	v_lshl_add_u64 v[126:127], v[134:135], 2, v[114:115]
	v_lshlrev_b64 v[126:127], 11, v[112:113]
	v_lshl_add_u64 v[126:127], s[68:69], 0, v[126:127]
	v_lshl_add_u64 v[126:127], v[134:135], 1, v[126:127]
	s_waitcnt vmcnt(15)
	v_mov_b32_e32 v114, v168
	v_mov_b32_e32 v115, v169
	v_mov_b32_e32 v116, v170
	v_mov_b32_e32 v117, v171
	v_mov_b32_e32 v118, v172
	v_mov_b32_e32 v119, v173
	v_mov_b32_e32 v120, v174
	v_mov_b32_e32 v121, v175
	v_mov_b32_e32 v122, v176
	v_mov_b32_e32 v123, v177
	v_mov_b32_e32 v124, v178
	v_mov_b32_e32 v125, v179
	v_mov_b32_e32 v142, v180
	v_mov_b32_e32 v143, v181
	v_mov_b32_e32 v144, v182
	v_mov_b32_e32 v145, v183
	s_mov_b64 s[100:101], 0x90000
	v_lshl_add_u64 v[164:165], v[162:163], 0, s[100:101]
	global_load_dwordx4 v[168:171], v[164:165], off
	global_load_dwordx4 v[172:175], v[164:165], off offset:16
	global_load_dwordx4 v[176:179], v[164:165], off offset:512
	global_load_dwordx4 v[180:183], v[164:165], off offset:528
	v_pk_add_f32 v[106:107], v[106:107], v[116:117]
	v_pk_add_f32 v[104:105], v[104:105], v[114:115]
	s_nop 0
	v_pk_add_f32 v[110:111], v[110:111], v[120:121]
	s_nop 0
	v_pk_add_f32 v[116:117], v[96:97], v[142:143]
	v_cvt_pk_bf16_f32 v96, v104, v105
	v_cvt_pk_bf16_f32 v97, v106, v107
	v_pk_add_f32 v[108:109], v[108:109], v[118:119]
	v_pk_add_f32 v[114:115], v[98:99], v[144:145]
	v_cvt_pk_bf16_f32 v98, v108, v109
	v_cvt_pk_bf16_f32 v99, v110, v111
	global_store_dwordx4 v[126:127], v[96:99], off sc0 nt
	v_lshlrev_b32_e32 v104, 16, v96
	v_lshlrev_b32_e32 v105, 16, v97
	v_and_b32_e32 v96, 0xffff0000, v96
	v_and_b32_e32 v97, 0xffff0000, v97
	v_pk_add_f32 v[102:103], v[102:103], v[124:125]
	v_and_b32_e32 v107, 0xffff0000, v98
	v_mul_f32_e32 v96, v96, v96
	v_mul_f32_e32 v97, v97, v97
	v_pk_add_f32 v[100:101], v[100:101], v[122:123]
	v_lshlrev_b32_e32 v106, 16, v98
	v_lshlrev_b32_e32 v108, 16, v99
	v_and_b32_e32 v109, 0xffff0000, v99
	v_cvt_pk_bf16_f32 v98, v100, v101
	v_cvt_pk_bf16_f32 v99, v102, v103
	v_mul_f32_e32 v102, v107, v107
	v_fmac_f32_e32 v96, v104, v104
	v_fmac_f32_e32 v97, v105, v105
	v_mul_f32_e32 v103, v109, v109
	v_and_b32_e32 v109, 0xffff0000, v98
	v_fmac_f32_e32 v102, v106, v106
	v_add_f32_e32 v96, v96, v97
	v_lshlrev_b32_e32 v107, 16, v98
	v_and_b32_e32 v111, 0xffff0000, v99
	v_fmac_f32_e32 v103, v108, v108
	v_mul_f32_e32 v104, v109, v109
	v_add_f32_e32 v96, v96, v102
	v_cvt_pk_bf16_f32 v100, v116, v117
	v_cvt_pk_bf16_f32 v101, v114, v115
	v_lshlrev_b32_e32 v110, 16, v99
	v_and_b32_e32 v115, 0xffff0000, v100
	v_mul_f32_e32 v105, v111, v111
	v_fmac_f32_e32 v104, v107, v107
	v_add_f32_e32 v96, v96, v103
	v_lshlrev_b32_e32 v114, 16, v100
	v_and_b32_e32 v117, 0xffff0000, v101
	v_mul_f32_e32 v106, v115, v115
	v_fmac_f32_e32 v105, v110, v110
	v_add_f32_e32 v96, v96, v104
	v_lshlrev_b32_e32 v116, 16, v101
	v_mul_f32_e32 v108, v117, v117
	v_fmac_f32_e32 v106, v114, v114
	v_add_f32_e32 v96, v96, v105
	v_add_f32_e32 v96, v96, v106
	v_fmac_f32_e32 v108, v116, v116
	v_add_f32_e32 v96, v96, v108
	ds_bpermute_b32 v97, v158, v96
	global_store_dwordx4 v[126:127], v[98:101], off offset:256 sc0 nt
	s_waitcnt lgkmcnt(0)
	v_add_f32_e32 v96, v96, v97
	ds_bpermute_b32 v97, v159, v96
	s_mov_b64 s[8:9], exec
	s_and_b64 s[4:5], s[8:9], vcc
	v_mov_b32_e32 v198, v246
	v_mov_b32_e32 v199, v247
	v_mov_b32_e32 v205, v249
	v_mov_b32_e32 v196, v251
	v_mov_b32_e32 v251, 0x260
	s_mov_b64 exec, s[4:5]
	s_cbranch_execz .LBB0_463
	v_lshlrev_b64 v[98:99], 6, v[112:113]
	v_lshl_add_u64 v[98:99], s[66:67], 0, v[98:99]
	v_lshl_add_u64 v[98:99], s[6:7], 2, v[98:99]
	s_lshl_b32 s38, s10, 2
	v_lshl_add_u64 v[98:99], v[98:99], 0, s[38:39]
	s_waitcnt lgkmcnt(0)
	v_add_f32_e32 v96, v96, v97
	global_store_dword v[98:99], v96, off
.LBB0_463:
	s_or_b64 exec, exec, s[8:9]
	v_or_b32_e32 v96, 32, v136
	s_waitcnt lgkmcnt(0)
	v_ashrrev_i32_e32 v97, 31, v96
	v_lshlrev_b64 v[98:99], 12, v[96:97]
	v_lshl_add_u64 v[98:99], s[44:45], 0, v[98:99]
	v_lshl_add_u64 v[110:111], v[134:135], 2, v[98:99]
	s_nop 0
	v_lshlrev_b64 v[114:115], 11, v[96:97]
	v_lshl_add_u64 v[114:115], s[68:69], 0, v[114:115]
	v_lshl_add_u64 v[114:115], v[134:135], 1, v[114:115]
	s_waitcnt vmcnt(18)
	v_mov_b32_e32 v98, v184
	v_mov_b32_e32 v99, v185
	v_mov_b32_e32 v100, v186
	v_mov_b32_e32 v101, v187
	v_mov_b32_e32 v102, v188
	v_mov_b32_e32 v103, v189
	v_mov_b32_e32 v104, v190
	v_mov_b32_e32 v105, v191
	v_mov_b32_e32 v106, v192
	v_mov_b32_e32 v107, v193
	v_mov_b32_e32 v108, v194
	v_mov_b32_e32 v109, v195
	v_mov_b32_e32 v110, v208
	v_mov_b32_e32 v111, v209
	v_mov_b32_e32 v112, v210
	v_mov_b32_e32 v113, v211
	s_mov_b64 s[100:101], 0xa0000
	v_lshl_add_u64 v[164:165], v[162:163], 0, s[100:101]
	global_load_dwordx4 v[184:187], v[164:165], off
	global_load_dwordx4 v[188:191], v[164:165], off offset:16
	global_load_dwordx4 v[192:195], v[164:165], off offset:512
	global_load_dwordx4 v[208:211], v[164:165], off offset:528
	v_pk_add_f32 v[90:91], v[90:91], v[100:101]
	v_pk_add_f32 v[88:89], v[88:89], v[98:99]
	s_nop 0
	v_pk_add_f32 v[94:95], v[94:95], v[104:105]
	s_nop 0
	v_pk_add_f32 v[100:101], v[80:81], v[110:111]
	v_cvt_pk_bf16_f32 v80, v88, v89
	v_cvt_pk_bf16_f32 v81, v90, v91
	v_pk_add_f32 v[92:93], v[92:93], v[102:103]
	v_pk_add_f32 v[98:99], v[82:83], v[112:113]
	v_cvt_pk_bf16_f32 v82, v92, v93
	v_cvt_pk_bf16_f32 v83, v94, v95
	global_store_dwordx4 v[114:115], v[80:83], off sc0 nt
	v_lshlrev_b32_e32 v88, 16, v80
	v_lshlrev_b32_e32 v89, 16, v81
	v_and_b32_e32 v80, 0xffff0000, v80
	v_and_b32_e32 v81, 0xffff0000, v81
	v_pk_add_f32 v[86:87], v[86:87], v[108:109]
	v_and_b32_e32 v91, 0xffff0000, v82
	v_mul_f32_e32 v80, v80, v80
	v_mul_f32_e32 v81, v81, v81
	v_pk_add_f32 v[84:85], v[84:85], v[106:107]
	v_lshlrev_b32_e32 v90, 16, v82
	v_lshlrev_b32_e32 v92, 16, v83
	v_and_b32_e32 v93, 0xffff0000, v83
	v_cvt_pk_bf16_f32 v82, v84, v85
	v_cvt_pk_bf16_f32 v83, v86, v87
	v_mul_f32_e32 v86, v91, v91
	v_fmac_f32_e32 v80, v88, v88
	v_fmac_f32_e32 v81, v89, v89
	v_mul_f32_e32 v87, v93, v93
	v_and_b32_e32 v93, 0xffff0000, v82
	v_fmac_f32_e32 v86, v90, v90
	v_add_f32_e32 v80, v80, v81
	v_lshlrev_b32_e32 v91, 16, v82
	v_and_b32_e32 v95, 0xffff0000, v83
	v_fmac_f32_e32 v87, v92, v92
	v_mul_f32_e32 v88, v93, v93
	v_add_f32_e32 v80, v80, v86
	v_cvt_pk_bf16_f32 v84, v100, v101
	v_cvt_pk_bf16_f32 v85, v98, v99
	v_lshlrev_b32_e32 v94, 16, v83
	v_and_b32_e32 v99, 0xffff0000, v84
	v_mul_f32_e32 v89, v95, v95
	v_fmac_f32_e32 v88, v91, v91
	v_add_f32_e32 v80, v80, v87
	v_lshlrev_b32_e32 v98, 16, v84
	v_and_b32_e32 v101, 0xffff0000, v85
	v_mul_f32_e32 v90, v99, v99
	v_fmac_f32_e32 v89, v94, v94
	v_add_f32_e32 v80, v80, v88
	v_lshlrev_b32_e32 v100, 16, v85
	v_mul_f32_e32 v92, v101, v101
	v_fmac_f32_e32 v90, v98, v98
	v_add_f32_e32 v80, v80, v89
	v_add_f32_e32 v80, v80, v90
	v_fmac_f32_e32 v92, v100, v100
	v_add_f32_e32 v80, v80, v92
	ds_bpermute_b32 v81, v158, v80
	global_store_dwordx4 v[114:115], v[82:85], off offset:256 sc0 nt
	s_waitcnt lgkmcnt(0)
	v_add_f32_e32 v80, v80, v81
	ds_bpermute_b32 v81, v159, v80
	s_and_saveexec_b64 s[8:9], vcc
	s_cbranch_execz .LBB0_465
	v_lshlrev_b64 v[82:83], 6, v[96:97]
	v_lshl_add_u64 v[82:83], s[66:67], 0, v[82:83]
	v_lshl_add_u64 v[82:83], s[6:7], 2, v[82:83]
	s_lshl_b32 s38, s10, 2
	v_lshl_add_u64 v[82:83], v[82:83], 0, s[38:39]
	s_waitcnt lgkmcnt(0)
	v_add_f32_e32 v80, v80, v81
	global_store_dword v[82:83], v80, off
.LBB0_465:
	s_or_b64 exec, exec, s[8:9]
	v_or_b32_e32 v80, 48, v136
	s_waitcnt lgkmcnt(0)
	v_ashrrev_i32_e32 v81, 31, v80
	v_lshlrev_b64 v[82:83], 12, v[80:81]
	v_lshl_add_u64 v[82:83], s[44:45], 0, v[82:83]
	v_lshl_add_u64 v[94:95], v[134:135], 2, v[82:83]
	s_nop 0
	v_lshlrev_b64 v[98:99], 11, v[80:81]
	v_lshl_add_u64 v[98:99], s[68:69], 0, v[98:99]
	v_lshl_add_u64 v[98:99], v[134:135], 1, v[98:99]
	s_waitcnt vmcnt(21)
	v_mov_b32_e32 v82, v212
	v_mov_b32_e32 v83, v213
	v_mov_b32_e32 v84, v214
	v_mov_b32_e32 v85, v215
	v_mov_b32_e32 v86, v216
	v_mov_b32_e32 v87, v217
	v_mov_b32_e32 v88, v218
	v_mov_b32_e32 v89, v219
	v_mov_b32_e32 v90, v220
	v_mov_b32_e32 v91, v221
	v_mov_b32_e32 v92, v222
	v_mov_b32_e32 v93, v223
	v_mov_b32_e32 v94, v224
	v_mov_b32_e32 v95, v225
	v_mov_b32_e32 v96, v226
	v_mov_b32_e32 v97, v227
	s_mov_b64 s[100:101], 0xb0000
	v_lshl_add_u64 v[164:165], v[162:163], 0, s[100:101]
	global_load_dwordx4 v[212:215], v[164:165], off
	global_load_dwordx4 v[216:219], v[164:165], off offset:16
	global_load_dwordx4 v[220:223], v[164:165], off offset:512
	global_load_dwordx4 v[224:227], v[164:165], off offset:528
	v_pk_add_f32 v[74:75], v[74:75], v[84:85]
	v_pk_add_f32 v[72:73], v[72:73], v[82:83]
	s_nop 0
	v_pk_add_f32 v[78:79], v[78:79], v[88:89]
	s_nop 0
	v_pk_add_f32 v[84:85], v[64:65], v[94:95]
	v_cvt_pk_bf16_f32 v64, v72, v73
	v_cvt_pk_bf16_f32 v65, v74, v75
	v_pk_add_f32 v[76:77], v[76:77], v[86:87]
	v_pk_add_f32 v[82:83], v[66:67], v[96:97]
	v_cvt_pk_bf16_f32 v66, v76, v77
	v_cvt_pk_bf16_f32 v67, v78, v79
	global_store_dwordx4 v[98:99], v[64:67], off sc0 nt
	v_lshlrev_b32_e32 v72, 16, v64
	v_lshlrev_b32_e32 v73, 16, v65
	v_and_b32_e32 v64, 0xffff0000, v64
	v_and_b32_e32 v65, 0xffff0000, v65
	v_pk_add_f32 v[70:71], v[70:71], v[92:93]
	v_and_b32_e32 v75, 0xffff0000, v66
	v_mul_f32_e32 v64, v64, v64
	v_mul_f32_e32 v65, v65, v65
	v_pk_add_f32 v[68:69], v[68:69], v[90:91]
	v_lshlrev_b32_e32 v74, 16, v66
	v_lshlrev_b32_e32 v76, 16, v67
	v_and_b32_e32 v77, 0xffff0000, v67
	v_cvt_pk_bf16_f32 v66, v68, v69
	v_cvt_pk_bf16_f32 v67, v70, v71
	v_mul_f32_e32 v70, v75, v75
	v_fmac_f32_e32 v64, v72, v72
	v_fmac_f32_e32 v65, v73, v73
	v_mul_f32_e32 v71, v77, v77
	v_and_b32_e32 v77, 0xffff0000, v66
	v_fmac_f32_e32 v70, v74, v74
	v_add_f32_e32 v64, v64, v65
	v_lshlrev_b32_e32 v75, 16, v66
	v_and_b32_e32 v79, 0xffff0000, v67
	v_fmac_f32_e32 v71, v76, v76
	v_mul_f32_e32 v72, v77, v77
	v_add_f32_e32 v64, v64, v70
	v_cvt_pk_bf16_f32 v68, v84, v85
	v_cvt_pk_bf16_f32 v69, v82, v83
	v_lshlrev_b32_e32 v78, 16, v67
	v_and_b32_e32 v83, 0xffff0000, v68
	v_mul_f32_e32 v73, v79, v79
	v_fmac_f32_e32 v72, v75, v75
	v_add_f32_e32 v64, v64, v71
	v_lshlrev_b32_e32 v82, 16, v68
	v_and_b32_e32 v85, 0xffff0000, v69
	v_mul_f32_e32 v74, v83, v83
	v_fmac_f32_e32 v73, v78, v78
	v_add_f32_e32 v64, v64, v72
	v_lshlrev_b32_e32 v84, 16, v69
	v_mul_f32_e32 v76, v85, v85
	v_fmac_f32_e32 v74, v82, v82
	v_add_f32_e32 v64, v64, v73
	v_add_f32_e32 v64, v64, v74
	v_fmac_f32_e32 v76, v84, v84
	v_add_f32_e32 v64, v64, v76
	ds_bpermute_b32 v65, v158, v64
	global_store_dwordx4 v[98:99], v[66:69], off offset:256 sc0 nt
	s_waitcnt lgkmcnt(0)
	v_add_f32_e32 v64, v64, v65
	ds_bpermute_b32 v65, v159, v64
	s_and_saveexec_b64 s[8:9], vcc
	s_cbranch_execz .LBB0_467
	v_lshlrev_b64 v[66:67], 6, v[80:81]
	v_lshl_add_u64 v[66:67], s[66:67], 0, v[66:67]
	v_lshl_add_u64 v[66:67], s[6:7], 2, v[66:67]
	s_lshl_b32 s38, s10, 2
	v_lshl_add_u64 v[66:67], v[66:67], 0, s[38:39]
	s_waitcnt lgkmcnt(0)
	v_add_f32_e32 v64, v64, v65
	global_store_dword v[66:67], v64, off
.LBB0_467:
	s_or_b64 exec, exec, s[8:9]
	v_add_u32_e32 v64, 0x80, v136
	s_waitcnt lgkmcnt(0)
	v_ashrrev_i32_e32 v65, 31, v64
	v_lshlrev_b64 v[66:67], 12, v[64:65]
	v_lshl_add_u64 v[66:67], s[44:45], 0, v[66:67]
	v_lshl_add_u64 v[78:79], v[134:135], 2, v[66:67]
	s_nop 0
	v_lshlrev_b64 v[82:83], 11, v[64:65]
	v_lshl_add_u64 v[82:83], s[68:69], 0, v[82:83]
	v_lshl_add_u64 v[82:83], v[134:135], 1, v[82:83]
	s_waitcnt vmcnt(24)
	v_mov_b32_e32 v66, v228
	v_mov_b32_e32 v67, v229
	v_mov_b32_e32 v68, v230
	v_mov_b32_e32 v69, v231
	v_mov_b32_e32 v70, v232
	v_mov_b32_e32 v71, v233
	v_mov_b32_e32 v72, v234
	v_mov_b32_e32 v73, v235
	v_mov_b32_e32 v74, v236
	v_mov_b32_e32 v75, v237
	v_mov_b32_e32 v76, v238
	v_mov_b32_e32 v77, v239
	v_mov_b32_e32 v78, v240
	v_mov_b32_e32 v79, v241
	v_mov_b32_e32 v80, v242
	v_mov_b32_e32 v81, v243
	v_pk_add_f32 v[58:59], v[58:59], v[68:69]
	v_pk_add_f32 v[56:57], v[56:57], v[66:67]
	s_nop 0
	v_pk_add_f32 v[62:63], v[62:63], v[72:73]
	s_nop 0
	v_pk_add_f32 v[68:69], v[48:49], v[78:79]
	v_cvt_pk_bf16_f32 v48, v56, v57
	v_cvt_pk_bf16_f32 v49, v58, v59
	v_pk_add_f32 v[60:61], v[60:61], v[70:71]
	v_pk_add_f32 v[66:67], v[50:51], v[80:81]
	v_cvt_pk_bf16_f32 v50, v60, v61
	v_cvt_pk_bf16_f32 v51, v62, v63
	global_store_dwordx4 v[82:83], v[48:51], off sc0 nt
	v_lshlrev_b32_e32 v56, 16, v48
	v_lshlrev_b32_e32 v57, 16, v49
	v_and_b32_e32 v48, 0xffff0000, v48
	v_and_b32_e32 v49, 0xffff0000, v49
	v_pk_add_f32 v[54:55], v[54:55], v[76:77]
	v_and_b32_e32 v59, 0xffff0000, v50
	v_mul_f32_e32 v48, v48, v48
	v_mul_f32_e32 v49, v49, v49
	v_pk_add_f32 v[52:53], v[52:53], v[74:75]
	v_lshlrev_b32_e32 v58, 16, v50
	v_lshlrev_b32_e32 v60, 16, v51
	v_and_b32_e32 v61, 0xffff0000, v51
	v_cvt_pk_bf16_f32 v50, v52, v53
	v_cvt_pk_bf16_f32 v51, v54, v55
	v_mul_f32_e32 v54, v59, v59
	v_fmac_f32_e32 v48, v56, v56
	v_fmac_f32_e32 v49, v57, v57
	v_mul_f32_e32 v55, v61, v61
	v_and_b32_e32 v61, 0xffff0000, v50
	v_fmac_f32_e32 v54, v58, v58
	v_add_f32_e32 v48, v48, v49
	v_lshlrev_b32_e32 v59, 16, v50
	v_and_b32_e32 v63, 0xffff0000, v51
	v_fmac_f32_e32 v55, v60, v60
	v_mul_f32_e32 v56, v61, v61
	v_add_f32_e32 v48, v48, v54
	v_cvt_pk_bf16_f32 v52, v68, v69
	v_cvt_pk_bf16_f32 v53, v66, v67
	v_lshlrev_b32_e32 v62, 16, v51
	v_and_b32_e32 v67, 0xffff0000, v52
	v_mul_f32_e32 v57, v63, v63
	v_fmac_f32_e32 v56, v59, v59
	v_add_f32_e32 v48, v48, v55
	v_lshlrev_b32_e32 v66, 16, v52
	v_and_b32_e32 v69, 0xffff0000, v53
	v_mul_f32_e32 v58, v67, v67
	v_fmac_f32_e32 v57, v62, v62
	v_add_f32_e32 v48, v48, v56
	v_lshlrev_b32_e32 v68, 16, v53
	v_mul_f32_e32 v60, v69, v69
	v_fmac_f32_e32 v58, v66, v66
	v_add_f32_e32 v48, v48, v57
	v_add_f32_e32 v48, v48, v58
	v_fmac_f32_e32 v60, v68, v68
	v_add_f32_e32 v48, v48, v60
	ds_bpermute_b32 v49, v158, v48
	global_store_dwordx4 v[82:83], v[50:53], off offset:256 sc0 nt
	s_waitcnt lgkmcnt(0)
	v_add_f32_e32 v48, v48, v49
	ds_bpermute_b32 v49, v159, v48
	s_and_saveexec_b64 s[8:9], vcc
	s_cbranch_execz .LBB0_469
	v_lshlrev_b64 v[50:51], 6, v[64:65]
	v_lshl_add_u64 v[50:51], s[66:67], 0, v[50:51]
	v_lshl_add_u64 v[50:51], s[6:7], 2, v[50:51]
	s_lshl_b32 s38, s10, 2
	v_lshl_add_u64 v[50:51], v[50:51], 0, s[38:39]
	s_waitcnt lgkmcnt(0)
	v_add_f32_e32 v48, v48, v49
	global_store_dword v[50:51], v48, off
.LBB0_469:
	s_or_b64 exec, exec, s[8:9]
	v_add_u32_e32 v48, 0x90, v136
	s_waitcnt lgkmcnt(0)
	v_ashrrev_i32_e32 v49, 31, v48
	v_lshlrev_b64 v[50:51], 12, v[48:49]
	v_lshl_add_u64 v[50:51], s[44:45], 0, v[50:51]
	v_lshl_add_u64 v[62:63], v[134:135], 2, v[50:51]
	s_nop 0
	v_lshlrev_b64 v[66:67], 11, v[48:49]
	v_lshl_add_u64 v[66:67], s[68:69], 0, v[66:67]
	v_lshl_add_u64 v[66:67], v[134:135], 1, v[66:67]
	s_waitcnt vmcnt(20)
	v_mov_b32_e32 v50, v168
	v_mov_b32_e32 v51, v169
	v_mov_b32_e32 v52, v170
	v_mov_b32_e32 v53, v171
	v_mov_b32_e32 v54, v172
	v_mov_b32_e32 v55, v173
	v_mov_b32_e32 v56, v174
	v_mov_b32_e32 v57, v175
	v_mov_b32_e32 v58, v176
	v_mov_b32_e32 v59, v177
	v_mov_b32_e32 v60, v178
	v_mov_b32_e32 v61, v179
	v_mov_b32_e32 v62, v180
	v_mov_b32_e32 v63, v181
	v_mov_b32_e32 v64, v182
	v_mov_b32_e32 v65, v183
	v_pk_add_f32 v[42:43], v[42:43], v[52:53]
	v_pk_add_f32 v[40:41], v[40:41], v[50:51]
	s_nop 0
	v_pk_add_f32 v[46:47], v[46:47], v[56:57]
	s_nop 0
	v_pk_add_f32 v[52:53], v[32:33], v[62:63]
	v_cvt_pk_bf16_f32 v32, v40, v41
	v_cvt_pk_bf16_f32 v33, v42, v43
	v_pk_add_f32 v[44:45], v[44:45], v[54:55]
	v_pk_add_f32 v[50:51], v[34:35], v[64:65]
	v_cvt_pk_bf16_f32 v34, v44, v45
	v_cvt_pk_bf16_f32 v35, v46, v47
	global_store_dwordx4 v[66:67], v[32:35], off sc0 nt
	v_lshlrev_b32_e32 v40, 16, v32
	v_lshlrev_b32_e32 v41, 16, v33
	v_and_b32_e32 v32, 0xffff0000, v32
	v_and_b32_e32 v33, 0xffff0000, v33
	v_pk_add_f32 v[38:39], v[38:39], v[60:61]
	v_and_b32_e32 v43, 0xffff0000, v34
	v_mul_f32_e32 v32, v32, v32
	v_mul_f32_e32 v33, v33, v33
	v_pk_add_f32 v[36:37], v[36:37], v[58:59]
	v_lshlrev_b32_e32 v42, 16, v34
	v_lshlrev_b32_e32 v44, 16, v35
	v_and_b32_e32 v45, 0xffff0000, v35
	v_cvt_pk_bf16_f32 v34, v36, v37
	v_cvt_pk_bf16_f32 v35, v38, v39
	v_mul_f32_e32 v38, v43, v43
	v_fmac_f32_e32 v32, v40, v40
	v_fmac_f32_e32 v33, v41, v41
	v_mul_f32_e32 v39, v45, v45
	v_and_b32_e32 v45, 0xffff0000, v34
	v_fmac_f32_e32 v38, v42, v42
	v_add_f32_e32 v32, v32, v33
	v_lshlrev_b32_e32 v43, 16, v34
	v_and_b32_e32 v47, 0xffff0000, v35
	v_fmac_f32_e32 v39, v44, v44
	v_mul_f32_e32 v40, v45, v45
	v_add_f32_e32 v32, v32, v38
	v_cvt_pk_bf16_f32 v36, v52, v53
	v_cvt_pk_bf16_f32 v37, v50, v51
	v_lshlrev_b32_e32 v46, 16, v35
	v_and_b32_e32 v51, 0xffff0000, v36
	v_mul_f32_e32 v41, v47, v47
	v_fmac_f32_e32 v40, v43, v43
	v_add_f32_e32 v32, v32, v39
	v_lshlrev_b32_e32 v50, 16, v36
	v_and_b32_e32 v53, 0xffff0000, v37
	v_mul_f32_e32 v42, v51, v51
	v_fmac_f32_e32 v41, v46, v46
	v_add_f32_e32 v32, v32, v40
	v_lshlrev_b32_e32 v52, 16, v37
	v_mul_f32_e32 v44, v53, v53
	v_fmac_f32_e32 v42, v50, v50
	v_add_f32_e32 v32, v32, v41
	v_add_f32_e32 v32, v32, v42
	v_fmac_f32_e32 v44, v52, v52
	v_add_f32_e32 v32, v32, v44
	ds_bpermute_b32 v33, v158, v32
	global_store_dwordx4 v[66:67], v[34:37], off offset:256 sc0 nt
	s_waitcnt lgkmcnt(0)
	v_add_f32_e32 v32, v32, v33
	ds_bpermute_b32 v33, v159, v32
	s_and_saveexec_b64 s[8:9], vcc
	s_cbranch_execz .LBB0_471
	v_lshlrev_b64 v[34:35], 6, v[48:49]
	v_lshl_add_u64 v[34:35], s[66:67], 0, v[34:35]
	v_lshl_add_u64 v[34:35], s[6:7], 2, v[34:35]
	s_lshl_b32 s38, s10, 2
	v_lshl_add_u64 v[34:35], v[34:35], 0, s[38:39]
	s_waitcnt lgkmcnt(0)
	v_add_f32_e32 v32, v32, v33
	global_store_dword v[34:35], v32, off
.LBB0_471:
	s_or_b64 exec, exec, s[8:9]
	v_add_u32_e32 v32, 0xa0, v136
	s_waitcnt lgkmcnt(0)
	v_ashrrev_i32_e32 v33, 31, v32
	v_lshlrev_b64 v[34:35], 12, v[32:33]
	v_lshl_add_u64 v[34:35], s[44:45], 0, v[34:35]
	v_lshl_add_u64 v[46:47], v[134:135], 2, v[34:35]
	s_nop 0
	v_lshlrev_b64 v[50:51], 11, v[32:33]
	v_lshl_add_u64 v[50:51], s[68:69], 0, v[50:51]
	v_lshl_add_u64 v[50:51], v[134:135], 1, v[50:51]
	s_waitcnt vmcnt(16)
	v_mov_b32_e32 v34, v184
	v_mov_b32_e32 v35, v185
	v_mov_b32_e32 v36, v186
	v_mov_b32_e32 v37, v187
	v_mov_b32_e32 v38, v188
	v_mov_b32_e32 v39, v189
	v_mov_b32_e32 v40, v190
	v_mov_b32_e32 v41, v191
	v_mov_b32_e32 v42, v192
	v_mov_b32_e32 v43, v193
	v_mov_b32_e32 v44, v194
	v_mov_b32_e32 v45, v195
	v_mov_b32_e32 v46, v208
	v_mov_b32_e32 v47, v209
	v_mov_b32_e32 v48, v210
	v_mov_b32_e32 v49, v211
	v_pk_add_f32 v[26:27], v[26:27], v[36:37]
	v_pk_add_f32 v[24:25], v[24:25], v[34:35]
	s_nop 0
	v_pk_add_f32 v[30:31], v[30:31], v[40:41]
	s_nop 0
	v_pk_add_f32 v[36:37], v[16:17], v[46:47]
	v_cvt_pk_bf16_f32 v16, v24, v25
	v_cvt_pk_bf16_f32 v17, v26, v27
	v_pk_add_f32 v[28:29], v[28:29], v[38:39]
	v_pk_add_f32 v[34:35], v[18:19], v[48:49]
	v_cvt_pk_bf16_f32 v18, v28, v29
	v_cvt_pk_bf16_f32 v19, v30, v31
	global_store_dwordx4 v[50:51], v[16:19], off sc0 nt
	v_lshlrev_b32_e32 v24, 16, v16
	v_lshlrev_b32_e32 v25, 16, v17
	v_and_b32_e32 v16, 0xffff0000, v16
	v_and_b32_e32 v17, 0xffff0000, v17
	v_pk_add_f32 v[22:23], v[22:23], v[44:45]
	v_and_b32_e32 v27, 0xffff0000, v18
	v_mul_f32_e32 v16, v16, v16
	v_mul_f32_e32 v17, v17, v17
	v_pk_add_f32 v[20:21], v[20:21], v[42:43]
	v_lshlrev_b32_e32 v26, 16, v18
	v_lshlrev_b32_e32 v28, 16, v19
	v_and_b32_e32 v29, 0xffff0000, v19
	v_cvt_pk_bf16_f32 v18, v20, v21
	v_cvt_pk_bf16_f32 v19, v22, v23
	v_mul_f32_e32 v22, v27, v27
	v_fmac_f32_e32 v16, v24, v24
	v_fmac_f32_e32 v17, v25, v25
	v_mul_f32_e32 v23, v29, v29
	v_and_b32_e32 v29, 0xffff0000, v18
	v_fmac_f32_e32 v22, v26, v26
	v_add_f32_e32 v16, v16, v17
	v_lshlrev_b32_e32 v27, 16, v18
	v_and_b32_e32 v31, 0xffff0000, v19
	v_fmac_f32_e32 v23, v28, v28
	v_mul_f32_e32 v24, v29, v29
	v_add_f32_e32 v16, v16, v22
	v_cvt_pk_bf16_f32 v20, v36, v37
	v_cvt_pk_bf16_f32 v21, v34, v35
	v_lshlrev_b32_e32 v30, 16, v19
	v_and_b32_e32 v35, 0xffff0000, v20
	v_mul_f32_e32 v25, v31, v31
	v_fmac_f32_e32 v24, v27, v27
	v_add_f32_e32 v16, v16, v23
	v_lshlrev_b32_e32 v34, 16, v20
	v_and_b32_e32 v37, 0xffff0000, v21
	v_mul_f32_e32 v26, v35, v35
	v_fmac_f32_e32 v25, v30, v30
	v_add_f32_e32 v16, v16, v24
	v_lshlrev_b32_e32 v36, 16, v21
	v_mul_f32_e32 v28, v37, v37
	v_fmac_f32_e32 v26, v34, v34
	v_add_f32_e32 v16, v16, v25
	v_add_f32_e32 v16, v16, v26
	v_fmac_f32_e32 v28, v36, v36
	v_add_f32_e32 v16, v16, v28
	ds_bpermute_b32 v17, v158, v16
	global_store_dwordx4 v[50:51], v[18:21], off offset:256 sc0 nt
	s_waitcnt lgkmcnt(0)
	v_add_f32_e32 v16, v16, v17
	ds_bpermute_b32 v17, v159, v16
	s_and_saveexec_b64 s[8:9], vcc
	s_cbranch_execz .LBB0_473
	v_lshlrev_b64 v[18:19], 6, v[32:33]
	v_lshl_add_u64 v[18:19], s[66:67], 0, v[18:19]
	v_lshl_add_u64 v[18:19], s[6:7], 2, v[18:19]
	s_lshl_b32 s38, s10, 2
	v_lshl_add_u64 v[18:19], v[18:19], 0, s[38:39]
	s_waitcnt lgkmcnt(0)
	v_add_f32_e32 v16, v16, v17
	global_store_dword v[18:19], v16, off
.LBB0_473:
	s_or_b64 exec, exec, s[8:9]
	v_add_u32_e32 v16, 0xb0, v136
	s_waitcnt lgkmcnt(0)
	v_ashrrev_i32_e32 v17, 31, v16
	v_lshlrev_b64 v[18:19], 12, v[16:17]
	v_lshl_add_u64 v[18:19], s[44:45], 0, v[18:19]
	v_lshl_add_u64 v[30:31], v[134:135], 2, v[18:19]
	s_nop 0
	v_lshlrev_b64 v[34:35], 11, v[16:17]
	v_lshl_add_u64 v[34:35], s[68:69], 0, v[34:35]
	v_lshl_add_u64 v[34:35], v[134:135], 1, v[34:35]
	s_waitcnt vmcnt(12)
	v_mov_b32_e32 v18, v212
	v_mov_b32_e32 v19, v213
	v_mov_b32_e32 v20, v214
	v_mov_b32_e32 v21, v215
	v_mov_b32_e32 v22, v216
	v_mov_b32_e32 v23, v217
	v_mov_b32_e32 v24, v218
	v_mov_b32_e32 v25, v219
	v_mov_b32_e32 v26, v220
	v_mov_b32_e32 v27, v221
	v_mov_b32_e32 v28, v222
	v_mov_b32_e32 v29, v223
	v_mov_b32_e32 v30, v224
	v_mov_b32_e32 v31, v225
	v_mov_b32_e32 v32, v226
	v_mov_b32_e32 v33, v227
	v_pk_add_f32 v[10:11], v[10:11], v[20:21]
	v_pk_add_f32 v[8:9], v[8:9], v[18:19]
	s_nop 0
	v_pk_add_f32 v[14:15], v[14:15], v[24:25]
	s_nop 0
	v_pk_add_f32 v[20:21], v[0:1], v[30:31]
	v_cvt_pk_bf16_f32 v0, v8, v9
	v_cvt_pk_bf16_f32 v1, v10, v11
	v_pk_add_f32 v[12:13], v[12:13], v[22:23]
	v_pk_add_f32 v[18:19], v[2:3], v[32:33]
	v_cvt_pk_bf16_f32 v2, v12, v13
	v_cvt_pk_bf16_f32 v3, v14, v15
	global_store_dwordx4 v[34:35], v[0:3], off sc0 nt
	v_lshlrev_b32_e32 v8, 16, v0
	v_lshlrev_b32_e32 v9, 16, v1
	v_and_b32_e32 v0, 0xffff0000, v0
	v_and_b32_e32 v1, 0xffff0000, v1
	v_pk_add_f32 v[6:7], v[6:7], v[28:29]
	v_and_b32_e32 v11, 0xffff0000, v2
	v_mul_f32_e32 v0, v0, v0
	v_mul_f32_e32 v1, v1, v1
	v_pk_add_f32 v[4:5], v[4:5], v[26:27]
	v_lshlrev_b32_e32 v10, 16, v2
	v_lshlrev_b32_e32 v12, 16, v3
	v_and_b32_e32 v13, 0xffff0000, v3
	v_cvt_pk_bf16_f32 v2, v4, v5
	v_cvt_pk_bf16_f32 v3, v6, v7
	v_mul_f32_e32 v6, v11, v11
	v_fmac_f32_e32 v0, v8, v8
	v_fmac_f32_e32 v1, v9, v9
	v_mul_f32_e32 v7, v13, v13
	v_and_b32_e32 v13, 0xffff0000, v2
	v_fmac_f32_e32 v6, v10, v10
	v_add_f32_e32 v0, v0, v1
	v_lshlrev_b32_e32 v11, 16, v2
	v_and_b32_e32 v15, 0xffff0000, v3
	v_fmac_f32_e32 v7, v12, v12
	v_mul_f32_e32 v8, v13, v13
	v_add_f32_e32 v0, v0, v6
	v_cvt_pk_bf16_f32 v4, v20, v21
	v_cvt_pk_bf16_f32 v5, v18, v19
	v_lshlrev_b32_e32 v14, 16, v3
	v_and_b32_e32 v19, 0xffff0000, v4
	v_mul_f32_e32 v9, v15, v15
	v_fmac_f32_e32 v8, v11, v11
	v_add_f32_e32 v0, v0, v7
	v_lshlrev_b32_e32 v18, 16, v4
	v_and_b32_e32 v21, 0xffff0000, v5
	v_mul_f32_e32 v10, v19, v19
	v_fmac_f32_e32 v9, v14, v14
	v_add_f32_e32 v0, v0, v8
	v_lshlrev_b32_e32 v20, 16, v5
	v_mul_f32_e32 v12, v21, v21
	v_fmac_f32_e32 v10, v18, v18
	v_add_f32_e32 v0, v0, v9
	v_add_f32_e32 v0, v0, v10
	v_fmac_f32_e32 v12, v20, v20
	v_add_f32_e32 v0, v0, v12
	ds_bpermute_b32 v1, v158, v0
	global_store_dwordx4 v[34:35], v[2:5], off offset:256 sc0 nt
	s_waitcnt lgkmcnt(0)
	v_add_f32_e32 v0, v0, v1
	ds_bpermute_b32 v1, v159, v0
	s_and_saveexec_b64 s[8:9], vcc
	s_cbranch_execz .LBB0_475
	v_lshlrev_b64 v[2:3], 6, v[16:17]
	v_lshl_add_u64 v[2:3], s[66:67], 0, v[2:3]
	v_lshl_add_u64 v[2:3], s[6:7], 2, v[2:3]
	s_lshl_b32 s38, s10, 2
	v_lshl_add_u64 v[2:3], v[2:3], 0, s[38:39]
	s_waitcnt lgkmcnt(0)
	v_add_f32_e32 v0, v0, v1
	global_store_dword v[2:3], v0, off

.LBB0_487:
	v_add_co_u32_e32 v16, vcc, 0xffff0000, v20
	v_add_u32_e32 v23, s4, v170
	s_nop 0
	v_addc_co_u32_e32 v17, vcc, -1, v21, vcc
	v_add_u32_e32 v24, 0x19000, v23
	ds_read_b32 v24, v24
	v_add_u32_e32 v25, 0x19200, v23
	ds_read_b32 v25, v25
	v_lshrrev_b32_e32 v26, 3, v22
	v_xor_b32_e32 v26, v26, v168
	v_lshlrev_b32_e32 v26, 4, v26
	v_add_u32_e32 v28, v169, v26
	s_addk_i32 s4, 0x80
	s_mov_b64 s[8:9], 0x20000
	s_waitcnt vmcnt(7)
	v_mov_b32_e32 v16, v216
	v_mov_b32_e32 v17, v217
	v_mov_b32_e32 v18, v218
	v_mov_b32_e32 v19, v219
	v_lshlrev_b32_e32 v27, 16, v16
	s_waitcnt lgkmcnt(1)
	v_sub_f32_e32 v27, v27, v24
	v_and_b32_e32 v16, 0xffff0000, v16
	s_waitcnt lgkmcnt(0)
	v_mul_f32_e32 v27, v25, v27
	v_sub_f32_e32 v16, v16, v24
	v_fma_f32 v27, v0, v27, v8
	v_mul_f32_e32 v16, v25, v16
	v_cvt_pk_bf16_f32 v27, v27, v27
	v_fma_f32 v16, v1, v16, v9
	ds_write_b16 v28, v27 offset:34816
	v_cvt_pk_bf16_f32 v16, v16, v16
	v_xad_u32 v27, v26, 16, v169
	ds_write_b16 v27, v16 offset:35072
	v_lshlrev_b32_e32 v16, 16, v17
	v_sub_f32_e32 v16, v16, v24
	v_mul_f32_e32 v16, v25, v16
	v_fma_f32 v16, v2, v16, v10
	v_cvt_pk_bf16_f32 v16, v16, v16
	v_xad_u32 v27, v26, 32, v169
	ds_write_b16 v27, v16 offset:35328
	v_and_b32_e32 v16, 0xffff0000, v17
	v_sub_f32_e32 v16, v16, v24
	v_mul_f32_e32 v16, v25, v16
	v_fma_f32 v16, v3, v16, v11
	v_cvt_pk_bf16_f32 v16, v16, v16
	v_xad_u32 v17, v26, 48, v169
	ds_write_b16 v17, v16 offset:35584
	v_lshlrev_b32_e32 v16, 16, v18
	v_sub_f32_e32 v16, v16, v24
	v_mul_f32_e32 v16, v25, v16
	v_fma_f32 v16, v4, v16, v12
	v_cvt_pk_bf16_f32 v16, v16, v16
	v_xad_u32 v17, v26, 64, v169
	ds_write_b16 v17, v16 offset:35840
	v_and_b32_e32 v16, 0xffff0000, v18
	v_sub_f32_e32 v16, v16, v24
	v_mul_f32_e32 v16, v25, v16
	v_fma_f32 v16, v5, v16, v13
	v_cvt_pk_bf16_f32 v16, v16, v16
	v_xad_u32 v17, v26, s20, v169
	ds_write_b16 v17, v16 offset:36096
	v_lshlrev_b32_e32 v16, 16, v19
	v_sub_f32_e32 v16, v16, v24
	v_mul_f32_e32 v16, v25, v16
	v_fma_f32 v16, v6, v16, v14
	v_cvt_pk_bf16_f32 v16, v16, v16
	v_xad_u32 v17, v26, s21, v169
	ds_write_b16 v17, v16 offset:36352
	v_and_b32_e32 v16, 0xffff0000, v19
	v_sub_f32_e32 v16, v16, v24
	v_mul_f32_e32 v16, v25, v16
	v_fma_f32 v16, v7, v16, v15
	v_cvt_pk_bf16_f32 v16, v16, v16
	v_xad_u32 v17, v26, s22, v169
	ds_write_b16 v17, v16 offset:36608
	v_add_u32_e32 v25, 0x19040, v23
	ds_read_b32 v25, v25
	v_add_u32_e32 v23, 0x19240, v23
	ds_read_b32 v23, v23
	v_add_u32_e32 v24, 16, v22
	v_lshrrev_b32_e32 v24, 3, v24
	v_xor_b32_e32 v24, v24, v168
	v_lshlrev_b32_e32 v24, 4, v24
	v_add_u32_e32 v27, v169, v24
	v_add_u32_e32 v22, 32, v22
	v_lshl_add_u64 v[20:21], v[20:21], 0, s[8:9]
	s_waitcnt vmcnt(6)
	v_mov_b32_e32 v16, v220
	v_mov_b32_e32 v17, v221
	v_mov_b32_e32 v18, v222
	v_mov_b32_e32 v19, v223
	v_lshlrev_b32_e32 v26, 16, v16
	s_waitcnt lgkmcnt(1)
	v_sub_f32_e32 v26, v26, v25
	v_and_b32_e32 v16, 0xffff0000, v16
	s_waitcnt lgkmcnt(0)
	v_mul_f32_e32 v26, v23, v26
	v_sub_f32_e32 v16, v16, v25
	v_fma_f32 v26, v0, v26, v8
	v_mul_f32_e32 v16, v23, v16
	v_cvt_pk_bf16_f32 v26, v26, v26
	v_fma_f32 v16, v1, v16, v9
	ds_write_b16 v27, v26 offset:34816
	v_cvt_pk_bf16_f32 v16, v16, v16
	v_xad_u32 v26, v24, 16, v169
	ds_write_b16 v26, v16 offset:35072
	v_lshlrev_b32_e32 v16, 16, v17
	v_sub_f32_e32 v16, v16, v25
	v_mul_f32_e32 v16, v23, v16
	v_fma_f32 v16, v2, v16, v10
	v_cvt_pk_bf16_f32 v16, v16, v16
	v_xad_u32 v26, v24, 32, v169
	ds_write_b16 v26, v16 offset:35328
	v_and_b32_e32 v16, 0xffff0000, v17
	v_sub_f32_e32 v16, v16, v25
	v_mul_f32_e32 v16, v23, v16
	v_fma_f32 v16, v3, v16, v11
	v_cvt_pk_bf16_f32 v16, v16, v16
	v_xad_u32 v17, v24, 48, v169
	ds_write_b16 v17, v16 offset:35584
	v_lshlrev_b32_e32 v16, 16, v18
	v_sub_f32_e32 v16, v16, v25
	v_mul_f32_e32 v16, v23, v16
	v_fma_f32 v16, v4, v16, v12
	v_cvt_pk_bf16_f32 v16, v16, v16
	v_xad_u32 v17, v24, 64, v169
	ds_write_b16 v17, v16 offset:35840
	v_and_b32_e32 v16, 0xffff0000, v18
	v_sub_f32_e32 v16, v16, v25
	v_mul_f32_e32 v16, v23, v16
	v_fma_f32 v16, v5, v16, v13
	v_cvt_pk_bf16_f32 v16, v16, v16
	v_xad_u32 v17, v24, s20, v169
	ds_write_b16 v17, v16 offset:36096
	v_lshlrev_b32_e32 v16, 16, v19
	v_sub_f32_e32 v16, v16, v25
	v_mul_f32_e32 v16, v23, v16
	v_fma_f32 v16, v6, v16, v14
	v_cvt_pk_bf16_f32 v16, v16, v16
	v_xad_u32 v17, v24, s21, v169
	ds_write_b16 v17, v16 offset:36352
	v_and_b32_e32 v16, 0xffff0000, v19
	v_sub_f32_e32 v16, v16, v25
	v_mul_f32_e32 v16, v23, v16
	v_fma_f32 v16, v7, v16, v15
	v_xad_u32 v17, v24, s22, v169
	v_cvt_pk_bf16_f32 v16, v16, v16
	ds_write_b16 v17, v16 offset:36608
	v_add_co_u32_e32 v16, vcc, 0xffff0000, v20
	v_add_u32_e32 v23, s4, v170
	s_nop 0
	v_addc_co_u32_e32 v17, vcc, -1, v21, vcc
	v_add_u32_e32 v24, 0x19000, v23
	ds_read_b32 v24, v24
	v_add_u32_e32 v25, 0x19200, v23
	ds_read_b32 v25, v25
	v_lshrrev_b32_e32 v26, 3, v22
	v_xor_b32_e32 v26, v26, v168
	v_lshlrev_b32_e32 v26, 4, v26
	v_add_u32_e32 v28, v169, v26
	s_addk_i32 s4, 0x80
	s_mov_b64 s[8:9], 0x20000
	s_waitcnt vmcnt(5)
	v_mov_b32_e32 v16, v224
	v_mov_b32_e32 v17, v225
	v_mov_b32_e32 v18, v226
	v_mov_b32_e32 v19, v227
	v_lshlrev_b32_e32 v27, 16, v16
	s_waitcnt lgkmcnt(1)
	v_sub_f32_e32 v27, v27, v24
	v_and_b32_e32 v16, 0xffff0000, v16
	s_waitcnt lgkmcnt(0)
	v_mul_f32_e32 v27, v25, v27
	v_sub_f32_e32 v16, v16, v24
	v_fma_f32 v27, v0, v27, v8
	v_mul_f32_e32 v16, v25, v16
	v_cvt_pk_bf16_f32 v27, v27, v27
	v_fma_f32 v16, v1, v16, v9
	ds_write_b16 v28, v27 offset:34816
	v_cvt_pk_bf16_f32 v16, v16, v16
	v_xad_u32 v27, v26, 16, v169
	ds_write_b16 v27, v16 offset:35072
	v_lshlrev_b32_e32 v16, 16, v17
	v_sub_f32_e32 v16, v16, v24
	v_mul_f32_e32 v16, v25, v16
	v_fma_f32 v16, v2, v16, v10
	v_cvt_pk_bf16_f32 v16, v16, v16
	v_xad_u32 v27, v26, 32, v169
	ds_write_b16 v27, v16 offset:35328
	v_and_b32_e32 v16, 0xffff0000, v17
	v_sub_f32_e32 v16, v16, v24
	v_mul_f32_e32 v16, v25, v16
	v_fma_f32 v16, v3, v16, v11
	v_cvt_pk_bf16_f32 v16, v16, v16
	v_xad_u32 v17, v26, 48, v169
	ds_write_b16 v17, v16 offset:35584
	v_lshlrev_b32_e32 v16, 16, v18
	v_sub_f32_e32 v16, v16, v24
	v_mul_f32_e32 v16, v25, v16
	v_fma_f32 v16, v4, v16, v12
	v_cvt_pk_bf16_f32 v16, v16, v16
	v_xad_u32 v17, v26, 64, v169
	ds_write_b16 v17, v16 offset:35840
	v_and_b32_e32 v16, 0xffff0000, v18
	v_sub_f32_e32 v16, v16, v24
	v_mul_f32_e32 v16, v25, v16
	v_fma_f32 v16, v5, v16, v13
	v_cvt_pk_bf16_f32 v16, v16, v16
	v_xad_u32 v17, v26, s20, v169
	ds_write_b16 v17, v16 offset:36096
	v_lshlrev_b32_e32 v16, 16, v19
	v_sub_f32_e32 v16, v16, v24
	v_mul_f32_e32 v16, v25, v16
	v_fma_f32 v16, v6, v16, v14
	v_cvt_pk_bf16_f32 v16, v16, v16
	v_xad_u32 v17, v26, s21, v169
	ds_write_b16 v17, v16 offset:36352
	v_and_b32_e32 v16, 0xffff0000, v19
	v_sub_f32_e32 v16, v16, v24
	v_mul_f32_e32 v16, v25, v16
	v_fma_f32 v16, v7, v16, v15
	v_cvt_pk_bf16_f32 v16, v16, v16
	v_xad_u32 v17, v26, s22, v169
	ds_write_b16 v17, v16 offset:36608
	v_add_u32_e32 v25, 0x19040, v23
	ds_read_b32 v25, v25
	v_add_u32_e32 v23, 0x19240, v23
	ds_read_b32 v23, v23
	v_add_u32_e32 v24, 16, v22
	v_lshrrev_b32_e32 v24, 3, v24
	v_xor_b32_e32 v24, v24, v168
	v_lshlrev_b32_e32 v24, 4, v24
	v_add_u32_e32 v27, v169, v24
	v_add_u32_e32 v22, 32, v22
	v_lshl_add_u64 v[20:21], v[20:21], 0, s[8:9]
	s_waitcnt vmcnt(4)
	v_mov_b32_e32 v16, v228
	v_mov_b32_e32 v17, v229
	v_mov_b32_e32 v18, v230
	v_mov_b32_e32 v19, v231
	v_lshlrev_b32_e32 v26, 16, v16
	s_waitcnt lgkmcnt(1)
	v_sub_f32_e32 v26, v26, v25
	v_and_b32_e32 v16, 0xffff0000, v16
	s_waitcnt lgkmcnt(0)
	v_mul_f32_e32 v26, v23, v26
	v_sub_f32_e32 v16, v16, v25
	v_fma_f32 v26, v0, v26, v8
	v_mul_f32_e32 v16, v23, v16
	v_cvt_pk_bf16_f32 v26, v26, v26
	v_fma_f32 v16, v1, v16, v9
	ds_write_b16 v27, v26 offset:34816
	v_cvt_pk_bf16_f32 v16, v16, v16
	v_xad_u32 v26, v24, 16, v169
	ds_write_b16 v26, v16 offset:35072
	v_lshlrev_b32_e32 v16, 16, v17
	v_sub_f32_e32 v16, v16, v25
	v_mul_f32_e32 v16, v23, v16
	v_fma_f32 v16, v2, v16, v10
	v_cvt_pk_bf16_f32 v16, v16, v16
	v_xad_u32 v26, v24, 32, v169
	ds_write_b16 v26, v16 offset:35328
	v_and_b32_e32 v16, 0xffff0000, v17
	v_sub_f32_e32 v16, v16, v25
	v_mul_f32_e32 v16, v23, v16
	v_fma_f32 v16, v3, v16, v11
	v_cvt_pk_bf16_f32 v16, v16, v16
	v_xad_u32 v17, v24, 48, v169
	ds_write_b16 v17, v16 offset:35584
	v_lshlrev_b32_e32 v16, 16, v18
	v_sub_f32_e32 v16, v16, v25
	v_mul_f32_e32 v16, v23, v16
	v_fma_f32 v16, v4, v16, v12
	v_cvt_pk_bf16_f32 v16, v16, v16
	v_xad_u32 v17, v24, 64, v169
	ds_write_b16 v17, v16 offset:35840
	v_and_b32_e32 v16, 0xffff0000, v18
	v_sub_f32_e32 v16, v16, v25
	v_mul_f32_e32 v16, v23, v16
	v_fma_f32 v16, v5, v16, v13
	v_cvt_pk_bf16_f32 v16, v16, v16
	v_xad_u32 v17, v24, s20, v169
	ds_write_b16 v17, v16 offset:36096
	v_lshlrev_b32_e32 v16, 16, v19
	v_sub_f32_e32 v16, v16, v25
	v_mul_f32_e32 v16, v23, v16
	v_fma_f32 v16, v6, v16, v14
	v_cvt_pk_bf16_f32 v16, v16, v16
	v_xad_u32 v17, v24, s21, v169
	ds_write_b16 v17, v16 offset:36352
	v_and_b32_e32 v16, 0xffff0000, v19
	v_sub_f32_e32 v16, v16, v25
	v_mul_f32_e32 v16, v23, v16
	v_fma_f32 v16, v7, v16, v15
	v_xad_u32 v17, v24, s22, v169
	v_cvt_pk_bf16_f32 v16, v16, v16
	ds_write_b16 v17, v16 offset:36608
	v_add_co_u32_e32 v16, vcc, 0xffff0000, v20
	v_add_u32_e32 v23, s4, v170
	s_nop 0
	v_addc_co_u32_e32 v17, vcc, -1, v21, vcc
	v_add_u32_e32 v24, 0x19000, v23
	ds_read_b32 v24, v24
	v_add_u32_e32 v25, 0x19200, v23
	ds_read_b32 v25, v25
	v_lshrrev_b32_e32 v26, 3, v22
	v_xor_b32_e32 v26, v26, v168
	v_lshlrev_b32_e32 v26, 4, v26
	v_add_u32_e32 v28, v169, v26
	s_addk_i32 s4, 0x80
	s_mov_b64 s[8:9], 0x20000
	s_waitcnt vmcnt(3)
	v_mov_b32_e32 v16, v232
	v_mov_b32_e32 v17, v233
	v_mov_b32_e32 v18, v234
	v_mov_b32_e32 v19, v235
	v_lshlrev_b32_e32 v27, 16, v16
	s_waitcnt lgkmcnt(1)
	v_sub_f32_e32 v27, v27, v24
	v_and_b32_e32 v16, 0xffff0000, v16
	s_waitcnt lgkmcnt(0)
	v_mul_f32_e32 v27, v25, v27
	v_sub_f32_e32 v16, v16, v24
	v_fma_f32 v27, v0, v27, v8
	v_mul_f32_e32 v16, v25, v16
	v_cvt_pk_bf16_f32 v27, v27, v27
	v_fma_f32 v16, v1, v16, v9
	ds_write_b16 v28, v27 offset:34816
	v_cvt_pk_bf16_f32 v16, v16, v16
	v_xad_u32 v27, v26, 16, v169
	ds_write_b16 v27, v16 offset:35072
	v_lshlrev_b32_e32 v16, 16, v17
	v_sub_f32_e32 v16, v16, v24
	v_mul_f32_e32 v16, v25, v16
	v_fma_f32 v16, v2, v16, v10
	v_cvt_pk_bf16_f32 v16, v16, v16
	v_xad_u32 v27, v26, 32, v169
	ds_write_b16 v27, v16 offset:35328
	v_and_b32_e32 v16, 0xffff0000, v17
	v_sub_f32_e32 v16, v16, v24
	v_mul_f32_e32 v16, v25, v16
	v_fma_f32 v16, v3, v16, v11
	v_cvt_pk_bf16_f32 v16, v16, v16
	v_xad_u32 v17, v26, 48, v169
	ds_write_b16 v17, v16 offset:35584
	v_lshlrev_b32_e32 v16, 16, v18
	v_sub_f32_e32 v16, v16, v24
	v_mul_f32_e32 v16, v25, v16
	v_fma_f32 v16, v4, v16, v12
	v_cvt_pk_bf16_f32 v16, v16, v16
	v_xad_u32 v17, v26, 64, v169
	ds_write_b16 v17, v16 offset:35840
	v_and_b32_e32 v16, 0xffff0000, v18
	v_sub_f32_e32 v16, v16, v24
	v_mul_f32_e32 v16, v25, v16
	v_fma_f32 v16, v5, v16, v13
	v_cvt_pk_bf16_f32 v16, v16, v16
	v_xad_u32 v17, v26, s20, v169
	ds_write_b16 v17, v16 offset:36096
	v_lshlrev_b32_e32 v16, 16, v19
	v_sub_f32_e32 v16, v16, v24
	v_mul_f32_e32 v16, v25, v16
	v_fma_f32 v16, v6, v16, v14
	v_cvt_pk_bf16_f32 v16, v16, v16
	v_xad_u32 v17, v26, s21, v169
	ds_write_b16 v17, v16 offset:36352
	v_and_b32_e32 v16, 0xffff0000, v19
	v_sub_f32_e32 v16, v16, v24
	v_mul_f32_e32 v16, v25, v16
	v_fma_f32 v16, v7, v16, v15
	v_cvt_pk_bf16_f32 v16, v16, v16
	v_xad_u32 v17, v26, s22, v169
	ds_write_b16 v17, v16 offset:36608
	v_add_u32_e32 v25, 0x19040, v23
	ds_read_b32 v25, v25
	v_add_u32_e32 v23, 0x19240, v23
	ds_read_b32 v23, v23
	v_add_u32_e32 v24, 16, v22
	v_lshrrev_b32_e32 v24, 3, v24
	v_xor_b32_e32 v24, v24, v168
	v_lshlrev_b32_e32 v24, 4, v24
	v_add_u32_e32 v27, v169, v24
	v_add_u32_e32 v22, 32, v22
	v_lshl_add_u64 v[20:21], v[20:21], 0, s[8:9]
	s_waitcnt vmcnt(2)
	v_mov_b32_e32 v16, v236
	v_mov_b32_e32 v17, v237
	v_mov_b32_e32 v18, v238
	v_mov_b32_e32 v19, v239
	v_lshlrev_b32_e32 v26, 16, v16
	s_waitcnt lgkmcnt(1)
	v_sub_f32_e32 v26, v26, v25
	v_and_b32_e32 v16, 0xffff0000, v16
	s_waitcnt lgkmcnt(0)
	v_mul_f32_e32 v26, v23, v26
	v_sub_f32_e32 v16, v16, v25
	v_fma_f32 v26, v0, v26, v8
	v_mul_f32_e32 v16, v23, v16
	v_cvt_pk_bf16_f32 v26, v26, v26
	v_fma_f32 v16, v1, v16, v9
	ds_write_b16 v27, v26 offset:34816
	v_cvt_pk_bf16_f32 v16, v16, v16
	v_xad_u32 v26, v24, 16, v169
	ds_write_b16 v26, v16 offset:35072
	v_lshlrev_b32_e32 v16, 16, v17
	v_sub_f32_e32 v16, v16, v25
	v_mul_f32_e32 v16, v23, v16
	v_fma_f32 v16, v2, v16, v10
	v_cvt_pk_bf16_f32 v16, v16, v16
	v_xad_u32 v26, v24, 32, v169
	ds_write_b16 v26, v16 offset:35328
	v_and_b32_e32 v16, 0xffff0000, v17
	v_sub_f32_e32 v16, v16, v25
	v_mul_f32_e32 v16, v23, v16
	v_fma_f32 v16, v3, v16, v11
	v_cvt_pk_bf16_f32 v16, v16, v16
	v_xad_u32 v17, v24, 48, v169
	ds_write_b16 v17, v16 offset:35584
	v_lshlrev_b32_e32 v16, 16, v18
	v_sub_f32_e32 v16, v16, v25
	v_mul_f32_e32 v16, v23, v16
	v_fma_f32 v16, v4, v16, v12
	v_cvt_pk_bf16_f32 v16, v16, v16
	v_xad_u32 v17, v24, 64, v169
	ds_write_b16 v17, v16 offset:35840
	v_and_b32_e32 v16, 0xffff0000, v18
	v_sub_f32_e32 v16, v16, v25
	v_mul_f32_e32 v16, v23, v16
	v_fma_f32 v16, v5, v16, v13
	v_cvt_pk_bf16_f32 v16, v16, v16
	v_xad_u32 v17, v24, s20, v169
	ds_write_b16 v17, v16 offset:36096
	v_lshlrev_b32_e32 v16, 16, v19
	v_sub_f32_e32 v16, v16, v25
	v_mul_f32_e32 v16, v23, v16
	v_fma_f32 v16, v6, v16, v14
	v_cvt_pk_bf16_f32 v16, v16, v16
	v_xad_u32 v17, v24, s21, v169
	ds_write_b16 v17, v16 offset:36352
	v_and_b32_e32 v16, 0xffff0000, v19
	v_sub_f32_e32 v16, v16, v25
	v_mul_f32_e32 v16, v23, v16
	v_fma_f32 v16, v7, v16, v15
	v_xad_u32 v17, v24, s22, v169
	v_cvt_pk_bf16_f32 v16, v16, v16
	ds_write_b16 v17, v16 offset:36608
	v_add_co_u32_e32 v16, vcc, 0xffff0000, v20
	v_add_u32_e32 v23, s4, v170
	s_nop 0
	v_addc_co_u32_e32 v17, vcc, -1, v21, vcc
	v_add_u32_e32 v24, 0x19000, v23
	ds_read_b32 v24, v24
	v_add_u32_e32 v25, 0x19200, v23
	ds_read_b32 v25, v25
	v_lshrrev_b32_e32 v26, 3, v22
	v_xor_b32_e32 v26, v26, v168
	v_lshlrev_b32_e32 v26, 4, v26
	v_add_u32_e32 v28, v169, v26
	s_addk_i32 s4, 0x80
	s_mov_b64 s[8:9], 0x20000
	s_waitcnt vmcnt(1)
	v_mov_b32_e32 v16, v240
	v_mov_b32_e32 v17, v241
	v_mov_b32_e32 v18, v242
	v_mov_b32_e32 v19, v243
	v_lshlrev_b32_e32 v27, 16, v16
	s_waitcnt lgkmcnt(1)
	v_sub_f32_e32 v27, v27, v24
	v_and_b32_e32 v16, 0xffff0000, v16
	s_waitcnt lgkmcnt(0)
	v_mul_f32_e32 v27, v25, v27
	v_sub_f32_e32 v16, v16, v24
	v_fma_f32 v27, v0, v27, v8
	v_mul_f32_e32 v16, v25, v16
	v_cvt_pk_bf16_f32 v27, v27, v27
	v_fma_f32 v16, v1, v16, v9
	ds_write_b16 v28, v27 offset:34816
	v_cvt_pk_bf16_f32 v16, v16, v16
	v_xad_u32 v27, v26, 16, v169
	ds_write_b16 v27, v16 offset:35072
	v_lshlrev_b32_e32 v16, 16, v17
	v_sub_f32_e32 v16, v16, v24
	v_mul_f32_e32 v16, v25, v16
	v_fma_f32 v16, v2, v16, v10
	v_cvt_pk_bf16_f32 v16, v16, v16
	v_xad_u32 v27, v26, 32, v169
	ds_write_b16 v27, v16 offset:35328
	v_and_b32_e32 v16, 0xffff0000, v17
	v_sub_f32_e32 v16, v16, v24
	v_mul_f32_e32 v16, v25, v16
	v_fma_f32 v16, v3, v16, v11
	v_cvt_pk_bf16_f32 v16, v16, v16
	v_xad_u32 v17, v26, 48, v169
	ds_write_b16 v17, v16 offset:35584
	v_lshlrev_b32_e32 v16, 16, v18
	v_sub_f32_e32 v16, v16, v24
	v_mul_f32_e32 v16, v25, v16
	v_fma_f32 v16, v4, v16, v12
	v_cvt_pk_bf16_f32 v16, v16, v16
	v_xad_u32 v17, v26, 64, v169
	ds_write_b16 v17, v16 offset:35840
	v_and_b32_e32 v16, 0xffff0000, v18
	v_sub_f32_e32 v16, v16, v24
	v_mul_f32_e32 v16, v25, v16
	v_fma_f32 v16, v5, v16, v13
	v_cvt_pk_bf16_f32 v16, v16, v16
	v_xad_u32 v17, v26, s20, v169
	ds_write_b16 v17, v16 offset:36096
	v_lshlrev_b32_e32 v16, 16, v19
	v_sub_f32_e32 v16, v16, v24
	v_mul_f32_e32 v16, v25, v16
	v_fma_f32 v16, v6, v16, v14
	v_cvt_pk_bf16_f32 v16, v16, v16
	v_xad_u32 v17, v26, s21, v169
	ds_write_b16 v17, v16 offset:36352
	v_and_b32_e32 v16, 0xffff0000, v19
	v_sub_f32_e32 v16, v16, v24
	v_mul_f32_e32 v16, v25, v16
	v_fma_f32 v16, v7, v16, v15
	v_cvt_pk_bf16_f32 v16, v16, v16
	v_xad_u32 v17, v26, s22, v169
	ds_write_b16 v17, v16 offset:36608
	v_add_u32_e32 v25, 0x19040, v23
	ds_read_b32 v25, v25
	v_add_u32_e32 v23, 0x19240, v23
	ds_read_b32 v23, v23
	v_add_u32_e32 v24, 16, v22
	v_lshrrev_b32_e32 v24, 3, v24
	v_xor_b32_e32 v24, v24, v168
	v_lshlrev_b32_e32 v24, 4, v24
	v_add_u32_e32 v27, v169, v24
	v_add_u32_e32 v22, 32, v22
	v_lshl_add_u64 v[20:21], v[20:21], 0, s[8:9]
	s_waitcnt vmcnt(0)
	v_mov_b32_e32 v16, v244
	v_mov_b32_e32 v17, v245
	v_mov_b32_e32 v18, v246
	v_mov_b32_e32 v19, v247
	v_lshlrev_b32_e32 v26, 16, v16
	s_waitcnt lgkmcnt(1)
	v_sub_f32_e32 v26, v26, v25
	v_and_b32_e32 v16, 0xffff0000, v16
	s_waitcnt lgkmcnt(0)
	v_mul_f32_e32 v26, v23, v26
	v_sub_f32_e32 v16, v16, v25
	v_fma_f32 v26, v0, v26, v8
	v_mul_f32_e32 v16, v23, v16
	v_cvt_pk_bf16_f32 v26, v26, v26
	v_fma_f32 v16, v1, v16, v9
	ds_write_b16 v27, v26 offset:34816
	v_cvt_pk_bf16_f32 v16, v16, v16
	v_xad_u32 v26, v24, 16, v169
	ds_write_b16 v26, v16 offset:35072
	v_lshlrev_b32_e32 v16, 16, v17
	v_sub_f32_e32 v16, v16, v25
	v_mul_f32_e32 v16, v23, v16
	v_fma_f32 v16, v2, v16, v10
	v_cvt_pk_bf16_f32 v16, v16, v16
	v_xad_u32 v26, v24, 32, v169
	ds_write_b16 v26, v16 offset:35328
	v_and_b32_e32 v16, 0xffff0000, v17
	v_sub_f32_e32 v16, v16, v25
	v_mul_f32_e32 v16, v23, v16
	v_fma_f32 v16, v3, v16, v11
	v_cvt_pk_bf16_f32 v16, v16, v16
	v_xad_u32 v17, v24, 48, v169
	ds_write_b16 v17, v16 offset:35584
	v_lshlrev_b32_e32 v16, 16, v18
	v_sub_f32_e32 v16, v16, v25
	v_mul_f32_e32 v16, v23, v16
	v_fma_f32 v16, v4, v16, v12
	v_cvt_pk_bf16_f32 v16, v16, v16
	v_xad_u32 v17, v24, 64, v169
	ds_write_b16 v17, v16 offset:35840
	v_and_b32_e32 v16, 0xffff0000, v18
	v_sub_f32_e32 v16, v16, v25
	v_mul_f32_e32 v16, v23, v16
	v_fma_f32 v16, v5, v16, v13
	v_cvt_pk_bf16_f32 v16, v16, v16
	v_xad_u32 v17, v24, s20, v169
	ds_write_b16 v17, v16 offset:36096
	v_lshlrev_b32_e32 v16, 16, v19
	v_sub_f32_e32 v16, v16, v25
	v_mul_f32_e32 v16, v23, v16
	v_fma_f32 v16, v6, v16, v14
	v_cvt_pk_bf16_f32 v16, v16, v16
	v_xad_u32 v17, v24, s21, v169
	ds_write_b16 v17, v16 offset:36352
	v_and_b32_e32 v16, 0xffff0000, v19
	v_sub_f32_e32 v16, v16, v25
	v_mul_f32_e32 v16, v23, v16
	v_fma_f32 v16, v7, v16, v15
	v_xad_u32 v17, v24, s22, v169
	v_cvt_pk_bf16_f32 v16, v16, v16
	ds_write_b16 v17, v16 offset:36608
	s_waitcnt lgkmcnt(0)
	s_barrier
	ds_read_b128 v[0:3], v178 offset:34816
	ds_read_b128 v[4:7], v179 offset:34816
	ds_read_b128 v[8:11], v180
	ds_read_b128 v[12:15], v180 offset:4352
	ds_read_b128 v[16:19], v180 offset:8704
	ds_read_b128 v[20:23], v180 offset:13056
	ds_read_b128 v[24:27], v180 offset:17408
	ds_read_b128 v[28:31], v180 offset:21760
	ds_read_b128 v[32:35], v180 offset:26112
	ds_read_b128 v[36:39], v180 offset:30464
	s_waitcnt lgkmcnt(7)
	v_mfma_f32_16x16x32_bf16 v[40:43], v[0:3], v[8:11], 0
	s_add_i32 s12, s12, s96
	s_mov_b64 s[74:75], 0
	s_cmpk_gt_i32 s12, 0x7ff
	s_waitcnt lgkmcnt(6)
	v_mfma_f32_16x16x32_bf16 v[44:47], v[0:3], v[12:15], 0
	s_waitcnt lgkmcnt(5)
	v_mfma_f32_16x16x32_bf16 v[48:51], v[0:3], v[16:19], 0
	s_waitcnt lgkmcnt(4)
	v_mfma_f32_16x16x32_bf16 v[52:55], v[0:3], v[20:23], 0
	s_waitcnt lgkmcnt(3)
	v_mfma_f32_16x16x32_bf16 v[56:59], v[0:3], v[24:27], 0
	s_waitcnt lgkmcnt(2)
	v_mfma_f32_16x16x32_bf16 v[60:63], v[0:3], v[28:31], 0
	s_waitcnt lgkmcnt(1)
	v_mfma_f32_16x16x32_bf16 v[64:67], v[0:3], v[32:35], 0
	s_waitcnt lgkmcnt(0)
	v_mfma_f32_16x16x32_bf16 v[0:3], v[0:3], v[36:39], 0
	v_mfma_f32_16x16x32_bf16 v[8:11], v[4:7], v[8:11], 0
	v_mfma_f32_16x16x32_bf16 v[12:15], v[4:7], v[12:15], 0
	v_mfma_f32_16x16x32_bf16 v[16:19], v[4:7], v[16:19], 0
	v_mfma_f32_16x16x32_bf16 v[20:23], v[4:7], v[20:23], 0
	v_mfma_f32_16x16x32_bf16 v[24:27], v[4:7], v[24:27], 0
	v_mfma_f32_16x16x32_bf16 v[28:31], v[4:7], v[28:31], 0
	v_mfma_f32_16x16x32_bf16 v[32:35], v[4:7], v[32:35], 0
	v_mfma_f32_16x16x32_bf16 v[4:7], v[4:7], v[36:39], 0
	ds_read_b128 v[36:39], v181 offset:34816
	ds_read_b128 v[68:71], v182 offset:34816
	ds_read_b128 v[72:75], v180 offset:64
	ds_read_b128 v[76:79], v180 offset:4416
	ds_read_b128 v[80:83], v180 offset:8768
	ds_read_b128 v[132:135], v180 offset:13120
	ds_read_b128 v[136:139], v180 offset:17472
	ds_read_b128 v[142:145], v180 offset:21824
	ds_read_b128 v[146:149], v180 offset:26176
	ds_read_b128 v[150:153], v180 offset:30528
	s_waitcnt lgkmcnt(7)
	v_mfma_f32_16x16x32_bf16 v[40:43], v[36:39], v[72:75], v[40:43]
	s_waitcnt lgkmcnt(6)
	v_mfma_f32_16x16x32_bf16 v[44:47], v[36:39], v[76:79], v[44:47]
	s_waitcnt lgkmcnt(5)
	v_mfma_f32_16x16x32_bf16 v[48:51], v[36:39], v[80:83], v[48:51]
	s_waitcnt lgkmcnt(4)
	v_mfma_f32_16x16x32_bf16 v[52:55], v[36:39], v[132:135], v[52:55]
	s_waitcnt lgkmcnt(3)
	v_mfma_f32_16x16x32_bf16 v[56:59], v[36:39], v[136:139], v[56:59]
	s_waitcnt lgkmcnt(2)
	v_mfma_f32_16x16x32_bf16 v[60:63], v[36:39], v[142:145], v[60:63]
	s_waitcnt lgkmcnt(1)
	v_mfma_f32_16x16x32_bf16 v[64:67], v[36:39], v[146:149], v[64:67]
	s_waitcnt lgkmcnt(0)
	v_mfma_f32_16x16x32_bf16 v[0:3], v[36:39], v[150:153], v[0:3]
	v_mfma_f32_16x16x32_bf16 v[8:11], v[68:71], v[72:75], v[8:11]
	v_mfma_f32_16x16x32_bf16 v[12:15], v[68:71], v[76:79], v[12:15]
	v_mfma_f32_16x16x32_bf16 v[16:19], v[68:71], v[80:83], v[16:19]
	v_mfma_f32_16x16x32_bf16 v[20:23], v[68:71], v[132:135], v[20:23]
	v_mfma_f32_16x16x32_bf16 v[24:27], v[68:71], v[136:139], v[24:27]
	v_mfma_f32_16x16x32_bf16 v[28:31], v[68:71], v[142:145], v[28:31]
	v_mfma_f32_16x16x32_bf16 v[32:35], v[68:71], v[146:149], v[32:35]
	v_mfma_f32_16x16x32_bf16 v[4:7], v[68:71], v[150:153], v[4:7]
	ds_read_b128 v[36:39], v183 offset:34816
	ds_read_b128 v[68:71], v184 offset:34816
	ds_read_b128 v[72:75], v180 offset:128
	ds_read_b128 v[76:79], v180 offset:4480
	ds_read_b128 v[80:83], v180 offset:8832
	ds_read_b128 v[132:135], v180 offset:13184
	ds_read_b128 v[136:139], v180 offset:17536
	ds_read_b128 v[142:145], v180 offset:21888
	ds_read_b128 v[146:149], v180 offset:26240
	ds_read_b128 v[150:153], v180 offset:30592
	s_waitcnt lgkmcnt(7)
	v_mfma_f32_16x16x32_bf16 v[40:43], v[36:39], v[72:75], v[40:43]
	s_waitcnt lgkmcnt(6)
	v_mfma_f32_16x16x32_bf16 v[44:47], v[36:39], v[76:79], v[44:47]
	s_waitcnt lgkmcnt(5)
	v_mfma_f32_16x16x32_bf16 v[48:51], v[36:39], v[80:83], v[48:51]
	s_waitcnt lgkmcnt(4)
	v_mfma_f32_16x16x32_bf16 v[52:55], v[36:39], v[132:135], v[52:55]
	s_waitcnt lgkmcnt(3)
	v_mfma_f32_16x16x32_bf16 v[56:59], v[36:39], v[136:139], v[56:59]
	s_waitcnt lgkmcnt(2)
	v_mfma_f32_16x16x32_bf16 v[154:157], v[36:39], v[142:145], v[60:63]
	s_waitcnt lgkmcnt(1)
	v_mfma_f32_16x16x32_bf16 v[64:67], v[36:39], v[146:149], v[64:67]
	s_waitcnt lgkmcnt(0)
	v_mfma_f32_16x16x32_bf16 v[0:3], v[36:39], v[150:153], v[0:3]
	v_mfma_f32_16x16x32_bf16 v[8:11], v[68:71], v[72:75], v[8:11]
	v_mfma_f32_16x16x32_bf16 v[16:19], v[68:71], v[80:83], v[16:19]
	v_mfma_f32_16x16x32_bf16 v[36:39], v[68:71], v[132:135], v[20:23]
	v_mfma_f32_16x16x32_bf16 v[24:27], v[68:71], v[136:139], v[24:27]
	v_mfma_f32_16x16x32_bf16 v[28:31], v[68:71], v[142:145], v[28:31]
	v_mfma_f32_16x16x32_bf16 v[32:35], v[68:71], v[146:149], v[32:35]
	v_mfma_f32_16x16x32_bf16 v[4:7], v[68:71], v[150:153], v[4:7]
	ds_read_b128 v[20:23], v185 offset:34816
	ds_read_b128 v[132:135], v186 offset:34816
	ds_read_b128 v[72:75], v180 offset:192
	ds_read_b128 v[80:83], v180 offset:4544
	ds_read_b128 v[136:139], v180 offset:8896
	ds_read_b128 v[142:145], v180 offset:13248
	ds_read_b128 v[146:149], v180 offset:17600
	ds_read_b128 v[150:153], v180 offset:21952
	ds_read_b128 v[158:161], v180 offset:26304
	ds_read_b128 v[162:165], v180 offset:30656
	v_mfma_f32_16x16x32_bf16 v[12:15], v[68:71], v[76:79], v[12:15]
	s_waitcnt lgkmcnt(7)
	v_mfma_f32_16x16x32_bf16 v[188:191], v[20:23], v[72:75], v[40:43]
	s_waitcnt lgkmcnt(6)
	v_mfma_f32_16x16x32_bf16 v[192:195], v[20:23], v[80:83], v[44:47]
	s_waitcnt lgkmcnt(5)
	v_mfma_f32_16x16x32_bf16 v[76:79], v[20:23], v[136:139], v[48:51]
	s_waitcnt lgkmcnt(4)
	v_mfma_f32_16x16x32_bf16 v[68:71], v[20:23], v[142:145], v[52:55]
	s_waitcnt lgkmcnt(3)
	v_mfma_f32_16x16x32_bf16 v[60:63], v[20:23], v[146:149], v[56:59]
	s_waitcnt lgkmcnt(2)
	v_mfma_f32_16x16x32_bf16 v[52:55], v[20:23], v[150:153], v[154:157]
	s_waitcnt lgkmcnt(1)
	v_mfma_f32_16x16x32_bf16 v[44:47], v[20:23], v[158:161], v[64:67]
	s_waitcnt lgkmcnt(0)
	v_mfma_f32_16x16x32_bf16 v[20:23], v[20:23], v[162:165], v[0:3]
	v_mfma_f32_16x16x32_bf16 v[56:59], v[132:135], v[146:149], v[24:27]
	v_mfma_f32_16x16x32_bf16 v[24:27], v[132:135], v[162:165], v[4:7]
	v_lshl_add_u64 v[164:165], s[6:7], 0, v[86:87]
	v_lshlrev_b64 v[0:1], 12, v[164:165]
	v_lshl_add_u64 v[0:1], v[88:89], 0, v[0:1]
	v_lshl_add_u64 v[162:163], s[6:7], 0, v[112:113]
	global_load_dwordx4 v[40:43], v[0:1], off
	v_lshlrev_b64 v[0:1], 12, v[162:163]
	v_mfma_f32_16x16x32_bf16 v[64:67], v[132:135], v[142:145], v[36:39]
	v_lshl_add_u64 v[0:1], v[88:89], 0, v[0:1]
	v_mfma_f32_16x16x32_bf16 v[36:39], v[132:135], v[158:161], v[32:35]
	v_lshl_add_u64 v[160:161], s[6:7], 0, v[114:115]
	v_lshl_add_u64 v[158:159], s[6:7], 0, v[116:117]
	s_nop 0
	global_load_dwordx4 v[32:35], v[0:1], off
	v_lshlrev_b64 v[0:1], 12, v[160:161]
	v_lshl_add_u64 v[0:1], v[88:89], 0, v[0:1]
	v_mfma_f32_16x16x32_bf16 v[48:51], v[132:135], v[150:153], v[28:31]
	s_nop 2
	global_load_dwordx4 v[28:31], v[0:1], off
	v_lshlrev_b64 v[0:1], 12, v[158:159]
	v_mfma_f32_16x16x32_bf16 v[154:157], v[132:135], v[72:75], v[8:11]
	v_lshl_add_u64 v[0:1], v[88:89], 0, v[0:1]
	v_mfma_f32_16x16x32_bf16 v[72:75], v[132:135], v[136:139], v[16:19]
	v_lshl_add_u64 v[138:139], s[6:7], 0, v[118:119]
	v_lshl_add_u64 v[136:137], s[6:7], 0, v[120:121]
	s_nop 0
	global_load_dwordx4 v[16:19], v[0:1], off
	v_lshlrev_b64 v[0:1], 12, v[138:139]
	v_lshl_add_u64 v[0:1], v[88:89], 0, v[0:1]
	v_mfma_f32_16x16x32_bf16 v[80:83], v[132:135], v[80:83], v[12:15]
	v_lshl_add_u64 v[134:135], s[6:7], 0, v[122:123]
	v_lshl_add_u64 v[132:133], s[6:7], 0, v[124:125]
	s_nop 0
	global_load_dwordx4 v[12:15], v[0:1], off
	v_lshlrev_b64 v[0:1], 12, v[136:137]
	v_lshl_add_u64 v[0:1], v[88:89], 0, v[0:1]
	global_load_dwordx4 v[8:11], v[0:1], off
	v_lshlrev_b64 v[0:1], 12, v[134:135]
	v_lshl_add_u64 v[0:1], v[88:89], 0, v[0:1]
	global_load_dwordx4 v[4:7], v[0:1], off
	v_lshlrev_b64 v[0:1], 12, v[132:133]
	v_lshl_add_u64 v[0:1], v[88:89], 0, v[0:1]
	global_load_dwordx4 v[0:3], v[0:1], off
	s_barrier
	v_mov_b32_e32 v142, v197
	s_nop 0
	v_pk_add_f32 v[144:145], v[190:191], v[142:143] op_sel_hi:[1,0]
	v_pk_add_f32 v[146:147], v[188:189], v[142:143] op_sel_hi:[1,0]
	s_nop 0
	v_cvt_pk_bf16_f32 v146, v146, v147
	v_cvt_pk_bf16_f32 v147, v144, v145
	v_pk_add_f32 v[144:145], v[156:157], v[142:143] op_sel_hi:[1,0]
	v_pk_add_f32 v[142:143], v[154:155], v[142:143] op_sel_hi:[1,0]
	ds_write_b64 v187, v[146:147] offset:34816
	v_cvt_pk_bf16_f32 v142, v142, v143
	v_cvt_pk_bf16_f32 v143, v144, v145
	ds_write_b64 v187, v[142:143] offset:34848
	v_mov_b32_e32 v142, v200
	s_nop 0
	v_pk_add_f32 v[146:147], v[192:193], v[142:143] op_sel_hi:[1,0]
	v_pk_add_f32 v[80:81], v[80:81], v[142:143] op_sel_hi:[1,0]
	v_pk_add_f32 v[144:145], v[194:195], v[142:143] op_sel_hi:[1,0]
	v_cvt_pk_bf16_f32 v146, v146, v147
	v_pk_add_f32 v[82:83], v[82:83], v[142:143] op_sel_hi:[1,0]
	v_cvt_pk_bf16_f32 v147, v144, v145
	ds_write_b64 v187, v[146:147] offset:43264
	v_cvt_pk_bf16_f32 v80, v80, v81
	v_cvt_pk_bf16_f32 v81, v82, v83
	ds_write_b64 v187, v[80:81] offset:43296
	v_mov_b32_e32 v80, v201
	s_nop 0
	v_pk_add_f32 v[76:77], v[76:77], v[80:81] op_sel_hi:[1,0]
	v_pk_add_f32 v[72:73], v[72:73], v[80:81] op_sel_hi:[1,0]
	v_pk_add_f32 v[78:79], v[78:79], v[80:81] op_sel_hi:[1,0]
	v_cvt_pk_bf16_f32 v76, v76, v77
	v_pk_add_f32 v[74:75], v[74:75], v[80:81] op_sel_hi:[1,0]
	v_cvt_pk_bf16_f32 v77, v78, v79
	ds_write_b64 v187, v[76:77] offset:51712
	v_cvt_pk_bf16_f32 v72, v72, v73
	v_cvt_pk_bf16_f32 v73, v74, v75
	ds_write_b64 v187, v[72:73] offset:51744
	v_mov_b32_e32 v72, v202
	s_nop 0
	v_pk_add_f32 v[68:69], v[68:69], v[72:73] op_sel_hi:[1,0]
	v_pk_add_f32 v[64:65], v[64:65], v[72:73] op_sel_hi:[1,0]
	v_pk_add_f32 v[70:71], v[70:71], v[72:73] op_sel_hi:[1,0]
	v_cvt_pk_bf16_f32 v68, v68, v69
	v_pk_add_f32 v[66:67], v[66:67], v[72:73] op_sel_hi:[1,0]
	v_cvt_pk_bf16_f32 v69, v70, v71
	ds_write_b64 v187, v[68:69] offset:60160
	v_cvt_pk_bf16_f32 v64, v64, v65
	v_cvt_pk_bf16_f32 v65, v66, v67
	ds_write_b64 v187, v[64:65] offset:60192
	v_mov_b32_e32 v64, v203
	s_nop 0
	v_pk_add_f32 v[60:61], v[60:61], v[64:65] op_sel_hi:[1,0]
	v_pk_add_f32 v[56:57], v[56:57], v[64:65] op_sel_hi:[1,0]
	v_pk_add_f32 v[62:63], v[62:63], v[64:65] op_sel_hi:[1,0]
	v_cvt_pk_bf16_f32 v60, v60, v61
	v_pk_add_f32 v[58:59], v[58:59], v[64:65] op_sel_hi:[1,0]
	v_cvt_pk_bf16_f32 v61, v62, v63
	ds_write_b64 v206, v[60:61] offset:34816
	v_cvt_pk_bf16_f32 v56, v56, v57
	v_cvt_pk_bf16_f32 v57, v58, v59
	ds_write_b64 v206, v[56:57] offset:34848
	v_mov_b32_e32 v56, v204
	s_nop 0
	v_pk_add_f32 v[52:53], v[52:53], v[56:57] op_sel_hi:[1,0]
	v_pk_add_f32 v[48:49], v[48:49], v[56:57] op_sel_hi:[1,0]
	v_pk_add_f32 v[54:55], v[54:55], v[56:57] op_sel_hi:[1,0]
	v_cvt_pk_bf16_f32 v52, v52, v53
	v_pk_add_f32 v[50:51], v[50:51], v[56:57] op_sel_hi:[1,0]
	v_cvt_pk_bf16_f32 v53, v54, v55
	ds_write_b64 v206, v[52:53] offset:43264
	v_cvt_pk_bf16_f32 v48, v48, v49
	v_cvt_pk_bf16_f32 v49, v50, v51
	ds_write_b64 v206, v[48:49] offset:43296
	v_mov_b32_e32 v48, v215
	s_nop 0
	v_pk_add_f32 v[44:45], v[44:45], v[48:49] op_sel_hi:[1,0]
	v_pk_add_f32 v[36:37], v[36:37], v[48:49] op_sel_hi:[1,0]
	v_pk_add_f32 v[46:47], v[46:47], v[48:49] op_sel_hi:[1,0]
	v_cvt_pk_bf16_f32 v44, v44, v45
	v_pk_add_f32 v[38:39], v[38:39], v[48:49] op_sel_hi:[1,0]
	v_cvt_pk_bf16_f32 v45, v46, v47
	ds_write_b64 v206, v[44:45] offset:51712
	v_cvt_pk_bf16_f32 v36, v36, v37
	v_cvt_pk_bf16_f32 v37, v38, v39
	ds_write_b64 v206, v[36:37] offset:51744
	v_mov_b32_e32 v36, v249
	s_waitcnt vmcnt(0)
	v_pk_add_f32 v[22:23], v[22:23], v[36:37] op_sel_hi:[1,0]
	v_pk_add_f32 v[20:21], v[20:21], v[36:37] op_sel_hi:[1,0]
	s_nop 0
	v_cvt_pk_bf16_f32 v20, v20, v21
	v_cvt_pk_bf16_f32 v21, v22, v23
	v_pk_add_f32 v[22:23], v[24:25], v[36:37] op_sel_hi:[1,0]
	ds_write_b64 v206, v[20:21] offset:60160
	v_pk_add_f32 v[20:21], v[26:27], v[36:37] op_sel_hi:[1,0]
	v_cvt_pk_bf16_f32 v22, v22, v23
	v_lshlrev_b32_e32 v24, 16, v40
	v_cvt_pk_bf16_f32 v23, v20, v21
	ds_write_b64 v206, v[22:23] offset:60192
	s_waitcnt lgkmcnt(0)
	s_barrier
	ds_read_b128 v[20:23], v207 offset:34816
	s_waitcnt lgkmcnt(0)
	v_lshlrev_b32_e32 v25, 16, v20
	v_mul_f32_e32 v24, v25, v24
	v_and_b32_e32 v20, 0xffff0000, v20
	v_and_b32_e32 v25, 0xffff0000, v40
	v_mul_f32_e32 v20, v20, v25
	v_cvt_pk_bf16_f32 v20, v24, v20
	v_lshlrev_b32_e32 v24, 16, v41
	v_lshlrev_b32_e32 v25, 16, v21
	v_mul_f32_e32 v24, v25, v24
	v_and_b32_e32 v21, 0xffff0000, v21
	v_and_b32_e32 v25, 0xffff0000, v41
	v_mul_f32_e32 v21, v21, v25
	v_cvt_pk_bf16_f32 v21, v24, v21
	v_lshlrev_b32_e32 v24, 16, v42
	v_lshlrev_b32_e32 v25, 16, v22
	v_mul_f32_e32 v24, v25, v24
	v_and_b32_e32 v22, 0xffff0000, v22
	v_and_b32_e32 v25, 0xffff0000, v42
	v_mul_f32_e32 v22, v22, v25
	v_cvt_pk_bf16_f32 v22, v24, v22
	v_lshlrev_b32_e32 v24, 16, v43
	v_lshlrev_b32_e32 v25, 16, v23
	v_mul_f32_e32 v24, v25, v24
	v_and_b32_e32 v23, 0xffff0000, v23
	v_and_b32_e32 v25, 0xffff0000, v43
	v_mul_f32_e32 v23, v23, v25
	v_cvt_pk_bf16_f32 v23, v24, v23
	v_lshlrev_b64 v[24:25], 11, v[164:165]
	v_lshl_add_u64 v[24:25], v[90:91], 0, v[24:25]
	global_store_dwordx4 v[24:25], v[20:23], off sc0 nt
	ds_read_b128 v[20:23], v208 offset:34816
	v_lshlrev_b32_e32 v24, 16, v32
	s_waitcnt lgkmcnt(0)
	v_lshlrev_b32_e32 v25, 16, v20
	v_mul_f32_e32 v24, v25, v24
	v_and_b32_e32 v20, 0xffff0000, v20
	v_and_b32_e32 v25, 0xffff0000, v32
	v_mul_f32_e32 v20, v20, v25
	v_cvt_pk_bf16_f32 v20, v24, v20
	v_lshlrev_b32_e32 v24, 16, v33
	v_lshlrev_b32_e32 v25, 16, v21
	v_mul_f32_e32 v24, v25, v24
	v_and_b32_e32 v21, 0xffff0000, v21
	v_and_b32_e32 v25, 0xffff0000, v33
	v_mul_f32_e32 v21, v21, v25
	v_cvt_pk_bf16_f32 v21, v24, v21
	v_lshlrev_b32_e32 v24, 16, v34
	v_lshlrev_b32_e32 v25, 16, v22
	v_mul_f32_e32 v24, v25, v24
	v_and_b32_e32 v22, 0xffff0000, v22
	v_and_b32_e32 v25, 0xffff0000, v34
	v_mul_f32_e32 v22, v22, v25
	v_cvt_pk_bf16_f32 v22, v24, v22
	v_lshlrev_b32_e32 v24, 16, v35
	v_lshlrev_b32_e32 v25, 16, v23
	v_mul_f32_e32 v24, v25, v24
	v_and_b32_e32 v23, 0xffff0000, v23
	v_and_b32_e32 v25, 0xffff0000, v35
	v_mul_f32_e32 v23, v23, v25
	v_cvt_pk_bf16_f32 v23, v24, v23
	v_lshlrev_b64 v[24:25], 11, v[162:163]
	v_lshl_add_u64 v[24:25], v[90:91], 0, v[24:25]
	global_store_dwordx4 v[24:25], v[20:23], off sc0 nt
	ds_read_b128 v[20:23], v209 offset:34816
	v_lshlrev_b32_e32 v24, 16, v28
	s_waitcnt lgkmcnt(0)
	v_lshlrev_b32_e32 v25, 16, v20
	v_mul_f32_e32 v24, v25, v24
	v_and_b32_e32 v20, 0xffff0000, v20
	v_and_b32_e32 v25, 0xffff0000, v28
	v_mul_f32_e32 v20, v20, v25
	v_cvt_pk_bf16_f32 v20, v24, v20
	v_lshlrev_b32_e32 v24, 16, v29
	v_lshlrev_b32_e32 v25, 16, v21
	v_mul_f32_e32 v24, v25, v24
	v_and_b32_e32 v21, 0xffff0000, v21
	v_and_b32_e32 v25, 0xffff0000, v29
	v_mul_f32_e32 v21, v21, v25
	v_cvt_pk_bf16_f32 v21, v24, v21
	v_lshlrev_b32_e32 v24, 16, v30
	v_lshlrev_b32_e32 v25, 16, v22
	v_mul_f32_e32 v24, v25, v24
	v_and_b32_e32 v22, 0xffff0000, v22
	v_and_b32_e32 v25, 0xffff0000, v30
	v_mul_f32_e32 v22, v22, v25
	v_cvt_pk_bf16_f32 v22, v24, v22
	v_lshlrev_b32_e32 v24, 16, v31
	v_lshlrev_b32_e32 v25, 16, v23
	v_mul_f32_e32 v24, v25, v24
	v_and_b32_e32 v23, 0xffff0000, v23
	v_and_b32_e32 v25, 0xffff0000, v31
	v_mul_f32_e32 v23, v23, v25
	v_cvt_pk_bf16_f32 v23, v24, v23
	v_lshlrev_b64 v[24:25], 11, v[160:161]
	v_lshl_add_u64 v[24:25], v[90:91], 0, v[24:25]
	global_store_dwordx4 v[24:25], v[20:23], off sc0 nt
	ds_read_b128 v[20:23], v210 offset:34816
	v_lshlrev_b32_e32 v24, 16, v16
	v_and_b32_e32 v16, 0xffff0000, v16
	s_waitcnt lgkmcnt(0)
	v_lshlrev_b32_e32 v25, 16, v20
	v_and_b32_e32 v20, 0xffff0000, v20
	v_mul_f32_e32 v24, v25, v24
	v_mul_f32_e32 v16, v20, v16
	v_cvt_pk_bf16_f32 v16, v24, v16
	v_lshlrev_b32_e32 v20, 16, v17
	v_lshlrev_b32_e32 v24, 16, v21
	v_and_b32_e32 v21, 0xffff0000, v21
	v_and_b32_e32 v17, 0xffff0000, v17
	v_mul_f32_e32 v20, v24, v20
	v_mul_f32_e32 v17, v21, v17
	v_cvt_pk_bf16_f32 v17, v20, v17
	v_lshlrev_b32_e32 v20, 16, v18
	v_lshlrev_b32_e32 v21, 16, v22
	v_mul_f32_e32 v20, v21, v20
	v_and_b32_e32 v21, 0xffff0000, v22
	v_and_b32_e32 v18, 0xffff0000, v18
	v_mul_f32_e32 v18, v21, v18
	v_cvt_pk_bf16_f32 v18, v20, v18
	v_lshlrev_b32_e32 v20, 16, v19
	v_lshlrev_b32_e32 v21, 16, v23
	v_mul_f32_e32 v20, v21, v20
	v_and_b32_e32 v21, 0xffff0000, v23
	v_and_b32_e32 v19, 0xffff0000, v19
	v_mul_f32_e32 v19, v21, v19
	v_cvt_pk_bf16_f32 v19, v20, v19
	v_lshlrev_b64 v[20:21], 11, v[158:159]
	v_lshl_add_u64 v[20:21], v[90:91], 0, v[20:21]
	global_store_dwordx4 v[20:21], v[16:19], off sc0 nt
	ds_read_b128 v[16:19], v211 offset:34816
	v_lshlrev_b32_e32 v20, 16, v12
	v_and_b32_e32 v12, 0xffff0000, v12
	s_waitcnt lgkmcnt(0)
	v_lshlrev_b32_e32 v21, 16, v16
	v_and_b32_e32 v16, 0xffff0000, v16
	v_mul_f32_e32 v20, v21, v20
	v_mul_f32_e32 v12, v16, v12
	v_cvt_pk_bf16_f32 v12, v20, v12
	v_lshlrev_b32_e32 v16, 16, v13
	v_lshlrev_b32_e32 v20, 16, v17
	v_and_b32_e32 v17, 0xffff0000, v17
	v_and_b32_e32 v13, 0xffff0000, v13
	v_mul_f32_e32 v16, v20, v16
	v_mul_f32_e32 v13, v17, v13
	v_cvt_pk_bf16_f32 v13, v16, v13
	v_lshlrev_b32_e32 v16, 16, v14
	v_lshlrev_b32_e32 v17, 16, v18
	v_mul_f32_e32 v16, v17, v16
	v_and_b32_e32 v17, 0xffff0000, v18
	v_and_b32_e32 v14, 0xffff0000, v14
	v_mul_f32_e32 v14, v17, v14
	v_cvt_pk_bf16_f32 v14, v16, v14
	v_lshlrev_b32_e32 v16, 16, v15
	v_lshlrev_b32_e32 v17, 16, v19
	v_mul_f32_e32 v16, v17, v16
	v_and_b32_e32 v17, 0xffff0000, v19
	v_and_b32_e32 v15, 0xffff0000, v15
	v_mul_f32_e32 v15, v17, v15
	v_cvt_pk_bf16_f32 v15, v16, v15
	v_lshlrev_b64 v[16:17], 11, v[138:139]
	v_lshl_add_u64 v[16:17], v[90:91], 0, v[16:17]
	global_store_dwordx4 v[16:17], v[12:15], off sc0 nt
	ds_read_b128 v[12:15], v212 offset:34816
	v_lshlrev_b32_e32 v16, 16, v8
	v_and_b32_e32 v8, 0xffff0000, v8
	s_waitcnt lgkmcnt(0)
	v_lshlrev_b32_e32 v17, 16, v12
	v_and_b32_e32 v12, 0xffff0000, v12
	v_mul_f32_e32 v16, v17, v16
	v_mul_f32_e32 v8, v12, v8
	v_cvt_pk_bf16_f32 v8, v16, v8
	v_lshlrev_b32_e32 v12, 16, v9
	v_lshlrev_b32_e32 v16, 16, v13
	v_and_b32_e32 v13, 0xffff0000, v13
	v_and_b32_e32 v9, 0xffff0000, v9
	v_mul_f32_e32 v12, v16, v12
	v_mul_f32_e32 v9, v13, v9
	v_cvt_pk_bf16_f32 v9, v12, v9
	v_lshlrev_b32_e32 v12, 16, v10
	v_lshlrev_b32_e32 v13, 16, v14
	v_mul_f32_e32 v12, v13, v12
	v_and_b32_e32 v13, 0xffff0000, v14
	v_and_b32_e32 v10, 0xffff0000, v10
	v_mul_f32_e32 v10, v13, v10
	v_cvt_pk_bf16_f32 v10, v12, v10
	v_lshlrev_b32_e32 v12, 16, v11
	v_lshlrev_b32_e32 v13, 16, v15
	v_mul_f32_e32 v12, v13, v12
	v_and_b32_e32 v13, 0xffff0000, v15
	v_and_b32_e32 v11, 0xffff0000, v11
	v_mul_f32_e32 v11, v13, v11
	v_cvt_pk_bf16_f32 v11, v12, v11
	v_lshlrev_b64 v[12:13], 11, v[136:137]
	v_lshl_add_u64 v[12:13], v[90:91], 0, v[12:13]
	global_store_dwordx4 v[12:13], v[8:11], off sc0 nt
	ds_read_b128 v[8:11], v213 offset:34816
	v_lshlrev_b32_e32 v12, 16, v4
	v_and_b32_e32 v4, 0xffff0000, v4
	s_waitcnt lgkmcnt(0)
	v_lshlrev_b32_e32 v13, 16, v8
	v_and_b32_e32 v8, 0xffff0000, v8
	v_mul_f32_e32 v12, v13, v12
	v_mul_f32_e32 v4, v8, v4
	v_cvt_pk_bf16_f32 v4, v12, v4
	v_lshlrev_b32_e32 v8, 16, v5
	v_lshlrev_b32_e32 v12, 16, v9
	v_and_b32_e32 v9, 0xffff0000, v9
	v_and_b32_e32 v5, 0xffff0000, v5
	v_mul_f32_e32 v8, v12, v8
	v_mul_f32_e32 v5, v9, v5
	v_cvt_pk_bf16_f32 v5, v8, v5
	v_lshlrev_b32_e32 v8, 16, v6
	v_lshlrev_b32_e32 v9, 16, v10
	v_mul_f32_e32 v8, v9, v8
	v_and_b32_e32 v9, 0xffff0000, v10
	v_and_b32_e32 v6, 0xffff0000, v6
	v_mul_f32_e32 v6, v9, v6
	v_cvt_pk_bf16_f32 v6, v8, v6
	v_lshlrev_b32_e32 v8, 16, v7
	v_lshlrev_b32_e32 v9, 16, v11
	v_mul_f32_e32 v8, v9, v8
	v_and_b32_e32 v9, 0xffff0000, v11
	v_and_b32_e32 v7, 0xffff0000, v7
	v_mul_f32_e32 v7, v9, v7
	v_cvt_pk_bf16_f32 v7, v8, v7
	v_lshlrev_b64 v[8:9], 11, v[134:135]
	v_lshl_add_u64 v[8:9], v[90:91], 0, v[8:9]
	global_store_dwordx4 v[8:9], v[4:7], off sc0 nt
	ds_read_b128 v[4:7], v214 offset:34816
	v_lshlrev_b32_e32 v8, 16, v0
	v_and_b32_e32 v0, 0xffff0000, v0
	s_waitcnt lgkmcnt(0)
	v_lshlrev_b32_e32 v9, 16, v4
	v_and_b32_e32 v4, 0xffff0000, v4
	v_mul_f32_e32 v8, v9, v8
	v_mul_f32_e32 v0, v4, v0
	v_cvt_pk_bf16_f32 v0, v8, v0
	v_lshlrev_b32_e32 v4, 16, v1
	v_lshlrev_b32_e32 v8, 16, v5
	v_and_b32_e32 v5, 0xffff0000, v5
	v_and_b32_e32 v1, 0xffff0000, v1
	v_mul_f32_e32 v4, v8, v4
	v_mul_f32_e32 v1, v5, v1
	v_cvt_pk_bf16_f32 v1, v4, v1
	v_lshlrev_b32_e32 v4, 16, v2
	v_lshlrev_b32_e32 v5, 16, v6
	v_mul_f32_e32 v4, v5, v4
	v_and_b32_e32 v5, 0xffff0000, v6
	v_and_b32_e32 v2, 0xffff0000, v2
	v_mul_f32_e32 v2, v5, v2
	v_cvt_pk_bf16_f32 v2, v4, v2
	v_lshlrev_b32_e32 v4, 16, v3
	v_lshlrev_b32_e32 v5, 16, v7
	v_mul_f32_e32 v4, v5, v4
	v_and_b32_e32 v5, 0xffff0000, v7
	v_and_b32_e32 v3, 0xffff0000, v3
	v_mul_f32_e32 v3, v5, v3
	v_cvt_pk_bf16_f32 v3, v4, v3
	v_lshlrev_b64 v[4:5], 11, v[132:133]
	v_lshl_add_u64 v[4:5], v[90:91], 0, v[4:5]
	global_store_dwordx4 v[4:5], v[0:3], off sc0 nt
	s_cbranch_scc0 .LBB0_482
	s_mov_b32 s50, s24
	s_mov_b32 s52, s28

.LBB0_559:
	s_waitcnt lgkmcnt(0)
	v_pk_mul_f32 v[120:121], v[120:121], v[164:165] op_sel_hi:[1,0]
	s_bfe_u32 s8, s4, 0x20006
	v_mul_f32_e32 v145, 0x3d372713, v121
	v_mul_f32_e32 v145, v121, v145
	v_fma_f32 v145, v121, v145, v121
	v_mul_f32_e32 v145, 0x3f4c422a, v145
	s_lshl_b32 s4, s95, 8
	s_lshl_b32 s5, s8, 5
	v_pk_mul_f32 v[126:127], v[126:127], v[164:165] op_sel_hi:[1,0]
	v_pk_mul_f32 v[122:123], v[122:123], v[164:165] op_sel_hi:[1,0]
	v_mul_f32_e32 v145, 0xc038aa3b, v145
	s_or_b32 s4, s5, s4
	v_exp_f32_e32 v145, v145
	v_mul_f32_e32 v147, 0x3d372713, v126
	v_mul_f32_e32 v148, 0x3d372713, v122
	v_lshl_or_b32 v160, v162, 3, s4
	v_lshlrev_b64 v[142:143], 12, v[158:159]
	v_mul_f32_e32 v147, v126, v147
	v_mul_f32_e32 v148, v122, v148
	v_ashrrev_i32_e32 v161, 31, v160
	v_lshl_add_u64 v[142:143], s[70:71], 0, v[142:143]
	v_fma_f32 v147, v126, v147, v126
	v_fma_f32 v148, v122, v148, v122
	v_cmp_eq_u32_e32 vcc, 0, v162
	v_lshl_add_u64 v[162:163], v[160:161], 1, v[142:143]
	v_pk_mul_f32 v[124:125], v[124:125], v[164:165] op_sel_hi:[1,0]
	v_mul_f32_e32 v143, 0x3d372713, v120
	v_mul_f32_e32 v147, 0x3f4c422a, v147
	v_mul_f32_e32 v148, 0x3f4c422a, v148
	v_mul_f32_e32 v142, 0x3d372713, v124
	v_mul_f32_e32 v143, v120, v143
	v_add_f32_e32 v145, 1.0, v145
	v_mul_f32_e32 v147, 0xc038aa3b, v147
	v_mul_f32_e32 v148, 0xc038aa3b, v148
	v_mul_f32_e32 v142, v124, v142
	v_fma_f32 v143, v120, v143, v120
	v_mul_f32_e32 v144, 0x3d372713, v125
	v_rcp_f32_e32 v145, v145
	v_exp_f32_e32 v147, v147
	v_exp_f32_e32 v148, v148
	v_fma_f32 v142, v124, v142, v124
	v_mul_f32_e32 v143, 0x3f4c422a, v143
	v_mul_f32_e32 v144, v125, v144
	v_mul_f32_e32 v142, 0x3f4c422a, v142
	v_mul_f32_e32 v143, 0xc038aa3b, v143
	v_fma_f32 v144, v125, v144, v125
	v_mul_f32_e32 v142, 0xc038aa3b, v142
	v_exp_f32_e32 v143, v143
	v_mul_f32_e32 v144, 0x3f4c422a, v144
	v_mul_f32_e32 v149, 0x3d372713, v123
	v_exp_f32_e32 v142, v142
	v_mul_f32_e32 v144, 0xc038aa3b, v144
	v_mul_f32_e32 v145, v121, v145
	v_add_f32_e32 v121, 1.0, v147
	v_add_f32_e32 v147, 1.0, v148
	v_mul_f32_e32 v148, 0x3d372713, v127
	v_mul_f32_e32 v149, v123, v149
	v_exp_f32_e32 v144, v144
	v_mul_f32_e32 v148, v127, v148
	v_fma_f32 v149, v123, v149, v123
	v_fma_f32 v148, v127, v148, v127
	v_mul_f32_e32 v149, 0x3f4c422a, v149
	v_add_f32_e32 v143, 1.0, v143
	v_mul_f32_e32 v148, 0x3f4c422a, v148
	v_mul_f32_e32 v149, 0xc038aa3b, v149
	v_add_f32_e32 v142, 1.0, v142
	v_rcp_f32_e32 v143, v143
	v_mul_f32_e32 v148, 0xc038aa3b, v148
	v_exp_f32_e32 v149, v149
	v_rcp_f32_e32 v142, v142
	v_add_f32_e32 v144, 1.0, v144
	v_exp_f32_e32 v148, v148
	v_rcp_f32_e32 v144, v144
	v_rcp_f32_e32 v147, v147
	v_rcp_f32_e32 v121, v121
	v_mul_f32_e32 v143, v120, v143
	v_add_f32_e32 v149, 1.0, v149
	v_mul_f32_e32 v146, v124, v142
	v_add_f32_e32 v148, 1.0, v148
	v_rcp_f32_e32 v149, v149
	v_fma_f32 v124, v124, v142, v143
	v_mul_f32_e32 v120, v125, v144
	v_rcp_f32_e32 v148, v148
	v_mul_f32_e32 v147, v122, v147
	v_add_f32_e32 v124, 0, v124
	v_fma_f32 v125, v125, v144, v145
	v_mul_f32_e32 v150, v126, v121
	v_mul_f32_e32 v142, v143, v143
	v_add_f32_e32 v124, v125, v124
	v_mul_f32_e32 v125, v145, v145
	v_fma_f32 v121, v126, v121, v147
	v_fmac_f32_e32 v142, v146, v146
	v_fmac_f32_e32 v125, v120, v120
	v_add_f32_e32 v121, v121, v124
	v_mul_f32_e32 v124, v147, v147
	v_mul_f32_e32 v123, v123, v149
	v_add_f32_e32 v125, v142, v125
	v_fmac_f32_e32 v124, v150, v150
	v_add_f32_e32 v124, v124, v125
	v_fma_f32 v125, v127, v148, v123
	v_mul_f32_e32 v122, v127, v148
	v_add_f32_e32 v125, v125, v121
	v_mul_f32_e32 v121, v123, v123
	v_fmac_f32_e32 v121, v122, v122
	v_add_f32_e32 v124, v121, v124
	v_cvt_pk_bf16_f32 v120, v146, v120
	v_cvt_pk_bf16_f32 v121, v150, v122
	v_cvt_pk_bf16_f32 v122, v143, v145
	v_cvt_pk_bf16_f32 v123, v147, v123
	v_pk_mul_f32 v[112:113], v[112:113], v[164:165] op_sel_hi:[1,0]
	global_store_dwordx4 v[162:163], v[120:123], off sc0 nt
	v_pk_mul_f32 v[118:119], v[118:119], v[164:165] op_sel_hi:[1,0]
	v_pk_mul_f32 v[114:115], v[114:115], v[164:165] op_sel_hi:[1,0]
	v_mul_f32_e32 v123, 0x3d372713, v113
	v_mul_f32_e32 v123, v113, v123
	v_fma_f32 v123, v113, v123, v113
	v_mul_f32_e32 v123, 0x3f4c422a, v123
	v_mul_f32_e32 v123, 0xc038aa3b, v123
	v_exp_f32_e32 v123, v123
	v_mul_f32_e32 v127, 0x3d372713, v118
	v_mul_f32_e32 v142, 0x3d372713, v114
	v_mul_f32_e32 v127, v118, v127
	v_mul_f32_e32 v142, v114, v142
	v_fma_f32 v127, v118, v127, v118
	v_fma_f32 v142, v114, v142, v114
	v_pk_mul_f32 v[116:117], v[116:117], v[164:165] op_sel_hi:[1,0]
	v_mul_f32_e32 v121, 0x3d372713, v112
	v_mul_f32_e32 v127, 0x3f4c422a, v127
	v_mul_f32_e32 v142, 0x3f4c422a, v142
	v_mul_f32_e32 v120, 0x3d372713, v116
	v_mul_f32_e32 v121, v112, v121
	v_add_f32_e32 v123, 1.0, v123
	v_mul_f32_e32 v127, 0xc038aa3b, v127
	v_mul_f32_e32 v142, 0xc038aa3b, v142
	v_mul_f32_e32 v120, v116, v120
	v_fma_f32 v121, v112, v121, v112
	v_mul_f32_e32 v122, 0x3d372713, v117
	v_rcp_f32_e32 v123, v123
	v_exp_f32_e32 v127, v127
	v_exp_f32_e32 v142, v142
	v_fma_f32 v120, v116, v120, v116
	v_mul_f32_e32 v121, 0x3f4c422a, v121
	v_mul_f32_e32 v122, v117, v122
	v_mul_f32_e32 v120, 0x3f4c422a, v120
	v_mul_f32_e32 v121, 0xc038aa3b, v121
	v_fma_f32 v122, v117, v122, v117
	v_mul_f32_e32 v120, 0xc038aa3b, v120
	v_exp_f32_e32 v121, v121
	v_mul_f32_e32 v122, 0x3f4c422a, v122
	v_mul_f32_e32 v143, 0x3d372713, v115
	v_exp_f32_e32 v120, v120
	v_mul_f32_e32 v122, 0xc038aa3b, v122
	v_mul_f32_e32 v113, v113, v123
	v_add_f32_e32 v123, 1.0, v127
	v_add_f32_e32 v127, 1.0, v142
	v_mul_f32_e32 v142, 0x3d372713, v119
	v_mul_f32_e32 v143, v115, v143
	v_exp_f32_e32 v122, v122
	v_mul_f32_e32 v142, v119, v142
	v_fma_f32 v143, v115, v143, v115
	v_fma_f32 v142, v119, v142, v119
	v_mul_f32_e32 v143, 0x3f4c422a, v143
	v_add_f32_e32 v121, 1.0, v121
	v_mul_f32_e32 v142, 0x3f4c422a, v142
	v_mul_f32_e32 v143, 0xc038aa3b, v143
	v_add_f32_e32 v120, 1.0, v120
	v_rcp_f32_e32 v121, v121
	v_mul_f32_e32 v142, 0xc038aa3b, v142
	v_exp_f32_e32 v143, v143
	v_rcp_f32_e32 v120, v120
	v_add_f32_e32 v122, 1.0, v122
	v_exp_f32_e32 v142, v142
	v_rcp_f32_e32 v122, v122
	v_rcp_f32_e32 v127, v127
	v_rcp_f32_e32 v123, v123
	v_mul_f32_e32 v112, v112, v121
	v_add_f32_e32 v143, 1.0, v143
	v_mul_f32_e32 v126, v116, v120
	v_add_f32_e32 v142, 1.0, v142
	v_rcp_f32_e32 v143, v143
	v_fma_f32 v116, v116, v120, v112
	v_mul_f32_e32 v121, v117, v122
	v_rcp_f32_e32 v142, v142
	v_mul_f32_e32 v114, v114, v127
	v_add_f32_e32 v116, v116, v125
	v_mul_f32_e32 v120, v112, v112
	v_fma_f32 v117, v117, v122, v113
	v_mul_f32_e32 v144, v118, v123
	v_fmac_f32_e32 v120, v126, v126
	v_add_f32_e32 v116, v117, v116
	v_mul_f32_e32 v117, v113, v113
	v_fma_f32 v118, v118, v123, v114
	v_add_f32_e32 v120, v120, v124
	v_fmac_f32_e32 v117, v121, v121
	v_add_f32_e32 v116, v118, v116
	v_mul_f32_e32 v118, v114, v114
	v_mul_f32_e32 v115, v115, v143
	v_add_f32_e32 v117, v117, v120
	v_fmac_f32_e32 v118, v144, v144
	v_add_f32_e32 v117, v118, v117
	v_fma_f32 v118, v119, v142, v115
	v_mul_f32_e32 v127, v119, v142
	v_add_f32_e32 v120, v118, v116
	v_mul_f32_e32 v116, v115, v115
	v_fmac_f32_e32 v116, v127, v127
	v_add_f32_e32 v122, v116, v117
	v_cvt_pk_bf16_f32 v116, v126, v121
	ds_bpermute_b32 v121, v168, v120
	ds_bpermute_b32 v123, v168, v122
	v_cvt_pk_bf16_f32 v117, v144, v127
	v_cvt_pk_bf16_f32 v118, v112, v113
	v_cvt_pk_bf16_f32 v119, v114, v115
	s_waitcnt lgkmcnt(0)
	v_add_f32_e32 v112, v120, v121
	v_add_f32_e32 v114, v122, v123
	ds_bpermute_b32 v113, v167, v112
	ds_bpermute_b32 v115, v167, v114
	s_cmp_gt_i32 s95, 3
	s_cselect_b64 s[4:5], -1, 0
	s_and_b64 s[58:59], s[4:5], vcc
	global_store_dwordx4 v[162:163], v[116:119], off offset:256 sc0 nt
	s_and_saveexec_b64 s[6:7], s[58:59]
	s_cbranch_execz .LBB0_561
	s_waitcnt lgkmcnt(0)
	v_add_f32_e32 v114, v114, v115
	v_add_f32_e32 v115, v112, v113
	s_lshl_b32 s4, s95, 2
	v_lshlrev_b64 v[112:113], 7, v[158:159]
	s_add_i32 s38, s4, -16
	v_lshl_add_u64 v[112:113], s[72:73], 0, v[112:113]
	v_lshl_add_u64 v[112:113], s[38:39], 2, v[112:113]
	s_lshl_b32 s38, s8, 2
	v_lshl_add_u64 v[112:113], v[112:113], 0, s[38:39]
	global_store_dword v[112:113], v115, off
	global_store_dword v[112:113], v114, off offset:64

.LBB0_565:
	s_waitcnt lgkmcnt(0)
	v_pk_mul_f32 v[108:109], v[108:109], v[116:117] op_sel_hi:[1,0]
	v_lshlrev_b64 v[114:115], 12, v[112:113]
	v_mul_f32_e32 v117, 0x3d372713, v108
	v_mul_f32_e32 v117, v108, v117
	v_fma_f32 v117, v108, v117, v108
	v_mul_f32_e32 v117, 0x3f4c422a, v117
	v_mul_f32_e32 v117, 0xc038aa3b, v117
	v_exp_f32_e32 v117, v117
	v_mul_f32_e32 v119, 0x3d372713, v109
	v_mul_f32_e32 v119, v109, v119
	v_fma_f32 v119, v109, v119, v109
	v_pk_mul_f32 v[104:105], v[104:105], v[116:117] op_sel_hi:[1,0]
	v_pk_mul_f32 v[110:111], v[110:111], v[116:117] op_sel_hi:[1,0]
	v_mul_f32_e32 v120, 0x3d372713, v105
	v_mul_f32_e32 v120, v105, v120
	v_fma_f32 v120, v105, v120, v105
	v_mul_f32_e32 v120, 0x3f4c422a, v120
	v_pk_mul_f32 v[106:107], v[106:107], v[116:117] op_sel_hi:[1,0]
	v_mul_f32_e32 v120, 0xc038aa3b, v120
	v_exp_f32_e32 v120, v120
	v_mul_f32_e32 v122, 0x3d372713, v110
	v_mul_f32_e32 v123, 0x3d372713, v106
	v_mul_f32_e32 v122, v110, v122
	v_mul_f32_e32 v123, v106, v123
	v_mul_f32_e32 v118, 0x3d372713, v104
	v_fma_f32 v122, v110, v122, v110
	v_fma_f32 v123, v106, v123, v106
	v_mul_f32_e32 v118, v104, v118
	v_mul_f32_e32 v122, 0x3f4c422a, v122
	v_mul_f32_e32 v123, 0x3f4c422a, v123
	v_fma_f32 v118, v104, v118, v104
	v_add_f32_e32 v120, 1.0, v120
	v_mul_f32_e32 v122, 0xc038aa3b, v122
	v_mul_f32_e32 v123, 0xc038aa3b, v123
	v_mul_f32_e32 v118, 0x3f4c422a, v118
	v_rcp_f32_e32 v120, v120
	v_exp_f32_e32 v122, v122
	v_exp_f32_e32 v123, v123
	v_mul_f32_e32 v118, 0xc038aa3b, v118
	v_exp_f32_e32 v118, v118
	v_mul_f32_e32 v119, 0x3f4c422a, v119
	v_mul_f32_e32 v119, 0xc038aa3b, v119
	v_mul_f32_e32 v124, 0x3d372713, v107
	v_exp_f32_e32 v119, v119
	v_mul_f32_e32 v120, v105, v120
	v_add_f32_e32 v105, 1.0, v122
	v_add_f32_e32 v122, 1.0, v123
	v_mul_f32_e32 v123, 0x3d372713, v111
	v_mul_f32_e32 v124, v107, v124
	v_mul_f32_e32 v123, v111, v123
	v_fma_f32 v124, v107, v124, v107
	v_add_f32_e32 v118, 1.0, v118
	v_fma_f32 v123, v111, v123, v111
	v_mul_f32_e32 v124, 0x3f4c422a, v124
	v_add_f32_e32 v117, 1.0, v117
	v_rcp_f32_e32 v118, v118
	v_mul_f32_e32 v123, 0x3f4c422a, v123
	v_mul_f32_e32 v124, 0xc038aa3b, v124
	v_rcp_f32_e32 v117, v117
	v_add_f32_e32 v119, 1.0, v119
	v_mul_f32_e32 v123, 0xc038aa3b, v123
	v_exp_f32_e32 v124, v124
	v_rcp_f32_e32 v119, v119
	v_exp_f32_e32 v123, v123
	v_rcp_f32_e32 v122, v122
	v_mul_f32_e32 v118, v104, v118
	v_rcp_f32_e32 v105, v105
	v_mul_f32_e32 v121, v108, v117
	v_add_f32_e32 v124, 1.0, v124
	v_fma_f32 v108, v108, v117, v118
	v_mul_f32_e32 v104, v109, v119
	v_add_f32_e32 v123, 1.0, v123
	v_rcp_f32_e32 v124, v124
	v_add_f32_e32 v108, 0, v108
	v_mul_f32_e32 v117, v118, v118
	v_fma_f32 v109, v109, v119, v120
	v_rcp_f32_e32 v123, v123
	v_mul_f32_e32 v122, v106, v122
	v_fmac_f32_e32 v117, v121, v121
	v_add_f32_e32 v108, v109, v108
	v_mul_f32_e32 v109, v120, v120
	v_mul_f32_e32 v125, v110, v105
	v_fmac_f32_e32 v109, v104, v104
	v_fma_f32 v105, v110, v105, v122
	v_pk_mul_f32 v[96:97], v[96:97], v[116:117] op_sel_hi:[1,0]
	v_add_f32_e32 v109, v117, v109
	v_add_f32_e32 v105, v105, v108
	v_mul_f32_e32 v108, v122, v122
	v_pk_mul_f32 v[100:101], v[100:101], v[116:117] op_sel_hi:[1,0]
	v_pk_mul_f32 v[102:103], v[102:103], v[116:117] op_sel_hi:[1,0]
	v_pk_mul_f32 v[98:99], v[98:99], v[116:117] op_sel_hi:[1,0]
	v_mul_f32_e32 v117, 0x3d372713, v97
	v_mul_f32_e32 v107, v107, v124
	v_fmac_f32_e32 v108, v125, v125
	v_mul_f32_e32 v117, v97, v117
	v_add_f32_e32 v108, v108, v109
	v_fma_f32 v109, v111, v123, v107
	v_fma_f32 v117, v97, v117, v97
	v_mul_f32_e32 v106, v111, v123
	v_add_f32_e32 v109, v109, v105
	v_mul_f32_e32 v105, v107, v107
	v_mul_f32_e32 v117, 0x3f4c422a, v117
	v_fmac_f32_e32 v105, v106, v106
	v_mul_f32_e32 v117, 0xc038aa3b, v117
	v_add_f32_e32 v108, v105, v108
	v_cvt_pk_bf16_f32 v104, v121, v104
	v_cvt_pk_bf16_f32 v105, v125, v106
	v_cvt_pk_bf16_f32 v106, v118, v120
	v_exp_f32_e32 v117, v117
	v_mul_f32_e32 v119, 0x3d372713, v102
	v_mul_f32_e32 v120, 0x3d372713, v98
	v_mul_f32_e32 v119, v102, v119
	v_mul_f32_e32 v120, v98, v120
	v_fma_f32 v119, v102, v119, v102
	v_fma_f32 v120, v98, v120, v98
	v_mul_f32_e32 v111, 0x3d372713, v96
	v_mul_f32_e32 v119, 0x3f4c422a, v119
	v_mul_f32_e32 v120, 0x3f4c422a, v120
	v_mul_f32_e32 v110, 0x3d372713, v100
	v_mul_f32_e32 v111, v96, v111
	v_add_f32_e32 v117, 1.0, v117
	v_mul_f32_e32 v119, 0xc038aa3b, v119
	v_mul_f32_e32 v120, 0xc038aa3b, v120
	v_mul_f32_e32 v110, v100, v110
	v_fma_f32 v111, v96, v111, v96
	v_mul_f32_e32 v116, 0x3d372713, v101
	v_rcp_f32_e32 v117, v117
	v_exp_f32_e32 v119, v119
	v_exp_f32_e32 v120, v120
	v_mul_f32_e32 v121, 0x3d372713, v99
	v_fma_f32 v110, v100, v110, v100
	v_mul_f32_e32 v111, 0x3f4c422a, v111
	v_mul_f32_e32 v116, v101, v116
	v_mul_f32_e32 v121, v99, v121
	v_mul_f32_e32 v110, 0x3f4c422a, v110
	v_mul_f32_e32 v111, 0xc038aa3b, v111
	v_fma_f32 v116, v101, v116, v101
	v_fma_f32 v121, v99, v121, v99
	v_mul_f32_e32 v110, 0xc038aa3b, v110
	v_exp_f32_e32 v111, v111
	v_mul_f32_e32 v116, 0x3f4c422a, v116
	v_mul_f32_e32 v121, 0x3f4c422a, v121
	v_exp_f32_e32 v110, v110
	v_mul_f32_e32 v116, 0xc038aa3b, v116
	v_mul_f32_e32 v117, v97, v117
	v_add_f32_e32 v97, 1.0, v119
	v_add_f32_e32 v119, 1.0, v120
	v_mul_f32_e32 v120, 0x3d372713, v103
	v_mul_f32_e32 v121, 0xc038aa3b, v121
	v_exp_f32_e32 v116, v116
	v_mul_f32_e32 v120, v103, v120
	v_exp_f32_e32 v121, v121
	v_fma_f32 v120, v103, v120, v103
	v_add_f32_e32 v111, 1.0, v111
	v_mul_f32_e32 v120, 0x3f4c422a, v120
	v_add_f32_e32 v110, 1.0, v110
	v_rcp_f32_e32 v111, v111
	v_mul_f32_e32 v120, 0xc038aa3b, v120
	v_rcp_f32_e32 v110, v110
	v_add_f32_e32 v116, 1.0, v116
	v_exp_f32_e32 v120, v120
	v_rcp_f32_e32 v119, v119
	v_add_f32_e32 v121, 1.0, v121
	v_rcp_f32_e32 v116, v116
	v_rcp_f32_e32 v121, v121
	v_rcp_f32_e32 v97, v97
	v_mul_f32_e32 v111, v96, v111
	v_add_f32_e32 v120, 1.0, v120
	v_mul_f32_e32 v119, v98, v119
	v_fma_f32 v98, v100, v110, v111
	v_mul_f32_e32 v118, v100, v110
	v_rcp_f32_e32 v120, v120
	v_mul_f32_e32 v121, v99, v121
	v_add_f32_e32 v98, v98, v109
	v_mul_f32_e32 v99, v111, v111
	v_fma_f32 v100, v101, v116, v117
	v_cvt_pk_bf16_f32 v107, v122, v107
	v_mul_f32_e32 v96, v101, v116
	v_mul_f32_e32 v122, v102, v97
	v_fmac_f32_e32 v99, v118, v118
	v_add_f32_e32 v98, v100, v98
	v_mul_f32_e32 v100, v117, v117
	v_fma_f32 v97, v102, v97, v119
	v_add_f32_e32 v99, v99, v108
	v_fmac_f32_e32 v100, v96, v96
	v_add_f32_e32 v97, v97, v98
	v_mul_f32_e32 v98, v119, v119
	v_add_f32_e32 v99, v100, v99
	v_fmac_f32_e32 v98, v122, v122
	v_add_f32_e32 v98, v98, v99
	v_fma_f32 v99, v103, v120, v121
	v_mul_f32_e32 v123, v103, v120
	v_add_f32_e32 v97, v99, v97
	v_mul_f32_e32 v99, v121, v121
	v_fmac_f32_e32 v99, v123, v123
	v_add_f32_e32 v98, v99, v98
	ds_bpermute_b32 v101, v168, v97
	ds_bpermute_b32 v99, v168, v98
	v_lshl_add_u64 v[114:115], s[70:71], 0, v[114:115]
	v_lshl_add_u64 v[114:115], v[160:161], 1, v[114:115]
	global_store_dwordx4 v[114:115], v[104:107], off sc0 nt
	v_cvt_pk_bf16_f32 v100, v118, v96
	s_waitcnt lgkmcnt(0)
	v_add_f32_e32 v96, v97, v101
	v_add_f32_e32 v98, v98, v99
	ds_bpermute_b32 v97, v167, v96
	ds_bpermute_b32 v99, v167, v98
	v_cvt_pk_bf16_f32 v101, v122, v123
	v_cvt_pk_bf16_f32 v102, v111, v117
	v_cvt_pk_bf16_f32 v103, v119, v121
	global_store_dwordx4 v[114:115], v[100:103], off offset:256 sc0 nt
	s_and_saveexec_b64 s[6:7], s[58:59]
	s_cbranch_execz .LBB0_567
	s_waitcnt lgkmcnt(0)
	v_add_f32_e32 v98, v98, v99
	v_add_f32_e32 v99, v96, v97
	s_lshl_b32 s4, s95, 2
	v_lshlrev_b64 v[96:97], 7, v[112:113]
	s_add_i32 s38, s4, -16
	v_lshl_add_u64 v[96:97], s[72:73], 0, v[96:97]
	v_lshl_add_u64 v[96:97], s[38:39], 2, v[96:97]
	s_lshl_b32 s38, s8, 2
	v_lshl_add_u64 v[96:97], v[96:97], 0, s[38:39]
	global_store_dword v[96:97], v99, off
	global_store_dword v[96:97], v98, off offset:64

.LBB0_571:
	s_waitcnt lgkmcnt(0)
	v_pk_mul_f32 v[92:93], v[92:93], v[100:101] op_sel_hi:[1,0]
	v_lshlrev_b64 v[98:99], 12, v[96:97]
	v_mul_f32_e32 v101, 0x3d372713, v92
	v_mul_f32_e32 v101, v92, v101
	v_fma_f32 v101, v92, v101, v92
	v_mul_f32_e32 v101, 0x3f4c422a, v101
	v_mul_f32_e32 v101, 0xc038aa3b, v101
	v_exp_f32_e32 v101, v101
	v_mul_f32_e32 v103, 0x3d372713, v93
	v_mul_f32_e32 v103, v93, v103
	v_fma_f32 v103, v93, v103, v93
	v_pk_mul_f32 v[88:89], v[88:89], v[100:101] op_sel_hi:[1,0]
	v_pk_mul_f32 v[94:95], v[94:95], v[100:101] op_sel_hi:[1,0]
	v_mul_f32_e32 v104, 0x3d372713, v89
	v_mul_f32_e32 v104, v89, v104
	v_fma_f32 v104, v89, v104, v89
	v_mul_f32_e32 v104, 0x3f4c422a, v104
	v_pk_mul_f32 v[90:91], v[90:91], v[100:101] op_sel_hi:[1,0]
	v_mul_f32_e32 v104, 0xc038aa3b, v104
	v_exp_f32_e32 v104, v104
	v_mul_f32_e32 v106, 0x3d372713, v94
	v_mul_f32_e32 v107, 0x3d372713, v90
	v_mul_f32_e32 v106, v94, v106
	v_mul_f32_e32 v107, v90, v107
	v_mul_f32_e32 v102, 0x3d372713, v88
	v_fma_f32 v106, v94, v106, v94
	v_fma_f32 v107, v90, v107, v90
	v_mul_f32_e32 v102, v88, v102
	v_mul_f32_e32 v106, 0x3f4c422a, v106
	v_mul_f32_e32 v107, 0x3f4c422a, v107
	v_fma_f32 v102, v88, v102, v88
	v_add_f32_e32 v104, 1.0, v104
	v_mul_f32_e32 v106, 0xc038aa3b, v106
	v_mul_f32_e32 v107, 0xc038aa3b, v107
	v_mul_f32_e32 v102, 0x3f4c422a, v102
	v_rcp_f32_e32 v104, v104
	v_exp_f32_e32 v106, v106
	v_exp_f32_e32 v107, v107
	v_mul_f32_e32 v102, 0xc038aa3b, v102
	v_exp_f32_e32 v102, v102
	v_mul_f32_e32 v103, 0x3f4c422a, v103
	v_mul_f32_e32 v103, 0xc038aa3b, v103
	v_mul_f32_e32 v108, 0x3d372713, v91
	v_exp_f32_e32 v103, v103
	v_mul_f32_e32 v104, v89, v104
	v_add_f32_e32 v89, 1.0, v106
	v_add_f32_e32 v106, 1.0, v107
	v_mul_f32_e32 v107, 0x3d372713, v95
	v_mul_f32_e32 v108, v91, v108
	v_mul_f32_e32 v107, v95, v107
	v_fma_f32 v108, v91, v108, v91
	v_add_f32_e32 v102, 1.0, v102
	v_fma_f32 v107, v95, v107, v95
	v_mul_f32_e32 v108, 0x3f4c422a, v108
	v_add_f32_e32 v101, 1.0, v101
	v_rcp_f32_e32 v102, v102
	v_mul_f32_e32 v107, 0x3f4c422a, v107
	v_mul_f32_e32 v108, 0xc038aa3b, v108
	v_rcp_f32_e32 v101, v101
	v_add_f32_e32 v103, 1.0, v103
	v_mul_f32_e32 v107, 0xc038aa3b, v107
	v_exp_f32_e32 v108, v108
	v_rcp_f32_e32 v103, v103
	v_exp_f32_e32 v107, v107
	v_rcp_f32_e32 v106, v106
	v_mul_f32_e32 v102, v88, v102
	v_rcp_f32_e32 v89, v89
	v_mul_f32_e32 v105, v92, v101
	v_add_f32_e32 v108, 1.0, v108
	v_fma_f32 v92, v92, v101, v102
	v_mul_f32_e32 v88, v93, v103
	v_add_f32_e32 v107, 1.0, v107
	v_rcp_f32_e32 v108, v108
	v_add_f32_e32 v92, 0, v92
	v_mul_f32_e32 v101, v102, v102
	v_fma_f32 v93, v93, v103, v104
	v_rcp_f32_e32 v107, v107
	v_mul_f32_e32 v106, v90, v106
	v_fmac_f32_e32 v101, v105, v105
	v_add_f32_e32 v92, v93, v92
	v_mul_f32_e32 v93, v104, v104
	v_mul_f32_e32 v109, v94, v89
	v_fmac_f32_e32 v93, v88, v88
	v_fma_f32 v89, v94, v89, v106
	v_pk_mul_f32 v[80:81], v[80:81], v[100:101] op_sel_hi:[1,0]
	v_add_f32_e32 v93, v101, v93
	v_add_f32_e32 v89, v89, v92
	v_mul_f32_e32 v92, v106, v106
	v_pk_mul_f32 v[84:85], v[84:85], v[100:101] op_sel_hi:[1,0]
	v_pk_mul_f32 v[86:87], v[86:87], v[100:101] op_sel_hi:[1,0]
	v_pk_mul_f32 v[82:83], v[82:83], v[100:101] op_sel_hi:[1,0]
	v_mul_f32_e32 v101, 0x3d372713, v81
	v_mul_f32_e32 v91, v91, v108
	v_fmac_f32_e32 v92, v109, v109
	v_mul_f32_e32 v101, v81, v101
	v_add_f32_e32 v92, v92, v93
	v_fma_f32 v93, v95, v107, v91
	v_fma_f32 v101, v81, v101, v81
	v_mul_f32_e32 v90, v95, v107
	v_add_f32_e32 v93, v93, v89
	v_mul_f32_e32 v89, v91, v91
	v_mul_f32_e32 v101, 0x3f4c422a, v101
	v_fmac_f32_e32 v89, v90, v90
	v_mul_f32_e32 v101, 0xc038aa3b, v101
	v_add_f32_e32 v92, v89, v92
	v_cvt_pk_bf16_f32 v88, v105, v88
	v_cvt_pk_bf16_f32 v89, v109, v90
	v_cvt_pk_bf16_f32 v90, v102, v104
	v_exp_f32_e32 v101, v101
	v_mul_f32_e32 v103, 0x3d372713, v86
	v_mul_f32_e32 v104, 0x3d372713, v82
	v_mul_f32_e32 v103, v86, v103
	v_mul_f32_e32 v104, v82, v104
	v_fma_f32 v103, v86, v103, v86
	v_fma_f32 v104, v82, v104, v82
	v_mul_f32_e32 v95, 0x3d372713, v80
	v_mul_f32_e32 v103, 0x3f4c422a, v103
	v_mul_f32_e32 v104, 0x3f4c422a, v104
	v_mul_f32_e32 v94, 0x3d372713, v84
	v_mul_f32_e32 v95, v80, v95
	v_add_f32_e32 v101, 1.0, v101
	v_mul_f32_e32 v103, 0xc038aa3b, v103
	v_mul_f32_e32 v104, 0xc038aa3b, v104
	v_mul_f32_e32 v94, v84, v94
	v_fma_f32 v95, v80, v95, v80
	v_mul_f32_e32 v100, 0x3d372713, v85
	v_rcp_f32_e32 v101, v101
	v_exp_f32_e32 v103, v103
	v_exp_f32_e32 v104, v104
	v_mul_f32_e32 v105, 0x3d372713, v83
	v_fma_f32 v94, v84, v94, v84
	v_mul_f32_e32 v95, 0x3f4c422a, v95
	v_mul_f32_e32 v100, v85, v100
	v_mul_f32_e32 v105, v83, v105
	v_mul_f32_e32 v94, 0x3f4c422a, v94
	v_mul_f32_e32 v95, 0xc038aa3b, v95
	v_fma_f32 v100, v85, v100, v85
	v_fma_f32 v105, v83, v105, v83
	v_mul_f32_e32 v94, 0xc038aa3b, v94
	v_exp_f32_e32 v95, v95
	v_mul_f32_e32 v100, 0x3f4c422a, v100
	v_mul_f32_e32 v105, 0x3f4c422a, v105
	v_exp_f32_e32 v94, v94
	v_mul_f32_e32 v100, 0xc038aa3b, v100
	v_mul_f32_e32 v101, v81, v101
	v_add_f32_e32 v81, 1.0, v103
	v_add_f32_e32 v103, 1.0, v104
	v_mul_f32_e32 v104, 0x3d372713, v87
	v_mul_f32_e32 v105, 0xc038aa3b, v105
	v_exp_f32_e32 v100, v100
	v_mul_f32_e32 v104, v87, v104
	v_exp_f32_e32 v105, v105
	v_fma_f32 v104, v87, v104, v87
	v_add_f32_e32 v95, 1.0, v95
	v_mul_f32_e32 v104, 0x3f4c422a, v104
	v_add_f32_e32 v94, 1.0, v94
	v_rcp_f32_e32 v95, v95
	v_mul_f32_e32 v104, 0xc038aa3b, v104
	v_rcp_f32_e32 v94, v94
	v_add_f32_e32 v100, 1.0, v100
	v_exp_f32_e32 v104, v104
	v_rcp_f32_e32 v103, v103
	v_add_f32_e32 v105, 1.0, v105
	v_rcp_f32_e32 v100, v100
	v_rcp_f32_e32 v105, v105
	v_rcp_f32_e32 v81, v81
	v_mul_f32_e32 v95, v80, v95
	v_add_f32_e32 v104, 1.0, v104
	v_mul_f32_e32 v103, v82, v103
	v_fma_f32 v82, v84, v94, v95
	v_mul_f32_e32 v102, v84, v94
	v_rcp_f32_e32 v104, v104
	v_mul_f32_e32 v105, v83, v105
	v_add_f32_e32 v82, v82, v93
	v_mul_f32_e32 v83, v95, v95
	v_fma_f32 v84, v85, v100, v101
	v_cvt_pk_bf16_f32 v91, v106, v91
	v_mul_f32_e32 v80, v85, v100
	v_mul_f32_e32 v106, v86, v81
	v_fmac_f32_e32 v83, v102, v102
	v_add_f32_e32 v82, v84, v82
	v_mul_f32_e32 v84, v101, v101
	v_fma_f32 v81, v86, v81, v103
	v_add_f32_e32 v83, v83, v92
	v_fmac_f32_e32 v84, v80, v80
	v_add_f32_e32 v81, v81, v82
	v_mul_f32_e32 v82, v103, v103
	v_add_f32_e32 v83, v84, v83
	v_fmac_f32_e32 v82, v106, v106
	v_add_f32_e32 v82, v82, v83
	v_fma_f32 v83, v87, v104, v105
	v_mul_f32_e32 v107, v87, v104
	v_add_f32_e32 v81, v83, v81
	v_mul_f32_e32 v83, v105, v105
	v_fmac_f32_e32 v83, v107, v107
	v_add_f32_e32 v82, v83, v82
	ds_bpermute_b32 v85, v168, v81
	ds_bpermute_b32 v83, v168, v82
	v_lshl_add_u64 v[98:99], s[70:71], 0, v[98:99]
	v_lshl_add_u64 v[98:99], v[160:161], 1, v[98:99]
	global_store_dwordx4 v[98:99], v[88:91], off sc0 nt
	v_cvt_pk_bf16_f32 v84, v102, v80
	s_waitcnt lgkmcnt(0)
	v_add_f32_e32 v80, v81, v85
	v_add_f32_e32 v82, v82, v83
	ds_bpermute_b32 v81, v167, v80
	ds_bpermute_b32 v83, v167, v82
	v_cvt_pk_bf16_f32 v85, v106, v107
	v_cvt_pk_bf16_f32 v86, v95, v101
	v_cvt_pk_bf16_f32 v87, v103, v105
	global_store_dwordx4 v[98:99], v[84:87], off offset:256 sc0 nt
	s_and_saveexec_b64 s[6:7], s[58:59]
	s_cbranch_execz .LBB0_573
	s_waitcnt lgkmcnt(0)
	v_add_f32_e32 v82, v82, v83
	v_add_f32_e32 v83, v80, v81
	s_lshl_b32 s4, s95, 2
	v_lshlrev_b64 v[80:81], 7, v[96:97]
	s_add_i32 s38, s4, -16
	v_lshl_add_u64 v[80:81], s[72:73], 0, v[80:81]
	v_lshl_add_u64 v[80:81], s[38:39], 2, v[80:81]
	s_lshl_b32 s38, s8, 2
	v_lshl_add_u64 v[80:81], v[80:81], 0, s[38:39]
	global_store_dword v[80:81], v83, off
	global_store_dword v[80:81], v82, off offset:64

.LBB0_577:
	s_waitcnt lgkmcnt(0)
	v_pk_mul_f32 v[76:77], v[76:77], v[84:85] op_sel_hi:[1,0]
	v_lshlrev_b64 v[82:83], 12, v[80:81]
	v_mul_f32_e32 v85, 0x3d372713, v76
	v_mul_f32_e32 v85, v76, v85
	v_fma_f32 v85, v76, v85, v76
	v_mul_f32_e32 v85, 0x3f4c422a, v85
	v_mul_f32_e32 v85, 0xc038aa3b, v85
	v_exp_f32_e32 v85, v85
	v_mul_f32_e32 v87, 0x3d372713, v77
	v_mul_f32_e32 v87, v77, v87
	v_fma_f32 v87, v77, v87, v77
	v_pk_mul_f32 v[72:73], v[72:73], v[84:85] op_sel_hi:[1,0]
	v_pk_mul_f32 v[78:79], v[78:79], v[84:85] op_sel_hi:[1,0]
	v_mul_f32_e32 v88, 0x3d372713, v73
	v_mul_f32_e32 v88, v73, v88
	v_fma_f32 v88, v73, v88, v73
	v_mul_f32_e32 v88, 0x3f4c422a, v88
	v_pk_mul_f32 v[74:75], v[74:75], v[84:85] op_sel_hi:[1,0]
	v_mul_f32_e32 v88, 0xc038aa3b, v88
	v_exp_f32_e32 v88, v88
	v_mul_f32_e32 v90, 0x3d372713, v78
	v_mul_f32_e32 v91, 0x3d372713, v74
	v_mul_f32_e32 v90, v78, v90
	v_mul_f32_e32 v91, v74, v91
	v_mul_f32_e32 v86, 0x3d372713, v72
	v_fma_f32 v90, v78, v90, v78
	v_fma_f32 v91, v74, v91, v74
	v_mul_f32_e32 v86, v72, v86
	v_mul_f32_e32 v90, 0x3f4c422a, v90
	v_mul_f32_e32 v91, 0x3f4c422a, v91
	v_fma_f32 v86, v72, v86, v72
	v_add_f32_e32 v88, 1.0, v88
	v_mul_f32_e32 v90, 0xc038aa3b, v90
	v_mul_f32_e32 v91, 0xc038aa3b, v91
	v_mul_f32_e32 v86, 0x3f4c422a, v86
	v_rcp_f32_e32 v88, v88
	v_exp_f32_e32 v90, v90
	v_exp_f32_e32 v91, v91
	v_mul_f32_e32 v86, 0xc038aa3b, v86
	v_exp_f32_e32 v86, v86
	v_mul_f32_e32 v87, 0x3f4c422a, v87
	v_mul_f32_e32 v87, 0xc038aa3b, v87
	v_mul_f32_e32 v92, 0x3d372713, v75
	v_exp_f32_e32 v87, v87
	v_mul_f32_e32 v88, v73, v88
	v_add_f32_e32 v73, 1.0, v90
	v_add_f32_e32 v90, 1.0, v91
	v_mul_f32_e32 v91, 0x3d372713, v79
	v_mul_f32_e32 v92, v75, v92
	v_mul_f32_e32 v91, v79, v91
	v_fma_f32 v92, v75, v92, v75
	v_add_f32_e32 v86, 1.0, v86
	v_fma_f32 v91, v79, v91, v79
	v_mul_f32_e32 v92, 0x3f4c422a, v92
	v_add_f32_e32 v85, 1.0, v85
	v_rcp_f32_e32 v86, v86
	v_mul_f32_e32 v91, 0x3f4c422a, v91
	v_mul_f32_e32 v92, 0xc038aa3b, v92
	v_rcp_f32_e32 v85, v85
	v_add_f32_e32 v87, 1.0, v87
	v_mul_f32_e32 v91, 0xc038aa3b, v91
	v_exp_f32_e32 v92, v92
	v_rcp_f32_e32 v87, v87
	v_exp_f32_e32 v91, v91
	v_rcp_f32_e32 v90, v90
	v_mul_f32_e32 v86, v72, v86
	v_rcp_f32_e32 v73, v73
	v_mul_f32_e32 v89, v76, v85
	v_add_f32_e32 v92, 1.0, v92
	v_fma_f32 v76, v76, v85, v86
	v_mul_f32_e32 v72, v77, v87
	v_add_f32_e32 v91, 1.0, v91
	v_rcp_f32_e32 v92, v92
	v_add_f32_e32 v76, 0, v76
	v_mul_f32_e32 v85, v86, v86
	v_fma_f32 v77, v77, v87, v88
	v_rcp_f32_e32 v91, v91
	v_mul_f32_e32 v90, v74, v90
	v_fmac_f32_e32 v85, v89, v89
	v_add_f32_e32 v76, v77, v76
	v_mul_f32_e32 v77, v88, v88
	v_mul_f32_e32 v93, v78, v73
	v_fmac_f32_e32 v77, v72, v72
	v_fma_f32 v73, v78, v73, v90
	v_pk_mul_f32 v[64:65], v[64:65], v[84:85] op_sel_hi:[1,0]
	v_add_f32_e32 v77, v85, v77
	v_add_f32_e32 v73, v73, v76
	v_mul_f32_e32 v76, v90, v90
	v_pk_mul_f32 v[68:69], v[68:69], v[84:85] op_sel_hi:[1,0]
	v_pk_mul_f32 v[70:71], v[70:71], v[84:85] op_sel_hi:[1,0]
	v_pk_mul_f32 v[66:67], v[66:67], v[84:85] op_sel_hi:[1,0]
	v_mul_f32_e32 v85, 0x3d372713, v65
	v_mul_f32_e32 v75, v75, v92
	v_fmac_f32_e32 v76, v93, v93
	v_mul_f32_e32 v85, v65, v85
	v_add_f32_e32 v76, v76, v77
	v_fma_f32 v77, v79, v91, v75
	v_fma_f32 v85, v65, v85, v65
	v_mul_f32_e32 v74, v79, v91
	v_add_f32_e32 v77, v77, v73
	v_mul_f32_e32 v73, v75, v75
	v_mul_f32_e32 v85, 0x3f4c422a, v85
	v_fmac_f32_e32 v73, v74, v74
	v_mul_f32_e32 v85, 0xc038aa3b, v85
	v_add_f32_e32 v76, v73, v76
	v_cvt_pk_bf16_f32 v72, v89, v72
	v_cvt_pk_bf16_f32 v73, v93, v74
	v_cvt_pk_bf16_f32 v74, v86, v88
	v_exp_f32_e32 v85, v85
	v_mul_f32_e32 v87, 0x3d372713, v70
	v_mul_f32_e32 v88, 0x3d372713, v66
	v_mul_f32_e32 v87, v70, v87
	v_mul_f32_e32 v88, v66, v88
	v_fma_f32 v87, v70, v87, v70
	v_fma_f32 v88, v66, v88, v66
	v_mul_f32_e32 v79, 0x3d372713, v64
	v_mul_f32_e32 v87, 0x3f4c422a, v87
	v_mul_f32_e32 v88, 0x3f4c422a, v88
	v_mul_f32_e32 v78, 0x3d372713, v68
	v_mul_f32_e32 v79, v64, v79
	v_add_f32_e32 v85, 1.0, v85
	v_mul_f32_e32 v87, 0xc038aa3b, v87
	v_mul_f32_e32 v88, 0xc038aa3b, v88
	v_mul_f32_e32 v78, v68, v78
	v_fma_f32 v79, v64, v79, v64
	v_mul_f32_e32 v84, 0x3d372713, v69
	v_rcp_f32_e32 v85, v85
	v_exp_f32_e32 v87, v87
	v_exp_f32_e32 v88, v88
	v_mul_f32_e32 v89, 0x3d372713, v67
	v_fma_f32 v78, v68, v78, v68
	v_mul_f32_e32 v79, 0x3f4c422a, v79
	v_mul_f32_e32 v84, v69, v84
	v_mul_f32_e32 v89, v67, v89
	v_mul_f32_e32 v78, 0x3f4c422a, v78
	v_mul_f32_e32 v79, 0xc038aa3b, v79
	v_fma_f32 v84, v69, v84, v69
	v_fma_f32 v89, v67, v89, v67
	v_mul_f32_e32 v78, 0xc038aa3b, v78
	v_exp_f32_e32 v79, v79
	v_mul_f32_e32 v84, 0x3f4c422a, v84
	v_mul_f32_e32 v89, 0x3f4c422a, v89
	v_exp_f32_e32 v78, v78
	v_mul_f32_e32 v84, 0xc038aa3b, v84
	v_mul_f32_e32 v85, v65, v85
	v_add_f32_e32 v65, 1.0, v87
	v_add_f32_e32 v87, 1.0, v88
	v_mul_f32_e32 v88, 0x3d372713, v71
	v_mul_f32_e32 v89, 0xc038aa3b, v89
	v_exp_f32_e32 v84, v84
	v_mul_f32_e32 v88, v71, v88
	v_exp_f32_e32 v89, v89
	v_fma_f32 v88, v71, v88, v71
	v_add_f32_e32 v79, 1.0, v79
	v_mul_f32_e32 v88, 0x3f4c422a, v88
	v_add_f32_e32 v78, 1.0, v78
	v_rcp_f32_e32 v79, v79
	v_mul_f32_e32 v88, 0xc038aa3b, v88
	v_rcp_f32_e32 v78, v78
	v_add_f32_e32 v84, 1.0, v84
	v_exp_f32_e32 v88, v88
	v_rcp_f32_e32 v87, v87
	v_add_f32_e32 v89, 1.0, v89
	v_rcp_f32_e32 v84, v84
	v_rcp_f32_e32 v89, v89
	v_rcp_f32_e32 v65, v65
	v_mul_f32_e32 v79, v64, v79
	v_add_f32_e32 v88, 1.0, v88
	v_mul_f32_e32 v87, v66, v87
	v_fma_f32 v66, v68, v78, v79
	v_mul_f32_e32 v86, v68, v78
	v_rcp_f32_e32 v88, v88
	v_mul_f32_e32 v89, v67, v89
	v_add_f32_e32 v66, v66, v77
	v_mul_f32_e32 v67, v79, v79
	v_fma_f32 v68, v69, v84, v85
	v_cvt_pk_bf16_f32 v75, v90, v75
	v_mul_f32_e32 v64, v69, v84
	v_mul_f32_e32 v90, v70, v65
	v_fmac_f32_e32 v67, v86, v86
	v_add_f32_e32 v66, v68, v66
	v_mul_f32_e32 v68, v85, v85
	v_fma_f32 v65, v70, v65, v87
	v_add_f32_e32 v67, v67, v76
	v_fmac_f32_e32 v68, v64, v64
	v_add_f32_e32 v65, v65, v66
	v_mul_f32_e32 v66, v87, v87
	v_add_f32_e32 v67, v68, v67
	v_fmac_f32_e32 v66, v90, v90
	v_add_f32_e32 v66, v66, v67
	v_fma_f32 v67, v71, v88, v89
	v_mul_f32_e32 v91, v71, v88
	v_add_f32_e32 v65, v67, v65
	v_mul_f32_e32 v67, v89, v89
	v_fmac_f32_e32 v67, v91, v91
	v_add_f32_e32 v66, v67, v66
	ds_bpermute_b32 v69, v168, v65
	ds_bpermute_b32 v67, v168, v66
	v_lshl_add_u64 v[82:83], s[70:71], 0, v[82:83]
	v_lshl_add_u64 v[82:83], v[160:161], 1, v[82:83]
	global_store_dwordx4 v[82:83], v[72:75], off sc0 nt
	v_cvt_pk_bf16_f32 v68, v86, v64
	s_waitcnt lgkmcnt(0)
	v_add_f32_e32 v64, v65, v69
	v_add_f32_e32 v66, v66, v67
	ds_bpermute_b32 v65, v167, v64
	ds_bpermute_b32 v67, v167, v66
	v_cvt_pk_bf16_f32 v69, v90, v91
	v_cvt_pk_bf16_f32 v70, v79, v85
	v_cvt_pk_bf16_f32 v71, v87, v89
	global_store_dwordx4 v[82:83], v[68:71], off offset:256 sc0 nt
	s_and_saveexec_b64 s[6:7], s[58:59]
	s_cbranch_execz .LBB0_579
	s_waitcnt lgkmcnt(0)
	v_add_f32_e32 v66, v66, v67
	v_add_f32_e32 v67, v64, v65
	s_lshl_b32 s4, s95, 2
	v_lshlrev_b64 v[64:65], 7, v[80:81]
	s_add_i32 s38, s4, -16
	v_lshl_add_u64 v[64:65], s[72:73], 0, v[64:65]
	v_lshl_add_u64 v[64:65], s[38:39], 2, v[64:65]
	s_lshl_b32 s38, s8, 2
	v_lshl_add_u64 v[64:65], v[64:65], 0, s[38:39]
	global_store_dword v[64:65], v67, off
	global_store_dword v[64:65], v66, off offset:64

.LBB0_583:
	s_waitcnt lgkmcnt(0)
	v_pk_mul_f32 v[60:61], v[60:61], v[68:69] op_sel_hi:[1,0]
	v_lshlrev_b64 v[66:67], 12, v[64:65]
	v_mul_f32_e32 v69, 0x3d372713, v60
	v_mul_f32_e32 v69, v60, v69
	v_fma_f32 v69, v60, v69, v60
	v_mul_f32_e32 v69, 0x3f4c422a, v69
	v_mul_f32_e32 v69, 0xc038aa3b, v69
	v_exp_f32_e32 v69, v69
	v_mul_f32_e32 v71, 0x3d372713, v61
	v_mul_f32_e32 v71, v61, v71
	v_fma_f32 v71, v61, v71, v61
	v_pk_mul_f32 v[56:57], v[56:57], v[68:69] op_sel_hi:[1,0]
	v_pk_mul_f32 v[62:63], v[62:63], v[68:69] op_sel_hi:[1,0]
	v_mul_f32_e32 v72, 0x3d372713, v57
	v_mul_f32_e32 v72, v57, v72
	v_fma_f32 v72, v57, v72, v57
	v_mul_f32_e32 v72, 0x3f4c422a, v72
	v_pk_mul_f32 v[58:59], v[58:59], v[68:69] op_sel_hi:[1,0]
	v_mul_f32_e32 v72, 0xc038aa3b, v72
	v_exp_f32_e32 v72, v72
	v_mul_f32_e32 v74, 0x3d372713, v62
	v_mul_f32_e32 v75, 0x3d372713, v58
	v_mul_f32_e32 v74, v62, v74
	v_mul_f32_e32 v75, v58, v75
	v_mul_f32_e32 v70, 0x3d372713, v56
	v_fma_f32 v74, v62, v74, v62
	v_fma_f32 v75, v58, v75, v58
	v_mul_f32_e32 v70, v56, v70
	v_mul_f32_e32 v74, 0x3f4c422a, v74
	v_mul_f32_e32 v75, 0x3f4c422a, v75
	v_fma_f32 v70, v56, v70, v56
	v_add_f32_e32 v72, 1.0, v72
	v_mul_f32_e32 v74, 0xc038aa3b, v74
	v_mul_f32_e32 v75, 0xc038aa3b, v75
	v_mul_f32_e32 v70, 0x3f4c422a, v70
	v_rcp_f32_e32 v72, v72
	v_exp_f32_e32 v74, v74
	v_exp_f32_e32 v75, v75
	v_mul_f32_e32 v70, 0xc038aa3b, v70
	v_exp_f32_e32 v70, v70
	v_mul_f32_e32 v71, 0x3f4c422a, v71
	v_mul_f32_e32 v71, 0xc038aa3b, v71
	v_mul_f32_e32 v76, 0x3d372713, v59
	v_exp_f32_e32 v71, v71
	v_mul_f32_e32 v72, v57, v72
	v_add_f32_e32 v57, 1.0, v74
	v_add_f32_e32 v74, 1.0, v75
	v_mul_f32_e32 v75, 0x3d372713, v63
	v_mul_f32_e32 v76, v59, v76
	v_mul_f32_e32 v75, v63, v75
	v_fma_f32 v76, v59, v76, v59
	v_add_f32_e32 v70, 1.0, v70
	v_fma_f32 v75, v63, v75, v63
	v_mul_f32_e32 v76, 0x3f4c422a, v76
	v_add_f32_e32 v69, 1.0, v69
	v_rcp_f32_e32 v70, v70
	v_mul_f32_e32 v75, 0x3f4c422a, v75
	v_mul_f32_e32 v76, 0xc038aa3b, v76
	v_rcp_f32_e32 v69, v69
	v_add_f32_e32 v71, 1.0, v71
	v_mul_f32_e32 v75, 0xc038aa3b, v75
	v_exp_f32_e32 v76, v76
	v_rcp_f32_e32 v71, v71
	v_exp_f32_e32 v75, v75
	v_rcp_f32_e32 v74, v74
	v_mul_f32_e32 v70, v56, v70
	v_rcp_f32_e32 v57, v57
	v_mul_f32_e32 v73, v60, v69
	v_add_f32_e32 v76, 1.0, v76
	v_fma_f32 v60, v60, v69, v70
	v_mul_f32_e32 v56, v61, v71
	v_add_f32_e32 v75, 1.0, v75
	v_rcp_f32_e32 v76, v76
	v_add_f32_e32 v60, 0, v60
	v_mul_f32_e32 v69, v70, v70
	v_fma_f32 v61, v61, v71, v72
	v_rcp_f32_e32 v75, v75
	v_mul_f32_e32 v74, v58, v74
	v_fmac_f32_e32 v69, v73, v73
	v_add_f32_e32 v60, v61, v60
	v_mul_f32_e32 v61, v72, v72
	v_mul_f32_e32 v77, v62, v57
	v_fmac_f32_e32 v61, v56, v56
	v_fma_f32 v57, v62, v57, v74
	v_pk_mul_f32 v[48:49], v[48:49], v[68:69] op_sel_hi:[1,0]
	v_add_f32_e32 v61, v69, v61
	v_add_f32_e32 v57, v57, v60
	v_mul_f32_e32 v60, v74, v74
	v_pk_mul_f32 v[52:53], v[52:53], v[68:69] op_sel_hi:[1,0]
	v_pk_mul_f32 v[54:55], v[54:55], v[68:69] op_sel_hi:[1,0]
	v_pk_mul_f32 v[50:51], v[50:51], v[68:69] op_sel_hi:[1,0]
	v_mul_f32_e32 v69, 0x3d372713, v49
	v_mul_f32_e32 v59, v59, v76
	v_fmac_f32_e32 v60, v77, v77
	v_mul_f32_e32 v69, v49, v69
	v_add_f32_e32 v60, v60, v61
	v_fma_f32 v61, v63, v75, v59
	v_fma_f32 v69, v49, v69, v49
	v_mul_f32_e32 v58, v63, v75
	v_add_f32_e32 v61, v61, v57
	v_mul_f32_e32 v57, v59, v59
	v_mul_f32_e32 v69, 0x3f4c422a, v69
	v_fmac_f32_e32 v57, v58, v58
	v_mul_f32_e32 v69, 0xc038aa3b, v69
	v_add_f32_e32 v60, v57, v60
	v_cvt_pk_bf16_f32 v56, v73, v56
	v_cvt_pk_bf16_f32 v57, v77, v58
	v_cvt_pk_bf16_f32 v58, v70, v72
	v_exp_f32_e32 v69, v69
	v_mul_f32_e32 v71, 0x3d372713, v54
	v_mul_f32_e32 v72, 0x3d372713, v50
	v_mul_f32_e32 v71, v54, v71
	v_mul_f32_e32 v72, v50, v72
	v_fma_f32 v71, v54, v71, v54
	v_fma_f32 v72, v50, v72, v50
	v_mul_f32_e32 v63, 0x3d372713, v48
	v_mul_f32_e32 v71, 0x3f4c422a, v71
	v_mul_f32_e32 v72, 0x3f4c422a, v72
	v_mul_f32_e32 v62, 0x3d372713, v52
	v_mul_f32_e32 v63, v48, v63
	v_add_f32_e32 v69, 1.0, v69
	v_mul_f32_e32 v71, 0xc038aa3b, v71
	v_mul_f32_e32 v72, 0xc038aa3b, v72
	v_mul_f32_e32 v62, v52, v62
	v_fma_f32 v63, v48, v63, v48
	v_mul_f32_e32 v68, 0x3d372713, v53
	v_rcp_f32_e32 v69, v69
	v_exp_f32_e32 v71, v71
	v_exp_f32_e32 v72, v72
	v_mul_f32_e32 v73, 0x3d372713, v51
	v_fma_f32 v62, v52, v62, v52
	v_mul_f32_e32 v63, 0x3f4c422a, v63
	v_mul_f32_e32 v68, v53, v68
	v_mul_f32_e32 v73, v51, v73
	v_mul_f32_e32 v62, 0x3f4c422a, v62
	v_mul_f32_e32 v63, 0xc038aa3b, v63
	v_fma_f32 v68, v53, v68, v53
	v_fma_f32 v73, v51, v73, v51
	v_mul_f32_e32 v62, 0xc038aa3b, v62
	v_exp_f32_e32 v63, v63
	v_mul_f32_e32 v68, 0x3f4c422a, v68
	v_mul_f32_e32 v73, 0x3f4c422a, v73
	v_exp_f32_e32 v62, v62
	v_mul_f32_e32 v68, 0xc038aa3b, v68
	v_mul_f32_e32 v69, v49, v69
	v_add_f32_e32 v49, 1.0, v71
	v_add_f32_e32 v71, 1.0, v72
	v_mul_f32_e32 v72, 0x3d372713, v55
	v_mul_f32_e32 v73, 0xc038aa3b, v73
	v_exp_f32_e32 v68, v68
	v_mul_f32_e32 v72, v55, v72
	v_exp_f32_e32 v73, v73
	v_fma_f32 v72, v55, v72, v55
	v_add_f32_e32 v63, 1.0, v63
	v_mul_f32_e32 v72, 0x3f4c422a, v72
	v_add_f32_e32 v62, 1.0, v62
	v_rcp_f32_e32 v63, v63
	v_mul_f32_e32 v72, 0xc038aa3b, v72
	v_rcp_f32_e32 v62, v62
	v_add_f32_e32 v68, 1.0, v68
	v_exp_f32_e32 v72, v72
	v_rcp_f32_e32 v71, v71
	v_add_f32_e32 v73, 1.0, v73
	v_rcp_f32_e32 v68, v68
	v_rcp_f32_e32 v73, v73
	v_rcp_f32_e32 v49, v49
	v_mul_f32_e32 v63, v48, v63
	v_add_f32_e32 v72, 1.0, v72
	v_mul_f32_e32 v71, v50, v71
	v_fma_f32 v50, v52, v62, v63
	v_mul_f32_e32 v70, v52, v62
	v_rcp_f32_e32 v72, v72
	v_mul_f32_e32 v73, v51, v73
	v_add_f32_e32 v50, v50, v61
	v_mul_f32_e32 v51, v63, v63
	v_fma_f32 v52, v53, v68, v69
	v_cvt_pk_bf16_f32 v59, v74, v59
	v_mul_f32_e32 v48, v53, v68
	v_mul_f32_e32 v74, v54, v49
	v_fmac_f32_e32 v51, v70, v70
	v_add_f32_e32 v50, v52, v50
	v_mul_f32_e32 v52, v69, v69
	v_fma_f32 v49, v54, v49, v71
	v_add_f32_e32 v51, v51, v60
	v_fmac_f32_e32 v52, v48, v48
	v_add_f32_e32 v49, v49, v50
	v_mul_f32_e32 v50, v71, v71
	v_add_f32_e32 v51, v52, v51
	v_fmac_f32_e32 v50, v74, v74
	v_add_f32_e32 v50, v50, v51
	v_fma_f32 v51, v55, v72, v73
	v_mul_f32_e32 v75, v55, v72
	v_add_f32_e32 v49, v51, v49
	v_mul_f32_e32 v51, v73, v73
	v_fmac_f32_e32 v51, v75, v75
	v_add_f32_e32 v50, v51, v50
	ds_bpermute_b32 v53, v168, v49
	ds_bpermute_b32 v51, v168, v50
	v_lshl_add_u64 v[66:67], s[70:71], 0, v[66:67]
	v_lshl_add_u64 v[66:67], v[160:161], 1, v[66:67]
	global_store_dwordx4 v[66:67], v[56:59], off sc0 nt
	v_cvt_pk_bf16_f32 v52, v70, v48
	s_waitcnt lgkmcnt(0)
	v_add_f32_e32 v48, v49, v53
	v_add_f32_e32 v50, v50, v51
	ds_bpermute_b32 v49, v167, v48
	ds_bpermute_b32 v51, v167, v50
	v_cvt_pk_bf16_f32 v53, v74, v75
	v_cvt_pk_bf16_f32 v54, v63, v69
	v_cvt_pk_bf16_f32 v55, v71, v73
	global_store_dwordx4 v[66:67], v[52:55], off offset:256 sc0 nt
	s_and_saveexec_b64 s[6:7], s[58:59]
	s_cbranch_execz .LBB0_585
	s_waitcnt lgkmcnt(0)
	v_add_f32_e32 v50, v50, v51
	v_add_f32_e32 v51, v48, v49
	s_lshl_b32 s4, s95, 2
	v_lshlrev_b64 v[48:49], 7, v[64:65]
	s_add_i32 s38, s4, -16
	v_lshl_add_u64 v[48:49], s[72:73], 0, v[48:49]
	v_lshl_add_u64 v[48:49], s[38:39], 2, v[48:49]
	s_lshl_b32 s38, s8, 2
	v_lshl_add_u64 v[48:49], v[48:49], 0, s[38:39]
	global_store_dword v[48:49], v51, off
	global_store_dword v[48:49], v50, off offset:64

.LBB0_589:
	s_waitcnt lgkmcnt(0)
	v_pk_mul_f32 v[44:45], v[44:45], v[52:53] op_sel_hi:[1,0]
	v_lshlrev_b64 v[50:51], 12, v[48:49]
	v_mul_f32_e32 v53, 0x3d372713, v44
	v_mul_f32_e32 v53, v44, v53
	v_fma_f32 v53, v44, v53, v44
	v_mul_f32_e32 v53, 0x3f4c422a, v53
	v_mul_f32_e32 v53, 0xc038aa3b, v53
	v_exp_f32_e32 v53, v53
	v_mul_f32_e32 v55, 0x3d372713, v45
	v_mul_f32_e32 v55, v45, v55
	v_fma_f32 v55, v45, v55, v45
	v_pk_mul_f32 v[40:41], v[40:41], v[52:53] op_sel_hi:[1,0]
	v_pk_mul_f32 v[46:47], v[46:47], v[52:53] op_sel_hi:[1,0]
	v_mul_f32_e32 v56, 0x3d372713, v41
	v_mul_f32_e32 v56, v41, v56
	v_fma_f32 v56, v41, v56, v41
	v_mul_f32_e32 v56, 0x3f4c422a, v56
	v_pk_mul_f32 v[42:43], v[42:43], v[52:53] op_sel_hi:[1,0]
	v_mul_f32_e32 v56, 0xc038aa3b, v56
	v_exp_f32_e32 v56, v56
	v_mul_f32_e32 v58, 0x3d372713, v46
	v_mul_f32_e32 v59, 0x3d372713, v42
	v_mul_f32_e32 v58, v46, v58
	v_mul_f32_e32 v59, v42, v59
	v_mul_f32_e32 v54, 0x3d372713, v40
	v_fma_f32 v58, v46, v58, v46
	v_fma_f32 v59, v42, v59, v42
	v_mul_f32_e32 v54, v40, v54
	v_mul_f32_e32 v58, 0x3f4c422a, v58
	v_mul_f32_e32 v59, 0x3f4c422a, v59
	v_fma_f32 v54, v40, v54, v40
	v_add_f32_e32 v56, 1.0, v56
	v_mul_f32_e32 v58, 0xc038aa3b, v58
	v_mul_f32_e32 v59, 0xc038aa3b, v59
	v_mul_f32_e32 v54, 0x3f4c422a, v54
	v_rcp_f32_e32 v56, v56
	v_exp_f32_e32 v58, v58
	v_exp_f32_e32 v59, v59
	v_mul_f32_e32 v54, 0xc038aa3b, v54
	v_exp_f32_e32 v54, v54
	v_mul_f32_e32 v55, 0x3f4c422a, v55
	v_mul_f32_e32 v55, 0xc038aa3b, v55
	v_mul_f32_e32 v60, 0x3d372713, v43
	v_exp_f32_e32 v55, v55
	v_mul_f32_e32 v56, v41, v56
	v_add_f32_e32 v41, 1.0, v58
	v_add_f32_e32 v58, 1.0, v59
	v_mul_f32_e32 v59, 0x3d372713, v47
	v_mul_f32_e32 v60, v43, v60
	v_mul_f32_e32 v59, v47, v59
	v_fma_f32 v60, v43, v60, v43
	v_add_f32_e32 v54, 1.0, v54
	v_fma_f32 v59, v47, v59, v47
	v_mul_f32_e32 v60, 0x3f4c422a, v60
	v_add_f32_e32 v53, 1.0, v53
	v_rcp_f32_e32 v54, v54
	v_mul_f32_e32 v59, 0x3f4c422a, v59
	v_mul_f32_e32 v60, 0xc038aa3b, v60
	v_rcp_f32_e32 v53, v53
	v_add_f32_e32 v55, 1.0, v55
	v_mul_f32_e32 v59, 0xc038aa3b, v59
	v_exp_f32_e32 v60, v60
	v_rcp_f32_e32 v55, v55
	v_exp_f32_e32 v59, v59
	v_rcp_f32_e32 v58, v58
	v_mul_f32_e32 v54, v40, v54
	v_rcp_f32_e32 v41, v41
	v_mul_f32_e32 v57, v44, v53
	v_add_f32_e32 v60, 1.0, v60
	v_fma_f32 v44, v44, v53, v54
	v_mul_f32_e32 v40, v45, v55
	v_add_f32_e32 v59, 1.0, v59
	v_rcp_f32_e32 v60, v60
	v_add_f32_e32 v44, 0, v44
	v_mul_f32_e32 v53, v54, v54
	v_fma_f32 v45, v45, v55, v56
	v_rcp_f32_e32 v59, v59
	v_mul_f32_e32 v58, v42, v58
	v_fmac_f32_e32 v53, v57, v57
	v_add_f32_e32 v44, v45, v44
	v_mul_f32_e32 v45, v56, v56
	v_mul_f32_e32 v61, v46, v41
	v_fmac_f32_e32 v45, v40, v40
	v_fma_f32 v41, v46, v41, v58
	v_pk_mul_f32 v[32:33], v[32:33], v[52:53] op_sel_hi:[1,0]
	v_add_f32_e32 v45, v53, v45
	v_add_f32_e32 v41, v41, v44
	v_mul_f32_e32 v44, v58, v58
	v_pk_mul_f32 v[36:37], v[36:37], v[52:53] op_sel_hi:[1,0]
	v_pk_mul_f32 v[38:39], v[38:39], v[52:53] op_sel_hi:[1,0]
	v_pk_mul_f32 v[34:35], v[34:35], v[52:53] op_sel_hi:[1,0]
	v_mul_f32_e32 v53, 0x3d372713, v33
	v_mul_f32_e32 v43, v43, v60
	v_fmac_f32_e32 v44, v61, v61
	v_mul_f32_e32 v53, v33, v53
	v_add_f32_e32 v44, v44, v45
	v_fma_f32 v45, v47, v59, v43
	v_fma_f32 v53, v33, v53, v33
	v_mul_f32_e32 v42, v47, v59
	v_add_f32_e32 v45, v45, v41
	v_mul_f32_e32 v41, v43, v43
	v_mul_f32_e32 v53, 0x3f4c422a, v53
	v_fmac_f32_e32 v41, v42, v42
	v_mul_f32_e32 v53, 0xc038aa3b, v53
	v_add_f32_e32 v44, v41, v44
	v_cvt_pk_bf16_f32 v40, v57, v40
	v_cvt_pk_bf16_f32 v41, v61, v42
	v_cvt_pk_bf16_f32 v42, v54, v56
	v_exp_f32_e32 v53, v53
	v_mul_f32_e32 v55, 0x3d372713, v38
	v_mul_f32_e32 v56, 0x3d372713, v34
	v_mul_f32_e32 v55, v38, v55
	v_mul_f32_e32 v56, v34, v56
	v_fma_f32 v55, v38, v55, v38
	v_fma_f32 v56, v34, v56, v34
	v_mul_f32_e32 v47, 0x3d372713, v32
	v_mul_f32_e32 v55, 0x3f4c422a, v55
	v_mul_f32_e32 v56, 0x3f4c422a, v56
	v_mul_f32_e32 v46, 0x3d372713, v36
	v_mul_f32_e32 v47, v32, v47
	v_add_f32_e32 v53, 1.0, v53
	v_mul_f32_e32 v55, 0xc038aa3b, v55
	v_mul_f32_e32 v56, 0xc038aa3b, v56
	v_mul_f32_e32 v46, v36, v46
	v_fma_f32 v47, v32, v47, v32
	v_mul_f32_e32 v52, 0x3d372713, v37
	v_rcp_f32_e32 v53, v53
	v_exp_f32_e32 v55, v55
	v_exp_f32_e32 v56, v56
	v_mul_f32_e32 v57, 0x3d372713, v35
	v_fma_f32 v46, v36, v46, v36
	v_mul_f32_e32 v47, 0x3f4c422a, v47
	v_mul_f32_e32 v52, v37, v52
	v_mul_f32_e32 v57, v35, v57
	v_mul_f32_e32 v46, 0x3f4c422a, v46
	v_mul_f32_e32 v47, 0xc038aa3b, v47
	v_fma_f32 v52, v37, v52, v37
	v_fma_f32 v57, v35, v57, v35
	v_mul_f32_e32 v46, 0xc038aa3b, v46
	v_exp_f32_e32 v47, v47
	v_mul_f32_e32 v52, 0x3f4c422a, v52
	v_mul_f32_e32 v57, 0x3f4c422a, v57
	v_exp_f32_e32 v46, v46
	v_mul_f32_e32 v52, 0xc038aa3b, v52
	v_mul_f32_e32 v53, v33, v53
	v_add_f32_e32 v33, 1.0, v55
	v_add_f32_e32 v55, 1.0, v56
	v_mul_f32_e32 v56, 0x3d372713, v39
	v_mul_f32_e32 v57, 0xc038aa3b, v57
	v_exp_f32_e32 v52, v52
	v_mul_f32_e32 v56, v39, v56
	v_exp_f32_e32 v57, v57
	v_fma_f32 v56, v39, v56, v39
	v_add_f32_e32 v47, 1.0, v47
	v_mul_f32_e32 v56, 0x3f4c422a, v56
	v_add_f32_e32 v46, 1.0, v46
	v_rcp_f32_e32 v47, v47
	v_mul_f32_e32 v56, 0xc038aa3b, v56
	v_rcp_f32_e32 v46, v46
	v_add_f32_e32 v52, 1.0, v52
	v_exp_f32_e32 v56, v56
	v_rcp_f32_e32 v55, v55
	v_add_f32_e32 v57, 1.0, v57
	v_rcp_f32_e32 v52, v52
	v_rcp_f32_e32 v57, v57
	v_rcp_f32_e32 v33, v33
	v_mul_f32_e32 v47, v32, v47
	v_add_f32_e32 v56, 1.0, v56
	v_mul_f32_e32 v55, v34, v55
	v_fma_f32 v34, v36, v46, v47
	v_mul_f32_e32 v54, v36, v46
	v_rcp_f32_e32 v56, v56
	v_mul_f32_e32 v57, v35, v57
	v_add_f32_e32 v34, v34, v45
	v_mul_f32_e32 v35, v47, v47
	v_fma_f32 v36, v37, v52, v53
	v_cvt_pk_bf16_f32 v43, v58, v43
	v_mul_f32_e32 v32, v37, v52
	v_mul_f32_e32 v58, v38, v33
	v_fmac_f32_e32 v35, v54, v54
	v_add_f32_e32 v34, v36, v34
	v_mul_f32_e32 v36, v53, v53
	v_fma_f32 v33, v38, v33, v55
	v_add_f32_e32 v35, v35, v44
	v_fmac_f32_e32 v36, v32, v32
	v_add_f32_e32 v33, v33, v34
	v_mul_f32_e32 v34, v55, v55
	v_add_f32_e32 v35, v36, v35
	v_fmac_f32_e32 v34, v58, v58
	v_add_f32_e32 v34, v34, v35
	v_fma_f32 v35, v39, v56, v57
	v_mul_f32_e32 v59, v39, v56
	v_add_f32_e32 v33, v35, v33
	v_mul_f32_e32 v35, v57, v57
	v_fmac_f32_e32 v35, v59, v59
	v_add_f32_e32 v34, v35, v34
	ds_bpermute_b32 v37, v168, v33
	ds_bpermute_b32 v35, v168, v34
	v_lshl_add_u64 v[50:51], s[70:71], 0, v[50:51]
	v_lshl_add_u64 v[50:51], v[160:161], 1, v[50:51]
	global_store_dwordx4 v[50:51], v[40:43], off sc0 nt
	v_cvt_pk_bf16_f32 v36, v54, v32
	s_waitcnt lgkmcnt(0)
	v_add_f32_e32 v32, v33, v37
	v_add_f32_e32 v34, v34, v35
	ds_bpermute_b32 v33, v167, v32
	ds_bpermute_b32 v35, v167, v34
	v_cvt_pk_bf16_f32 v37, v58, v59
	v_cvt_pk_bf16_f32 v38, v47, v53
	v_cvt_pk_bf16_f32 v39, v55, v57
	global_store_dwordx4 v[50:51], v[36:39], off offset:256 sc0 nt
	s_and_saveexec_b64 s[6:7], s[58:59]
	s_cbranch_execz .LBB0_591
	s_waitcnt lgkmcnt(0)
	v_add_f32_e32 v34, v34, v35
	v_add_f32_e32 v35, v32, v33
	s_lshl_b32 s4, s95, 2
	v_lshlrev_b64 v[32:33], 7, v[48:49]
	s_add_i32 s38, s4, -16
	v_lshl_add_u64 v[32:33], s[72:73], 0, v[32:33]
	v_lshl_add_u64 v[32:33], s[38:39], 2, v[32:33]
	s_lshl_b32 s38, s8, 2
	v_lshl_add_u64 v[32:33], v[32:33], 0, s[38:39]
	global_store_dword v[32:33], v35, off
	global_store_dword v[32:33], v34, off offset:64

.LBB0_595:
	s_waitcnt lgkmcnt(0)
	v_pk_mul_f32 v[28:29], v[28:29], v[36:37] op_sel_hi:[1,0]
	v_lshlrev_b64 v[34:35], 12, v[32:33]
	v_mul_f32_e32 v37, 0x3d372713, v28
	v_mul_f32_e32 v37, v28, v37
	v_fma_f32 v37, v28, v37, v28
	v_mul_f32_e32 v37, 0x3f4c422a, v37
	v_mul_f32_e32 v37, 0xc038aa3b, v37
	v_exp_f32_e32 v37, v37
	v_mul_f32_e32 v39, 0x3d372713, v29
	v_mul_f32_e32 v39, v29, v39
	v_fma_f32 v39, v29, v39, v29
	v_pk_mul_f32 v[24:25], v[24:25], v[36:37] op_sel_hi:[1,0]
	v_pk_mul_f32 v[30:31], v[30:31], v[36:37] op_sel_hi:[1,0]
	v_mul_f32_e32 v40, 0x3d372713, v25
	v_mul_f32_e32 v40, v25, v40
	v_fma_f32 v40, v25, v40, v25
	v_mul_f32_e32 v40, 0x3f4c422a, v40
	v_pk_mul_f32 v[26:27], v[26:27], v[36:37] op_sel_hi:[1,0]
	v_mul_f32_e32 v40, 0xc038aa3b, v40
	v_exp_f32_e32 v40, v40
	v_mul_f32_e32 v42, 0x3d372713, v30
	v_mul_f32_e32 v43, 0x3d372713, v26
	v_mul_f32_e32 v42, v30, v42
	v_mul_f32_e32 v43, v26, v43
	v_mul_f32_e32 v38, 0x3d372713, v24
	v_fma_f32 v42, v30, v42, v30
	v_fma_f32 v43, v26, v43, v26
	v_mul_f32_e32 v38, v24, v38
	v_mul_f32_e32 v42, 0x3f4c422a, v42
	v_mul_f32_e32 v43, 0x3f4c422a, v43
	v_fma_f32 v38, v24, v38, v24
	v_add_f32_e32 v40, 1.0, v40
	v_mul_f32_e32 v42, 0xc038aa3b, v42
	v_mul_f32_e32 v43, 0xc038aa3b, v43
	v_mul_f32_e32 v38, 0x3f4c422a, v38
	v_rcp_f32_e32 v40, v40
	v_exp_f32_e32 v42, v42
	v_exp_f32_e32 v43, v43
	v_mul_f32_e32 v38, 0xc038aa3b, v38
	v_exp_f32_e32 v38, v38
	v_mul_f32_e32 v39, 0x3f4c422a, v39
	v_mul_f32_e32 v39, 0xc038aa3b, v39
	v_mul_f32_e32 v44, 0x3d372713, v27
	v_exp_f32_e32 v39, v39
	v_mul_f32_e32 v40, v25, v40
	v_add_f32_e32 v25, 1.0, v42
	v_add_f32_e32 v42, 1.0, v43
	v_mul_f32_e32 v43, 0x3d372713, v31
	v_mul_f32_e32 v44, v27, v44
	v_mul_f32_e32 v43, v31, v43
	v_fma_f32 v44, v27, v44, v27
	v_add_f32_e32 v38, 1.0, v38
	v_fma_f32 v43, v31, v43, v31
	v_mul_f32_e32 v44, 0x3f4c422a, v44
	v_add_f32_e32 v37, 1.0, v37
	v_rcp_f32_e32 v38, v38
	v_mul_f32_e32 v43, 0x3f4c422a, v43
	v_mul_f32_e32 v44, 0xc038aa3b, v44
	v_rcp_f32_e32 v37, v37
	v_add_f32_e32 v39, 1.0, v39
	v_mul_f32_e32 v43, 0xc038aa3b, v43
	v_exp_f32_e32 v44, v44
	v_rcp_f32_e32 v39, v39
	v_exp_f32_e32 v43, v43
	v_rcp_f32_e32 v42, v42
	v_mul_f32_e32 v38, v24, v38
	v_rcp_f32_e32 v25, v25
	v_mul_f32_e32 v41, v28, v37
	v_add_f32_e32 v44, 1.0, v44
	v_fma_f32 v28, v28, v37, v38
	v_mul_f32_e32 v24, v29, v39
	v_add_f32_e32 v43, 1.0, v43
	v_rcp_f32_e32 v44, v44
	v_add_f32_e32 v28, 0, v28
	v_mul_f32_e32 v37, v38, v38
	v_fma_f32 v29, v29, v39, v40
	v_rcp_f32_e32 v43, v43
	v_mul_f32_e32 v42, v26, v42
	v_fmac_f32_e32 v37, v41, v41
	v_add_f32_e32 v28, v29, v28
	v_mul_f32_e32 v29, v40, v40
	v_mul_f32_e32 v45, v30, v25
	v_fmac_f32_e32 v29, v24, v24
	v_fma_f32 v25, v30, v25, v42
	v_pk_mul_f32 v[16:17], v[16:17], v[36:37] op_sel_hi:[1,0]
	v_add_f32_e32 v29, v37, v29
	v_add_f32_e32 v25, v25, v28
	v_mul_f32_e32 v28, v42, v42
	v_pk_mul_f32 v[20:21], v[20:21], v[36:37] op_sel_hi:[1,0]
	v_pk_mul_f32 v[22:23], v[22:23], v[36:37] op_sel_hi:[1,0]
	v_pk_mul_f32 v[18:19], v[18:19], v[36:37] op_sel_hi:[1,0]
	v_mul_f32_e32 v37, 0x3d372713, v17
	v_mul_f32_e32 v27, v27, v44
	v_fmac_f32_e32 v28, v45, v45
	v_mul_f32_e32 v37, v17, v37
	v_add_f32_e32 v28, v28, v29
	v_fma_f32 v29, v31, v43, v27
	v_fma_f32 v37, v17, v37, v17
	v_mul_f32_e32 v26, v31, v43
	v_add_f32_e32 v29, v29, v25
	v_mul_f32_e32 v25, v27, v27
	v_mul_f32_e32 v37, 0x3f4c422a, v37
	v_fmac_f32_e32 v25, v26, v26
	v_mul_f32_e32 v37, 0xc038aa3b, v37
	v_add_f32_e32 v28, v25, v28
	v_cvt_pk_bf16_f32 v24, v41, v24
	v_cvt_pk_bf16_f32 v25, v45, v26
	v_cvt_pk_bf16_f32 v26, v38, v40
	v_exp_f32_e32 v37, v37
	v_mul_f32_e32 v39, 0x3d372713, v22
	v_mul_f32_e32 v40, 0x3d372713, v18
	v_mul_f32_e32 v39, v22, v39
	v_mul_f32_e32 v40, v18, v40
	v_fma_f32 v39, v22, v39, v22
	v_fma_f32 v40, v18, v40, v18
	v_mul_f32_e32 v31, 0x3d372713, v16
	v_mul_f32_e32 v39, 0x3f4c422a, v39
	v_mul_f32_e32 v40, 0x3f4c422a, v40
	v_mul_f32_e32 v30, 0x3d372713, v20
	v_mul_f32_e32 v31, v16, v31
	v_add_f32_e32 v37, 1.0, v37
	v_mul_f32_e32 v39, 0xc038aa3b, v39
	v_mul_f32_e32 v40, 0xc038aa3b, v40
	v_mul_f32_e32 v30, v20, v30
	v_fma_f32 v31, v16, v31, v16
	v_mul_f32_e32 v36, 0x3d372713, v21
	v_rcp_f32_e32 v37, v37
	v_exp_f32_e32 v39, v39
	v_exp_f32_e32 v40, v40
	v_mul_f32_e32 v41, 0x3d372713, v19
	v_fma_f32 v30, v20, v30, v20
	v_mul_f32_e32 v31, 0x3f4c422a, v31
	v_mul_f32_e32 v36, v21, v36
	v_mul_f32_e32 v41, v19, v41
	v_mul_f32_e32 v30, 0x3f4c422a, v30
	v_mul_f32_e32 v31, 0xc038aa3b, v31
	v_fma_f32 v36, v21, v36, v21
	v_fma_f32 v41, v19, v41, v19
	v_mul_f32_e32 v30, 0xc038aa3b, v30
	v_exp_f32_e32 v31, v31
	v_mul_f32_e32 v36, 0x3f4c422a, v36
	v_mul_f32_e32 v41, 0x3f4c422a, v41
	v_exp_f32_e32 v30, v30
	v_mul_f32_e32 v36, 0xc038aa3b, v36
	v_mul_f32_e32 v37, v17, v37
	v_add_f32_e32 v17, 1.0, v39
	v_add_f32_e32 v39, 1.0, v40
	v_mul_f32_e32 v40, 0x3d372713, v23
	v_mul_f32_e32 v41, 0xc038aa3b, v41
	v_exp_f32_e32 v36, v36
	v_mul_f32_e32 v40, v23, v40
	v_exp_f32_e32 v41, v41
	v_fma_f32 v40, v23, v40, v23
	v_add_f32_e32 v31, 1.0, v31
	v_mul_f32_e32 v40, 0x3f4c422a, v40
	v_add_f32_e32 v30, 1.0, v30
	v_rcp_f32_e32 v31, v31
	v_mul_f32_e32 v40, 0xc038aa3b, v40
	v_rcp_f32_e32 v30, v30
	v_add_f32_e32 v36, 1.0, v36
	v_exp_f32_e32 v40, v40
	v_rcp_f32_e32 v39, v39
	v_add_f32_e32 v41, 1.0, v41
	v_rcp_f32_e32 v36, v36
	v_rcp_f32_e32 v41, v41
	v_rcp_f32_e32 v17, v17
	v_mul_f32_e32 v31, v16, v31
	v_add_f32_e32 v40, 1.0, v40
	v_mul_f32_e32 v39, v18, v39
	v_fma_f32 v18, v20, v30, v31
	v_mul_f32_e32 v38, v20, v30
	v_rcp_f32_e32 v40, v40
	v_mul_f32_e32 v41, v19, v41
	v_add_f32_e32 v18, v18, v29
	v_mul_f32_e32 v19, v31, v31
	v_fma_f32 v20, v21, v36, v37
	v_cvt_pk_bf16_f32 v27, v42, v27
	v_mul_f32_e32 v16, v21, v36
	v_mul_f32_e32 v42, v22, v17
	v_fmac_f32_e32 v19, v38, v38
	v_add_f32_e32 v18, v20, v18
	v_mul_f32_e32 v20, v37, v37
	v_fma_f32 v17, v22, v17, v39
	v_add_f32_e32 v19, v19, v28
	v_fmac_f32_e32 v20, v16, v16
	v_add_f32_e32 v17, v17, v18
	v_mul_f32_e32 v18, v39, v39
	v_add_f32_e32 v19, v20, v19
	v_fmac_f32_e32 v18, v42, v42
	v_add_f32_e32 v18, v18, v19
	v_fma_f32 v19, v23, v40, v41
	v_mul_f32_e32 v43, v23, v40
	v_add_f32_e32 v17, v19, v17
	v_mul_f32_e32 v19, v41, v41
	v_fmac_f32_e32 v19, v43, v43
	v_add_f32_e32 v18, v19, v18
	ds_bpermute_b32 v21, v168, v17
	ds_bpermute_b32 v19, v168, v18
	v_lshl_add_u64 v[34:35], s[70:71], 0, v[34:35]
	v_lshl_add_u64 v[34:35], v[160:161], 1, v[34:35]
	global_store_dwordx4 v[34:35], v[24:27], off sc0 nt
	v_cvt_pk_bf16_f32 v20, v38, v16
	s_waitcnt lgkmcnt(0)
	v_add_f32_e32 v16, v17, v21
	v_add_f32_e32 v18, v18, v19
	ds_bpermute_b32 v17, v167, v16
	ds_bpermute_b32 v19, v167, v18
	v_cvt_pk_bf16_f32 v21, v42, v43
	v_cvt_pk_bf16_f32 v22, v31, v37
	v_cvt_pk_bf16_f32 v23, v39, v41
	global_store_dwordx4 v[34:35], v[20:23], off offset:256 sc0 nt
	s_and_saveexec_b64 s[6:7], s[58:59]
	s_cbranch_execz .LBB0_597
	s_waitcnt lgkmcnt(0)
	v_add_f32_e32 v18, v18, v19
	v_add_f32_e32 v19, v16, v17
	s_lshl_b32 s4, s95, 2
	v_lshlrev_b64 v[16:17], 7, v[32:33]
	s_add_i32 s38, s4, -16
	v_lshl_add_u64 v[16:17], s[72:73], 0, v[16:17]
	v_lshl_add_u64 v[16:17], s[38:39], 2, v[16:17]
	s_lshl_b32 s38, s8, 2
	v_lshl_add_u64 v[16:17], v[16:17], 0, s[38:39]
	global_store_dword v[16:17], v19, off
	global_store_dword v[16:17], v18, off offset:64

.LBB0_601:
	s_waitcnt lgkmcnt(0)
	v_pk_mul_f32 v[12:13], v[12:13], v[20:21] op_sel_hi:[1,0]
	v_lshlrev_b64 v[18:19], 12, v[16:17]
	v_mul_f32_e32 v21, 0x3d372713, v12
	v_mul_f32_e32 v21, v12, v21
	v_fma_f32 v21, v12, v21, v12
	v_mul_f32_e32 v21, 0x3f4c422a, v21
	v_mul_f32_e32 v21, 0xc038aa3b, v21
	v_exp_f32_e32 v21, v21
	v_mul_f32_e32 v23, 0x3d372713, v13
	v_mul_f32_e32 v23, v13, v23
	v_fma_f32 v23, v13, v23, v13
	v_pk_mul_f32 v[8:9], v[8:9], v[20:21] op_sel_hi:[1,0]
	v_pk_mul_f32 v[14:15], v[14:15], v[20:21] op_sel_hi:[1,0]
	v_mul_f32_e32 v24, 0x3d372713, v9
	v_mul_f32_e32 v24, v9, v24
	v_fma_f32 v24, v9, v24, v9
	v_mul_f32_e32 v24, 0x3f4c422a, v24
	v_pk_mul_f32 v[10:11], v[10:11], v[20:21] op_sel_hi:[1,0]
	v_mul_f32_e32 v24, 0xc038aa3b, v24
	v_exp_f32_e32 v24, v24
	v_mul_f32_e32 v26, 0x3d372713, v14
	v_mul_f32_e32 v27, 0x3d372713, v10
	v_mul_f32_e32 v26, v14, v26
	v_mul_f32_e32 v27, v10, v27
	v_mul_f32_e32 v22, 0x3d372713, v8
	v_fma_f32 v26, v14, v26, v14
	v_fma_f32 v27, v10, v27, v10
	v_mul_f32_e32 v22, v8, v22
	v_mul_f32_e32 v26, 0x3f4c422a, v26
	v_mul_f32_e32 v27, 0x3f4c422a, v27
	v_fma_f32 v22, v8, v22, v8
	v_add_f32_e32 v24, 1.0, v24
	v_mul_f32_e32 v26, 0xc038aa3b, v26
	v_mul_f32_e32 v27, 0xc038aa3b, v27
	v_mul_f32_e32 v22, 0x3f4c422a, v22
	v_rcp_f32_e32 v24, v24
	v_exp_f32_e32 v26, v26
	v_exp_f32_e32 v27, v27
	v_mul_f32_e32 v22, 0xc038aa3b, v22
	v_exp_f32_e32 v22, v22
	v_mul_f32_e32 v23, 0x3f4c422a, v23
	v_mul_f32_e32 v23, 0xc038aa3b, v23
	v_mul_f32_e32 v28, 0x3d372713, v11
	v_exp_f32_e32 v23, v23
	v_mul_f32_e32 v24, v9, v24
	v_add_f32_e32 v9, 1.0, v26
	v_add_f32_e32 v26, 1.0, v27
	v_mul_f32_e32 v27, 0x3d372713, v15
	v_mul_f32_e32 v28, v11, v28
	v_mul_f32_e32 v27, v15, v27
	v_fma_f32 v28, v11, v28, v11
	v_add_f32_e32 v22, 1.0, v22
	v_fma_f32 v27, v15, v27, v15
	v_mul_f32_e32 v28, 0x3f4c422a, v28
	v_add_f32_e32 v21, 1.0, v21
	v_rcp_f32_e32 v22, v22
	v_mul_f32_e32 v27, 0x3f4c422a, v27
	v_mul_f32_e32 v28, 0xc038aa3b, v28
	v_rcp_f32_e32 v21, v21
	v_add_f32_e32 v23, 1.0, v23
	v_mul_f32_e32 v27, 0xc038aa3b, v27
	v_exp_f32_e32 v28, v28
	v_rcp_f32_e32 v23, v23
	v_exp_f32_e32 v27, v27
	v_rcp_f32_e32 v26, v26
	v_mul_f32_e32 v22, v8, v22
	v_rcp_f32_e32 v9, v9
	v_mul_f32_e32 v25, v12, v21
	v_add_f32_e32 v28, 1.0, v28
	v_fma_f32 v12, v12, v21, v22
	v_mul_f32_e32 v8, v13, v23
	v_add_f32_e32 v27, 1.0, v27
	v_rcp_f32_e32 v28, v28
	v_add_f32_e32 v12, 0, v12
	v_mul_f32_e32 v21, v22, v22
	v_fma_f32 v13, v13, v23, v24
	v_rcp_f32_e32 v27, v27
	v_mul_f32_e32 v26, v10, v26
	v_fmac_f32_e32 v21, v25, v25
	v_add_f32_e32 v12, v13, v12
	v_mul_f32_e32 v13, v24, v24
	v_mul_f32_e32 v29, v14, v9
	v_fmac_f32_e32 v13, v8, v8
	v_fma_f32 v9, v14, v9, v26
	v_pk_mul_f32 v[0:1], v[0:1], v[20:21] op_sel_hi:[1,0]
	v_add_f32_e32 v13, v21, v13
	v_add_f32_e32 v9, v9, v12
	v_mul_f32_e32 v12, v26, v26
	v_pk_mul_f32 v[4:5], v[4:5], v[20:21] op_sel_hi:[1,0]
	v_pk_mul_f32 v[6:7], v[6:7], v[20:21] op_sel_hi:[1,0]
	v_pk_mul_f32 v[2:3], v[2:3], v[20:21] op_sel_hi:[1,0]
	v_mul_f32_e32 v21, 0x3d372713, v1
	v_mul_f32_e32 v11, v11, v28
	v_fmac_f32_e32 v12, v29, v29
	v_mul_f32_e32 v21, v1, v21
	v_add_f32_e32 v12, v12, v13
	v_fma_f32 v13, v15, v27, v11
	v_fma_f32 v21, v1, v21, v1
	v_mul_f32_e32 v10, v15, v27
	v_add_f32_e32 v13, v13, v9
	v_mul_f32_e32 v9, v11, v11
	v_mul_f32_e32 v21, 0x3f4c422a, v21
	v_fmac_f32_e32 v9, v10, v10
	v_mul_f32_e32 v21, 0xc038aa3b, v21
	v_add_f32_e32 v12, v9, v12
	v_cvt_pk_bf16_f32 v8, v25, v8
	v_cvt_pk_bf16_f32 v9, v29, v10
	v_cvt_pk_bf16_f32 v10, v22, v24
	v_exp_f32_e32 v21, v21
	v_mul_f32_e32 v23, 0x3d372713, v6
	v_mul_f32_e32 v24, 0x3d372713, v2
	v_mul_f32_e32 v23, v6, v23
	v_mul_f32_e32 v24, v2, v24
	v_fma_f32 v23, v6, v23, v6
	v_fma_f32 v24, v2, v24, v2
	v_mul_f32_e32 v15, 0x3d372713, v0
	v_mul_f32_e32 v23, 0x3f4c422a, v23
	v_mul_f32_e32 v24, 0x3f4c422a, v24
	v_mul_f32_e32 v14, 0x3d372713, v4
	v_mul_f32_e32 v15, v0, v15
	v_add_f32_e32 v21, 1.0, v21
	v_mul_f32_e32 v23, 0xc038aa3b, v23
	v_mul_f32_e32 v24, 0xc038aa3b, v24
	v_mul_f32_e32 v14, v4, v14
	v_fma_f32 v15, v0, v15, v0
	v_mul_f32_e32 v20, 0x3d372713, v5
	v_rcp_f32_e32 v21, v21
	v_exp_f32_e32 v23, v23
	v_exp_f32_e32 v24, v24
	v_mul_f32_e32 v25, 0x3d372713, v3
	v_fma_f32 v14, v4, v14, v4
	v_mul_f32_e32 v15, 0x3f4c422a, v15
	v_mul_f32_e32 v20, v5, v20
	v_mul_f32_e32 v25, v3, v25
	v_mul_f32_e32 v14, 0x3f4c422a, v14
	v_mul_f32_e32 v15, 0xc038aa3b, v15
	v_fma_f32 v20, v5, v20, v5
	v_fma_f32 v25, v3, v25, v3
	v_mul_f32_e32 v14, 0xc038aa3b, v14
	v_exp_f32_e32 v15, v15
	v_mul_f32_e32 v20, 0x3f4c422a, v20
	v_mul_f32_e32 v25, 0x3f4c422a, v25
	v_exp_f32_e32 v14, v14
	v_mul_f32_e32 v20, 0xc038aa3b, v20
	v_mul_f32_e32 v21, v1, v21
	v_add_f32_e32 v1, 1.0, v23
	v_add_f32_e32 v23, 1.0, v24
	v_mul_f32_e32 v24, 0x3d372713, v7
	v_mul_f32_e32 v25, 0xc038aa3b, v25
	v_exp_f32_e32 v20, v20
	v_mul_f32_e32 v24, v7, v24
	v_exp_f32_e32 v25, v25
	v_fma_f32 v24, v7, v24, v7
	v_add_f32_e32 v15, 1.0, v15
	v_mul_f32_e32 v24, 0x3f4c422a, v24
	v_add_f32_e32 v14, 1.0, v14
	v_rcp_f32_e32 v15, v15
	v_mul_f32_e32 v24, 0xc038aa3b, v24
	v_rcp_f32_e32 v14, v14
	v_add_f32_e32 v20, 1.0, v20
	v_exp_f32_e32 v24, v24
	v_rcp_f32_e32 v23, v23
	v_add_f32_e32 v25, 1.0, v25
	v_rcp_f32_e32 v20, v20
	v_rcp_f32_e32 v25, v25
	v_rcp_f32_e32 v1, v1
	v_mul_f32_e32 v15, v0, v15
	v_add_f32_e32 v24, 1.0, v24
	v_mul_f32_e32 v23, v2, v23
	v_fma_f32 v2, v4, v14, v15
	v_mul_f32_e32 v22, v4, v14
	v_rcp_f32_e32 v24, v24
	v_mul_f32_e32 v25, v3, v25
	v_add_f32_e32 v2, v2, v13
	v_mul_f32_e32 v3, v15, v15
	v_fma_f32 v4, v5, v20, v21
	v_cvt_pk_bf16_f32 v11, v26, v11
	v_mul_f32_e32 v0, v5, v20
	v_mul_f32_e32 v26, v6, v1
	v_fmac_f32_e32 v3, v22, v22
	v_add_f32_e32 v2, v4, v2
	v_mul_f32_e32 v4, v21, v21
	v_fma_f32 v1, v6, v1, v23
	v_add_f32_e32 v3, v3, v12
	v_fmac_f32_e32 v4, v0, v0
	v_add_f32_e32 v1, v1, v2
	v_mul_f32_e32 v2, v23, v23
	v_add_f32_e32 v3, v4, v3
	v_fmac_f32_e32 v2, v26, v26
	v_add_f32_e32 v2, v2, v3
	v_fma_f32 v3, v7, v24, v25
	v_mul_f32_e32 v27, v7, v24
	v_add_f32_e32 v1, v3, v1
	v_mul_f32_e32 v3, v25, v25
	v_fmac_f32_e32 v3, v27, v27
	v_add_f32_e32 v2, v3, v2
	ds_bpermute_b32 v5, v168, v1
	ds_bpermute_b32 v3, v168, v2
	v_lshl_add_u64 v[18:19], s[70:71], 0, v[18:19]
	v_lshl_add_u64 v[18:19], v[160:161], 1, v[18:19]
	global_store_dwordx4 v[18:19], v[8:11], off sc0 nt
	v_cvt_pk_bf16_f32 v4, v22, v0
	s_waitcnt lgkmcnt(0)
	v_add_f32_e32 v0, v1, v5
	v_add_f32_e32 v2, v2, v3
	ds_bpermute_b32 v1, v167, v0
	ds_bpermute_b32 v3, v167, v2
	v_cvt_pk_bf16_f32 v5, v26, v27
	v_cvt_pk_bf16_f32 v6, v15, v21
	v_cvt_pk_bf16_f32 v7, v23, v25
	global_store_dwordx4 v[18:19], v[4:7], off offset:256 sc0 nt
	s_and_saveexec_b64 s[6:7], s[58:59]
	s_cbranch_execz .LBB0_603
	s_waitcnt lgkmcnt(0)
	v_add_f32_e32 v2, v2, v3
	v_add_f32_e32 v3, v0, v1
	s_lshl_b32 s4, s95, 2
	v_lshlrev_b64 v[0:1], 7, v[16:17]
	s_add_i32 s38, s4, -16
	v_lshl_add_u64 v[0:1], s[72:73], 0, v[0:1]
	v_lshl_add_u64 v[0:1], s[38:39], 2, v[0:1]
	s_lshl_b32 s38, s8, 2
	v_lshl_add_u64 v[0:1], v[0:1], 0, s[38:39]
	global_store_dword v[0:1], v3, off
	global_store_dword v[0:1], v2, off offset:64

.LBB0_678:
	s_mov_b32 s8, -1
	s_getreg_b32 s9, hwreg(HW_REG_HW_ID, 0, 6)
	s_and_b32 s9, s9, 63
	s_lshl_b32 s9, s9, 2
	s_add_i32 s9, s9, 0
	s_add_i32 s9, s9, 0x20200
	v_mov_b32_e32 v134, s9
	ds_read_b32 v134, v134
	v_mbcnt_lo_u32_b32 v135, s8, 0
	v_mbcnt_hi_u32_b32 v135, s8, v135
	s_lshl_b32 s9, s67, 8
	v_pk_mul_f32 v[126:127], v[126:127], s[34:35] op_sel_hi:[1,0]
	s_waitcnt lgkmcnt(0)
	v_readfirstlane_b32 s8, v134
	v_pk_mul_f32 v[124:125], v[124:125], s[34:35] op_sel_hi:[1,0]
	v_pk_mul_f32 v[144:145], v[122:123], s[34:35] op_sel_hi:[1,0]
	v_lshl_add_u32 v134, s8, 6, v135
	v_pk_mul_f32 v[122:123], v[120:121], s[34:35] op_sel_hi:[1,0]
	v_readfirstlane_b32 s8, v134
	s_ashr_i32 s10, s8, 2
	s_lshr_b32 s8, s8, 1
	s_and_b32 s8, s8, 0x60
	s_or_b32 s8, s8, s9
	v_lshrrev_b32_e32 v135, 1, v134
	v_and_or_b32 v136, v135, 24, s8
	s_lshl_b32 s8, s66, 4
	s_and_b32 s8, s8, 0xffffff00
	s_andn2_b32 s10, s10, 63
	v_and_or_b32 v134, v134, 15, s8
	s_lshl_b32 s8, s66, 21
	v_add_u32_e32 v134, s10, v134
	s_and_b32 s8, s8, 0x1e00000
	s_add_u32 s8, s81, s8
	v_ashrrev_i32_e32 v135, 31, v134
	v_ashrrev_i32_e32 v137, 31, v136
	s_addc_u32 s9, s25, 0
	v_lshlrev_b64 v[142:143], 11, v[134:135]
	v_lshl_add_u64 v[142:143], s[8:9], 0, v[142:143]
	v_lshlrev_b64 v[136:137], 1, v[136:137]
	v_lshl_add_u64 v[142:143], v[142:143], 0, v[136:137]
	v_cvt_pk_bf16_f32 v120, v124, v125
	v_cvt_pk_bf16_f32 v121, v126, v127
	v_cvt_pk_bf16_f32 v122, v122, v123
	v_cvt_pk_bf16_f32 v123, v144, v145
	global_store_dwordx4 v[142:143], v[120:123], off sc0 nt
	v_pk_mul_f32 v[116:117], v[116:117], s[34:35] op_sel_hi:[1,0]
	v_pk_mul_f32 v[118:119], v[118:119], s[34:35] op_sel_hi:[1,0]
	v_pk_mul_f32 v[120:121], v[114:115], s[34:35] op_sel_hi:[1,0]
	v_pk_mul_f32 v[114:115], v[112:113], s[34:35] op_sel_hi:[1,0]
	v_cvt_pk_bf16_f32 v112, v116, v117
	v_cvt_pk_bf16_f32 v113, v118, v119
	v_pk_mul_f32 v[110:111], v[110:111], s[34:35] op_sel_hi:[1,0]
	v_cvt_pk_bf16_f32 v114, v114, v115
	v_cvt_pk_bf16_f32 v115, v120, v121
	global_store_dwordx4 v[142:143], v[112:115], off offset:256 sc0 nt
	v_pk_mul_f32 v[108:109], v[108:109], s[34:35] op_sel_hi:[1,0]
	v_pk_mul_f32 v[100:101], v[100:101], s[34:35] op_sel_hi:[1,0]
	v_or_b32_e32 v112, 16, v134
	v_ashrrev_i32_e32 v113, 31, v112
	v_lshlrev_b64 v[112:113], 11, v[112:113]
	v_lshl_add_u64 v[112:113], s[8:9], 0, v[112:113]
	v_lshl_add_u64 v[112:113], v[112:113], 0, v[136:137]
	v_pk_mul_f32 v[114:115], v[106:107], s[34:35] op_sel_hi:[1,0]
	v_pk_mul_f32 v[106:107], v[104:105], s[34:35] op_sel_hi:[1,0]
	v_cvt_pk_bf16_f32 v104, v108, v109
	v_cvt_pk_bf16_f32 v105, v110, v111
	v_pk_mul_f32 v[102:103], v[102:103], s[34:35] op_sel_hi:[1,0]
	v_cvt_pk_bf16_f32 v106, v106, v107
	v_cvt_pk_bf16_f32 v107, v114, v115
	global_store_dwordx4 v[112:113], v[104:107], off sc0 nt
	v_pk_mul_f32 v[94:95], v[94:95], s[34:35] op_sel_hi:[1,0]
	v_pk_mul_f32 v[92:93], v[92:93], s[34:35] op_sel_hi:[1,0]
	v_pk_mul_f32 v[104:105], v[98:99], s[34:35] op_sel_hi:[1,0]
	v_pk_mul_f32 v[98:99], v[96:97], s[34:35] op_sel_hi:[1,0]
	v_cvt_pk_bf16_f32 v96, v100, v101
	v_cvt_pk_bf16_f32 v97, v102, v103
	v_pk_mul_f32 v[84:85], v[84:85], s[34:35] op_sel_hi:[1,0]
	v_cvt_pk_bf16_f32 v98, v98, v99
	v_cvt_pk_bf16_f32 v99, v104, v105
	global_store_dwordx4 v[112:113], v[96:99], off offset:256 sc0 nt
	v_pk_mul_f32 v[86:87], v[86:87], s[34:35] op_sel_hi:[1,0]
	v_pk_mul_f32 v[70:71], v[70:71], s[34:35] op_sel_hi:[1,0]
	v_or_b32_e32 v96, 32, v134
	v_ashrrev_i32_e32 v97, 31, v96
	v_lshlrev_b64 v[96:97], 11, v[96:97]
	v_lshl_add_u64 v[96:97], s[8:9], 0, v[96:97]
	v_lshl_add_u64 v[96:97], v[96:97], 0, v[136:137]
	v_pk_mul_f32 v[98:99], v[90:91], s[34:35] op_sel_hi:[1,0]
	v_pk_mul_f32 v[90:91], v[88:89], s[34:35] op_sel_hi:[1,0]
	v_cvt_pk_bf16_f32 v88, v92, v93
	v_cvt_pk_bf16_f32 v89, v94, v95
	v_pk_mul_f32 v[68:69], v[68:69], s[34:35] op_sel_hi:[1,0]
	v_cvt_pk_bf16_f32 v90, v90, v91
	v_cvt_pk_bf16_f32 v91, v98, v99
	global_store_dwordx4 v[96:97], v[88:91], off sc0 nt
	v_pk_mul_f32 v[52:53], v[52:53], s[34:35] op_sel_hi:[1,0]
	v_pk_mul_f32 v[54:55], v[54:55], s[34:35] op_sel_hi:[1,0]
	v_pk_mul_f32 v[88:89], v[82:83], s[34:35] op_sel_hi:[1,0]
	v_pk_mul_f32 v[82:83], v[80:81], s[34:35] op_sel_hi:[1,0]
	v_cvt_pk_bf16_f32 v80, v84, v85
	v_cvt_pk_bf16_f32 v81, v86, v87
	v_pk_mul_f32 v[56:57], v[56:57], s[34:35] op_sel_hi:[1,0]
	v_cvt_pk_bf16_f32 v82, v82, v83
	v_cvt_pk_bf16_f32 v83, v88, v89
	global_store_dwordx4 v[96:97], v[80:83], off offset:256 sc0 nt
	v_pk_mul_f32 v[46:47], v[46:47], s[34:35] op_sel_hi:[1,0]
	v_pk_mul_f32 v[44:45], v[44:45], s[34:35] op_sel_hi:[1,0]
	v_or_b32_e32 v80, 48, v134
	v_ashrrev_i32_e32 v81, 31, v80
	v_lshlrev_b64 v[80:81], 11, v[80:81]
	v_lshl_add_u64 v[80:81], s[8:9], 0, v[80:81]
	v_lshl_add_u64 v[80:81], v[80:81], 0, v[136:137]
	v_pk_mul_f32 v[82:83], v[66:67], s[34:35] op_sel_hi:[1,0]
	v_pk_mul_f32 v[66:67], v[64:65], s[34:35] op_sel_hi:[1,0]
	v_cvt_pk_bf16_f32 v64, v68, v69
	v_cvt_pk_bf16_f32 v65, v70, v71
	v_pk_mul_f32 v[36:37], v[36:37], s[34:35] op_sel_hi:[1,0]
	v_cvt_pk_bf16_f32 v66, v66, v67
	v_cvt_pk_bf16_f32 v67, v82, v83
	global_store_dwordx4 v[80:81], v[64:67], off sc0 nt
	v_pk_mul_f32 v[38:39], v[38:39], s[34:35] op_sel_hi:[1,0]
	v_pk_mul_f32 v[30:31], v[30:31], s[34:35] op_sel_hi:[1,0]
	v_pk_mul_f32 v[64:65], v[50:51], s[34:35] op_sel_hi:[1,0]
	v_pk_mul_f32 v[50:51], v[48:49], s[34:35] op_sel_hi:[1,0]
	v_cvt_pk_bf16_f32 v48, v52, v53
	v_cvt_pk_bf16_f32 v49, v54, v55
	v_pk_mul_f32 v[54:55], v[74:75], s[34:35] op_sel_hi:[1,0]
	v_cvt_pk_bf16_f32 v50, v50, v51
	v_cvt_pk_bf16_f32 v51, v64, v65
	global_store_dwordx4 v[80:81], v[48:51], off offset:256 sc0 nt
	v_pk_mul_f32 v[64:65], v[72:73], s[34:35] op_sel_hi:[1,0]
	v_pk_mul_f32 v[28:29], v[28:29], s[34:35] op_sel_hi:[1,0]
	v_add_u32_e32 v48, 0x80, v134
	v_ashrrev_i32_e32 v49, 31, v48
	v_lshlrev_b64 v[48:49], 11, v[48:49]
	v_lshl_add_u64 v[48:49], s[8:9], 0, v[48:49]
	v_lshl_add_u64 v[52:53], v[48:49], 0, v[136:137]
	v_pk_mul_f32 v[48:49], v[76:77], s[34:35] op_sel_hi:[1,0]
	v_pk_mul_f32 v[50:51], v[78:79], s[34:35] op_sel_hi:[1,0]
	v_cvt_pk_bf16_f32 v48, v48, v49
	v_pk_mul_f32 v[20:21], v[20:21], s[34:35] op_sel_hi:[1,0]
	v_cvt_pk_bf16_f32 v49, v50, v51
	v_cvt_pk_bf16_f32 v50, v64, v65
	v_cvt_pk_bf16_f32 v51, v54, v55
	global_store_dwordx4 v[52:53], v[48:51], off sc0 nt
	v_pk_mul_f32 v[54:55], v[58:59], s[34:35] op_sel_hi:[1,0]
	v_pk_mul_f32 v[22:23], v[22:23], s[34:35] op_sel_hi:[1,0]
	v_pk_mul_f32 v[48:49], v[60:61], s[34:35] op_sel_hi:[1,0]
	v_pk_mul_f32 v[50:51], v[62:63], s[34:35] op_sel_hi:[1,0]
	v_cvt_pk_bf16_f32 v48, v48, v49
	v_pk_mul_f32 v[14:15], v[14:15], s[34:35] op_sel_hi:[1,0]
	v_cvt_pk_bf16_f32 v49, v50, v51
	v_cvt_pk_bf16_f32 v50, v56, v57
	v_cvt_pk_bf16_f32 v51, v54, v55
	global_store_dwordx4 v[52:53], v[48:51], off offset:256 sc0 nt
	v_pk_mul_f32 v[12:13], v[12:13], s[34:35] op_sel_hi:[1,0]
	s_andn2_b64 vcc, exec, s[42:43]
	v_add_u32_e32 v48, 0x90, v134
	v_ashrrev_i32_e32 v49, 31, v48
	v_lshlrev_b64 v[48:49], 11, v[48:49]
	v_lshl_add_u64 v[48:49], s[8:9], 0, v[48:49]
	v_lshl_add_u64 v[48:49], v[48:49], 0, v[136:137]
	v_pk_mul_f32 v[50:51], v[42:43], s[34:35] op_sel_hi:[1,0]
	v_pk_mul_f32 v[42:43], v[40:41], s[34:35] op_sel_hi:[1,0]
	v_cvt_pk_bf16_f32 v40, v44, v45
	v_cvt_pk_bf16_f32 v41, v46, v47
	v_mov_b32_e32 v196, v251
	v_cvt_pk_bf16_f32 v42, v42, v43
	v_cvt_pk_bf16_f32 v43, v50, v51
	global_store_dwordx4 v[48:49], v[40:43], off sc0 nt
	v_mov_b32_e32 v251, v250
	v_mov_b32_e32 v250, v204
	v_pk_mul_f32 v[40:41], v[34:35], s[34:35] op_sel_hi:[1,0]
	v_pk_mul_f32 v[34:35], v[32:33], s[34:35] op_sel_hi:[1,0]
	v_cvt_pk_bf16_f32 v32, v36, v37
	v_cvt_pk_bf16_f32 v33, v38, v39
	v_pk_mul_f32 v[6:7], v[6:7], s[34:35] op_sel_hi:[1,0]
	v_cvt_pk_bf16_f32 v34, v34, v35
	v_cvt_pk_bf16_f32 v35, v40, v41
	global_store_dwordx4 v[48:49], v[32:35], off offset:256 sc0 nt
	v_pk_mul_f32 v[4:5], v[4:5], s[34:35] op_sel_hi:[1,0]
	s_nop 0
	v_add_u32_e32 v32, 0xa0, v134
	v_ashrrev_i32_e32 v33, 31, v32
	v_lshlrev_b64 v[32:33], 11, v[32:33]
	v_lshl_add_u64 v[32:33], s[8:9], 0, v[32:33]
	v_lshl_add_u64 v[32:33], v[32:33], 0, v[136:137]
	v_pk_mul_f32 v[34:35], v[26:27], s[34:35] op_sel_hi:[1,0]
	v_pk_mul_f32 v[26:27], v[24:25], s[34:35] op_sel_hi:[1,0]
	v_cvt_pk_bf16_f32 v24, v28, v29
	v_cvt_pk_bf16_f32 v25, v30, v31
	s_nop 0
	v_cvt_pk_bf16_f32 v26, v26, v27
	v_cvt_pk_bf16_f32 v27, v34, v35
	global_store_dwordx4 v[32:33], v[24:27], off sc0 nt
	s_nop 1
	v_pk_mul_f32 v[24:25], v[18:19], s[34:35] op_sel_hi:[1,0]
	v_pk_mul_f32 v[18:19], v[16:17], s[34:35] op_sel_hi:[1,0]
	v_cvt_pk_bf16_f32 v16, v20, v21
	v_cvt_pk_bf16_f32 v17, v22, v23
	s_nop 0
	v_cvt_pk_bf16_f32 v18, v18, v19
	v_cvt_pk_bf16_f32 v19, v24, v25
	global_store_dwordx4 v[32:33], v[16:19], off offset:256 sc0 nt
	s_nop 1
	v_add_u32_e32 v16, 0xb0, v134
	v_ashrrev_i32_e32 v17, 31, v16
	v_lshlrev_b64 v[16:17], 11, v[16:17]
	v_lshl_add_u64 v[16:17], s[8:9], 0, v[16:17]
	v_lshl_add_u64 v[16:17], v[16:17], 0, v[136:137]
	v_pk_mul_f32 v[18:19], v[10:11], s[34:35] op_sel_hi:[1,0]
	v_pk_mul_f32 v[10:11], v[8:9], s[34:35] op_sel_hi:[1,0]
	v_cvt_pk_bf16_f32 v8, v12, v13
	v_cvt_pk_bf16_f32 v9, v14, v15
	s_mov_b64 s[8:9], -1
	v_cvt_pk_bf16_f32 v10, v10, v11
	v_cvt_pk_bf16_f32 v11, v18, v19
	global_store_dwordx4 v[16:17], v[8:11], off sc0 nt
	s_nop 1
	v_pk_mul_f32 v[8:9], v[2:3], s[34:35] op_sel_hi:[1,0]
	v_pk_mul_f32 v[2:3], v[0:1], s[34:35] op_sel_hi:[1,0]
	v_cvt_pk_bf16_f32 v0, v4, v5
	v_cvt_pk_bf16_f32 v1, v6, v7
	s_nop 0
	v_cvt_pk_bf16_f32 v2, v2, v3
	v_cvt_pk_bf16_f32 v3, v8, v9
	global_store_dwordx4 v[16:17], v[0:3], off offset:256 sc0 nt
	s_cbranch_vccnz .LBB0_669
	s_andn2_b64 vcc, exec, s[46:47]
	s_cbranch_vccnz .LBB0_668
	s_barrier
	s_branch .LBB0_668

.LBB0_696:
	s_mov_b32 s8, -1
	s_getreg_b32 s9, hwreg(HW_REG_HW_ID, 0, 6)
	s_and_b32 s9, s9, 63
	s_lshl_b32 s9, s9, 2
	s_add_i32 s9, s9, 0
	s_add_i32 s9, s9, 0x20200
	v_mov_b32_e32 v136, s9
	ds_read_b32 v136, v136
	v_mbcnt_lo_u32_b32 v137, s8, 0
	v_mbcnt_hi_u32_b32 v137, s8, v137
	s_lshl_b32 s9, s56, 8
	v_mov_b32_e32 v250, v252
	s_waitcnt lgkmcnt(0)
	v_readfirstlane_b32 s8, v136
	v_mov_b32_e32 v251, 0x260
	v_mov_b32_e32 v252, 0x3e000000
	v_lshl_add_u32 v136, s8, 6, v137
	v_cvt_pk_bf16_f32 v120, v120, v121
	v_cvt_pk_bf16_f32 v121, v122, v123
	v_cvt_pk_bf16_f32 v122, v112, v113
	v_cvt_pk_bf16_f32 v123, v114, v115
	v_mov_b32_e32 v198, 0x3eaaaaab
	v_readfirstlane_b32 s8, v136
	s_ashr_i32 s10, s8, 2
	s_lshr_b32 s8, s8, 1
	s_and_b32 s8, s8, 0x60
	v_lshrrev_b32_e32 v137, 1, v136
	s_andn2_b32 s10, s10, 63
	v_and_or_b32 v140, v137, 24, s8
	v_and_or_b32 v136, v136, 15, s9
	s_lshl_b32 s8, s55, 4
	v_add_u32_e32 v142, s10, v136
	s_and_b32 s10, s8, 0xffffff00
	s_lshl_b32 s8, s55, 21
	s_ashr_i32 s11, s10, 31
	s_and_b32 s8, s8, 0x1e00000
	v_ashrrev_i32_e32 v143, 31, v142
	s_add_u32 s8, s16, s8
	s_addc_u32 s9, s17, 0
	v_lshlrev_b64 v[136:137], 11, v[142:143]
	v_lshl_add_u64 v[136:137], s[8:9], 0, v[136:137]
	s_lshl_b64 s[10:11], s[10:11], 1
	v_lshl_add_u64 v[136:137], v[136:137], 0, s[10:11]
	v_lshlrev_b32_e32 v140, 1, v140
	v_lshl_add_u64 v[136:137], v[136:137], 0, v[140:141]
	global_store_dwordx4 v[136:137], v[120:123], off sc0 nt
	v_cvt_pk_bf16_f32 v112, v124, v125
	v_cvt_pk_bf16_f32 v113, v126, v127
	v_cvt_pk_bf16_f32 v114, v116, v117
	v_cvt_pk_bf16_f32 v115, v118, v119
	global_store_dwordx4 v[136:137], v[112:115], off offset:256 sc0 nt
	v_cvt_pk_bf16_f32 v104, v104, v105
	v_cvt_pk_bf16_f32 v105, v106, v107
	v_cvt_pk_bf16_f32 v106, v96, v97
	v_cvt_pk_bf16_f32 v107, v98, v99
	v_mov_b32_e32 v199, 0x3e800000
	s_nop 0
	v_or_b32_e32 v112, 16, v142
	v_ashrrev_i32_e32 v113, 31, v112
	v_lshlrev_b64 v[112:113], 11, v[112:113]
	v_lshl_add_u64 v[112:113], s[8:9], 0, v[112:113]
	v_lshl_add_u64 v[112:113], v[112:113], 0, s[10:11]
	v_lshl_add_u64 v[112:113], v[112:113], 0, v[140:141]
	global_store_dwordx4 v[112:113], v[104:107], off sc0 nt
	v_cvt_pk_bf16_f32 v96, v108, v109
	v_cvt_pk_bf16_f32 v97, v110, v111
	v_cvt_pk_bf16_f32 v98, v100, v101
	v_cvt_pk_bf16_f32 v99, v102, v103
	global_store_dwordx4 v[112:113], v[96:99], off offset:256 sc0 nt
	v_cvt_pk_bf16_f32 v88, v88, v89
	v_cvt_pk_bf16_f32 v89, v90, v91
	v_cvt_pk_bf16_f32 v90, v80, v81
	v_cvt_pk_bf16_f32 v91, v82, v83
	v_mov_b32_e32 v204, 0x3e4ccccd
	s_nop 0
	v_or_b32_e32 v96, 32, v142
	v_ashrrev_i32_e32 v97, 31, v96
	v_lshlrev_b64 v[96:97], 11, v[96:97]
	v_lshl_add_u64 v[96:97], s[8:9], 0, v[96:97]
	v_lshl_add_u64 v[96:97], v[96:97], 0, s[10:11]
	v_lshl_add_u64 v[96:97], v[96:97], 0, v[140:141]
	global_store_dwordx4 v[96:97], v[88:91], off sc0 nt
	v_cvt_pk_bf16_f32 v80, v92, v93
	v_cvt_pk_bf16_f32 v81, v94, v95
	v_cvt_pk_bf16_f32 v82, v84, v85
	v_cvt_pk_bf16_f32 v83, v86, v87
	global_store_dwordx4 v[96:97], v[80:83], off offset:256 sc0 nt
	v_cvt_pk_bf16_f32 v56, v56, v57
	v_cvt_pk_bf16_f32 v57, v58, v59
	v_cvt_pk_bf16_f32 v58, v48, v49
	v_cvt_pk_bf16_f32 v59, v50, v51
	v_mov_b32_e32 v205, 0x3e2aaaab
	s_nop 0
	v_or_b32_e32 v80, 48, v142
	v_ashrrev_i32_e32 v81, 31, v80
	v_lshlrev_b64 v[80:81], 11, v[80:81]
	v_lshl_add_u64 v[80:81], s[8:9], 0, v[80:81]
	v_lshl_add_u64 v[80:81], v[80:81], 0, s[10:11]
	v_lshl_add_u64 v[80:81], v[80:81], 0, v[140:141]
	global_store_dwordx4 v[80:81], v[56:59], off sc0 nt
	v_cvt_pk_bf16_f32 v48, v60, v61
	v_cvt_pk_bf16_f32 v49, v62, v63
	v_cvt_pk_bf16_f32 v50, v52, v53
	v_cvt_pk_bf16_f32 v51, v54, v55
	s_mov_b64 s[8:9], 0x40000
	v_add_co_u32_e32 v54, vcc, s2, v136
	global_store_dwordx4 v[80:81], v[48:51], off offset:256 sc0 nt
	v_lshl_add_u64 v[52:53], v[136:137], 0, s[8:9]
	v_addc_co_u32_e32 v55, vcc, 0, v137, vcc
	v_cvt_pk_bf16_f32 v48, v76, v77
	v_cvt_pk_bf16_f32 v49, v78, v79
	v_cvt_pk_bf16_f32 v50, v68, v69
	v_cvt_pk_bf16_f32 v51, v70, v71
	global_store_dwordx4 v[54:55], v[48:51], off sc0 nt
	s_mov_b64 s[8:9], 0x48000
	v_mov_b32_e32 v196, 0x3e124925
	v_cvt_pk_bf16_f32 v48, v72, v73
	v_cvt_pk_bf16_f32 v49, v74, v75
	v_cvt_pk_bf16_f32 v50, v64, v65
	v_cvt_pk_bf16_f32 v51, v66, v67
	global_store_dwordx4 v[52:53], v[48:51], off offset:256 sc0 nt
	v_cvt_pk_bf16_f32 v44, v44, v45
	v_cvt_pk_bf16_f32 v45, v46, v47
	v_cvt_pk_bf16_f32 v46, v36, v37
	v_add_co_u32_e32 v36, vcc, s3, v136
	s_nop 0
	v_lshl_add_u64 v[48:49], v[136:137], 0, s[8:9]
	v_addc_co_u32_e32 v37, vcc, 0, v137, vcc
	v_cvt_pk_bf16_f32 v47, v38, v39
	global_store_dwordx4 v[36:37], v[44:47], off sc0 nt
	v_cvt_pk_bf16_f32 v36, v40, v41
	v_cvt_pk_bf16_f32 v37, v42, v43
	v_cvt_pk_bf16_f32 v38, v32, v33
	v_cvt_pk_bf16_f32 v39, v34, v35
	global_store_dwordx4 v[48:49], v[36:39], off offset:256 sc0 nt
	s_mov_b64 s[8:9], 0x50000
	v_cvt_pk_bf16_f32 v28, v28, v29
	v_cvt_pk_bf16_f32 v29, v30, v31
	v_cvt_pk_bf16_f32 v30, v20, v21
	v_add_co_u32_e32 v20, vcc, s71, v136
	v_lshl_add_u64 v[32:33], v[136:137], 0, s[8:9]
	s_nop 0
	v_addc_co_u32_e32 v21, vcc, 0, v137, vcc
	v_cvt_pk_bf16_f32 v31, v22, v23
	global_store_dwordx4 v[20:21], v[28:31], off sc0 nt
	v_cvt_pk_bf16_f32 v20, v24, v25
	v_cvt_pk_bf16_f32 v21, v26, v27
	v_cvt_pk_bf16_f32 v22, v16, v17
	v_cvt_pk_bf16_f32 v23, v18, v19
	global_store_dwordx4 v[32:33], v[20:23], off offset:256 sc0 nt
	v_cvt_pk_bf16_f32 v12, v12, v13
	v_cvt_pk_bf16_f32 v13, v14, v15
	v_cvt_pk_bf16_f32 v14, v4, v5
	v_add_co_u32_e32 v4, vcc, s72, v136
	s_mov_b64 s[8:9], 0x58000
	s_nop 0
	v_addc_co_u32_e32 v5, vcc, 0, v137, vcc
	v_lshl_add_u64 v[16:17], v[136:137], 0, s[8:9]
	s_andn2_b64 vcc, exec, s[40:41]
	s_mov_b64 s[8:9], -1
	v_cvt_pk_bf16_f32 v15, v6, v7
	global_store_dwordx4 v[4:5], v[12:15], off sc0 nt
	v_cvt_pk_bf16_f32 v4, v8, v9
	v_cvt_pk_bf16_f32 v5, v10, v11
	v_cvt_pk_bf16_f32 v6, v0, v1
	v_cvt_pk_bf16_f32 v7, v2, v3
	global_store_dwordx4 v[16:17], v[4:7], off offset:256 sc0 nt
	s_cbranch_vccnz .LBB0_687
	s_andn2_b64 vcc, exec, s[6:7]
	s_cbranch_vccnz .LBB0_686
	s_barrier
	s_branch .LBB0_686

.LBB0_717:
	s_mov_b32 s6, -1
	s_lshl_b32 s5, s5, 8
	v_mbcnt_lo_u32_b32 v138, s6, 0
	v_mbcnt_hi_u32_b32 v138, s6, v138
	s_getreg_b32 s6, hwreg(HW_REG_HW_ID, 0, 6)
	s_and_b32 s6, s6, 63
	s_lshl_b32 s6, s6, 2
	s_add_i32 s6, s6, 0
	s_add_i32 s6, s6, 0x20200
	v_mov_b32_e32 v139, s6
	ds_read_b32 v139, v139
	s_lshl_b32 s4, s4, 8
	s_waitcnt lgkmcnt(0)
	v_readfirstlane_b32 s6, v139
	s_nop 1
	v_lshl_add_u32 v139, s6, 6, v138
	s_nop 0
	v_readfirstlane_b32 s6, v139
	s_ashr_i32 s7, s6, 2
	s_andn2_b32 s7, s7, 63
	v_lshrrev_b32_e32 v138, 1, v139
	v_and_or_b32 v139, v139, 15, s5
	v_add_u32_e32 v162, s7, v139
	v_ashrrev_i32_e32 v163, 31, v162
	v_lshl_add_u64 v[158:159], v[162:163], 2, s[44:45]
	global_load_dword v142, v[158:159], off
	s_lshr_b32 s6, s6, 1
	s_and_b32 s6, s6, 0x60
	s_or_b32 s4, s6, s4
	v_and_or_b32 v138, v138, 24, s4
	v_ashrrev_i32_e32 v139, 31, v138
	v_lshlrev_b64 v[144:145], 14, v[162:163]
	v_lshl_add_u64 v[144:145], s[64:65], 0, v[144:145]
	v_lshlrev_b64 v[160:161], 1, v[138:139]
	v_lshl_add_u64 v[138:139], v[144:145], 0, v[160:161]
	s_mov_b64 s[4:5], 0x200000
	s_mov_b64 s[6:7], -1
	s_waitcnt vmcnt(0)
	v_pk_mul_f32 v[126:127], v[126:127], v[142:143] op_sel_hi:[1,0]
	v_pk_mul_f32 v[124:125], v[124:125], v[142:143] op_sel_hi:[1,0]
	v_pk_mul_f32 v[144:145], v[122:123], v[142:143] op_sel_hi:[1,0]
	v_pk_mul_f32 v[122:123], v[120:121], v[142:143] op_sel_hi:[1,0]
	v_cvt_pk_bf16_f32 v120, v124, v125
	v_cvt_pk_bf16_f32 v121, v126, v127
	v_pk_mul_f32 v[116:117], v[116:117], v[142:143] op_sel_hi:[1,0]
	v_cvt_pk_bf16_f32 v122, v122, v123
	v_cvt_pk_bf16_f32 v123, v144, v145
	global_store_dwordx4 v[138:139], v[120:123], off sc0 nt
	v_pk_mul_f32 v[118:119], v[118:119], v[142:143] op_sel_hi:[1,0]
	s_nop 0
	v_pk_mul_f32 v[120:121], v[114:115], v[142:143] op_sel_hi:[1,0]
	v_pk_mul_f32 v[114:115], v[112:113], v[142:143] op_sel_hi:[1,0]
	v_cvt_pk_bf16_f32 v112, v116, v117
	v_cvt_pk_bf16_f32 v113, v118, v119
	s_nop 0
	v_cvt_pk_bf16_f32 v114, v114, v115
	v_cvt_pk_bf16_f32 v115, v120, v121
	global_store_dwordx4 v[138:139], v[112:115], off offset:256 sc0 nt
	s_nop 1
	v_or_b32_e32 v112, 16, v162
	v_ashrrev_i32_e32 v113, 31, v112
	v_lshl_add_u64 v[114:115], v[112:113], 2, s[44:45]
	global_load_dword v114, v[114:115], off
	v_lshlrev_b64 v[112:113], 14, v[112:113]
	v_lshl_add_u64 v[112:113], s[64:65], 0, v[112:113]
	v_lshl_add_u64 v[112:113], v[112:113], 0, v[160:161]
	s_waitcnt vmcnt(0)
	v_pk_mul_f32 v[110:111], v[110:111], v[114:115] op_sel_hi:[1,0]
	v_pk_mul_f32 v[108:109], v[108:109], v[114:115] op_sel_hi:[1,0]
	v_pk_mul_f32 v[116:117], v[106:107], v[114:115] op_sel_hi:[1,0]
	v_pk_mul_f32 v[106:107], v[104:105], v[114:115] op_sel_hi:[1,0]
	v_cvt_pk_bf16_f32 v104, v108, v109
	v_cvt_pk_bf16_f32 v105, v110, v111
	v_pk_mul_f32 v[100:101], v[100:101], v[114:115] op_sel_hi:[1,0]
	v_cvt_pk_bf16_f32 v106, v106, v107
	v_cvt_pk_bf16_f32 v107, v116, v117
	global_store_dwordx4 v[112:113], v[104:107], off sc0 nt
	v_pk_mul_f32 v[102:103], v[102:103], v[114:115] op_sel_hi:[1,0]
	s_nop 0
	v_pk_mul_f32 v[104:105], v[98:99], v[114:115] op_sel_hi:[1,0]
	v_pk_mul_f32 v[98:99], v[96:97], v[114:115] op_sel_hi:[1,0]
	v_cvt_pk_bf16_f32 v96, v100, v101
	v_cvt_pk_bf16_f32 v97, v102, v103
	s_nop 0
	v_cvt_pk_bf16_f32 v98, v98, v99
	v_cvt_pk_bf16_f32 v99, v104, v105
	global_store_dwordx4 v[112:113], v[96:99], off offset:256 sc0 nt
	s_nop 1
	v_or_b32_e32 v96, 32, v162
	v_ashrrev_i32_e32 v97, 31, v96
	v_lshl_add_u64 v[98:99], v[96:97], 2, s[44:45]
	global_load_dword v98, v[98:99], off
	v_lshlrev_b64 v[96:97], 14, v[96:97]
	v_lshl_add_u64 v[96:97], s[64:65], 0, v[96:97]
	v_lshl_add_u64 v[96:97], v[96:97], 0, v[160:161]
	s_waitcnt vmcnt(0)
	v_pk_mul_f32 v[94:95], v[94:95], v[98:99] op_sel_hi:[1,0]
	v_pk_mul_f32 v[92:93], v[92:93], v[98:99] op_sel_hi:[1,0]
	v_pk_mul_f32 v[100:101], v[90:91], v[98:99] op_sel_hi:[1,0]
	v_pk_mul_f32 v[90:91], v[88:89], v[98:99] op_sel_hi:[1,0]
	v_cvt_pk_bf16_f32 v88, v92, v93
	v_cvt_pk_bf16_f32 v89, v94, v95
	v_pk_mul_f32 v[84:85], v[84:85], v[98:99] op_sel_hi:[1,0]
	v_cvt_pk_bf16_f32 v90, v90, v91
	v_cvt_pk_bf16_f32 v91, v100, v101
	global_store_dwordx4 v[96:97], v[88:91], off sc0 nt
	v_pk_mul_f32 v[86:87], v[86:87], v[98:99] op_sel_hi:[1,0]
	s_nop 0
	v_pk_mul_f32 v[88:89], v[82:83], v[98:99] op_sel_hi:[1,0]
	v_pk_mul_f32 v[82:83], v[80:81], v[98:99] op_sel_hi:[1,0]
	v_cvt_pk_bf16_f32 v80, v84, v85
	v_cvt_pk_bf16_f32 v81, v86, v87
	s_nop 0
	v_cvt_pk_bf16_f32 v82, v82, v83
	v_cvt_pk_bf16_f32 v83, v88, v89
	global_store_dwordx4 v[96:97], v[80:83], off offset:256 sc0 nt
	s_nop 1
	v_or_b32_e32 v80, 48, v162
	v_ashrrev_i32_e32 v81, 31, v80
	v_lshl_add_u64 v[82:83], v[80:81], 2, s[44:45]
	global_load_dword v82, v[82:83], off
	v_lshlrev_b64 v[80:81], 14, v[80:81]
	v_lshl_add_u64 v[80:81], s[64:65], 0, v[80:81]
	v_lshl_add_u64 v[80:81], v[80:81], 0, v[160:161]
	s_waitcnt vmcnt(0)
	v_pk_mul_f32 v[78:79], v[78:79], v[82:83] op_sel_hi:[1,0]
	v_pk_mul_f32 v[76:77], v[76:77], v[82:83] op_sel_hi:[1,0]
	v_pk_mul_f32 v[84:85], v[74:75], v[82:83] op_sel_hi:[1,0]
	v_pk_mul_f32 v[74:75], v[72:73], v[82:83] op_sel_hi:[1,0]
	v_cvt_pk_bf16_f32 v72, v76, v77
	v_cvt_pk_bf16_f32 v73, v78, v79
	v_pk_mul_f32 v[70:71], v[70:71], v[82:83] op_sel_hi:[1,0]
	v_cvt_pk_bf16_f32 v74, v74, v75
	v_cvt_pk_bf16_f32 v75, v84, v85
	global_store_dwordx4 v[80:81], v[72:75], off sc0 nt
	v_pk_mul_f32 v[68:69], v[68:69], v[82:83] op_sel_hi:[1,0]
	s_nop 0
	v_pk_mul_f32 v[72:73], v[66:67], v[82:83] op_sel_hi:[1,0]
	v_pk_mul_f32 v[66:67], v[64:65], v[82:83] op_sel_hi:[1,0]
	v_cvt_pk_bf16_f32 v64, v68, v69
	v_cvt_pk_bf16_f32 v65, v70, v71
	s_nop 0
	v_cvt_pk_bf16_f32 v66, v66, v67
	v_cvt_pk_bf16_f32 v67, v72, v73
	global_store_dwordx4 v[80:81], v[64:67], off offset:256 sc0 nt
	global_load_dword v64, v[158:159], off offset:512
	s_waitcnt vmcnt(0)
	v_pk_mul_f32 v[60:61], v[60:61], v[64:65] op_sel_hi:[1,0]
	v_lshl_add_u64 v[66:67], v[138:139], 0, s[4:5]
	s_mov_b32 s4, 0x200000
	v_pk_mul_f32 v[68:69], v[58:59], v[64:65] op_sel_hi:[1,0]
	v_pk_mul_f32 v[58:59], v[56:57], v[64:65] op_sel_hi:[1,0]
	v_cvt_pk_bf16_f32 v56, v60, v61
	v_add_co_u32_e32 v60, vcc, s4, v138
	v_pk_mul_f32 v[62:63], v[62:63], v[64:65] op_sel_hi:[1,0]
	s_nop 0
	v_addc_co_u32_e32 v61, vcc, 0, v139, vcc
	v_cvt_pk_bf16_f32 v57, v62, v63
	v_cvt_pk_bf16_f32 v58, v58, v59
	v_cvt_pk_bf16_f32 v59, v68, v69
	global_store_dwordx4 v[60:61], v[56:59], off sc0 nt
	v_pk_mul_f32 v[54:55], v[54:55], v[64:65] op_sel_hi:[1,0]
	v_pk_mul_f32 v[52:53], v[52:53], v[64:65] op_sel_hi:[1,0]
	v_pk_mul_f32 v[56:57], v[50:51], v[64:65] op_sel_hi:[1,0]
	v_pk_mul_f32 v[50:51], v[48:49], v[64:65] op_sel_hi:[1,0]
	v_cvt_pk_bf16_f32 v48, v52, v53
	v_cvt_pk_bf16_f32 v49, v54, v55
	s_mov_b64 s[4:5], 0x240000
	v_cvt_pk_bf16_f32 v50, v50, v51
	v_cvt_pk_bf16_f32 v51, v56, v57
	global_store_dwordx4 v[66:67], v[48:51], off offset:256 sc0 nt
	global_load_dword v48, v[158:159], off offset:576
	s_waitcnt vmcnt(0)
	v_pk_mul_f32 v[44:45], v[44:45], v[48:49] op_sel_hi:[1,0]
	v_lshl_add_u64 v[50:51], v[138:139], 0, s[4:5]
	s_mov_b32 s4, 0x240000
	v_pk_mul_f32 v[52:53], v[42:43], v[48:49] op_sel_hi:[1,0]
	v_pk_mul_f32 v[42:43], v[40:41], v[48:49] op_sel_hi:[1,0]
	v_cvt_pk_bf16_f32 v40, v44, v45
	v_add_co_u32_e32 v44, vcc, s4, v138
	v_pk_mul_f32 v[46:47], v[46:47], v[48:49] op_sel_hi:[1,0]
	s_nop 0
	v_addc_co_u32_e32 v45, vcc, 0, v139, vcc
	v_cvt_pk_bf16_f32 v41, v46, v47
	v_cvt_pk_bf16_f32 v42, v42, v43
	v_cvt_pk_bf16_f32 v43, v52, v53
	global_store_dwordx4 v[44:45], v[40:43], off sc0 nt
	v_pk_mul_f32 v[38:39], v[38:39], v[48:49] op_sel_hi:[1,0]
	v_pk_mul_f32 v[36:37], v[36:37], v[48:49] op_sel_hi:[1,0]
	v_pk_mul_f32 v[40:41], v[34:35], v[48:49] op_sel_hi:[1,0]
	v_pk_mul_f32 v[34:35], v[32:33], v[48:49] op_sel_hi:[1,0]
	v_cvt_pk_bf16_f32 v32, v36, v37
	v_cvt_pk_bf16_f32 v33, v38, v39
	s_mov_b64 s[4:5], 0x280000
	v_cvt_pk_bf16_f32 v34, v34, v35
	v_cvt_pk_bf16_f32 v35, v40, v41
	global_store_dwordx4 v[50:51], v[32:35], off offset:256 sc0 nt
	global_load_dword v32, v[158:159], off offset:640
	s_waitcnt vmcnt(0)
	v_pk_mul_f32 v[28:29], v[28:29], v[32:33] op_sel_hi:[1,0]
	v_lshl_add_u64 v[34:35], v[138:139], 0, s[4:5]
	s_mov_b32 s4, 0x280000
	v_pk_mul_f32 v[36:37], v[26:27], v[32:33] op_sel_hi:[1,0]
	v_pk_mul_f32 v[26:27], v[24:25], v[32:33] op_sel_hi:[1,0]
	v_cvt_pk_bf16_f32 v24, v28, v29
	v_add_co_u32_e32 v28, vcc, s4, v138
	v_pk_mul_f32 v[30:31], v[30:31], v[32:33] op_sel_hi:[1,0]
	s_nop 0
	v_addc_co_u32_e32 v29, vcc, 0, v139, vcc
	v_cvt_pk_bf16_f32 v25, v30, v31
	v_cvt_pk_bf16_f32 v26, v26, v27
	v_cvt_pk_bf16_f32 v27, v36, v37
	global_store_dwordx4 v[28:29], v[24:27], off sc0 nt
	v_pk_mul_f32 v[22:23], v[22:23], v[32:33] op_sel_hi:[1,0]
	v_pk_mul_f32 v[20:21], v[20:21], v[32:33] op_sel_hi:[1,0]
	v_pk_mul_f32 v[24:25], v[18:19], v[32:33] op_sel_hi:[1,0]
	v_pk_mul_f32 v[18:19], v[16:17], v[32:33] op_sel_hi:[1,0]
	v_cvt_pk_bf16_f32 v16, v20, v21
	v_cvt_pk_bf16_f32 v17, v22, v23
	s_mov_b64 s[4:5], 0x2c0000
	v_cvt_pk_bf16_f32 v18, v18, v19
	v_cvt_pk_bf16_f32 v19, v24, v25
	global_store_dwordx4 v[34:35], v[16:19], off offset:256 sc0 nt
	global_load_dword v16, v[158:159], off offset:704
	s_waitcnt vmcnt(0)
	v_pk_mul_f32 v[12:13], v[12:13], v[16:17] op_sel_hi:[1,0]
	v_lshl_add_u64 v[18:19], v[138:139], 0, s[4:5]
	s_mov_b32 s4, 0x2c0000
	v_pk_mul_f32 v[20:21], v[10:11], v[16:17] op_sel_hi:[1,0]
	v_pk_mul_f32 v[10:11], v[8:9], v[16:17] op_sel_hi:[1,0]
	v_cvt_pk_bf16_f32 v8, v12, v13
	v_add_co_u32_e32 v12, vcc, s4, v138
	v_pk_mul_f32 v[14:15], v[14:15], v[16:17] op_sel_hi:[1,0]
	s_nop 0
	v_addc_co_u32_e32 v13, vcc, 0, v139, vcc
	v_cvt_pk_bf16_f32 v9, v14, v15
	v_cvt_pk_bf16_f32 v10, v10, v11
	v_cvt_pk_bf16_f32 v11, v20, v21
	global_store_dwordx4 v[12:13], v[8:11], off sc0 nt
	s_andn2_b64 vcc, exec, s[40:41]
	v_pk_mul_f32 v[6:7], v[6:7], v[16:17] op_sel_hi:[1,0]
	v_pk_mul_f32 v[8:9], v[2:3], v[16:17] op_sel_hi:[1,0]
	v_pk_mul_f32 v[2:3], v[0:1], v[16:17] op_sel_hi:[1,0]
	v_pk_mul_f32 v[4:5], v[4:5], v[16:17] op_sel_hi:[1,0]
	s_nop 0
	v_cvt_pk_bf16_f32 v0, v4, v5
	v_cvt_pk_bf16_f32 v1, v6, v7
	v_cvt_pk_bf16_f32 v2, v2, v3
	v_cvt_pk_bf16_f32 v3, v8, v9
	global_store_dwordx4 v[18:19], v[0:3], off offset:256 sc0 nt
	s_cbranch_vccnz .LBB0_706
	s_andn2_b64 vcc, exec, s[42:43]
	s_cbranch_vccnz .LBB0_705
	s_barrier
	s_branch .LBB0_705
